# v40: v39 plus removal of 363 register-init moves ahead of fp8 pack pairs (both halves written before any read); s_nop kept between lo/hi pack where they became adjacent
# baseline (speedup 1.0000x reference)
.LBB0_213:
	s_mul_hi_i32 s0, s18, 0x2aaaaaab
	s_lshr_b32 s1, s0, 31
	s_ashr_i32 s0, s0, 8
	s_add_i32 s8, s0, s1
	s_mul_i32 s0, s8, 0xfffffa00
	s_add_i32 s21, s18, s0
	s_lshr_b32 s0, s21, 22
	s_and_b32 s0, s0, 0x1ff
	s_add_i32 s22, s21, s0
	s_and_b32 s0, s22, 0xfe00
	s_sub_i32 s0, s21, s0
	s_sext_i32_i16 s1, s0
	s_bfe_u32 s1, s1, 0x5001a
	s_add_i32 s1, s0, s1
	s_sext_i32_i16 s6, s1
	s_and_b32 s1, s1, 0xffe0
	s_lshl_b32 s20, s6, 1
	s_sub_i32 s0, s0, s1
	s_andn2_b32 s20, s20, 63
	s_sext_i32_i16 s19, s0
	s_lshl_b32 s6, s19, 5
	v_or_b32_e32 v16, s20, v52
	s_mov_b64 s[10:11], -1
	s_cmpk_gt_i32 s21, 0x3ff
	v_ashrrev_i32_e32 v17, 31, v16
	v_or_b32_e32 v14, 8, v16
	v_or_b32_e32 v12, 16, v16
	v_or_b32_e32 v10, 24, v16
	v_or_b32_e32 v8, 32, v16
	v_or_b32_e32 v6, 40, v16
	v_or_b32_e32 v4, 48, v16
	v_or_b32_e32 v2, 56, v16
	s_cbranch_scc0 .LBB0_215
	s_ashr_i32 s9, s8, 31
	s_lshl_b64 s[0:1], s[8:9], 20
	s_lshl_b64 s[10:11], s[8:9], 22
	s_add_u32 s9, s34, s10
	s_addc_u32 s10, s35, s11
	s_add_u32 s11, s5, s0
	s_addc_u32 s23, s16, s1
	s_ashr_i32 s7, s6, 31
	s_lshl_b64 s[0:1], s[6:7], 2
	s_add_u32 s0, s9, s0
	s_addc_u32 s1, s10, s1
	v_lshl_add_u64 v[48:49], v[36:37], 2, s[0:1]
	v_lshlrev_b64 v[28:29], 12, v[16:17]
	v_ashrrev_i32_e32 v15, 31, v14
	v_lshl_add_u64 v[40:41], v[48:49], 0, v[28:29]
	v_lshlrev_b64 v[28:29], 12, v[14:15]
	v_ashrrev_i32_e32 v13, 31, v12
	v_lshl_add_u64 v[42:43], v[48:49], 0, v[28:29]
	global_load_dwordx4 v[28:31], v[40:41], off nt
	global_load_dwordx4 v[32:35], v[42:43], off nt
	v_lshlrev_b64 v[40:41], 12, v[12:13]
	v_ashrrev_i32_e32 v11, 31, v10
	v_lshl_add_u64 v[62:63], v[48:49], 0, v[40:41]
	v_lshlrev_b64 v[40:41], 12, v[10:11]
	v_ashrrev_i32_e32 v9, 31, v8
	v_lshl_add_u64 v[64:65], v[48:49], 0, v[40:41]
	global_load_dwordx4 v[40:43], v[62:63], off nt
	global_load_dwordx4 v[44:47], v[64:65], off nt
	v_lshlrev_b64 v[62:63], 12, v[8:9]
	v_ashrrev_i32_e32 v7, 31, v6
	v_lshl_add_u64 v[70:71], v[48:49], 0, v[62:63]
	v_lshlrev_b64 v[62:63], 12, v[6:7]
	v_lshl_add_u64 v[72:73], v[48:49], 0, v[62:63]
	global_load_dwordx4 v[62:65], v[70:71], off nt
	global_load_dwordx4 v[66:69], v[72:73], off nt
	v_ashrrev_i32_e32 v5, 31, v4
	v_lshlrev_b64 v[70:71], 12, v[4:5]
	v_lshl_add_u64 v[70:71], v[48:49], 0, v[70:71]
	v_ashrrev_i32_e32 v3, 31, v2
	global_load_dwordx4 v[70:73], v[70:71], off nt
	v_lshlrev_b64 v[74:75], 12, v[2:3]
	v_lshl_add_u64 v[48:49], v[48:49], 0, v[74:75]
	global_load_dwordx4 v[74:77], v[48:49], off nt
	v_mov_b32_e32 v48, 0
	v_mov_b32_e32 v49, 0
	s_ashr_i32 s1, s20, 31
	v_or_b32_e32 v78, s6, v52
	s_add_u32 s0, s11, s20
	v_ashrrev_i32_e32 v79, 31, v78
	s_addc_u32 s1, s23, s1
	v_lshlrev_b64 v[78:79], 10, v[78:79]
	v_mov_b32_e32 v80, 0
	v_mov_b32_e32 v81, 0
	s_waitcnt vmcnt(0)
	ds_write2_b32 v57, v28, v29 offset1:1
	ds_write2_b32 v57, v30, v31 offset0:2 offset1:3
	ds_write2_b32 v58, v32, v33 offset1:1
	ds_write2_b32 v58, v34, v35 offset0:2 offset1:3
	ds_write2_b32 v59, v40, v41 offset1:1
	ds_write2_b32 v59, v42, v43 offset0:2 offset1:3
	ds_write2_b32 v60, v44, v45 offset1:1
	ds_write2_b32 v60, v46, v47 offset0:2 offset1:3
	ds_write2_b32 v18, v62, v63 offset1:1
	ds_write2_b32 v19, v64, v65 offset1:1
	ds_write2_b32 v20, v66, v67 offset1:1
	ds_write2_b32 v21, v68, v69 offset1:1
	ds_write2_b32 v22, v70, v71 offset1:1
	ds_write2_b32 v23, v72, v73 offset1:1
	ds_write2_b32 v24, v74, v75 offset1:1
	ds_write2_b32 v25, v76, v77 offset1:1
	s_waitcnt lgkmcnt(0)
	ds_read2_b32 v[28:29], v53 offset1:33
	ds_read2_b32 v[30:31], v53 offset0:66 offset1:99
	ds_read2_b32 v[32:33], v53 offset0:132 offset1:165
	ds_read2_b32 v[34:35], v53 offset0:198 offset1:231
	s_waitcnt lgkmcnt(0)
	v_mul_f32_e32 v7, 0x43000000, v30
	v_mul_f32_e32 v3, 0x43000000, v28
	v_mul_f32_e32 v5, 0x43000000, v29
	v_mul_f32_e32 v11, 0x43000000, v32
	v_mul_f32_e32 v13, 0x43000000, v33
	v_med3_f32 v3, v3, s17, v26
	v_med3_f32 v5, v5, s17, v26
	v_med3_f32 v11, v11, s17, v26
	v_med3_f32 v13, v13, s17, v26
	v_cvt_pk_fp8_f32 v48, v3, v5
	v_cvt_pk_fp8_f32 v49, v11, v13
	v_mul_f32_e32 v9, 0x43000000, v31
	v_mul_f32_e32 v15, 0x43000000, v34
	v_mul_f32_e32 v27, 0x43000000, v35
	v_med3_f32 v7, v7, s17, v26
	v_med3_f32 v9, v9, s17, v26
	v_med3_f32 v3, v15, s17, v26
	v_med3_f32 v5, v27, s17, v26
	v_cvt_pk_fp8_f32 v48, v7, v9 op_sel:[0,0,1]
	v_cvt_pk_fp8_f32 v49, v3, v5 op_sel:[0,0,1]
	v_lshl_add_u64 v[28:29], s[0:1], 0, v[38:39]
	v_lshl_add_u64 v[30:31], v[28:29], 0, v[78:79]
	global_store_dwordx2 v[30:31], v[48:49], off nt
	ds_read2_b32 v[30:31], v54 offset1:33
	ds_read2_b32 v[32:33], v54 offset0:66 offset1:99
	ds_read2_b32 v[34:35], v54 offset0:132 offset1:165
	ds_read2_b32 v[40:41], v54 offset0:198 offset1:231
	s_waitcnt lgkmcnt(0)
	v_mul_f32_e32 v7, 0x43000000, v32
	v_mul_f32_e32 v3, 0x43000000, v30
	v_mul_f32_e32 v5, 0x43000000, v31
	v_mul_f32_e32 v11, 0x43000000, v34
	v_mul_f32_e32 v13, 0x43000000, v35
	v_med3_f32 v3, v3, s17, v26
	v_med3_f32 v5, v5, s17, v26
	v_med3_f32 v11, v11, s17, v26
	v_med3_f32 v13, v13, s17, v26
	v_cvt_pk_fp8_f32 v80, v3, v5
	v_cvt_pk_fp8_f32 v81, v11, v13
	v_mul_f32_e32 v9, 0x43000000, v33
	v_mul_f32_e32 v15, 0x43000000, v40
	v_mul_f32_e32 v27, 0x43000000, v41
	v_med3_f32 v7, v7, s17, v26
	v_med3_f32 v9, v9, s17, v26
	v_med3_f32 v3, v15, s17, v26
	v_med3_f32 v5, v27, s17, v26
	v_cvt_pk_fp8_f32 v80, v7, v9 op_sel:[0,0,1]
	v_cvt_pk_fp8_f32 v81, v3, v5 op_sel:[0,0,1]
	v_or_b32_e32 v30, s6, v1
	v_ashrrev_i32_e32 v31, 31, v30
	v_lshlrev_b64 v[30:31], 10, v[30:31]
	v_lshl_add_u64 v[30:31], v[28:29], 0, v[30:31]
	global_store_dwordx2 v[30:31], v[80:81], off nt
	ds_read2_b32 v[30:31], v55 offset1:33
	ds_read2_b32 v[32:33], v55 offset0:66 offset1:99
	ds_read2_b32 v[34:35], v55 offset0:198 offset1:231
	s_waitcnt lgkmcnt(0)
	v_mul_f32_e32 v3, 0x43000000, v30
	v_mul_f32_e32 v5, 0x43000000, v31
	v_mul_f32_e32 v7, 0x43000000, v32
	v_mul_f32_e32 v9, 0x43000000, v33
	v_med3_f32 v3, v3, s17, v26
	v_med3_f32 v5, v5, s17, v26
	ds_read2_b32 v[32:33], v55 offset0:132 offset1:165
	v_cvt_pk_fp8_f32 v30, v3, v5
	v_med3_f32 v3, v7, s17, v26
	v_med3_f32 v5, v9, s17, v26
	v_cvt_pk_fp8_f32 v30, v3, v5 op_sel:[0,0,1]
	s_waitcnt lgkmcnt(0)
	v_mul_f32_e32 v3, 0x43000000, v32
	v_mul_f32_e32 v5, 0x43000000, v33
	v_med3_f32 v3, v3, s17, v26
	v_med3_f32 v5, v5, s17, v26
	v_cvt_pk_fp8_f32 v31, v3, v5
	v_mul_f32_e32 v7, 0x43000000, v34
	v_mul_f32_e32 v3, 0x43000000, v35
	v_med3_f32 v5, v7, s17, v26
	v_med3_f32 v3, v3, s17, v26
	v_cvt_pk_fp8_f32 v31, v5, v3 op_sel:[0,0,1]
	v_or_b32_e32 v32, s6, v50
	v_ashrrev_i32_e32 v33, 31, v32
	v_lshlrev_b64 v[32:33], 10, v[32:33]
	v_lshl_add_u64 v[32:33], v[28:29], 0, v[32:33]
	global_store_dwordx2 v[32:33], v[30:31], off nt
	ds_read2_b32 v[30:31], v56 offset1:33
	ds_read2_b32 v[32:33], v56 offset0:66 offset1:99
	ds_read2_b32 v[34:35], v56 offset0:198 offset1:231
	s_waitcnt lgkmcnt(0)
	v_mul_f32_e32 v3, 0x43000000, v30
	v_mul_f32_e32 v5, 0x43000000, v31
	v_mul_f32_e32 v7, 0x43000000, v32
	v_mul_f32_e32 v9, 0x43000000, v33
	v_med3_f32 v3, v3, s17, v26
	v_med3_f32 v5, v5, s17, v26
	ds_read2_b32 v[32:33], v56 offset0:132 offset1:165
	v_cvt_pk_fp8_f32 v30, v3, v5
	v_med3_f32 v3, v7, s17, v26
	v_med3_f32 v5, v9, s17, v26
	v_cvt_pk_fp8_f32 v30, v3, v5 op_sel:[0,0,1]
	s_waitcnt lgkmcnt(0)
	v_mul_f32_e32 v3, 0x43000000, v32
	v_mul_f32_e32 v5, 0x43000000, v33
	v_med3_f32 v3, v3, s17, v26
	v_med3_f32 v5, v5, s17, v26
	v_cvt_pk_fp8_f32 v31, v3, v5
	v_mul_f32_e32 v7, 0x43000000, v34
	v_mul_f32_e32 v3, 0x43000000, v35
	v_med3_f32 v5, v7, s17, v26
	v_med3_f32 v3, v3, s17, v26
	v_cvt_pk_fp8_f32 v31, v5, v3 op_sel:[0,0,1]
	v_or_b32_e32 v32, s6, v51
	v_ashrrev_i32_e32 v33, 31, v32
	v_lshlrev_b64 v[32:33], 10, v[32:33]
	v_lshl_add_u64 v[28:29], v[28:29], 0, v[32:33]
	global_store_dwordx2 v[28:29], v[30:31], off nt
	s_waitcnt lgkmcnt(0)
	s_cbranch_execnz .LBB0_212
	s_branch .LBB0_216

.LBB0_216:
	s_sext_i32_i16 s0, s22
	s_lshr_b32 s10, s0, 9
	s_addk_i32 s21, 0x1ff
	s_cmpk_lt_u32 s21, 0x3ff
	s_cselect_b32 s7, s13, s15
	s_cselect_b32 s11, s12, s14
	s_ashr_i32 s9, s8, 31
	s_lshl_b64 s[0:1], s[8:9], 22
	s_add_u32 s11, s11, s0
	s_addc_u32 s21, s7, s1
	s_lshl_b64 s[0:1], s[8:9], 21
	s_add_u32 s8, s3, s0
	s_addc_u32 s9, s4, s1
	s_ashr_i32 s7, s6, 31
	s_lshl_b64 s[0:1], s[6:7], 2
	s_add_u32 s0, s11, s0
	s_addc_u32 s1, s21, s1
	v_ashrrev_i32_e32 v15, 31, v14
	v_ashrrev_i32_e32 v13, 31, v12
	v_ashrrev_i32_e32 v11, 31, v10
	v_ashrrev_i32_e32 v9, 31, v8
	v_lshl_add_u64 v[48:49], v[36:37], 2, s[0:1]
	v_lshlrev_b64 v[16:17], 12, v[16:17]
	v_lshlrev_b64 v[14:15], 12, v[14:15]
	v_lshlrev_b64 v[12:13], 12, v[12:13]
	v_lshlrev_b64 v[10:11], 12, v[10:11]
	v_lshlrev_b64 v[8:9], 12, v[8:9]
	v_ashrrev_i32_e32 v7, 31, v6
	v_lshl_add_u64 v[32:33], v[48:49], 0, v[16:17]
	v_lshl_add_u64 v[34:35], v[48:49], 0, v[14:15]
	v_lshl_add_u64 v[40:41], v[48:49], 0, v[12:13]
	v_lshl_add_u64 v[42:43], v[48:49], 0, v[10:11]
	v_lshl_add_u64 v[44:45], v[48:49], 0, v[8:9]
	v_lshlrev_b64 v[6:7], 12, v[6:7]
	global_load_dwordx4 v[14:17], v[32:33], off nt
	global_load_dwordx4 v[28:31], v[34:35], off nt
	global_load_dwordx4 v[10:13], v[40:41], off nt
	s_nop 0
	global_load_dwordx4 v[32:35], v[42:43], off nt
	v_lshl_add_u64 v[46:47], v[48:49], 0, v[6:7]
	global_load_dwordx4 v[6:9], v[44:45], off nt
	global_load_dwordx4 v[40:43], v[46:47], off nt
	v_ashrrev_i32_e32 v5, 31, v4
	v_lshlrev_b64 v[4:5], 12, v[4:5]
	v_lshl_add_u64 v[4:5], v[48:49], 0, v[4:5]
	v_ashrrev_i32_e32 v3, 31, v2
	global_load_dwordx4 v[44:47], v[4:5], off nt
	v_lshlrev_b64 v[2:3], 12, v[2:3]
	v_lshl_add_u64 v[2:3], v[48:49], 0, v[2:3]
	global_load_dwordx4 v[2:5], v[2:3], off nt
	s_sext_i32_i16 s0, s10
	s_lshl_b32 s7, s0, 7
	s_ashr_i32 s1, s20, 31
	v_mov_b32_e32 v48, 0
	v_mov_b32_e32 v49, 0
	s_add_u32 s0, s8, s20
	s_addc_u32 s1, s9, s1
	s_lshl_b32 s8, s19, 6
	v_lshl_add_u64 v[62:63], s[0:1], 0, v[38:39]
	s_and_b32 s0, s8, 0xffffff00
	s_and_b32 s6, s6, 0x60
	s_add_i32 s0, s0, s7
	s_or_b32 s0, s0, s6
	s_waitcnt vmcnt(0)
	ds_write2_b32 v57, v14, v15 offset1:1
	ds_write2_b32 v57, v16, v17 offset0:2 offset1:3
	ds_write2_b32 v58, v28, v29 offset1:1
	ds_write2_b32 v58, v30, v31 offset0:2 offset1:3
	ds_write2_b32 v59, v10, v11 offset1:1
	ds_write2_b32 v59, v12, v13 offset0:2 offset1:3
	ds_write2_b32 v60, v32, v33 offset1:1
	ds_write2_b32 v60, v34, v35 offset0:2 offset1:3
	ds_write2_b32 v18, v6, v7 offset1:1
	ds_write2_b32 v19, v8, v9 offset1:1
	ds_write2_b32 v20, v40, v41 offset1:1
	ds_write2_b32 v21, v42, v43 offset1:1
	ds_write2_b32 v22, v44, v45 offset1:1
	ds_write2_b32 v23, v46, v47 offset1:1
	ds_write2_b32 v24, v2, v3 offset1:1
	ds_write2_b32 v25, v4, v5 offset1:1
	s_waitcnt lgkmcnt(0)
	ds_read2_b32 v[2:3], v53 offset1:33
	ds_read2_b32 v[6:7], v53 offset0:66 offset1:99
	ds_read2_b32 v[8:9], v53 offset0:132 offset1:165
	ds_read2_b32 v[10:11], v53 offset0:198 offset1:231
	v_or_b32_e32 v4, s0, v52
	s_waitcnt lgkmcnt(0)
	v_mul_f32_e32 v5, 0x42800000, v6
	v_mul_f32_e32 v2, 0x42800000, v2
	v_mul_f32_e32 v3, 0x42800000, v3
	v_mul_f32_e32 v6, 0x42800000, v7
	v_mul_f32_e32 v7, 0x42800000, v8
	v_mul_f32_e32 v8, 0x42800000, v9
	v_med3_f32 v2, v2, s17, v26
	v_med3_f32 v3, v3, s17, v26
	v_med3_f32 v7, v7, s17, v26
	v_med3_f32 v8, v8, s17, v26
	v_cvt_pk_fp8_f32 v48, v2, v3
	v_cvt_pk_fp8_f32 v49, v7, v8
	v_mul_f32_e32 v9, 0x42800000, v10
	v_mul_f32_e32 v10, 0x42800000, v11
	v_med3_f32 v5, v5, s17, v26
	v_med3_f32 v6, v6, s17, v26
	v_med3_f32 v2, v9, s17, v26
	v_med3_f32 v3, v10, s17, v26
	v_cvt_pk_fp8_f32 v48, v5, v6 op_sel:[0,0,1]
	v_cvt_pk_fp8_f32 v49, v2, v3 op_sel:[0,0,1]
	v_ashrrev_i32_e32 v5, 31, v4
	v_lshlrev_b64 v[2:3], 10, v[4:5]
	v_lshl_add_u64 v[2:3], v[62:63], 0, v[2:3]
	global_store_dwordx2 v[2:3], v[48:49], off nt
	ds_read2_b32 v[2:3], v54 offset1:33
	ds_read2_b32 v[6:7], v54 offset0:66 offset1:99
	ds_read2_b32 v[8:9], v54 offset0:132 offset1:165
	ds_read2_b32 v[10:11], v54 offset0:198 offset1:231
	s_waitcnt lgkmcnt(0)
	v_mul_f32_e32 v2, 0x42800000, v2
	v_mul_f32_e32 v3, 0x42800000, v3
	v_med3_f32 v2, v2, s17, v26
	v_med3_f32 v3, v3, s17, v26
	v_cvt_pk_fp8_f32 v4, v2, v3
	v_mul_f32_e32 v5, 0x42800000, v6
	v_mul_f32_e32 v6, 0x42800000, v7
	v_med3_f32 v3, v5, s17, v26
	v_med3_f32 v5, v6, s17, v26
	v_mul_f32_e32 v2, 0x42800000, v8
	v_cvt_pk_fp8_f32 v4, v3, v5 op_sel:[0,0,1]
	v_mul_f32_e32 v3, 0x42800000, v9
	v_med3_f32 v2, v2, s17, v26
	v_med3_f32 v3, v3, s17, v26
	v_cvt_pk_fp8_f32 v5, v2, v3
	v_mul_f32_e32 v6, 0x42800000, v10
	v_mul_f32_e32 v2, 0x42800000, v11
	v_med3_f32 v3, v6, s17, v26
	v_med3_f32 v2, v2, s17, v26
	v_cvt_pk_fp8_f32 v5, v3, v2 op_sel:[0,0,1]
	v_or_b32_e32 v2, s0, v1
	v_ashrrev_i32_e32 v3, 31, v2
	v_lshlrev_b64 v[2:3], 10, v[2:3]
	v_lshl_add_u64 v[2:3], v[62:63], 0, v[2:3]
	global_store_dwordx2 v[2:3], v[4:5], off nt
	ds_read2_b32 v[2:3], v55 offset1:33
	ds_read2_b32 v[4:5], v55 offset0:66 offset1:99
	s_waitcnt lgkmcnt(0)
	v_mul_f32_e32 v2, 0x42800000, v2
	v_mul_f32_e32 v3, 0x42800000, v3
	v_mul_f32_e32 v6, 0x42800000, v4
	v_med3_f32 v4, v2, s17, v26
	v_med3_f32 v3, v3, s17, v26
	v_mul_f32_e32 v8, 0x42800000, v5
	v_cvt_pk_fp8_f32 v2, v4, v3
	ds_read2_b32 v[4:5], v55 offset0:132 offset1:165
	v_med3_f32 v3, v6, s17, v26
	ds_read2_b32 v[6:7], v55 offset0:198 offset1:231
	v_med3_f32 v8, v8, s17, v26
	v_cvt_pk_fp8_f32 v2, v3, v8 op_sel:[0,0,1]
	s_waitcnt lgkmcnt(0)
	v_mul_f32_e32 v3, 0x42800000, v4
	v_mul_f32_e32 v4, 0x42800000, v5
	v_mul_f32_e32 v5, 0x42800000, v6
	v_med3_f32 v6, v3, s17, v26
	v_med3_f32 v4, v4, s17, v26
	v_cvt_pk_fp8_f32 v3, v6, v4
	v_mul_f32_e32 v4, 0x42800000, v7
	v_med3_f32 v5, v5, s17, v26
	v_med3_f32 v4, v4, s17, v26
	v_cvt_pk_fp8_f32 v3, v5, v4 op_sel:[0,0,1]
	v_or_b32_e32 v4, s0, v50
	v_ashrrev_i32_e32 v5, 31, v4
	v_lshlrev_b64 v[4:5], 10, v[4:5]
	v_lshl_add_u64 v[4:5], v[62:63], 0, v[4:5]
	global_store_dwordx2 v[4:5], v[2:3], off nt
	ds_read2_b32 v[2:3], v56 offset1:33
	ds_read2_b32 v[4:5], v56 offset0:66 offset1:99
	s_waitcnt lgkmcnt(0)
	v_mul_f32_e32 v2, 0x42800000, v2
	v_mul_f32_e32 v3, 0x42800000, v3
	v_mul_f32_e32 v6, 0x42800000, v4
	v_med3_f32 v4, v2, s17, v26
	v_med3_f32 v3, v3, s17, v26
	v_mul_f32_e32 v8, 0x42800000, v5
	v_cvt_pk_fp8_f32 v2, v4, v3
	ds_read2_b32 v[4:5], v56 offset0:132 offset1:165
	v_med3_f32 v3, v6, s17, v26
	ds_read2_b32 v[6:7], v56 offset0:198 offset1:231
	v_med3_f32 v8, v8, s17, v26
	v_cvt_pk_fp8_f32 v2, v3, v8 op_sel:[0,0,1]
	s_waitcnt lgkmcnt(0)
	v_mul_f32_e32 v3, 0x42800000, v4
	v_mul_f32_e32 v4, 0x42800000, v5
	v_mul_f32_e32 v5, 0x42800000, v6
	v_med3_f32 v6, v3, s17, v26
	v_med3_f32 v4, v4, s17, v26
	v_cvt_pk_fp8_f32 v3, v6, v4
	v_mul_f32_e32 v4, 0x42800000, v7
	v_med3_f32 v5, v5, s17, v26
	v_med3_f32 v4, v4, s17, v26
	v_cvt_pk_fp8_f32 v3, v5, v4 op_sel:[0,0,1]
	v_or_b32_e32 v4, s0, v51
	v_ashrrev_i32_e32 v5, 31, v4
	v_lshlrev_b64 v[4:5], 10, v[4:5]
	v_lshl_add_u64 v[4:5], v[62:63], 0, v[4:5]
	global_store_dwordx2 v[4:5], v[2:3], off nt
	s_waitcnt lgkmcnt(0)
	s_branch .LBB0_212

.LBB0_458:
	s_waitcnt vmcnt(0) lgkmcnt(0)
	v_lshlrev_b32_e32 v85, 16, v37
	v_lshlrev_b32_e32 v84, 16, v36
	v_and_b32_e32 v37, 0xffff0000, v37
	v_and_b32_e32 v36, 0xffff0000, v36
	v_pk_add_f32 v[68:69], v[84:85], v[36:37]
	v_lshlrev_b32_e32 v87, 16, v35
	v_lshlrev_b32_e32 v86, 16, v34
	v_and_b32_e32 v35, 0xffff0000, v35
	v_and_b32_e32 v34, 0xffff0000, v34
	v_lshlrev_b32_e32 v46, 16, v39
	v_and_b32_e32 v48, 0xffff0000, v39
	v_add_f32_e32 v39, v68, v69
	v_pk_add_f32 v[68:69], v[86:87], v[34:35]
	v_lshlrev_b32_e32 v42, 16, v40
	v_and_b32_e32 v43, 0xffff0000, v40
	v_lshlrev_b32_e32 v40, 16, v41
	v_and_b32_e32 v41, 0xffff0000, v41
	v_pk_add_f32 v[68:69], v[68:69], v[68:69] op_sel_hi:[0,1]
	v_lshlrev_b32_e32 v44, 16, v38
	v_and_b32_e32 v38, 0xffff0000, v38
	v_add_f32_e32 v49, 0, v39
	v_add_f32_e32 v45, v42, v43
	v_add_f32_e32 v39, v40, v41
	v_mov_b32_e32 v47, v69
	v_pk_add_f32 v[70:71], v[44:45], v[38:39]
	v_pk_add_f32 v[68:69], v[46:47], v[48:49]
	s_min_u32 s0, s36, 29
	v_pk_add_f32 v[68:69], v[70:71], v[68:69]
	s_lshl_b32 s0, s0, 3
	v_add_f32_e32 v39, v68, v69
	s_add_i32 s18, s35, s0
	s_nop 0
	v_add_f32_dpp v39, v39, v39 quad_perm:[1,0,3,2] row_mask:0xf bank_mask:0xf bound_ctrl:1
	s_nop 1
	v_add_f32_dpp v39, v39, v39 quad_perm:[2,3,0,1] row_mask:0xf bank_mask:0xf bound_ctrl:1
	s_nop 1
	v_add_f32_dpp v39, v39, v39 row_half_mirror row_mask:0xf bank_mask:0xf bound_ctrl:1
	s_nop 1
	v_add_f32_dpp v39, v39, v39 row_mirror row_mask:0xf bank_mask:0xf bound_ctrl:1
	s_nop 0
	v_readlane_b32 s19, v39, 16
	v_readlane_b32 s20, v39, 48
	v_readlane_b32 s0, v39, 0
	v_readlane_b32 s1, v39, 32
	v_mov_b32_e32 v68, s19
	v_mov_b32_e32 v69, s20
	v_pk_add_f32 v[68:69], s[0:1], v[68:69]
	s_nop 0
	v_add_f32_e32 v39, v68, v69
	v_fmac_f32_e32 v36, 0xba800000, v39
	v_fmac_f32_e32 v37, 0xba800000, v39
	v_fmac_f32_e32 v85, 0xba800000, v39
	v_fmac_f32_e32 v84, 0xba800000, v39
	v_mov_b32_e32 v88, v85
	v_mov_b32_e32 v89, v37
	v_mov_b32_e32 v85, v36
	v_fmac_f32_e32 v34, 0xba800000, v39
	v_fmac_f32_e32 v35, 0xba800000, v39
	v_fmac_f32_e32 v87, 0xba800000, v39
	v_pk_mul_f32 v[68:69], v[88:89], v[88:89]
	v_pk_mul_f32 v[36:37], v[84:85], v[84:85]
	v_fmac_f32_e32 v86, 0xba800000, v39
	v_mov_b32_e32 v90, v87
	v_mov_b32_e32 v91, v35
	v_mov_b32_e32 v87, v34
	v_pk_mov_b32 v[70:71], v[36:37], v[68:69] op_sel:[1,0]
	v_mov_b32_e32 v37, v69
	v_pk_mul_f32 v[68:69], v[90:91], v[90:91]
	v_pk_mul_f32 v[34:35], v[86:87], v[86:87]
	v_pk_add_f32 v[36:37], v[70:71], v[36:37]
	v_pk_mov_b32 v[70:71], v[34:35], v[68:69] op_sel:[1,0]
	v_mov_b32_e32 v35, v69
	v_pk_add_f32 v[34:35], v[70:71], v[34:35]
	v_fmac_f32_e32 v42, 0xba800000, v39
	v_pk_add_f32 v[34:35], v[34:35], v[34:35] op_sel_hi:[0,1]
	v_fmac_f32_e32 v43, 0xba800000, v39
	v_fmac_f32_e32 v40, 0xba800000, v39
	v_mul_f32_e32 v34, v42, v42
	v_fmac_f32_e32 v41, 0xba800000, v39
	v_pk_fma_f32 v[68:69], v[42:43], v[42:43], v[34:35] op_sel_hi:[1,1,0]
	v_mul_f32_e32 v34, v40, v40
	v_pk_add_f32 v[36:37], v[36:37], v[36:37] op_sel_hi:[0,1]
	v_pk_fma_f32 v[70:71], v[40:41], v[40:41], v[34:35] op_sel_hi:[1,1,0]
	v_fmac_f32_e32 v48, 0xba800000, v39
	v_fmac_f32_e32 v46, 0xba800000, v39
	v_fmac_f32_e32 v38, 0xba800000, v39
	v_fmac_f32_e32 v44, 0xba800000, v39
	v_mul_f32_e32 v68, v44, v44
	v_mul_f32_e32 v70, v38, v38
	v_mul_f32_e32 v36, v46, v46
	v_mul_f32_e32 v34, v48, v48
	v_pk_add_f32 v[68:69], v[68:69], v[70:71]
	v_pk_add_f32 v[34:35], v[36:37], v[34:35]
	v_mov_b32_e32 v47, v48
	v_pk_add_f32 v[34:35], v[68:69], v[34:35]
	s_nop 0
	v_add_f32_e32 v34, v34, v35
	s_nop 1
	v_add_f32_dpp v34, v34, v34 quad_perm:[1,0,3,2] row_mask:0xf bank_mask:0xf bound_ctrl:1
	s_nop 1
	v_add_f32_dpp v34, v34, v34 quad_perm:[2,3,0,1] row_mask:0xf bank_mask:0xf bound_ctrl:1
	s_nop 1
	v_add_f32_dpp v34, v34, v34 row_half_mirror row_mask:0xf bank_mask:0xf bound_ctrl:1
	s_nop 1
	v_add_f32_dpp v34, v34, v34 row_mirror row_mask:0xf bank_mask:0xf bound_ctrl:1
	s_nop 0
	v_readlane_b32 s19, v34, 16
	v_readlane_b32 s20, v34, 48
	v_readlane_b32 s0, v34, 0
	v_readlane_b32 s1, v34, 32
	v_mov_b32_e32 v34, s19
	v_mov_b32_e32 v35, s20
	v_pk_add_f32 v[34:35], s[0:1], v[34:35]
	s_ashr_i32 s19, s18, 31
	v_add_f32_e32 v34, v34, v35
	v_fmamk_f32 v34, v34, 0x3a800000, v80
	v_mul_f32_e32 v35, 0x4f800000, v34
	v_cmp_gt_f32_e32 vcc, s7, v34
	s_lshl_b64 s[0:1], s[18:19], 11
	s_and_b32 s20, s36, 3
	v_cndmask_b32_e32 v36, v34, v35, vcc
	v_lshl_add_u64 v[34:35], v[54:55], 0, s[0:1]
	global_load_dwordx2 v[68:69], v[34:35], off
	global_load_dwordx2 v[70:71], v[34:35], off offset:512
	global_load_dwordx2 v[72:73], v[34:35], off offset:1024
	global_load_dwordx2 v[74:75], v[34:35], off offset:1536
	v_sqrt_f32_e32 v37, v36
	s_mul_i32 s30, s20, 0x810
	s_add_i32 s30, s87, s30
	v_add_u32_e32 v39, -1, v37
	v_fma_f32 v45, -v39, v37, v36
	v_cmp_ge_f32_e64 s[18:19], 0, v45
	v_add_u32_e32 v45, 1, v37
	s_nop 0
	v_cndmask_b32_e64 v39, v37, v39, s[18:19]
	v_fma_f32 v37, -v45, v37, v36
	v_cmp_lt_f32_e64 s[18:19], 0, v37
	s_nop 1
	v_cndmask_b32_e64 v37, v39, v45, s[18:19]
	v_mul_f32_e32 v39, 0x37800000, v37
	v_cndmask_b32_e32 v37, v37, v39, vcc
	v_cmp_class_f32_e32 vcc, v36, v81
	s_add_i32 s18, s4, s34
	s_ashr_i32 s19, s18, 31
	v_cndmask_b32_e32 v36, v37, v36, vcc
	v_div_scale_f32 v37, s[0:1], v36, v36, 1.0
	v_rcp_f32_e32 v39, v37
	s_lshl_b64 s[0:1], s[18:19], 11
	v_fma_f32 v34, -v37, v39, 1.0
	v_fmac_f32_e32 v39, v34, v39
	v_div_scale_f32 v34, vcc, 1.0, v36, 1.0
	v_mul_f32_e32 v35, v34, v39
	v_fma_f32 v45, -v37, v35, v34
	v_fmac_f32_e32 v35, v45, v39
	v_fma_f32 v34, -v37, v35, v34
	v_div_fmas_f32 v34, v34, v39, v35
	v_div_fixup_f32 v34, v34, v36, 1.0
	v_mov_b32_e32 v45, v38
	v_pk_mul_f32 v[36:37], v[84:85], v[34:35] op_sel_hi:[1,0]
	v_pk_mul_f32 v[84:85], v[88:89], v[34:35] op_sel_hi:[1,0]
	v_pk_mul_f32 v[38:39], v[44:45], v[34:35] op_sel_hi:[1,0]
	v_mov_b32_e32 v44, v150
	v_pk_fma_f32 v[84:85], v[4:5], v[84:85], v[12:13]
	v_pk_fma_f32 v[36:37], v[2:3], v[36:37], v[10:11]
	v_pk_mul_f32 v[86:87], v[86:87], v[34:35] op_sel_hi:[1,0]
	v_pk_mul_f32 v[88:89], v[90:91], v[34:35] op_sel_hi:[1,0]
	v_pk_fma_f32 v[86:87], v[6:7], v[86:87], v[14:15]
	v_pk_fma_f32 v[88:89], v[8:9], v[88:89], v[16:17]
	v_pk_mul_f32 v[42:43], v[42:43], v[34:35] op_sel_hi:[1,0]
	v_pk_mul_f32 v[40:41], v[40:41], v[34:35] op_sel_hi:[1,0]
	v_pk_mul_f32 v[34:35], v[46:47], v[34:35] op_sel_hi:[1,0]
	v_lshl_add_u32 v48, v44, 3, s30
	v_cvt_pk_bf16_f32 v44, v36, v37
	v_cvt_pk_bf16_f32 v45, v84, v85
	v_lshl_add_u64 v[46:47], v[56:57], 0, s[0:1]
	v_pk_fma_f32 v[40:41], v[20:21], v[40:41], v[28:29]
	v_pk_fma_f32 v[42:43], v[18:19], v[42:43], v[26:27]
	global_store_dwordx2 v[46:47], v[44:45], off nt
	ds_write_b64 v48, v[44:45] offset:33024
	v_cvt_pk_bf16_f32 v44, v86, v87
	v_cvt_pk_bf16_f32 v45, v88, v89
	v_pk_fma_f32 v[34:35], v[24:25], v[34:35], v[32:33]
	v_pk_fma_f32 v[38:39], v[22:23], v[38:39], v[30:31]
	global_store_dwordx2 v[46:47], v[44:45], off offset:512 nt
	ds_write_b64 v48, v[44:45] offset:33536
	v_cvt_pk_bf16_f32 v44, v42, v43
	v_cvt_pk_bf16_f32 v45, v40, v41
	global_store_dwordx2 v[46:47], v[44:45], off offset:1024 nt
	ds_write_b64 v48, v[44:45] offset:34048
	v_cvt_pk_bf16_f32 v44, v38, v39
	v_cvt_pk_bf16_f32 v45, v34, v35
	global_store_dwordx2 v[46:47], v[44:45], off offset:1536 nt
	ds_write_b64 v48, v[44:45] offset:34560
	v_med3_f32 v36, v36, s38, v82
	v_med3_f32 v37, v37, s38, v82
	v_cvt_pk_fp8_f32 v44, v36, v37
	v_med3_f32 v36, v84, s38, v82
	v_med3_f32 v37, v85, s38, v82
	v_med3_f32 v45, v86, s38, v82
	v_cvt_pk_fp8_f32 v44, v36, v37 op_sel:[0,0,1]
	v_med3_f32 v46, v87, s38, v82
	v_cvt_pk_fp8_f32 v47, v45, v46
	s_lshl_b64 s[0:1], s[18:19], 10
	v_lshl_add_u64 v[36:37], v[58:59], 0, s[0:1]
	global_store_dword v[36:37], v44, off
	v_med3_f32 v44, v88, s38, v82
	v_med3_f32 v45, v89, s38, v82
	v_cvt_pk_fp8_f32 v47, v44, v45 op_sel:[0,0,1]
	v_med3_f32 v42, v42, s38, v82
	v_med3_f32 v43, v43, s38, v82
	v_cvt_pk_fp8_f32 v44, v42, v43
	v_med3_f32 v38, v38, s38, v82
	v_med3_f32 v39, v39, s38, v82
	v_cvt_pk_fp8_f32 v42, v38, v39
	v_med3_f32 v34, v34, s38, v82
	v_med3_f32 v35, v35, s38, v82
	v_med3_f32 v40, v40, s38, v82
	v_med3_f32 v41, v41, s38, v82
	v_cvt_pk_fp8_f32 v42, v34, v35 op_sel:[0,0,1]
	v_cvt_pk_fp8_f32 v44, v40, v41 op_sel:[0,0,1]
	s_cmp_lg_u32 s20, 3
	global_store_dword v[36:37], v47, off offset:256
	global_store_dword v[36:37], v44, off offset:512
	global_store_dword v[36:37], v42, off offset:768
	s_cbranch_scc1 .LBB0_457
	v_mov_b32_e32 v100, v150
	s_nop 0
	v_and_b32_e32 v34, 3, v100
	v_mul_u32_u24_e32 v34, 0x810, v34
	v_and_b32_e32 v38, -16, v100
	v_add3_u32 v83, s87, v34, v38
	ds_read_b128 v[34:37], v83 offset:33024
	v_and_b32_e32 v39, 15, v100
	v_mul_u32_u24_e32 v39, 0x810, v39
	v_add3_u32 v101, 0, v39, v38
	ds_read_b128 v[38:41], v83 offset:33088
	ds_read_b128 v[42:45], v101
	ds_read_b128 v[46:49], v101 offset:64
	s_waitcnt lgkmcnt(0)
	v_mfma_f32_16x16x32_bf16 v[38:41], v[38:41], v[46:49], 0
	v_cmp_gt_i32_e32 vcc, 16, v100
	v_mfma_f32_16x16x32_bf16 v[34:37], v[34:37], v[42:45], 0
	ds_read_b128 v[42:45], v83 offset:33152
	ds_read_b128 v[46:49], v83 offset:33216
	ds_read_b128 v[84:87], v101 offset:128
	ds_read_b128 v[88:91], v101 offset:192
	s_waitcnt lgkmcnt(0)
	v_mfma_f32_16x16x32_bf16 v[42:45], v[42:45], v[84:87], 0
	ds_read_b128 v[84:87], v83 offset:33280
	v_mfma_f32_16x16x32_bf16 v[46:49], v[46:49], v[88:91], 0
	ds_read_b128 v[88:91], v83 offset:33344
	ds_read_b128 v[92:95], v101 offset:256
	ds_read_b128 v[96:99], v101 offset:320
	s_waitcnt lgkmcnt(0)
	v_mfma_f32_16x16x32_bf16 v[34:37], v[84:87], v[92:95], v[34:37]
	ds_read_b128 v[84:87], v83 offset:33408
	v_mfma_f32_16x16x32_bf16 v[38:41], v[88:91], v[96:99], v[38:41]
	ds_read_b128 v[88:91], v83 offset:33472
	ds_read_b128 v[92:95], v101 offset:384
	ds_read_b128 v[96:99], v101 offset:448
	s_waitcnt lgkmcnt(0)
	v_mfma_f32_16x16x32_bf16 v[42:45], v[84:87], v[92:95], v[42:45]
	ds_read_b128 v[84:87], v83 offset:33536
	v_mfma_f32_16x16x32_bf16 v[46:49], v[88:91], v[96:99], v[46:49]
	ds_read_b128 v[88:91], v83 offset:33600
	ds_read_b128 v[92:95], v101 offset:512
	ds_read_b128 v[96:99], v101 offset:576
	s_waitcnt lgkmcnt(0)
	v_mfma_f32_16x16x32_bf16 v[34:37], v[84:87], v[92:95], v[34:37]
	ds_read_b128 v[84:87], v83 offset:33664
	v_mfma_f32_16x16x32_bf16 v[38:41], v[88:91], v[96:99], v[38:41]
	ds_read_b128 v[88:91], v83 offset:33728
	ds_read_b128 v[92:95], v101 offset:640
	ds_read_b128 v[96:99], v101 offset:704
	s_waitcnt lgkmcnt(0)
	v_mfma_f32_16x16x32_bf16 v[42:45], v[84:87], v[92:95], v[42:45]
	ds_read_b128 v[84:87], v83 offset:33792
	ds_read_b128 v[92:95], v83 offset:33856
	v_mfma_f32_16x16x32_bf16 v[46:49], v[88:91], v[96:99], v[46:49]
	ds_read_b128 v[88:91], v101 offset:768
	ds_read_b128 v[96:99], v101 offset:832
	s_waitcnt lgkmcnt(0)
	v_mfma_f32_16x16x32_bf16 v[34:37], v[84:87], v[88:91], v[34:37]
	ds_read_b128 v[84:87], v83 offset:33920
	ds_read_b128 v[88:91], v83 offset:33984
	v_mfma_f32_16x16x32_bf16 v[38:41], v[92:95], v[96:99], v[38:41]
	ds_read_b128 v[92:95], v101 offset:896
	ds_read_b128 v[96:99], v101 offset:960
	s_waitcnt lgkmcnt(0)
	v_mfma_f32_16x16x32_bf16 v[42:45], v[84:87], v[92:95], v[42:45]
	ds_read_b128 v[84:87], v83 offset:34048
	ds_read_b128 v[92:95], v83 offset:34112
	v_mfma_f32_16x16x32_bf16 v[46:49], v[88:91], v[96:99], v[46:49]
	ds_read_b128 v[88:91], v101 offset:1024
	ds_read_b128 v[96:99], v101 offset:1088
	s_waitcnt lgkmcnt(0)
	v_mfma_f32_16x16x32_bf16 v[34:37], v[84:87], v[88:91], v[34:37]
	ds_read_b128 v[84:87], v83 offset:34176
	ds_read_b128 v[88:91], v83 offset:34240
	v_mfma_f32_16x16x32_bf16 v[38:41], v[92:95], v[96:99], v[38:41]
	ds_read_b128 v[92:95], v101 offset:1152
	ds_read_b128 v[96:99], v101 offset:1216
	s_waitcnt lgkmcnt(0)
	v_mfma_f32_16x16x32_bf16 v[42:45], v[84:87], v[92:95], v[42:45]
	ds_read_b128 v[84:87], v83 offset:34304
	ds_read_b128 v[92:95], v83 offset:34368
	v_mfma_f32_16x16x32_bf16 v[46:49], v[88:91], v[96:99], v[46:49]
	ds_read_b128 v[88:91], v101 offset:1280
	ds_read_b128 v[96:99], v101 offset:1344
	s_waitcnt lgkmcnt(0)
	v_mfma_f32_16x16x32_bf16 v[34:37], v[84:87], v[88:91], v[34:37]
	ds_read_b128 v[84:87], v83 offset:34432
	ds_read_b128 v[88:91], v83 offset:34496
	v_mfma_f32_16x16x32_bf16 v[38:41], v[92:95], v[96:99], v[38:41]
	ds_read_b128 v[92:95], v101 offset:1408
	ds_read_b128 v[96:99], v101 offset:1472
	s_waitcnt lgkmcnt(0)
	v_mfma_f32_16x16x32_bf16 v[42:45], v[84:87], v[92:95], v[42:45]
	ds_read_b128 v[84:87], v83 offset:34560
	ds_read_b128 v[92:95], v83 offset:34624
	v_mfma_f32_16x16x32_bf16 v[46:49], v[88:91], v[96:99], v[46:49]
	ds_read_b128 v[88:91], v101 offset:1536
	ds_read_b128 v[96:99], v101 offset:1600
	s_waitcnt lgkmcnt(0)
	v_mfma_f32_16x16x32_bf16 v[34:37], v[84:87], v[88:91], v[34:37]
	ds_read_b128 v[84:87], v83 offset:34688
	ds_read_b128 v[88:91], v83 offset:34752
	v_mfma_f32_16x16x32_bf16 v[38:41], v[92:95], v[96:99], v[38:41]
	ds_read_b128 v[92:95], v101 offset:1664
	ds_read_b128 v[96:99], v101 offset:1728
	s_waitcnt lgkmcnt(0)
	v_mfma_f32_16x16x32_bf16 v[42:45], v[84:87], v[92:95], v[42:45]
	ds_read_b128 v[84:87], v83 offset:34816
	ds_read_b128 v[92:95], v83 offset:34880
	v_mfma_f32_16x16x32_bf16 v[46:49], v[88:91], v[96:99], v[46:49]
	ds_read_b128 v[88:91], v101 offset:1792
	ds_read_b128 v[96:99], v101 offset:1856
	s_waitcnt lgkmcnt(0)
	v_mfma_f32_16x16x32_bf16 v[34:37], v[84:87], v[88:91], v[34:37]
	ds_read_b128 v[84:87], v83 offset:34944
	ds_read_b128 v[88:91], v83 offset:35008
	v_mfma_f32_16x16x32_bf16 v[38:41], v[92:95], v[96:99], v[38:41]
	ds_read_b128 v[92:95], v101 offset:1920
	ds_read_b128 v[96:99], v101 offset:1984
	v_ashrrev_i32_e32 v101, 31, v100
	s_waitcnt lgkmcnt(0)
	v_mfma_f32_16x16x32_bf16 v[42:45], v[84:87], v[92:95], v[42:45]
	s_nop 2
	v_add_f32_e64 v34, v34, v38
	v_add_f32_e64 v35, v35, v39
	v_mfma_f32_16x16x32_bf16 v[46:49], v[88:91], v[96:99], v[46:49]
	s_nop 7
	v_pk_add_f32 v[38:39], v[42:43], v[46:47]
	s_nop 0
	v_pk_add_f32 v[38:39], v[34:35], v[38:39]
	s_nop 1
	v_mov_b32_dpp v34, v38 quad_perm:[1,0,3,2] row_mask:0xf bank_mask:0xf bound_ctrl:1
	v_max_f32_e32 v34, v34, v34
	v_max_f32_e32 v34, v38, v34
	s_nop 1
	v_mov_b32_dpp v35, v34 quad_perm:[2,3,0,1] row_mask:0xf bank_mask:0xf bound_ctrl:1
	v_max_f32_e32 v35, v35, v35
	v_max_f32_e32 v34, v34, v35
	s_nop 1
	v_mov_b32_dpp v35, v34 row_half_mirror row_mask:0xf bank_mask:0xf bound_ctrl:1
	v_max_f32_e32 v35, v35, v35
	v_max_f32_e32 v34, v34, v35
	s_nop 1
	v_mov_b32_dpp v35, v34 row_mirror row_mask:0xf bank_mask:0xf bound_ctrl:1
	v_max_f32_e32 v35, v35, v35
	v_max_f32_e32 v34, v34, v35
	v_sub_f32_e32 v34, v38, v34
	v_mul_f32_e32 v34, 0x3fb8aa3b, v34
	v_exp_f32_e32 v38, v34
	v_lshlrev_b64 v[34:35], 13, v[100:101]
	v_lshl_add_u64 v[34:35], s[26:27], 0, v[34:35]
	v_add_f32_dpp v42, v38, v38 quad_perm:[1,0,3,2] row_mask:0xf bank_mask:0xf bound_ctrl:1
	s_nop 1
	v_add_f32_dpp v42, v42, v42 quad_perm:[2,3,0,1] row_mask:0xf bank_mask:0xf bound_ctrl:1
	s_nop 1
	v_add_f32_dpp v42, v42, v42 row_half_mirror row_mask:0xf bank_mask:0xf bound_ctrl:1
	s_nop 1
	v_mov_b32_dpp v43, v42 row_mirror row_mask:0xf bank_mask:0xf bound_ctrl:1
	s_and_saveexec_b64 s[30:31], vcc
	s_cbranch_execz .LBB0_461
	v_add_f32_e32 v42, v42, v43
	v_rcp_f32_e32 v42, v42
	s_sub_i32 s19, s18, 24
	s_ashr_i32 s0, s19, 11
	s_ashr_i32 s1, s0, 31
	s_and_b32 s19, s19, 0x7ff
	s_lshl_b64 s[0:1], s[0:1], 17
	v_mul_f32_e32 v38, v38, v42
	v_lshl_add_u64 v[42:43], v[34:35], 0, s[0:1]
	s_lshl_b32 s20, s19, 2
	v_lshl_add_u64 v[42:43], v[42:43], 0, s[20:21]
	global_store_dword v[42:43], v38, off

.Lpeel_exit_2:
	s_mov_b32 s98, 0x3b000000
	s_mov_b32 s99, 0xbcb8aa3b
	s_mov_b32 s100, 1.0
	v_pk_mul_f32 v[236:237], v[158:159], s[98:99] op_sel_hi:[1,0]
	v_pk_mul_f32 v[234:235], v[158:159], s[98:99] op_sel:[0,1] op_sel_hi:[1,1]
	v_exp_f32_e32 v234, v234
	v_exp_f32_e32 v235, v235
	s_nop 0
	v_pk_add_f32 v[234:235], v[234:235], s[100:101] op_sel_hi:[1,0]
	v_rcp_f32_e32 v234, v234
	v_rcp_f32_e32 v235, v235
	s_nop 0
	v_pk_mul_f32 v[236:237], v[236:237], v[234:235]
	v_pk_mul_f32 v[236:237], v[236:237], v[154:155]
	s_ashr_i32 s29, s28, 31
	s_ashr_i32 s27, s26, 31
	s_lshl_b64 s[10:11], s[28:29], 18
	s_lshl_b64 s[26:27], s[26:27], 15
	v_mov_b32_e32 v3, v195
	s_add_u32 s0, s6, s10
	v_med3_f32 v5, v236, s40, v190
	s_nop 15
	s_nop 15
	v_mov_b32_e32 v2, v196
	v_pk_mul_f32 v[238:239], v[160:161], s[98:99] op_sel_hi:[1,0]
	v_pk_mul_f32 v[234:235], v[160:161], s[98:99] op_sel:[0,1] op_sel_hi:[1,1]
	v_exp_f32_e32 v234, v234
	v_exp_f32_e32 v235, v235
	s_nop 0
	v_pk_add_f32 v[234:235], v[234:235], s[100:101] op_sel_hi:[1,0]
	v_rcp_f32_e32 v234, v234
	v_rcp_f32_e32 v235, v235
	s_nop 0
	v_pk_mul_f32 v[238:239], v[238:239], v[234:235]
	v_pk_mul_f32 v[238:239], v[238:239], v[156:157]
	v_add_u32_e32 v4, s49, v3
	s_addc_u32 s1, s7, s11
	s_add_u32 s10, s0, s26
	v_lshl_add_u32 v2, v2, 3, s50
	s_addc_u32 s11, s1, s27
	v_ashrrev_i32_e32 v3, 31, v2
	s_and_b64 vcc, exec, s[8:9]
	v_pk_mul_f32 v[240:241], v[150:151], s[98:99] op_sel_hi:[1,0]
	v_pk_mul_f32 v[234:235], v[150:151], s[98:99] op_sel:[0,1] op_sel_hi:[1,1]
	v_exp_f32_e32 v234, v234
	v_exp_f32_e32 v235, v235
	s_nop 0
	v_pk_add_f32 v[234:235], v[234:235], s[100:101] op_sel_hi:[1,0]
	v_rcp_f32_e32 v234, v234
	v_rcp_f32_e32 v235, v235
	s_nop 0
	v_pk_mul_f32 v[240:241], v[240:241], v[234:235]
	v_pk_mul_f32 v[240:241], v[240:241], v[146:147]
	v_mov_b32_e32 v174, v200
	v_mov_b32_e32 v172, v199
	v_mov_b32_e32 v170, v198
	v_mov_b32_e32 v168, v171
	s_mov_b32 s26, s24
	s_mov_b32 s28, s54
	s_mov_b64 s[30:31], s[12:13]
	v_pk_mul_f32 v[242:243], v[152:153], s[98:99] op_sel_hi:[1,0]
	v_pk_mul_f32 v[234:235], v[152:153], s[98:99] op_sel:[0,1] op_sel_hi:[1,1]
	v_exp_f32_e32 v234, v234
	v_exp_f32_e32 v235, v235
	s_nop 0
	v_pk_add_f32 v[234:235], v[234:235], s[100:101] op_sel_hi:[1,0]
	v_rcp_f32_e32 v234, v234
	v_rcp_f32_e32 v235, v235
	s_nop 0
	v_pk_mul_f32 v[242:243], v[242:243], v[234:235]
	v_pk_mul_f32 v[242:243], v[242:243], v[148:149]
	s_nop 0
	s_nop 0
	v_med3_f32 v13, v237, s40, v190
	v_cvt_pk_fp8_f32 v6, v5, v13
	v_med3_f32 v5, v238, s40, v190
	v_med3_f32 v7, v239, s40, v190
	v_med3_f32 v8, v241, s40, v190
	v_cvt_pk_fp8_f32 v6, v5, v7 op_sel:[0,0,1]
	v_med3_f32 v5, v240, s40, v190
	v_cvt_pk_fp8_f32 v7, v5, v8
	v_med3_f32 v5, v242, s40, v190
	v_med3_f32 v8, v243, s40, v190
	v_cvt_pk_fp8_f32 v7, v5, v8 op_sel:[0,0,1]
	v_ashrrev_i32_e32 v5, 31, v4
	v_lshlrev_b64 v[8:9], 7, v[4:5]
	v_lshl_add_u64 v[8:9], s[10:11], 0, v[8:9]
	v_lshl_add_u64 v[8:9], v[8:9], 0, v[2:3]
	v_pk_mul_f32 v[244:245], v[142:143], s[98:99] op_sel_hi:[1,0]
	v_pk_mul_f32 v[234:235], v[142:143], s[98:99] op_sel:[0,1] op_sel_hi:[1,1]
	v_exp_f32_e32 v234, v234
	v_exp_f32_e32 v235, v235
	s_nop 0
	v_pk_add_f32 v[234:235], v[234:235], s[100:101] op_sel_hi:[1,0]
	v_rcp_f32_e32 v234, v234
	v_rcp_f32_e32 v235, v235
	s_nop 0
	v_pk_mul_f32 v[244:245], v[244:245], v[234:235]
	v_pk_mul_f32 v[244:245], v[244:245], v[138:139]
	global_store_dwordx2 v[8:9], v[6:7], off
	s_nop 0
	s_nop 0
	v_med3_f32 v5, v244, s40, v190
	s_nop 0
	v_pk_mul_f32 v[246:247], v[144:145], s[98:99] op_sel_hi:[1,0]
	v_pk_mul_f32 v[234:235], v[144:145], s[98:99] op_sel:[0,1] op_sel_hi:[1,1]
	v_exp_f32_e32 v234, v234
	v_exp_f32_e32 v235, v235
	s_nop 0
	v_pk_add_f32 v[234:235], v[234:235], s[100:101] op_sel_hi:[1,0]
	v_rcp_f32_e32 v234, v234
	v_rcp_f32_e32 v235, v235
	s_nop 0
	v_pk_mul_f32 v[246:247], v[246:247], v[234:235]
	v_pk_mul_f32 v[246:247], v[246:247], v[140:141]
	v_med3_f32 v7, v245, s40, v190
	s_nop 0
	s_nop 0
	s_nop 0
	v_pk_mul_f32 v[248:249], v[134:135], s[98:99] op_sel_hi:[1,0]
	v_pk_mul_f32 v[234:235], v[134:135], s[98:99] op_sel:[0,1] op_sel_hi:[1,1]
	v_exp_f32_e32 v234, v234
	v_exp_f32_e32 v235, v235
	s_nop 0
	v_pk_add_f32 v[234:235], v[234:235], s[100:101] op_sel_hi:[1,0]
	v_rcp_f32_e32 v234, v234
	v_rcp_f32_e32 v235, v235
	s_nop 0
	v_pk_mul_f32 v[248:249], v[248:249], v[234:235]
	v_pk_mul_f32 v[248:249], v[248:249], v[130:131]
	s_nop 0
	s_nop 0
	s_nop 0
	s_nop 0
	v_pk_mul_f32 v[250:251], v[136:137], s[98:99] op_sel_hi:[1,0]
	v_pk_mul_f32 v[234:235], v[136:137], s[98:99] op_sel:[0,1] op_sel_hi:[1,1]
	v_exp_f32_e32 v234, v234
	v_exp_f32_e32 v235, v235
	s_nop 0
	v_pk_add_f32 v[234:235], v[234:235], s[100:101] op_sel_hi:[1,0]
	v_rcp_f32_e32 v234, v234
	v_rcp_f32_e32 v235, v235
	s_nop 0
	v_pk_mul_f32 v[250:251], v[250:251], v[234:235]
	v_pk_mul_f32 v[250:251], v[250:251], v[132:133]
	s_nop 0
	s_nop 0
	s_nop 0
	s_nop 0
	v_cvt_pk_fp8_f32 v8, v5, v7
	v_med3_f32 v5, v246, s40, v190
	v_med3_f32 v7, v247, s40, v190
	v_cvt_pk_fp8_f32 v8, v5, v7 op_sel:[0,0,1]
	v_med3_f32 v5, v248, s40, v190
	v_med3_f32 v7, v249, s40, v190
	v_cvt_pk_fp8_f32 v9, v5, v7
	v_add_u32_e32 v6, 16, v4
	v_med3_f32 v5, v250, s40, v190
	v_med3_f32 v7, v251, s40, v190
	v_cvt_pk_fp8_f32 v9, v5, v7 op_sel:[0,0,1]
	v_ashrrev_i32_e32 v7, 31, v6
	v_lshlrev_b64 v[6:7], 7, v[6:7]
	v_lshl_add_u64 v[6:7], s[10:11], 0, v[6:7]
	v_lshl_add_u64 v[6:7], v[6:7], 0, v[2:3]
	v_pk_mul_f32 v[236:237], v[126:127], s[98:99] op_sel_hi:[1,0]
	v_pk_mul_f32 v[234:235], v[126:127], s[98:99] op_sel:[0,1] op_sel_hi:[1,1]
	v_exp_f32_e32 v234, v234
	v_exp_f32_e32 v235, v235
	s_nop 0
	v_pk_add_f32 v[234:235], v[234:235], s[100:101] op_sel_hi:[1,0]
	v_rcp_f32_e32 v234, v234
	v_rcp_f32_e32 v235, v235
	s_nop 0
	v_pk_mul_f32 v[236:237], v[236:237], v[234:235]
	v_pk_mul_f32 v[236:237], v[236:237], v[122:123]
	global_store_dwordx2 v[6:7], v[8:9], off
	s_nop 0
	s_nop 0
	v_med3_f32 v5, v236, s40, v190
	s_nop 0
	v_pk_mul_f32 v[238:239], v[128:129], s[98:99] op_sel_hi:[1,0]
	v_pk_mul_f32 v[234:235], v[128:129], s[98:99] op_sel:[0,1] op_sel_hi:[1,1]
	v_exp_f32_e32 v234, v234
	v_exp_f32_e32 v235, v235
	s_nop 0
	v_pk_add_f32 v[234:235], v[234:235], s[100:101] op_sel_hi:[1,0]
	v_rcp_f32_e32 v234, v234
	v_rcp_f32_e32 v235, v235
	s_nop 0
	v_pk_mul_f32 v[238:239], v[238:239], v[234:235]
	v_pk_mul_f32 v[238:239], v[238:239], v[124:125]
	v_med3_f32 v7, v237, s40, v190
	s_nop 0
	s_nop 0
	s_nop 0
	v_pk_mul_f32 v[240:241], v[118:119], s[98:99] op_sel_hi:[1,0]
	v_pk_mul_f32 v[234:235], v[118:119], s[98:99] op_sel:[0,1] op_sel_hi:[1,1]
	v_exp_f32_e32 v234, v234
	v_exp_f32_e32 v235, v235
	s_nop 0
	v_pk_add_f32 v[234:235], v[234:235], s[100:101] op_sel_hi:[1,0]
	v_rcp_f32_e32 v234, v234
	v_rcp_f32_e32 v235, v235
	s_nop 0
	v_pk_mul_f32 v[240:241], v[240:241], v[234:235]
	v_pk_mul_f32 v[240:241], v[240:241], v[114:115]
	s_nop 0
	s_nop 0
	s_nop 0
	s_nop 0
	v_pk_mul_f32 v[242:243], v[120:121], s[98:99] op_sel_hi:[1,0]
	v_pk_mul_f32 v[234:235], v[120:121], s[98:99] op_sel:[0,1] op_sel_hi:[1,1]
	v_exp_f32_e32 v234, v234
	v_exp_f32_e32 v235, v235
	s_nop 0
	v_pk_add_f32 v[234:235], v[234:235], s[100:101] op_sel_hi:[1,0]
	v_rcp_f32_e32 v234, v234
	v_rcp_f32_e32 v235, v235
	s_nop 0
	v_pk_mul_f32 v[242:243], v[242:243], v[234:235]
	v_pk_mul_f32 v[242:243], v[242:243], v[116:117]
	s_nop 0
	s_nop 0
	s_nop 0
	s_nop 0
	v_cvt_pk_fp8_f32 v8, v5, v7
	v_med3_f32 v5, v238, s40, v190
	v_med3_f32 v7, v239, s40, v190
	v_cvt_pk_fp8_f32 v8, v5, v7 op_sel:[0,0,1]
	v_med3_f32 v5, v240, s40, v190
	v_med3_f32 v7, v241, s40, v190
	v_cvt_pk_fp8_f32 v9, v5, v7
	v_add_u32_e32 v6, 32, v4
	v_med3_f32 v5, v242, s40, v190
	v_med3_f32 v7, v243, s40, v190
	v_cvt_pk_fp8_f32 v9, v5, v7 op_sel:[0,0,1]
	v_ashrrev_i32_e32 v7, 31, v6
	v_lshlrev_b64 v[6:7], 7, v[6:7]
	v_lshl_add_u64 v[6:7], s[10:11], 0, v[6:7]
	v_lshl_add_u64 v[6:7], v[6:7], 0, v[2:3]
	v_pk_mul_f32 v[244:245], v[110:111], s[98:99] op_sel_hi:[1,0]
	v_pk_mul_f32 v[234:235], v[110:111], s[98:99] op_sel:[0,1] op_sel_hi:[1,1]
	v_exp_f32_e32 v234, v234
	v_exp_f32_e32 v235, v235
	s_nop 0
	v_pk_add_f32 v[234:235], v[234:235], s[100:101] op_sel_hi:[1,0]
	v_rcp_f32_e32 v234, v234
	v_rcp_f32_e32 v235, v235
	s_nop 0
	v_pk_mul_f32 v[244:245], v[244:245], v[234:235]
	v_pk_mul_f32 v[244:245], v[244:245], v[106:107]
	global_store_dwordx2 v[6:7], v[8:9], off
	s_nop 0
	s_nop 0
	v_med3_f32 v5, v244, s40, v190
	s_nop 0
	v_pk_mul_f32 v[246:247], v[112:113], s[98:99] op_sel_hi:[1,0]
	v_pk_mul_f32 v[234:235], v[112:113], s[98:99] op_sel:[0,1] op_sel_hi:[1,1]
	v_exp_f32_e32 v234, v234
	v_exp_f32_e32 v235, v235
	s_nop 0
	v_pk_add_f32 v[234:235], v[234:235], s[100:101] op_sel_hi:[1,0]
	v_rcp_f32_e32 v234, v234
	v_rcp_f32_e32 v235, v235
	s_nop 0
	v_pk_mul_f32 v[246:247], v[246:247], v[234:235]
	v_pk_mul_f32 v[246:247], v[246:247], v[108:109]
	v_med3_f32 v7, v245, s40, v190
	s_nop 0
	s_nop 0
	s_nop 0
	v_pk_mul_f32 v[248:249], v[102:103], s[98:99] op_sel_hi:[1,0]
	v_pk_mul_f32 v[234:235], v[102:103], s[98:99] op_sel:[0,1] op_sel_hi:[1,1]
	v_exp_f32_e32 v234, v234
	v_exp_f32_e32 v235, v235
	s_nop 0
	v_pk_add_f32 v[234:235], v[234:235], s[100:101] op_sel_hi:[1,0]
	v_rcp_f32_e32 v234, v234
	v_rcp_f32_e32 v235, v235
	s_nop 0
	v_pk_mul_f32 v[248:249], v[248:249], v[234:235]
	v_pk_mul_f32 v[248:249], v[248:249], v[98:99]
	s_nop 0
	s_nop 0
	s_nop 0
	s_nop 0
	v_pk_mul_f32 v[250:251], v[104:105], s[98:99] op_sel_hi:[1,0]
	v_pk_mul_f32 v[234:235], v[104:105], s[98:99] op_sel:[0,1] op_sel_hi:[1,1]
	v_exp_f32_e32 v234, v234
	v_exp_f32_e32 v235, v235
	s_nop 0
	v_pk_add_f32 v[234:235], v[234:235], s[100:101] op_sel_hi:[1,0]
	v_rcp_f32_e32 v234, v234
	v_rcp_f32_e32 v235, v235
	s_nop 0
	v_pk_mul_f32 v[250:251], v[250:251], v[234:235]
	v_pk_mul_f32 v[250:251], v[250:251], v[100:101]
	s_nop 0
	s_nop 0
	s_nop 0
	s_nop 0
	v_cvt_pk_fp8_f32 v8, v5, v7
	v_med3_f32 v5, v246, s40, v190
	v_med3_f32 v7, v247, s40, v190
	v_cvt_pk_fp8_f32 v8, v5, v7 op_sel:[0,0,1]
	v_med3_f32 v5, v248, s40, v190
	v_med3_f32 v7, v249, s40, v190
	v_cvt_pk_fp8_f32 v9, v5, v7
	v_add_u32_e32 v6, 48, v4
	v_med3_f32 v5, v250, s40, v190
	v_med3_f32 v7, v251, s40, v190
	v_cvt_pk_fp8_f32 v9, v5, v7 op_sel:[0,0,1]
	v_ashrrev_i32_e32 v7, 31, v6
	v_lshlrev_b64 v[6:7], 7, v[6:7]
	v_lshl_add_u64 v[6:7], s[10:11], 0, v[6:7]
	v_lshl_add_u64 v[6:7], v[6:7], 0, v[2:3]
	v_pk_mul_f32 v[236:237], v[94:95], s[98:99] op_sel_hi:[1,0]
	v_pk_mul_f32 v[234:235], v[94:95], s[98:99] op_sel:[0,1] op_sel_hi:[1,1]
	v_exp_f32_e32 v234, v234
	v_exp_f32_e32 v235, v235
	s_nop 0
	v_pk_add_f32 v[234:235], v[234:235], s[100:101] op_sel_hi:[1,0]
	v_rcp_f32_e32 v234, v234
	v_rcp_f32_e32 v235, v235
	s_nop 0
	v_pk_mul_f32 v[236:237], v[236:237], v[234:235]
	v_pk_mul_f32 v[236:237], v[236:237], v[90:91]
	global_store_dwordx2 v[6:7], v[8:9], off
	v_add_u32_e32 v6, 0x80, v4
	s_nop 0
	v_med3_f32 v5, v236, s40, v190
	s_nop 0
	v_pk_mul_f32 v[238:239], v[96:97], s[98:99] op_sel_hi:[1,0]
	v_pk_mul_f32 v[234:235], v[96:97], s[98:99] op_sel:[0,1] op_sel_hi:[1,1]
	v_exp_f32_e32 v234, v234
	v_exp_f32_e32 v235, v235
	s_nop 0
	v_pk_add_f32 v[234:235], v[234:235], s[100:101] op_sel_hi:[1,0]
	v_rcp_f32_e32 v234, v234
	v_rcp_f32_e32 v235, v235
	s_nop 0
	v_pk_mul_f32 v[238:239], v[238:239], v[234:235]
	v_pk_mul_f32 v[238:239], v[238:239], v[92:93]
	v_med3_f32 v7, v237, s40, v190
	s_nop 0
	s_nop 0
	s_nop 0
	v_pk_mul_f32 v[240:241], v[86:87], s[98:99] op_sel_hi:[1,0]
	v_pk_mul_f32 v[234:235], v[86:87], s[98:99] op_sel:[0,1] op_sel_hi:[1,1]
	v_exp_f32_e32 v234, v234
	v_exp_f32_e32 v235, v235
	s_nop 0
	v_pk_add_f32 v[234:235], v[234:235], s[100:101] op_sel_hi:[1,0]
	v_rcp_f32_e32 v234, v234
	v_rcp_f32_e32 v235, v235
	s_nop 0
	v_pk_mul_f32 v[240:241], v[240:241], v[234:235]
	v_pk_mul_f32 v[240:241], v[240:241], v[82:83]
	s_nop 0
	s_nop 0
	s_nop 0
	s_nop 0
	v_pk_mul_f32 v[242:243], v[88:89], s[98:99] op_sel_hi:[1,0]
	v_pk_mul_f32 v[234:235], v[88:89], s[98:99] op_sel:[0,1] op_sel_hi:[1,1]
	v_exp_f32_e32 v234, v234
	v_exp_f32_e32 v235, v235
	s_nop 0
	v_pk_add_f32 v[234:235], v[234:235], s[100:101] op_sel_hi:[1,0]
	v_rcp_f32_e32 v234, v234
	v_rcp_f32_e32 v235, v235
	s_nop 0
	v_pk_mul_f32 v[242:243], v[242:243], v[234:235]
	v_pk_mul_f32 v[242:243], v[242:243], v[84:85]
	s_nop 0
	s_nop 0
	s_nop 0
	s_nop 0
	v_cvt_pk_fp8_f32 v8, v5, v7
	v_med3_f32 v5, v238, s40, v190
	v_med3_f32 v7, v239, s40, v190
	v_cvt_pk_fp8_f32 v8, v5, v7 op_sel:[0,0,1]
	v_med3_f32 v5, v240, s40, v190
	v_med3_f32 v7, v241, s40, v190
	v_cvt_pk_fp8_f32 v9, v5, v7
	v_med3_f32 v5, v242, s40, v190
	v_med3_f32 v7, v243, s40, v190
	v_cvt_pk_fp8_f32 v9, v5, v7 op_sel:[0,0,1]
	v_ashrrev_i32_e32 v7, 31, v6
	v_lshlrev_b64 v[6:7], 7, v[6:7]
	v_lshl_add_u64 v[6:7], s[10:11], 0, v[6:7]
	v_lshl_add_u64 v[6:7], v[6:7], 0, v[2:3]
	v_pk_mul_f32 v[244:245], v[78:79], s[98:99] op_sel_hi:[1,0]
	v_pk_mul_f32 v[234:235], v[78:79], s[98:99] op_sel:[0,1] op_sel_hi:[1,1]
	v_exp_f32_e32 v234, v234
	v_exp_f32_e32 v235, v235
	s_nop 0
	v_pk_add_f32 v[234:235], v[234:235], s[100:101] op_sel_hi:[1,0]
	v_rcp_f32_e32 v234, v234
	v_rcp_f32_e32 v235, v235
	s_nop 0
	v_pk_mul_f32 v[244:245], v[244:245], v[234:235]
	v_pk_mul_f32 v[244:245], v[244:245], v[74:75]
	global_store_dwordx2 v[6:7], v[8:9], off
	s_nop 0
	s_nop 0
	v_med3_f32 v5, v244, s40, v190
	s_nop 0
	v_pk_mul_f32 v[246:247], v[80:81], s[98:99] op_sel_hi:[1,0]
	v_pk_mul_f32 v[234:235], v[80:81], s[98:99] op_sel:[0,1] op_sel_hi:[1,1]
	v_exp_f32_e32 v234, v234
	v_exp_f32_e32 v235, v235
	s_nop 0
	v_pk_add_f32 v[234:235], v[234:235], s[100:101] op_sel_hi:[1,0]
	v_rcp_f32_e32 v234, v234
	v_rcp_f32_e32 v235, v235
	s_nop 0
	v_pk_mul_f32 v[246:247], v[246:247], v[234:235]
	v_pk_mul_f32 v[246:247], v[246:247], v[76:77]
	v_med3_f32 v7, v245, s40, v190
	s_nop 0
	s_nop 0
	s_nop 0
	v_pk_mul_f32 v[248:249], v[70:71], s[98:99] op_sel_hi:[1,0]
	v_pk_mul_f32 v[234:235], v[70:71], s[98:99] op_sel:[0,1] op_sel_hi:[1,1]
	v_exp_f32_e32 v234, v234
	v_exp_f32_e32 v235, v235
	s_nop 0
	v_pk_add_f32 v[234:235], v[234:235], s[100:101] op_sel_hi:[1,0]
	v_rcp_f32_e32 v234, v234
	v_rcp_f32_e32 v235, v235
	s_nop 0
	v_pk_mul_f32 v[248:249], v[248:249], v[234:235]
	v_pk_mul_f32 v[248:249], v[248:249], v[66:67]
	s_nop 0
	s_nop 0
	s_nop 0
	s_nop 0
	v_pk_mul_f32 v[250:251], v[72:73], s[98:99] op_sel_hi:[1,0]
	v_pk_mul_f32 v[234:235], v[72:73], s[98:99] op_sel:[0,1] op_sel_hi:[1,1]
	v_exp_f32_e32 v234, v234
	v_exp_f32_e32 v235, v235
	s_nop 0
	v_pk_add_f32 v[234:235], v[234:235], s[100:101] op_sel_hi:[1,0]
	v_rcp_f32_e32 v234, v234
	v_rcp_f32_e32 v235, v235
	s_nop 0
	v_pk_mul_f32 v[250:251], v[250:251], v[234:235]
	v_pk_mul_f32 v[250:251], v[250:251], v[68:69]
	s_nop 0
	s_nop 0
	s_nop 0
	s_nop 0
	v_cvt_pk_fp8_f32 v8, v5, v7
	v_med3_f32 v5, v246, s40, v190
	v_med3_f32 v7, v247, s40, v190
	v_cvt_pk_fp8_f32 v8, v5, v7 op_sel:[0,0,1]
	v_med3_f32 v5, v248, s40, v190
	v_med3_f32 v7, v249, s40, v190
	v_cvt_pk_fp8_f32 v9, v5, v7
	v_add_u32_e32 v6, 0x90, v4
	v_med3_f32 v5, v250, s40, v190
	v_med3_f32 v7, v251, s40, v190
	v_cvt_pk_fp8_f32 v9, v5, v7 op_sel:[0,0,1]
	v_ashrrev_i32_e32 v7, 31, v6
	v_lshlrev_b64 v[6:7], 7, v[6:7]
	v_lshl_add_u64 v[6:7], s[10:11], 0, v[6:7]
	v_lshl_add_u64 v[6:7], v[6:7], 0, v[2:3]
	v_pk_mul_f32 v[236:237], v[62:63], s[98:99] op_sel_hi:[1,0]
	v_pk_mul_f32 v[234:235], v[62:63], s[98:99] op_sel:[0,1] op_sel_hi:[1,1]
	v_exp_f32_e32 v234, v234
	v_exp_f32_e32 v235, v235
	s_nop 0
	v_pk_add_f32 v[234:235], v[234:235], s[100:101] op_sel_hi:[1,0]
	v_rcp_f32_e32 v234, v234
	v_rcp_f32_e32 v235, v235
	s_nop 0
	v_pk_mul_f32 v[236:237], v[236:237], v[234:235]
	v_pk_mul_f32 v[236:237], v[236:237], v[58:59]
	global_store_dwordx2 v[6:7], v[8:9], off
	s_nop 0
	s_nop 0
	v_med3_f32 v5, v236, s40, v190
	s_nop 0
	v_pk_mul_f32 v[238:239], v[64:65], s[98:99] op_sel_hi:[1,0]
	v_pk_mul_f32 v[234:235], v[64:65], s[98:99] op_sel:[0,1] op_sel_hi:[1,1]
	v_exp_f32_e32 v234, v234
	v_exp_f32_e32 v235, v235
	s_nop 0
	v_pk_add_f32 v[234:235], v[234:235], s[100:101] op_sel_hi:[1,0]
	v_rcp_f32_e32 v234, v234
	v_rcp_f32_e32 v235, v235
	s_nop 0
	v_pk_mul_f32 v[238:239], v[238:239], v[234:235]
	v_pk_mul_f32 v[238:239], v[238:239], v[60:61]
	v_med3_f32 v7, v237, s40, v190
	s_nop 0
	s_nop 0
	s_nop 0
	v_pk_mul_f32 v[240:241], v[54:55], s[98:99] op_sel_hi:[1,0]
	v_pk_mul_f32 v[234:235], v[54:55], s[98:99] op_sel:[0,1] op_sel_hi:[1,1]
	v_exp_f32_e32 v234, v234
	v_exp_f32_e32 v235, v235
	s_nop 0
	v_pk_add_f32 v[234:235], v[234:235], s[100:101] op_sel_hi:[1,0]
	v_rcp_f32_e32 v234, v234
	v_rcp_f32_e32 v235, v235
	s_nop 0
	v_pk_mul_f32 v[240:241], v[240:241], v[234:235]
	v_pk_mul_f32 v[240:241], v[240:241], v[50:51]
	s_nop 0
	s_nop 0
	s_nop 0
	s_nop 0
	v_pk_mul_f32 v[242:243], v[56:57], s[98:99] op_sel_hi:[1,0]
	v_pk_mul_f32 v[234:235], v[56:57], s[98:99] op_sel:[0,1] op_sel_hi:[1,1]
	v_exp_f32_e32 v234, v234
	v_exp_f32_e32 v235, v235
	s_nop 0
	v_pk_add_f32 v[234:235], v[234:235], s[100:101] op_sel_hi:[1,0]
	v_rcp_f32_e32 v234, v234
	v_rcp_f32_e32 v235, v235
	s_nop 0
	v_pk_mul_f32 v[242:243], v[242:243], v[234:235]
	v_pk_mul_f32 v[242:243], v[242:243], v[52:53]
	s_nop 0
	s_nop 0
	s_nop 0
	s_nop 0
	v_cvt_pk_fp8_f32 v8, v5, v7
	v_med3_f32 v5, v238, s40, v190
	v_med3_f32 v7, v239, s40, v190
	v_cvt_pk_fp8_f32 v8, v5, v7 op_sel:[0,0,1]
	v_med3_f32 v5, v240, s40, v190
	v_med3_f32 v7, v241, s40, v190
	v_cvt_pk_fp8_f32 v9, v5, v7
	v_add_u32_e32 v6, 0xa0, v4
	v_med3_f32 v5, v242, s40, v190
	v_med3_f32 v7, v243, s40, v190
	v_cvt_pk_fp8_f32 v9, v5, v7 op_sel:[0,0,1]
	v_ashrrev_i32_e32 v7, 31, v6
	v_lshlrev_b64 v[6:7], 7, v[6:7]
	v_lshl_add_u64 v[6:7], s[10:11], 0, v[6:7]
	v_lshl_add_u64 v[6:7], v[6:7], 0, v[2:3]
	v_pk_mul_f32 v[244:245], v[46:47], s[98:99] op_sel_hi:[1,0]
	v_pk_mul_f32 v[234:235], v[46:47], s[98:99] op_sel:[0,1] op_sel_hi:[1,1]
	v_exp_f32_e32 v234, v234
	v_exp_f32_e32 v235, v235
	s_nop 0
	v_pk_add_f32 v[234:235], v[234:235], s[100:101] op_sel_hi:[1,0]
	v_rcp_f32_e32 v234, v234
	v_rcp_f32_e32 v235, v235
	s_nop 0
	v_pk_mul_f32 v[244:245], v[244:245], v[234:235]
	v_pk_mul_f32 v[244:245], v[244:245], v[42:43]
	global_store_dwordx2 v[6:7], v[8:9], off
	v_add_u32_e32 v4, 0xb0, v4
	s_nop 0
	v_med3_f32 v5, v244, s40, v190
	s_nop 0
	v_pk_mul_f32 v[246:247], v[48:49], s[98:99] op_sel_hi:[1,0]
	v_pk_mul_f32 v[234:235], v[48:49], s[98:99] op_sel:[0,1] op_sel_hi:[1,1]
	v_exp_f32_e32 v234, v234
	v_exp_f32_e32 v235, v235
	s_nop 0
	v_pk_add_f32 v[234:235], v[234:235], s[100:101] op_sel_hi:[1,0]
	v_rcp_f32_e32 v234, v234
	v_rcp_f32_e32 v235, v235
	s_nop 0
	v_pk_mul_f32 v[246:247], v[246:247], v[234:235]
	v_pk_mul_f32 v[246:247], v[246:247], v[44:45]
	s_nop 0
	s_nop 0
	v_pk_mul_f32 v[248:249], v[38:39], s[98:99] op_sel_hi:[1,0]
	v_pk_mul_f32 v[234:235], v[38:39], s[98:99] op_sel:[0,1] op_sel_hi:[1,1]
	v_exp_f32_e32 v234, v234
	v_exp_f32_e32 v235, v235
	s_nop 0
	v_pk_add_f32 v[234:235], v[234:235], s[100:101] op_sel_hi:[1,0]
	v_rcp_f32_e32 v234, v234
	v_rcp_f32_e32 v235, v235
	s_nop 0
	v_pk_mul_f32 v[248:249], v[248:249], v[234:235]
	v_pk_mul_f32 v[248:249], v[248:249], v[34:35]
	s_nop 0
	s_nop 0
	v_pk_mul_f32 v[250:251], v[40:41], s[98:99] op_sel_hi:[1,0]
	v_pk_mul_f32 v[234:235], v[40:41], s[98:99] op_sel:[0,1] op_sel_hi:[1,1]
	v_exp_f32_e32 v234, v234
	v_exp_f32_e32 v235, v235
	s_nop 0
	v_pk_add_f32 v[234:235], v[234:235], s[100:101] op_sel_hi:[1,0]
	v_rcp_f32_e32 v234, v234
	v_rcp_f32_e32 v235, v235
	s_nop 0
	v_pk_mul_f32 v[250:251], v[250:251], v[234:235]
	v_pk_mul_f32 v[250:251], v[250:251], v[36:37]
	s_nop 0
	s_nop 0
	v_med3_f32 v13, v245, s40, v190
	v_cvt_pk_fp8_f32 v6, v5, v13
	v_med3_f32 v5, v246, s40, v190
	v_med3_f32 v7, v247, s40, v190
	v_med3_f32 v8, v249, s40, v190
	v_cvt_pk_fp8_f32 v6, v5, v7 op_sel:[0,0,1]
	v_med3_f32 v5, v248, s40, v190
	v_cvt_pk_fp8_f32 v7, v5, v8
	v_med3_f32 v5, v250, s40, v190
	v_med3_f32 v8, v251, s40, v190
	v_cvt_pk_fp8_f32 v7, v5, v8 op_sel:[0,0,1]
	v_ashrrev_i32_e32 v5, 31, v4
	v_lshlrev_b64 v[4:5], 7, v[4:5]
	v_lshl_add_u64 v[4:5], s[10:11], 0, v[4:5]
	v_lshl_add_u64 v[2:3], v[4:5], 0, v[2:3]
	global_store_dwordx2 v[2:3], v[6:7], off
	s_cbranch_vccz .LBB0_677
	s_waitcnt vmcnt(0)
	s_cmpk_gt_u32 s42, 0xff
	s_cbranch_scc1 .LBB0_623
	s_barrier
	s_branch .LBB0_623

.Lpeel_exit_3:
	v_pk_mul_f32 v[10:11], v[142:143], s[14:15] op_sel_hi:[1,0]
	v_pk_mul_f32 v[8:9], v[144:145], s[14:15] op_sel_hi:[1,0]
	v_med3_f32 v5, v10, s47, v173
	v_med3_f32 v11, v11, s47, v173
	v_cvt_pk_fp8_f32 v10, v5, v11
	v_mov_b32_e32 v3, v166
	v_mov_b32_e32 v2, v167
	s_lshl_b32 s0, s48, 8
	v_pk_mul_f32 v[14:15], v[138:139], s[14:15] op_sel_hi:[1,0]
	v_med3_f32 v5, v8, s47, v173
	v_med3_f32 v8, v9, s47, v173
	s_nop 15
	s_nop 15
	s_or_b32 s0, s0, s42
	v_cvt_pk_fp8_f32 v10, v5, v8 op_sel:[0,0,1]
	v_med3_f32 v5, v14, s47, v173
	v_med3_f32 v8, v15, s47, v173
	v_lshl_add_u32 v2, v2, 3, s0
	s_lshl_b32 s0, s24, 8
	v_cvt_pk_fp8_f32 v11, v5, v8
	s_add_i32 s0, s0, s41
	v_add_u32_e32 v4, s0, v3
	v_pk_mul_f32 v[12:13], v[140:141], s[14:15] op_sel_hi:[1,0]
	v_mov_b32_e32 v6, v4
	v_med3_f32 v5, v12, s47, v173
	v_med3_f32 v8, v13, s47, v173
	v_cvt_pk_fp8_f32 v11, v5, v8 op_sel:[0,0,1]
	v_ashrrev_i32_e32 v7, 31, v6
	v_lshlrev_b64 v[6:7], 10, v[6:7]
	v_ashrrev_i32_e32 v3, 31, v2
	v_lshl_add_u64 v[6:7], s[10:11], 0, v[6:7]
	v_lshl_add_u64 v[6:7], v[6:7], 0, v[2:3]
	global_store_dwordx2 v[6:7], v[10:11], off
	v_pk_mul_f32 v[10:11], v[134:135], s[14:15] op_sel_hi:[1,0]
	v_pk_mul_f32 v[8:9], v[136:137], s[14:15] op_sel_hi:[1,0]
	v_med3_f32 v5, v10, s47, v173
	v_med3_f32 v11, v11, s47, v173
	v_cvt_pk_fp8_f32 v10, v5, v11
	v_pk_mul_f32 v[14:15], v[130:131], s[14:15] op_sel_hi:[1,0]
	v_med3_f32 v5, v8, s47, v173
	v_med3_f32 v8, v9, s47, v173
	v_cvt_pk_fp8_f32 v10, v5, v8 op_sel:[0,0,1]
	v_med3_f32 v5, v14, s47, v173
	v_med3_f32 v8, v15, s47, v173
	v_cvt_pk_fp8_f32 v11, v5, v8
	v_pk_mul_f32 v[12:13], v[132:133], s[14:15] op_sel_hi:[1,0]
	v_pk_mul_f32 v[14:15], v[122:123], s[14:15] op_sel_hi:[1,0]
	v_med3_f32 v5, v12, s47, v173
	v_med3_f32 v8, v13, s47, v173
	v_cvt_pk_fp8_f32 v11, v5, v8 op_sel:[0,0,1]
	v_pk_mul_f32 v[8:9], v[128:129], s[14:15] op_sel_hi:[1,0]
	v_pk_mul_f32 v[12:13], v[124:125], s[14:15] op_sel_hi:[1,0]
	s_and_b64 vcc, exec, s[8:9]
	global_store_dwordx2 v[6:7], v[10:11], off offset:128
	v_pk_mul_f32 v[10:11], v[126:127], s[14:15] op_sel_hi:[1,0]
	v_add_u32_e32 v6, 16, v4
	v_med3_f32 v5, v10, s47, v173
	v_med3_f32 v11, v11, s47, v173
	v_cvt_pk_fp8_f32 v10, v5, v11
	v_med3_f32 v5, v8, s47, v173
	v_med3_f32 v8, v9, s47, v173
	v_cvt_pk_fp8_f32 v10, v5, v8 op_sel:[0,0,1]
	v_med3_f32 v5, v14, s47, v173
	v_med3_f32 v8, v15, s47, v173
	v_cvt_pk_fp8_f32 v11, v5, v8
	v_med3_f32 v5, v12, s47, v173
	v_med3_f32 v8, v13, s47, v173
	v_cvt_pk_fp8_f32 v11, v5, v8 op_sel:[0,0,1]
	v_ashrrev_i32_e32 v7, 31, v6
	v_lshlrev_b64 v[6:7], 10, v[6:7]
	v_lshl_add_u64 v[6:7], s[10:11], 0, v[6:7]
	v_lshl_add_u64 v[6:7], v[6:7], 0, v[2:3]
	global_store_dwordx2 v[6:7], v[10:11], off
	v_pk_mul_f32 v[10:11], v[118:119], s[14:15] op_sel_hi:[1,0]
	v_pk_mul_f32 v[8:9], v[120:121], s[14:15] op_sel_hi:[1,0]
	v_med3_f32 v5, v10, s47, v173
	v_med3_f32 v11, v11, s47, v173
	v_cvt_pk_fp8_f32 v10, v5, v11
	v_pk_mul_f32 v[14:15], v[114:115], s[14:15] op_sel_hi:[1,0]
	v_med3_f32 v5, v8, s47, v173
	v_med3_f32 v8, v9, s47, v173
	v_cvt_pk_fp8_f32 v10, v5, v8 op_sel:[0,0,1]
	v_med3_f32 v5, v14, s47, v173
	v_med3_f32 v8, v15, s47, v173
	v_cvt_pk_fp8_f32 v11, v5, v8
	v_pk_mul_f32 v[12:13], v[116:117], s[14:15] op_sel_hi:[1,0]
	v_pk_mul_f32 v[14:15], v[106:107], s[14:15] op_sel_hi:[1,0]
	v_med3_f32 v5, v12, s47, v173
	v_med3_f32 v8, v13, s47, v173
	v_cvt_pk_fp8_f32 v11, v5, v8 op_sel:[0,0,1]
	v_pk_mul_f32 v[8:9], v[112:113], s[14:15] op_sel_hi:[1,0]
	v_pk_mul_f32 v[12:13], v[108:109], s[14:15] op_sel_hi:[1,0]
	s_mov_b32 s48, s16
	global_store_dwordx2 v[6:7], v[10:11], off offset:128
	v_pk_mul_f32 v[10:11], v[110:111], s[14:15] op_sel_hi:[1,0]
	v_add_u32_e32 v6, 32, v4
	v_med3_f32 v5, v10, s47, v173
	v_med3_f32 v11, v11, s47, v173
	v_cvt_pk_fp8_f32 v10, v5, v11
	v_med3_f32 v5, v8, s47, v173
	v_med3_f32 v8, v9, s47, v173
	v_cvt_pk_fp8_f32 v10, v5, v8 op_sel:[0,0,1]
	v_med3_f32 v5, v14, s47, v173
	v_med3_f32 v8, v15, s47, v173
	v_cvt_pk_fp8_f32 v11, v5, v8
	v_med3_f32 v5, v12, s47, v173
	v_med3_f32 v8, v13, s47, v173
	v_cvt_pk_fp8_f32 v11, v5, v8 op_sel:[0,0,1]
	v_ashrrev_i32_e32 v7, 31, v6
	v_lshlrev_b64 v[6:7], 10, v[6:7]
	v_lshl_add_u64 v[6:7], s[10:11], 0, v[6:7]
	v_lshl_add_u64 v[6:7], v[6:7], 0, v[2:3]
	global_store_dwordx2 v[6:7], v[10:11], off
	v_pk_mul_f32 v[10:11], v[102:103], s[14:15] op_sel_hi:[1,0]
	v_pk_mul_f32 v[8:9], v[104:105], s[14:15] op_sel_hi:[1,0]
	v_med3_f32 v5, v10, s47, v173
	v_med3_f32 v11, v11, s47, v173
	v_cvt_pk_fp8_f32 v10, v5, v11
	v_pk_mul_f32 v[14:15], v[98:99], s[14:15] op_sel_hi:[1,0]
	v_med3_f32 v5, v8, s47, v173
	v_med3_f32 v8, v9, s47, v173
	v_cvt_pk_fp8_f32 v10, v5, v8 op_sel:[0,0,1]
	v_med3_f32 v5, v14, s47, v173
	v_med3_f32 v8, v15, s47, v173
	v_cvt_pk_fp8_f32 v11, v5, v8
	v_pk_mul_f32 v[12:13], v[100:101], s[14:15] op_sel_hi:[1,0]
	v_pk_mul_f32 v[14:15], v[90:91], s[14:15] op_sel_hi:[1,0]
	v_med3_f32 v5, v12, s47, v173
	v_med3_f32 v8, v13, s47, v173
	v_cvt_pk_fp8_f32 v11, v5, v8 op_sel:[0,0,1]
	v_pk_mul_f32 v[8:9], v[96:97], s[14:15] op_sel_hi:[1,0]
	v_pk_mul_f32 v[12:13], v[92:93], s[14:15] op_sel_hi:[1,0]
	s_mov_b32 s24, s18
	global_store_dwordx2 v[6:7], v[10:11], off offset:128
	v_pk_mul_f32 v[10:11], v[94:95], s[14:15] op_sel_hi:[1,0]
	v_add_u32_e32 v6, 48, v4
	v_med3_f32 v5, v10, s47, v173
	v_med3_f32 v11, v11, s47, v173
	v_cvt_pk_fp8_f32 v10, v5, v11
	v_med3_f32 v5, v8, s47, v173
	v_med3_f32 v8, v9, s47, v173
	v_cvt_pk_fp8_f32 v10, v5, v8 op_sel:[0,0,1]
	v_med3_f32 v5, v14, s47, v173
	v_med3_f32 v8, v15, s47, v173
	v_cvt_pk_fp8_f32 v11, v5, v8
	v_med3_f32 v5, v12, s47, v173
	v_med3_f32 v8, v13, s47, v173
	v_cvt_pk_fp8_f32 v11, v5, v8 op_sel:[0,0,1]
	v_ashrrev_i32_e32 v7, 31, v6
	v_lshlrev_b64 v[6:7], 10, v[6:7]
	v_lshl_add_u64 v[6:7], s[10:11], 0, v[6:7]
	v_lshl_add_u64 v[6:7], v[6:7], 0, v[2:3]
	global_store_dwordx2 v[6:7], v[10:11], off
	v_pk_mul_f32 v[10:11], v[86:87], s[14:15] op_sel_hi:[1,0]
	v_pk_mul_f32 v[8:9], v[88:89], s[14:15] op_sel_hi:[1,0]
	v_med3_f32 v5, v10, s47, v173
	v_med3_f32 v11, v11, s47, v173
	v_cvt_pk_fp8_f32 v10, v5, v11
	v_pk_mul_f32 v[14:15], v[82:83], s[14:15] op_sel_hi:[1,0]
	v_med3_f32 v5, v8, s47, v173
	v_med3_f32 v8, v9, s47, v173
	v_cvt_pk_fp8_f32 v10, v5, v8 op_sel:[0,0,1]
	v_med3_f32 v5, v14, s47, v173
	v_med3_f32 v8, v15, s47, v173
	v_cvt_pk_fp8_f32 v11, v5, v8
	v_pk_mul_f32 v[12:13], v[84:85], s[14:15] op_sel_hi:[1,0]
	v_pk_mul_f32 v[14:15], v[74:75], s[14:15] op_sel_hi:[1,0]
	v_med3_f32 v5, v12, s47, v173
	v_med3_f32 v8, v13, s47, v173
	v_cvt_pk_fp8_f32 v11, v5, v8 op_sel:[0,0,1]
	v_pk_mul_f32 v[8:9], v[80:81], s[14:15] op_sel_hi:[1,0]
	v_pk_mul_f32 v[12:13], v[76:77], s[14:15] op_sel_hi:[1,0]
	s_mov_b64 s[26:27], s[22:23]
	global_store_dwordx2 v[6:7], v[10:11], off offset:128
	v_pk_mul_f32 v[10:11], v[78:79], s[14:15] op_sel_hi:[1,0]
	v_add_u32_e32 v6, 0x80, v4
	v_med3_f32 v5, v10, s47, v173
	v_med3_f32 v11, v11, s47, v173
	v_cvt_pk_fp8_f32 v10, v5, v11
	v_med3_f32 v5, v8, s47, v173
	v_med3_f32 v8, v9, s47, v173
	v_cvt_pk_fp8_f32 v10, v5, v8 op_sel:[0,0,1]
	v_med3_f32 v5, v14, s47, v173
	v_med3_f32 v8, v15, s47, v173
	v_cvt_pk_fp8_f32 v11, v5, v8
	v_med3_f32 v5, v12, s47, v173
	v_med3_f32 v8, v13, s47, v173
	v_cvt_pk_fp8_f32 v11, v5, v8 op_sel:[0,0,1]
	v_ashrrev_i32_e32 v7, 31, v6
	v_lshlrev_b64 v[6:7], 10, v[6:7]
	v_lshl_add_u64 v[6:7], s[10:11], 0, v[6:7]
	v_lshl_add_u64 v[6:7], v[6:7], 0, v[2:3]
	global_store_dwordx2 v[6:7], v[10:11], off
	v_pk_mul_f32 v[10:11], v[70:71], s[14:15] op_sel_hi:[1,0]
	v_pk_mul_f32 v[8:9], v[72:73], s[14:15] op_sel_hi:[1,0]
	v_med3_f32 v5, v10, s47, v173
	v_med3_f32 v11, v11, s47, v173
	v_cvt_pk_fp8_f32 v10, v5, v11
	v_pk_mul_f32 v[14:15], v[66:67], s[14:15] op_sel_hi:[1,0]
	v_med3_f32 v5, v8, s47, v173
	v_med3_f32 v8, v9, s47, v173
	v_cvt_pk_fp8_f32 v10, v5, v8 op_sel:[0,0,1]
	v_med3_f32 v5, v14, s47, v173
	v_med3_f32 v8, v15, s47, v173
	v_cvt_pk_fp8_f32 v11, v5, v8
	v_pk_mul_f32 v[12:13], v[68:69], s[14:15] op_sel_hi:[1,0]
	v_pk_mul_f32 v[14:15], v[58:59], s[14:15] op_sel_hi:[1,0]
	v_med3_f32 v5, v12, s47, v173
	v_med3_f32 v8, v13, s47, v173
	v_cvt_pk_fp8_f32 v11, v5, v8 op_sel:[0,0,1]
	v_pk_mul_f32 v[8:9], v[64:65], s[14:15] op_sel_hi:[1,0]
	v_pk_mul_f32 v[12:13], v[60:61], s[14:15] op_sel_hi:[1,0]
	s_mov_b64 s[28:29], s[20:21]
	global_store_dwordx2 v[6:7], v[10:11], off offset:128
	v_pk_mul_f32 v[10:11], v[62:63], s[14:15] op_sel_hi:[1,0]
	v_add_u32_e32 v6, 0x90, v4
	v_med3_f32 v5, v10, s47, v173
	v_med3_f32 v11, v11, s47, v173
	v_cvt_pk_fp8_f32 v10, v5, v11
	v_med3_f32 v5, v8, s47, v173
	v_med3_f32 v8, v9, s47, v173
	v_cvt_pk_fp8_f32 v10, v5, v8 op_sel:[0,0,1]
	v_med3_f32 v5, v14, s47, v173
	v_med3_f32 v8, v15, s47, v173
	v_cvt_pk_fp8_f32 v11, v5, v8
	v_med3_f32 v5, v12, s47, v173
	v_med3_f32 v8, v13, s47, v173
	v_cvt_pk_fp8_f32 v11, v5, v8 op_sel:[0,0,1]
	v_ashrrev_i32_e32 v7, 31, v6
	v_lshlrev_b64 v[6:7], 10, v[6:7]
	v_lshl_add_u64 v[6:7], s[10:11], 0, v[6:7]
	v_lshl_add_u64 v[6:7], v[6:7], 0, v[2:3]
	global_store_dwordx2 v[6:7], v[10:11], off
	v_pk_mul_f32 v[10:11], v[54:55], s[14:15] op_sel_hi:[1,0]
	v_pk_mul_f32 v[8:9], v[56:57], s[14:15] op_sel_hi:[1,0]
	v_med3_f32 v5, v10, s47, v173
	v_med3_f32 v11, v11, s47, v173
	v_cvt_pk_fp8_f32 v10, v5, v11
	v_pk_mul_f32 v[14:15], v[50:51], s[14:15] op_sel_hi:[1,0]
	v_med3_f32 v5, v8, s47, v173
	v_med3_f32 v8, v9, s47, v173
	v_cvt_pk_fp8_f32 v10, v5, v8 op_sel:[0,0,1]
	v_med3_f32 v5, v14, s47, v173
	v_med3_f32 v8, v15, s47, v173
	v_cvt_pk_fp8_f32 v11, v5, v8
	v_pk_mul_f32 v[12:13], v[52:53], s[14:15] op_sel_hi:[1,0]
	v_pk_mul_f32 v[14:15], v[42:43], s[14:15] op_sel_hi:[1,0]
	v_med3_f32 v5, v12, s47, v173
	v_med3_f32 v8, v13, s47, v173
	v_cvt_pk_fp8_f32 v11, v5, v8 op_sel:[0,0,1]
	v_pk_mul_f32 v[8:9], v[48:49], s[14:15] op_sel_hi:[1,0]
	v_pk_mul_f32 v[12:13], v[44:45], s[14:15] op_sel_hi:[1,0]
	global_store_dwordx2 v[6:7], v[10:11], off offset:128
	v_pk_mul_f32 v[10:11], v[46:47], s[14:15] op_sel_hi:[1,0]
	v_add_u32_e32 v6, 0xa0, v4
	v_med3_f32 v5, v10, s47, v173
	v_med3_f32 v11, v11, s47, v173
	v_cvt_pk_fp8_f32 v10, v5, v11
	v_med3_f32 v5, v8, s47, v173
	v_med3_f32 v8, v9, s47, v173
	v_cvt_pk_fp8_f32 v10, v5, v8 op_sel:[0,0,1]
	v_med3_f32 v5, v14, s47, v173
	v_med3_f32 v8, v15, s47, v173
	v_cvt_pk_fp8_f32 v11, v5, v8
	v_med3_f32 v5, v12, s47, v173
	v_med3_f32 v8, v13, s47, v173
	v_cvt_pk_fp8_f32 v11, v5, v8 op_sel:[0,0,1]
	v_ashrrev_i32_e32 v7, 31, v6
	v_lshlrev_b64 v[6:7], 10, v[6:7]
	v_lshl_add_u64 v[6:7], s[10:11], 0, v[6:7]
	v_lshl_add_u64 v[6:7], v[6:7], 0, v[2:3]
	global_store_dwordx2 v[6:7], v[10:11], off
	v_pk_mul_f32 v[10:11], v[38:39], s[14:15] op_sel_hi:[1,0]
	v_pk_mul_f32 v[8:9], v[40:41], s[14:15] op_sel_hi:[1,0]
	v_med3_f32 v5, v10, s47, v173
	v_med3_f32 v11, v11, s47, v173
	v_cvt_pk_fp8_f32 v10, v5, v11
	v_pk_mul_f32 v[14:15], v[34:35], s[14:15] op_sel_hi:[1,0]
	v_med3_f32 v5, v8, s47, v173
	v_med3_f32 v8, v9, s47, v173
	v_cvt_pk_fp8_f32 v10, v5, v8 op_sel:[0,0,1]
	v_med3_f32 v5, v14, s47, v173
	v_med3_f32 v8, v15, s47, v173
	v_cvt_pk_fp8_f32 v11, v5, v8
	v_pk_mul_f32 v[12:13], v[36:37], s[14:15] op_sel_hi:[1,0]
	v_add_u32_e32 v4, 0xb0, v4
	v_med3_f32 v5, v12, s47, v173
	v_med3_f32 v8, v13, s47, v173
	v_cvt_pk_fp8_f32 v11, v5, v8 op_sel:[0,0,1]
	v_pk_mul_f32 v[8:9], v[28:29], s[14:15] op_sel_hi:[1,0]
	global_store_dwordx2 v[6:7], v[10:11], off offset:128
	v_pk_mul_f32 v[6:7], v[30:31], s[14:15] op_sel_hi:[1,0]
	v_pk_mul_f32 v[10:11], v[26:27], s[14:15] op_sel_hi:[1,0]
	v_ashrrev_i32_e32 v5, 31, v4
	v_med3_f32 v12, v6, s47, v173
	v_med3_f32 v7, v7, s47, v173
	v_lshlrev_b64 v[4:5], 10, v[4:5]
	v_cvt_pk_fp8_f32 v6, v12, v7
	v_lshl_add_u64 v[4:5], s[10:11], 0, v[4:5]
	v_lshl_add_u64 v[2:3], v[4:5], 0, v[2:3]
	v_pk_mul_f32 v[4:5], v[32:33], s[14:15] op_sel_hi:[1,0]
	v_med3_f32 v4, v4, s47, v173
	v_med3_f32 v5, v5, s47, v173
	v_cvt_pk_fp8_f32 v6, v4, v5 op_sel:[0,0,1]
	v_med3_f32 v4, v10, s47, v173
	v_med3_f32 v5, v11, s47, v173
	v_cvt_pk_fp8_f32 v7, v4, v5
	v_med3_f32 v4, v8, s47, v173
	v_med3_f32 v5, v9, s47, v173
	v_pk_mul_f32 v[10:11], v[18:19], s[14:15] op_sel_hi:[1,0]
	v_cvt_pk_fp8_f32 v7, v4, v5 op_sel:[0,0,1]
	v_pk_mul_f32 v[4:5], v[24:25], s[14:15] op_sel_hi:[1,0]
	v_pk_mul_f32 v[8:9], v[20:21], s[14:15] op_sel_hi:[1,0]
	v_med3_f32 v4, v4, s47, v173
	global_store_dwordx2 v[2:3], v[6:7], off
	v_pk_mul_f32 v[6:7], v[22:23], s[14:15] op_sel_hi:[1,0]
	v_med3_f32 v5, v5, s47, v173
	v_med3_f32 v12, v6, s47, v173
	v_med3_f32 v7, v7, s47, v173
	v_cvt_pk_fp8_f32 v6, v12, v7
	s_nop 0
	v_cvt_pk_fp8_f32 v6, v4, v5 op_sel:[0,0,1]
	v_med3_f32 v4, v10, s47, v173
	v_med3_f32 v5, v11, s47, v173
	v_cvt_pk_fp8_f32 v7, v4, v5
	v_med3_f32 v4, v8, s47, v173
	v_med3_f32 v5, v9, s47, v173
	v_cvt_pk_fp8_f32 v7, v4, v5 op_sel:[0,0,1]
	global_store_dwordx2 v[2:3], v[6:7], off offset:128
	s_cbranch_vccz .LBB0_748
	s_waitcnt vmcnt(0)
	s_cmpk_gt_u32 s4, 0xff
	s_cbranch_scc1 .LBB0_759
	s_barrier

.LBB0_830:
	s_mul_hi_i32 s0, s21, 0x2aaaaaab
	s_lshr_b32 s1, s0, 31
	s_ashr_i32 s0, s0, 8
	s_add_i32 s16, s0, s1
	s_mul_i32 s0, s16, 0xfffffa00
	s_add_i32 s24, s21, s0
	s_lshr_b32 s0, s24, 22
	s_and_b32 s0, s0, 0x1ff
	s_add_i32 s25, s24, s0
	s_and_b32 s0, s25, 0xfe00
	s_sub_i32 s0, s24, s0
	s_sext_i32_i16 s1, s0
	s_bfe_u32 s1, s1, 0x5001a
	s_add_i32 s1, s0, s1
	s_sext_i32_i16 s8, s1
	s_and_b32 s1, s1, 0xffe0
	s_lshl_b32 s23, s8, 1
	s_sub_i32 s0, s0, s1
	s_andn2_b32 s23, s23, 63
	s_sext_i32_i16 s22, s0
	s_lshl_b32 s8, s22, 5
	v_or_b32_e32 v20, s23, v26
	s_mov_b64 s[18:19], -1
	s_cmpk_gt_i32 s24, 0x3ff
	v_ashrrev_i32_e32 v21, 31, v20
	v_or_b32_e32 v18, 8, v20
	v_or_b32_e32 v16, 16, v20
	v_or_b32_e32 v14, 24, v20
	v_or_b32_e32 v12, 32, v20
	v_or_b32_e32 v10, 40, v20
	v_or_b32_e32 v8, 48, v20
	v_or_b32_e32 v6, 56, v20
	s_cbranch_scc0 .LBB0_832
	s_ashr_i32 s17, s16, 31
	s_lshl_b64 s[0:1], s[16:17], 20
	s_lshl_b64 s[18:19], s[16:17], 22
	s_add_u32 s17, s10, s18
	s_addc_u32 s18, s11, s19
	s_add_u32 s19, s6, s0
	s_addc_u32 s26, s7, s1
	s_ashr_i32 s9, s8, 31
	s_lshl_b64 s[0:1], s[8:9], 2
	s_add_u32 s0, s17, s0
	s_addc_u32 s1, s18, s1
	v_lshl_add_u64 v[72:73], s[0:1], 0, v[2:3]
	v_lshlrev_b64 v[22:23], 12, v[20:21]
	v_lshl_add_u64 v[22:23], v[72:73], 0, v[22:23]
	v_ashrrev_i32_e32 v19, 31, v18
	global_load_dwordx4 v[22:25], v[22:23], off nt
	v_lshlrev_b64 v[48:49], 12, v[18:19]
	v_lshl_add_u64 v[48:49], v[72:73], 0, v[48:49]
	v_ashrrev_i32_e32 v17, 31, v16
	global_load_dwordx4 v[48:51], v[48:49], off nt
	v_lshlrev_b64 v[52:53], 12, v[16:17]
	v_lshl_add_u64 v[52:53], v[72:73], 0, v[52:53]
	v_ashrrev_i32_e32 v15, 31, v14
	global_load_dwordx4 v[52:55], v[52:53], off nt
	v_lshlrev_b64 v[56:57], 12, v[14:15]
	v_lshl_add_u64 v[56:57], v[72:73], 0, v[56:57]
	v_ashrrev_i32_e32 v13, 31, v12
	global_load_dwordx4 v[56:59], v[56:57], off nt
	v_lshlrev_b64 v[60:61], 12, v[12:13]
	v_lshl_add_u64 v[60:61], v[72:73], 0, v[60:61]
	v_ashrrev_i32_e32 v11, 31, v10
	global_load_dwordx4 v[60:63], v[60:61], off nt
	v_lshlrev_b64 v[64:65], 12, v[10:11]
	v_lshl_add_u64 v[64:65], v[72:73], 0, v[64:65]
	v_ashrrev_i32_e32 v9, 31, v8
	global_load_dwordx4 v[64:67], v[64:65], off nt
	v_lshlrev_b64 v[68:69], 12, v[8:9]
	v_lshl_add_u64 v[68:69], v[72:73], 0, v[68:69]
	v_ashrrev_i32_e32 v7, 31, v6
	global_load_dwordx4 v[68:71], v[68:69], off nt
	v_lshlrev_b64 v[74:75], 12, v[6:7]
	v_lshl_add_u64 v[72:73], v[72:73], 0, v[74:75]
	global_load_dwordx4 v[72:75], v[72:73], off nt
	s_ashr_i32 s1, s23, 31
	s_add_u32 s0, s19, s23
	s_addc_u32 s1, s26, s1
	s_waitcnt vmcnt(0)
	ds_write2_b32 v31, v22, v23 offset1:1
	ds_write2_b32 v31, v24, v25 offset0:2 offset1:3
	s_waitcnt vmcnt(6)
	ds_write2_b32 v32, v48, v49 offset1:1
	ds_write2_b32 v33, v50, v51 offset1:1
	s_waitcnt vmcnt(5)
	ds_write2_b32 v34, v52, v53 offset1:1
	ds_write2_b32 v35, v54, v55 offset1:1
	s_waitcnt vmcnt(4)
	ds_write2_b32 v36, v56, v57 offset1:1
	ds_write2_b32 v37, v58, v59 offset1:1
	s_waitcnt vmcnt(3)
	ds_write2_b32 v38, v60, v61 offset1:1
	ds_write2_b32 v39, v62, v63 offset1:1
	s_waitcnt vmcnt(2)
	ds_write2_b32 v40, v64, v65 offset1:1
	ds_write2_b32 v41, v66, v67 offset1:1
	s_waitcnt vmcnt(1)
	ds_write2_b32 v42, v68, v69 offset1:1
	ds_write2_b32 v43, v70, v71 offset1:1
	s_waitcnt vmcnt(0)
	ds_write2_b32 v44, v72, v73 offset1:1
	ds_write2_b32 v45, v74, v75 offset1:1
	s_waitcnt lgkmcnt(0)
	ds_read_b32 v7, v30
	ds_read_b32 v9, v30 offset:132
	ds_read_b32 v11, v30 offset:264
	ds_read_b32 v13, v30 offset:396
	s_waitcnt lgkmcnt(0)
	v_mul_f32_e32 v7, 0x43000000, v7
	s_waitcnt lgkmcnt(2)
	v_mul_f32_e32 v9, 0x43000000, v9
	v_med3_f32 v7, v7, s20, v46
	v_med3_f32 v9, v9, s20, v46
	v_cvt_pk_fp8_f32 v24, v7, v9
	s_waitcnt lgkmcnt(1)
	v_mul_f32_e32 v11, 0x43000000, v11
	s_waitcnt lgkmcnt(0)
	v_mul_f32_e32 v13, 0x43000000, v13
	v_med3_f32 v7, v11, s20, v46
	v_med3_f32 v9, v13, s20, v46
	v_cvt_pk_fp8_f32 v24, v7, v9 op_sel:[0,0,1]
	ds_read_b32 v7, v30 offset:528
	ds_read_b32 v9, v30 offset:660
	ds_read_b32 v11, v30 offset:792
	ds_read_b32 v13, v30 offset:924
	s_waitcnt lgkmcnt(3)
	v_mul_f32_e32 v7, 0x43000000, v7
	s_waitcnt lgkmcnt(2)
	v_mul_f32_e32 v9, 0x43000000, v9
	v_med3_f32 v7, v7, s20, v46
	v_med3_f32 v9, v9, s20, v46
	v_cvt_pk_fp8_f32 v25, v7, v9
	s_waitcnt lgkmcnt(1)
	v_mul_f32_e32 v11, 0x43000000, v11
	s_waitcnt lgkmcnt(0)
	v_mul_f32_e32 v13, 0x43000000, v13
	v_med3_f32 v7, v11, s20, v46
	v_med3_f32 v9, v13, s20, v46
	v_cvt_pk_fp8_f32 v25, v7, v9 op_sel:[0,0,1]
	v_or_b32_e32 v48, s8, v26
	v_ashrrev_i32_e32 v49, 31, v48
	v_lshl_add_u64 v[22:23], s[0:1], 0, v[4:5]
	v_lshlrev_b64 v[48:49], 10, v[48:49]
	v_lshl_add_u64 v[48:49], v[22:23], 0, v[48:49]
	global_store_dwordx2 v[48:49], v[24:25], off nt
	ds_read_b32 v7, v30 offset:32
	ds_read_b32 v9, v30 offset:164
	ds_read_b32 v11, v30 offset:296
	ds_read_b32 v13, v30 offset:428
	s_waitcnt lgkmcnt(0)
	v_mul_f32_e32 v7, 0x43000000, v7
	v_mul_f32_e32 v9, 0x43000000, v9
	v_med3_f32 v7, v7, s20, v46
	v_med3_f32 v9, v9, s20, v46
	v_cvt_pk_fp8_f32 v24, v7, v9
	v_mul_f32_e32 v11, 0x43000000, v11
	v_mul_f32_e32 v13, 0x43000000, v13
	v_med3_f32 v7, v11, s20, v46
	v_med3_f32 v9, v13, s20, v46
	v_cvt_pk_fp8_f32 v24, v7, v9 op_sel:[0,0,1]
	ds_read_b32 v7, v30 offset:560
	ds_read_b32 v9, v30 offset:692
	ds_read_b32 v11, v30 offset:824
	ds_read_b32 v13, v30 offset:956
	s_waitcnt lgkmcnt(0)
	v_mul_f32_e32 v7, 0x43000000, v7
	v_mul_f32_e32 v9, 0x43000000, v9
	v_med3_f32 v7, v7, s20, v46
	v_med3_f32 v9, v9, s20, v46
	v_cvt_pk_fp8_f32 v25, v7, v9
	v_mul_f32_e32 v11, 0x43000000, v11
	v_mul_f32_e32 v13, 0x43000000, v13
	v_med3_f32 v7, v11, s20, v46
	v_med3_f32 v9, v13, s20, v46
	v_cvt_pk_fp8_f32 v25, v7, v9 op_sel:[0,0,1]
	v_or_b32_e32 v48, s8, v27
	v_ashrrev_i32_e32 v49, 31, v48
	v_lshlrev_b64 v[48:49], 10, v[48:49]
	v_lshl_add_u64 v[48:49], v[22:23], 0, v[48:49]
	global_store_dwordx2 v[48:49], v[24:25], off nt
	ds_read_b32 v7, v30 offset:64
	ds_read_b32 v9, v30 offset:196
	ds_read_b32 v11, v30 offset:328
	ds_read_b32 v13, v30 offset:460
	s_waitcnt lgkmcnt(0)
	v_mul_f32_e32 v7, 0x43000000, v7
	v_mul_f32_e32 v9, 0x43000000, v9
	v_med3_f32 v7, v7, s20, v46
	v_med3_f32 v9, v9, s20, v46
	v_cvt_pk_fp8_f32 v24, v7, v9
	v_mul_f32_e32 v11, 0x43000000, v11
	v_mul_f32_e32 v13, 0x43000000, v13
	v_med3_f32 v7, v11, s20, v46
	v_med3_f32 v9, v13, s20, v46
	v_cvt_pk_fp8_f32 v24, v7, v9 op_sel:[0,0,1]
	ds_read_b32 v7, v30 offset:592
	ds_read_b32 v9, v30 offset:724
	ds_read_b32 v11, v30 offset:856
	ds_read_b32 v13, v30 offset:988
	s_waitcnt lgkmcnt(0)
	v_mul_f32_e32 v7, 0x43000000, v7
	v_mul_f32_e32 v9, 0x43000000, v9
	v_med3_f32 v7, v7, s20, v46
	v_med3_f32 v9, v9, s20, v46
	v_cvt_pk_fp8_f32 v25, v7, v9
	v_mul_f32_e32 v11, 0x43000000, v11
	v_mul_f32_e32 v13, 0x43000000, v13
	v_med3_f32 v7, v11, s20, v46
	v_med3_f32 v9, v13, s20, v46
	v_cvt_pk_fp8_f32 v25, v7, v9 op_sel:[0,0,1]
	v_or_b32_e32 v48, s8, v28
	v_ashrrev_i32_e32 v49, 31, v48
	v_lshlrev_b64 v[48:49], 10, v[48:49]
	v_lshl_add_u64 v[48:49], v[22:23], 0, v[48:49]
	global_store_dwordx2 v[48:49], v[24:25], off nt
	ds_read_b32 v7, v30 offset:96
	ds_read_b32 v9, v30 offset:228
	ds_read_b32 v11, v30 offset:360
	ds_read_b32 v13, v30 offset:492
	s_waitcnt lgkmcnt(0)
	v_mul_f32_e32 v7, 0x43000000, v7
	v_mul_f32_e32 v9, 0x43000000, v9
	v_med3_f32 v7, v7, s20, v46
	v_med3_f32 v9, v9, s20, v46
	v_cvt_pk_fp8_f32 v24, v7, v9
	v_mul_f32_e32 v11, 0x43000000, v11
	v_mul_f32_e32 v13, 0x43000000, v13
	v_med3_f32 v7, v11, s20, v46
	v_med3_f32 v9, v13, s20, v46
	v_cvt_pk_fp8_f32 v24, v7, v9 op_sel:[0,0,1]
	ds_read_b32 v7, v30 offset:624
	ds_read_b32 v9, v30 offset:756
	ds_read_b32 v11, v30 offset:888
	ds_read_b32 v13, v30 offset:1020
	s_waitcnt lgkmcnt(0)
	v_mul_f32_e32 v7, 0x43000000, v7
	v_mul_f32_e32 v9, 0x43000000, v9
	v_med3_f32 v7, v7, s20, v46
	v_med3_f32 v9, v9, s20, v46
	v_cvt_pk_fp8_f32 v25, v7, v9
	v_mul_f32_e32 v11, 0x43000000, v11
	v_mul_f32_e32 v13, 0x43000000, v13
	v_med3_f32 v7, v11, s20, v46
	v_med3_f32 v9, v13, s20, v46
	v_cvt_pk_fp8_f32 v25, v7, v9 op_sel:[0,0,1]
	v_or_b32_e32 v48, s8, v29
	v_ashrrev_i32_e32 v49, 31, v48
	v_lshlrev_b64 v[48:49], 10, v[48:49]
	v_lshl_add_u64 v[22:23], v[22:23], 0, v[48:49]
	global_store_dwordx2 v[22:23], v[24:25], off nt
	s_waitcnt lgkmcnt(0)
	s_cbranch_execnz .LBB0_829
	s_branch .LBB0_833

.LBB0_833:
	s_sext_i32_i16 s0, s25
	s_lshr_b32 s0, s0, 9
	s_addk_i32 s24, 0x1ff
	s_cmpk_lt_u32 s24, 0x3ff
	s_cselect_b32 s9, s13, s15
	s_cselect_b32 s19, s12, s14
	s_ashr_i32 s17, s16, 31
	s_sext_i32_i16 s18, s0
	s_lshl_b64 s[0:1], s[16:17], 22
	s_add_u32 s19, s19, s0
	s_addc_u32 s24, s9, s1
	s_lshl_b64 s[0:1], s[16:17], 21
	s_add_u32 s16, s4, s0
	s_addc_u32 s17, s5, s1
	s_ashr_i32 s9, s8, 31
	s_lshl_b64 s[0:1], s[8:9], 2
	s_add_u32 s0, s19, s0
	s_addc_u32 s1, s24, s1
	v_lshl_add_u64 v[22:23], s[0:1], 0, v[2:3]
	s_mov_b64 s[0:1], 0x4000000
	v_lshl_add_u64 v[24:25], v[22:23], 0, s[0:1]
	v_lshlrev_b64 v[20:21], 12, v[20:21]
	v_lshl_add_u64 v[20:21], v[24:25], 0, v[20:21]
	v_ashrrev_i32_e32 v19, 31, v18
	global_load_dwordx4 v[20:23], v[20:21], off nt
	v_lshlrev_b64 v[18:19], 12, v[18:19]
	v_lshl_add_u64 v[18:19], v[24:25], 0, v[18:19]
	v_ashrrev_i32_e32 v17, 31, v16
	global_load_dwordx4 v[48:51], v[18:19], off nt
	v_lshlrev_b64 v[16:17], 12, v[16:17]
	v_lshl_add_u64 v[16:17], v[24:25], 0, v[16:17]
	v_ashrrev_i32_e32 v15, 31, v14
	global_load_dwordx4 v[16:19], v[16:17], off nt
	v_lshlrev_b64 v[14:15], 12, v[14:15]
	v_lshl_add_u64 v[14:15], v[24:25], 0, v[14:15]
	v_ashrrev_i32_e32 v13, 31, v12
	global_load_dwordx4 v[52:55], v[14:15], off nt
	v_lshlrev_b64 v[12:13], 12, v[12:13]
	v_lshl_add_u64 v[12:13], v[24:25], 0, v[12:13]
	v_ashrrev_i32_e32 v11, 31, v10
	global_load_dwordx4 v[12:15], v[12:13], off nt
	v_lshlrev_b64 v[10:11], 12, v[10:11]
	v_lshl_add_u64 v[10:11], v[24:25], 0, v[10:11]
	v_ashrrev_i32_e32 v9, 31, v8
	global_load_dwordx4 v[56:59], v[10:11], off nt
	v_lshlrev_b64 v[8:9], 12, v[8:9]
	v_lshl_add_u64 v[8:9], v[24:25], 0, v[8:9]
	v_ashrrev_i32_e32 v7, 31, v6
	global_load_dwordx4 v[8:11], v[8:9], off nt
	v_lshlrev_b64 v[6:7], 12, v[6:7]
	v_lshl_add_u64 v[6:7], v[24:25], 0, v[6:7]
	global_load_dwordx4 v[60:63], v[6:7], off nt
	s_lshl_b32 s1, s18, 7
	s_ashr_i32 s0, s23, 31
	s_add_u32 s16, s16, s23
	s_addc_u32 s17, s17, s0
	s_lshl_b32 s0, s22, 6
	s_and_b32 s0, s0, 0xffffff00
	s_add_i32 s0, s0, s1
	s_and_b32 s1, s8, 0x60
	s_or_b32 s8, s0, s1
	v_lshl_add_u64 v[6:7], s[16:17], 0, v[4:5]
	s_waitcnt vmcnt(0)
	ds_write2_b32 v31, v20, v21 offset1:1
	ds_write2_b32 v31, v22, v23 offset0:2 offset1:3
	ds_write2_b32 v32, v48, v49 offset1:1
	ds_write2_b32 v33, v50, v51 offset1:1
	ds_write2_b32 v34, v16, v17 offset1:1
	ds_write2_b32 v35, v18, v19 offset1:1
	ds_write2_b32 v36, v52, v53 offset1:1
	ds_write2_b32 v37, v54, v55 offset1:1
	ds_write2_b32 v38, v12, v13 offset1:1
	ds_write2_b32 v39, v14, v15 offset1:1
	ds_write2_b32 v40, v56, v57 offset1:1
	ds_write2_b32 v41, v58, v59 offset1:1
	ds_write2_b32 v42, v8, v9 offset1:1
	ds_write2_b32 v43, v10, v11 offset1:1
	ds_write2_b32 v44, v60, v61 offset1:1
	ds_write2_b32 v45, v62, v63 offset1:1
	s_waitcnt lgkmcnt(0)
	ds_read_b32 v8, v30
	ds_read_b32 v9, v30 offset:132
	ds_read_b32 v10, v30 offset:264
	ds_read_b32 v11, v30 offset:396
	s_waitcnt lgkmcnt(0)
	v_mul_f32_e32 v8, 0x42800000, v8
	v_mul_f32_e32 v9, 0x42800000, v9
	v_med3_f32 v12, v8, s20, v46
	v_med3_f32 v9, v9, s20, v46
	v_cvt_pk_fp8_f32 v8, v12, v9
	v_mul_f32_e32 v10, 0x42800000, v10
	v_mul_f32_e32 v11, 0x42800000, v11
	v_med3_f32 v9, v10, s20, v46
	v_med3_f32 v10, v11, s20, v46
	v_cvt_pk_fp8_f32 v8, v9, v10 op_sel:[0,0,1]
	ds_read_b32 v9, v30 offset:528
	ds_read_b32 v10, v30 offset:660
	ds_read_b32 v11, v30 offset:792
	ds_read_b32 v12, v30 offset:924
	s_waitcnt lgkmcnt(3)
	v_mul_f32_e32 v9, 0x42800000, v9
	s_waitcnt lgkmcnt(2)
	v_mul_f32_e32 v10, 0x42800000, v10
	v_med3_f32 v13, v9, s20, v46
	v_med3_f32 v10, v10, s20, v46
	v_cvt_pk_fp8_f32 v9, v13, v10
	s_waitcnt lgkmcnt(1)
	v_mul_f32_e32 v11, 0x42800000, v11
	s_waitcnt lgkmcnt(0)
	v_mul_f32_e32 v12, 0x42800000, v12
	v_med3_f32 v10, v11, s20, v46
	v_med3_f32 v11, v12, s20, v46
	v_cvt_pk_fp8_f32 v9, v10, v11 op_sel:[0,0,1]
	v_or_b32_e32 v10, s8, v26
	v_ashrrev_i32_e32 v11, 31, v10
	v_lshlrev_b64 v[10:11], 10, v[10:11]
	v_lshl_add_u64 v[10:11], v[6:7], 0, v[10:11]
	global_store_dwordx2 v[10:11], v[8:9], off nt
	ds_read_b32 v8, v30 offset:32
	ds_read_b32 v9, v30 offset:164
	ds_read_b32 v10, v30 offset:296
	ds_read_b32 v11, v30 offset:428
	s_waitcnt lgkmcnt(0)
	v_mul_f32_e32 v8, 0x42800000, v8
	v_mul_f32_e32 v9, 0x42800000, v9
	v_med3_f32 v12, v8, s20, v46
	v_med3_f32 v9, v9, s20, v46
	v_cvt_pk_fp8_f32 v8, v12, v9
	v_mul_f32_e32 v10, 0x42800000, v10
	v_mul_f32_e32 v11, 0x42800000, v11
	v_med3_f32 v9, v10, s20, v46
	v_med3_f32 v10, v11, s20, v46
	v_cvt_pk_fp8_f32 v8, v9, v10 op_sel:[0,0,1]
	ds_read_b32 v9, v30 offset:560
	ds_read_b32 v10, v30 offset:692
	ds_read_b32 v11, v30 offset:824
	ds_read_b32 v12, v30 offset:956
	s_waitcnt lgkmcnt(0)
	v_mul_f32_e32 v9, 0x42800000, v9
	v_mul_f32_e32 v10, 0x42800000, v10
	v_med3_f32 v13, v9, s20, v46
	v_med3_f32 v10, v10, s20, v46
	v_cvt_pk_fp8_f32 v9, v13, v10
	v_mul_f32_e32 v11, 0x42800000, v11
	v_mul_f32_e32 v12, 0x42800000, v12
	v_med3_f32 v10, v11, s20, v46
	v_med3_f32 v11, v12, s20, v46
	v_cvt_pk_fp8_f32 v9, v10, v11 op_sel:[0,0,1]
	v_or_b32_e32 v10, s8, v27
	v_ashrrev_i32_e32 v11, 31, v10
	v_lshlrev_b64 v[10:11], 10, v[10:11]
	v_lshl_add_u64 v[10:11], v[6:7], 0, v[10:11]
	global_store_dwordx2 v[10:11], v[8:9], off nt
	ds_read_b32 v8, v30 offset:64
	ds_read_b32 v9, v30 offset:196
	ds_read_b32 v10, v30 offset:328
	ds_read_b32 v11, v30 offset:460
	s_waitcnt lgkmcnt(0)
	v_mul_f32_e32 v8, 0x42800000, v8
	v_mul_f32_e32 v9, 0x42800000, v9
	v_med3_f32 v12, v8, s20, v46
	v_med3_f32 v9, v9, s20, v46
	v_cvt_pk_fp8_f32 v8, v12, v9
	v_mul_f32_e32 v10, 0x42800000, v10
	v_mul_f32_e32 v11, 0x42800000, v11
	v_med3_f32 v9, v10, s20, v46
	v_med3_f32 v10, v11, s20, v46
	v_cvt_pk_fp8_f32 v8, v9, v10 op_sel:[0,0,1]
	ds_read_b32 v9, v30 offset:592
	ds_read_b32 v10, v30 offset:724
	ds_read_b32 v11, v30 offset:856
	ds_read_b32 v12, v30 offset:988
	s_waitcnt lgkmcnt(0)
	v_mul_f32_e32 v9, 0x42800000, v9
	v_mul_f32_e32 v10, 0x42800000, v10
	v_med3_f32 v13, v9, s20, v46
	v_med3_f32 v10, v10, s20, v46
	v_cvt_pk_fp8_f32 v9, v13, v10
	v_mul_f32_e32 v11, 0x42800000, v11
	v_mul_f32_e32 v12, 0x42800000, v12
	v_med3_f32 v10, v11, s20, v46
	v_med3_f32 v11, v12, s20, v46
	v_cvt_pk_fp8_f32 v9, v10, v11 op_sel:[0,0,1]
	v_or_b32_e32 v10, s8, v28
	v_ashrrev_i32_e32 v11, 31, v10
	v_lshlrev_b64 v[10:11], 10, v[10:11]
	v_lshl_add_u64 v[10:11], v[6:7], 0, v[10:11]
	global_store_dwordx2 v[10:11], v[8:9], off nt
	ds_read_b32 v8, v30 offset:96
	ds_read_b32 v9, v30 offset:228
	ds_read_b32 v10, v30 offset:360
	ds_read_b32 v11, v30 offset:492
	s_waitcnt lgkmcnt(0)
	v_mul_f32_e32 v8, 0x42800000, v8
	v_mul_f32_e32 v9, 0x42800000, v9
	v_med3_f32 v12, v8, s20, v46
	v_med3_f32 v9, v9, s20, v46
	v_cvt_pk_fp8_f32 v8, v12, v9
	v_mul_f32_e32 v10, 0x42800000, v10
	v_mul_f32_e32 v11, 0x42800000, v11
	v_med3_f32 v9, v10, s20, v46
	v_med3_f32 v10, v11, s20, v46
	v_cvt_pk_fp8_f32 v8, v9, v10 op_sel:[0,0,1]
	ds_read_b32 v9, v30 offset:624
	ds_read_b32 v10, v30 offset:756
	ds_read_b32 v11, v30 offset:888
	ds_read_b32 v12, v30 offset:1020
	s_waitcnt lgkmcnt(0)
	v_mul_f32_e32 v9, 0x42800000, v9
	v_mul_f32_e32 v10, 0x42800000, v10
	v_med3_f32 v13, v9, s20, v46
	v_med3_f32 v10, v10, s20, v46
	v_cvt_pk_fp8_f32 v9, v13, v10
	v_mul_f32_e32 v11, 0x42800000, v11
	v_mul_f32_e32 v12, 0x42800000, v12
	v_med3_f32 v10, v11, s20, v46
	v_med3_f32 v11, v12, s20, v46
	v_cvt_pk_fp8_f32 v9, v10, v11 op_sel:[0,0,1]
	v_or_b32_e32 v10, s8, v29
	v_ashrrev_i32_e32 v11, 31, v10
	v_lshlrev_b64 v[10:11], 10, v[10:11]
	v_lshl_add_u64 v[6:7], v[6:7], 0, v[10:11]
	global_store_dwordx2 v[6:7], v[8:9], off nt
	s_waitcnt lgkmcnt(0)
	s_branch .LBB0_829

.LBB0_1071:
	s_waitcnt vmcnt(0) lgkmcnt(0)
	v_lshlrev_b32_e32 v77, 16, v37
	v_lshlrev_b32_e32 v76, 16, v36
	v_and_b32_e32 v37, 0xffff0000, v37
	v_and_b32_e32 v36, 0xffff0000, v36
	v_pk_add_f32 v[68:69], v[76:77], v[36:37]
	v_lshlrev_b32_e32 v87, 16, v35
	v_lshlrev_b32_e32 v86, 16, v34
	v_and_b32_e32 v35, 0xffff0000, v35
	v_and_b32_e32 v34, 0xffff0000, v34
	v_lshlrev_b32_e32 v46, 16, v39
	v_and_b32_e32 v48, 0xffff0000, v39
	v_add_f32_e32 v39, v68, v69
	v_pk_add_f32 v[68:69], v[86:87], v[34:35]
	v_lshlrev_b32_e32 v42, 16, v40
	v_and_b32_e32 v43, 0xffff0000, v40
	v_lshlrev_b32_e32 v40, 16, v41
	v_and_b32_e32 v41, 0xffff0000, v41
	v_pk_add_f32 v[68:69], v[68:69], v[68:69] op_sel_hi:[0,1]
	v_lshlrev_b32_e32 v44, 16, v38
	v_and_b32_e32 v38, 0xffff0000, v38
	v_add_f32_e32 v49, 0, v39
	v_add_f32_e32 v45, v42, v43
	v_add_f32_e32 v39, v40, v41
	v_mov_b32_e32 v47, v69
	v_pk_add_f32 v[70:71], v[44:45], v[38:39]
	v_pk_add_f32 v[68:69], v[46:47], v[48:49]
	s_min_u32 s0, s24, 29
	v_pk_add_f32 v[68:69], v[70:71], v[68:69]
	s_lshl_b32 s0, s0, 3
	v_add_f32_e32 v39, v68, v69
	s_add_i32 s20, s11, s0
	s_nop 0
	v_add_f32_dpp v39, v39, v39 quad_perm:[1,0,3,2] row_mask:0xf bank_mask:0xf bound_ctrl:1
	s_nop 1
	v_add_f32_dpp v39, v39, v39 quad_perm:[2,3,0,1] row_mask:0xf bank_mask:0xf bound_ctrl:1
	s_nop 1
	v_add_f32_dpp v39, v39, v39 row_half_mirror row_mask:0xf bank_mask:0xf bound_ctrl:1
	s_nop 1
	v_add_f32_dpp v39, v39, v39 row_mirror row_mask:0xf bank_mask:0xf bound_ctrl:1
	s_nop 0
	v_readlane_b32 s21, v39, 16
	v_readlane_b32 s22, v39, 48
	v_readlane_b32 s0, v39, 0
	v_readlane_b32 s1, v39, 32
	v_mov_b32_e32 v68, s21
	v_mov_b32_e32 v69, s22
	v_pk_add_f32 v[68:69], s[0:1], v[68:69]
	s_nop 0
	v_add_f32_e32 v39, v68, v69
	v_fmac_f32_e32 v36, 0xba800000, v39
	v_fmac_f32_e32 v37, 0xba800000, v39
	v_fmac_f32_e32 v77, 0xba800000, v39
	v_fmac_f32_e32 v76, 0xba800000, v39
	v_mov_b32_e32 v88, v77
	v_mov_b32_e32 v89, v37
	v_mov_b32_e32 v77, v36
	v_fmac_f32_e32 v34, 0xba800000, v39
	v_fmac_f32_e32 v35, 0xba800000, v39
	v_fmac_f32_e32 v87, 0xba800000, v39
	v_pk_mul_f32 v[68:69], v[88:89], v[88:89]
	v_pk_mul_f32 v[36:37], v[76:77], v[76:77]
	v_fmac_f32_e32 v86, 0xba800000, v39
	v_mov_b32_e32 v90, v87
	v_mov_b32_e32 v91, v35
	v_mov_b32_e32 v87, v34
	v_pk_mov_b32 v[70:71], v[36:37], v[68:69] op_sel:[1,0]
	v_mov_b32_e32 v37, v69
	v_pk_mul_f32 v[68:69], v[90:91], v[90:91]
	v_pk_mul_f32 v[34:35], v[86:87], v[86:87]
	v_pk_add_f32 v[36:37], v[70:71], v[36:37]
	v_pk_mov_b32 v[70:71], v[34:35], v[68:69] op_sel:[1,0]
	v_mov_b32_e32 v35, v69
	v_pk_add_f32 v[34:35], v[70:71], v[34:35]
	v_fmac_f32_e32 v42, 0xba800000, v39
	v_pk_add_f32 v[34:35], v[34:35], v[34:35] op_sel_hi:[0,1]
	v_fmac_f32_e32 v43, 0xba800000, v39
	v_fmac_f32_e32 v40, 0xba800000, v39
	v_mul_f32_e32 v34, v42, v42
	v_fmac_f32_e32 v41, 0xba800000, v39
	v_pk_fma_f32 v[68:69], v[42:43], v[42:43], v[34:35] op_sel_hi:[1,1,0]
	v_mul_f32_e32 v34, v40, v40
	v_pk_add_f32 v[36:37], v[36:37], v[36:37] op_sel_hi:[0,1]
	v_pk_fma_f32 v[70:71], v[40:41], v[40:41], v[34:35] op_sel_hi:[1,1,0]
	v_fmac_f32_e32 v48, 0xba800000, v39
	v_fmac_f32_e32 v46, 0xba800000, v39
	v_fmac_f32_e32 v38, 0xba800000, v39
	v_fmac_f32_e32 v44, 0xba800000, v39
	v_mul_f32_e32 v68, v44, v44
	v_mul_f32_e32 v70, v38, v38
	v_mul_f32_e32 v36, v46, v46
	v_mul_f32_e32 v34, v48, v48
	v_pk_add_f32 v[68:69], v[68:69], v[70:71]
	v_pk_add_f32 v[34:35], v[36:37], v[34:35]
	v_mov_b32_e32 v47, v48
	v_pk_add_f32 v[34:35], v[68:69], v[34:35]
	s_nop 0
	v_add_f32_e32 v34, v34, v35
	s_nop 1
	v_add_f32_dpp v34, v34, v34 quad_perm:[1,0,3,2] row_mask:0xf bank_mask:0xf bound_ctrl:1
	s_nop 1
	v_add_f32_dpp v34, v34, v34 quad_perm:[2,3,0,1] row_mask:0xf bank_mask:0xf bound_ctrl:1
	s_nop 1
	v_add_f32_dpp v34, v34, v34 row_half_mirror row_mask:0xf bank_mask:0xf bound_ctrl:1
	s_nop 1
	v_add_f32_dpp v34, v34, v34 row_mirror row_mask:0xf bank_mask:0xf bound_ctrl:1
	s_nop 0
	v_readlane_b32 s21, v34, 16
	v_readlane_b32 s22, v34, 48
	v_readlane_b32 s0, v34, 0
	v_readlane_b32 s1, v34, 32
	v_mov_b32_e32 v34, s21
	v_mov_b32_e32 v35, s22
	v_pk_add_f32 v[34:35], s[0:1], v[34:35]
	s_mov_b32 s0, 0xf800000
	v_add_f32_e32 v34, v34, v35
	v_fmamk_f32 v34, v34, 0x3a800000, v82
	s_ashr_i32 s21, s20, 31
	v_mul_f32_e32 v35, 0x4f800000, v34
	v_cmp_gt_f32_e32 vcc, s0, v34
	s_lshl_b64 s[0:1], s[20:21], 11
	s_and_b32 s22, s24, 3
	v_cndmask_b32_e32 v36, v34, v35, vcc
	v_lshl_add_u64 v[34:35], v[54:55], 0, s[0:1]
	global_load_dwordx2 v[68:69], v[34:35], off
	global_load_dwordx2 v[70:71], v[34:35], off offset:512
	global_load_dwordx2 v[72:73], v[34:35], off offset:1024
	global_load_dwordx2 v[74:75], v[34:35], off offset:1536
	v_sqrt_f32_e32 v37, v36
	s_mul_i32 s23, s22, 0x810
	s_add_i32 s23, s87, s23
	v_add_u32_e32 v39, -1, v37
	v_fma_f32 v45, -v39, v37, v36
	v_cmp_ge_f32_e64 s[20:21], 0, v45
	v_add_u32_e32 v45, 1, v37
	s_nop 0
	v_cndmask_b32_e64 v39, v37, v39, s[20:21]
	v_fma_f32 v37, -v45, v37, v36
	v_cmp_lt_f32_e64 s[20:21], 0, v37
	s_nop 1
	v_cndmask_b32_e64 v37, v39, v45, s[20:21]
	v_mul_f32_e32 v39, 0x37800000, v37
	v_cndmask_b32_e32 v37, v37, v39, vcc
	v_cmp_class_f32_e32 vcc, v36, v83
	s_add_i32 s20, s4, s10
	s_ashr_i32 s21, s20, 31
	v_cndmask_b32_e32 v36, v37, v36, vcc
	v_div_scale_f32 v37, s[0:1], v36, v36, 1.0
	v_rcp_f32_e32 v39, v37
	s_lshl_b64 s[0:1], s[20:21], 11
	v_fma_f32 v34, -v37, v39, 1.0
	v_fmac_f32_e32 v39, v34, v39
	v_div_scale_f32 v34, vcc, 1.0, v36, 1.0
	v_mul_f32_e32 v35, v34, v39
	v_fma_f32 v45, -v37, v35, v34
	v_fmac_f32_e32 v35, v45, v39
	v_fma_f32 v34, -v37, v35, v34
	v_div_fmas_f32 v34, v34, v39, v35
	v_div_fixup_f32 v34, v34, v36, 1.0
	v_mov_b32_e32 v45, v38
	v_pk_mul_f32 v[36:37], v[76:77], v[34:35] op_sel_hi:[1,0]
	v_pk_mul_f32 v[76:77], v[88:89], v[34:35] op_sel_hi:[1,0]
	v_pk_mul_f32 v[38:39], v[44:45], v[34:35] op_sel_hi:[1,0]
	v_mov_b32_e32 v44, v168
	v_pk_fma_f32 v[76:77], v[4:5], v[76:77], v[12:13]
	v_pk_fma_f32 v[36:37], v[2:3], v[36:37], v[10:11]
	v_pk_mul_f32 v[86:87], v[86:87], v[34:35] op_sel_hi:[1,0]
	v_pk_mul_f32 v[88:89], v[90:91], v[34:35] op_sel_hi:[1,0]
	v_pk_fma_f32 v[86:87], v[6:7], v[86:87], v[14:15]
	v_pk_fma_f32 v[88:89], v[8:9], v[88:89], v[16:17]
	v_pk_mul_f32 v[42:43], v[42:43], v[34:35] op_sel_hi:[1,0]
	v_pk_mul_f32 v[40:41], v[40:41], v[34:35] op_sel_hi:[1,0]
	v_pk_mul_f32 v[34:35], v[46:47], v[34:35] op_sel_hi:[1,0]
	v_lshl_add_u32 v48, v44, 3, s23
	v_cvt_pk_bf16_f32 v44, v36, v37
	v_cvt_pk_bf16_f32 v45, v76, v77
	v_lshl_add_u64 v[46:47], v[56:57], 0, s[0:1]
	v_pk_fma_f32 v[40:41], v[20:21], v[40:41], v[28:29]
	v_pk_fma_f32 v[42:43], v[18:19], v[42:43], v[26:27]
	global_store_dwordx2 v[46:47], v[44:45], off nt
	ds_write_b64 v48, v[44:45] offset:33024
	v_cvt_pk_bf16_f32 v44, v86, v87
	v_cvt_pk_bf16_f32 v45, v88, v89
	v_pk_fma_f32 v[34:35], v[24:25], v[34:35], v[32:33]
	v_pk_fma_f32 v[38:39], v[22:23], v[38:39], v[30:31]
	global_store_dwordx2 v[46:47], v[44:45], off offset:512 nt
	ds_write_b64 v48, v[44:45] offset:33536
	v_cvt_pk_bf16_f32 v44, v42, v43
	v_cvt_pk_bf16_f32 v45, v40, v41
	global_store_dwordx2 v[46:47], v[44:45], off offset:1024 nt
	ds_write_b64 v48, v[44:45] offset:34048
	v_cvt_pk_bf16_f32 v44, v38, v39
	v_cvt_pk_bf16_f32 v45, v34, v35
	global_store_dwordx2 v[46:47], v[44:45], off offset:1536 nt
	ds_write_b64 v48, v[44:45] offset:34560
	v_med3_f32 v36, v36, s6, v84
	v_med3_f32 v37, v37, s6, v84
	v_cvt_pk_fp8_f32 v44, v36, v37
	v_med3_f32 v36, v76, s6, v84
	v_med3_f32 v37, v77, s6, v84
	v_med3_f32 v45, v86, s6, v84
	v_cvt_pk_fp8_f32 v44, v36, v37 op_sel:[0,0,1]
	v_med3_f32 v46, v87, s6, v84
	v_cvt_pk_fp8_f32 v47, v45, v46
	s_lshl_b64 s[0:1], s[20:21], 10
	v_lshl_add_u64 v[36:37], v[58:59], 0, s[0:1]
	global_store_dword v[36:37], v44, off
	v_med3_f32 v44, v88, s6, v84
	v_med3_f32 v45, v89, s6, v84
	v_cvt_pk_fp8_f32 v47, v44, v45 op_sel:[0,0,1]
	v_med3_f32 v42, v42, s6, v84
	v_med3_f32 v43, v43, s6, v84
	v_cvt_pk_fp8_f32 v44, v42, v43
	v_med3_f32 v38, v38, s6, v84
	v_med3_f32 v39, v39, s6, v84
	v_cvt_pk_fp8_f32 v42, v38, v39
	v_med3_f32 v34, v34, s6, v84
	v_med3_f32 v35, v35, s6, v84
	v_med3_f32 v40, v40, s6, v84
	v_med3_f32 v41, v41, s6, v84
	v_cvt_pk_fp8_f32 v42, v34, v35 op_sel:[0,0,1]
	v_cvt_pk_fp8_f32 v44, v40, v41 op_sel:[0,0,1]
	s_cmp_lg_u32 s22, 3
	global_store_dword v[36:37], v47, off offset:256
	global_store_dword v[36:37], v44, off offset:512
	global_store_dword v[36:37], v42, off offset:768
	s_cbranch_scc1 .LBB0_1070
	v_mov_b32_e32 v76, v168
	s_nop 0
	v_and_b32_e32 v34, 3, v76
	v_mul_u32_u24_e32 v34, 0x810, v34
	v_and_b32_e32 v35, -16, v76
	v_add3_u32 v77, s87, v34, v35
	v_and_b32_e32 v34, 15, v76
	v_mul_u32_u24_e32 v34, 0x810, v34
	v_add3_u32 v85, 0, v34, v35
	ds_read_b128 v[34:37], v77 offset:33024
	ds_read_b128 v[38:41], v85
	s_waitcnt lgkmcnt(0)
	v_mfma_f32_16x16x32_bf16 v[34:37], v[34:37], v[38:41], 0
	ds_read_b128 v[38:41], v77 offset:33088
	ds_read_b128 v[42:45], v85 offset:64
	v_cmp_gt_i32_e32 vcc, 16, v76
	s_waitcnt lgkmcnt(0)
	v_mfma_f32_16x16x32_bf16 v[38:41], v[38:41], v[42:45], 0
	ds_read_b128 v[42:45], v77 offset:33152
	ds_read_b128 v[46:49], v85 offset:128
	s_waitcnt lgkmcnt(0)
	v_mfma_f32_16x16x32_bf16 v[42:45], v[42:45], v[46:49], 0
	ds_read_b128 v[46:49], v77 offset:33216
	ds_read_b128 v[86:89], v85 offset:192
	s_waitcnt lgkmcnt(0)
	v_mfma_f32_16x16x32_bf16 v[46:49], v[46:49], v[86:89], 0
	ds_read_b128 v[86:89], v77 offset:33280
	ds_read_b128 v[90:93], v85 offset:256
	s_waitcnt lgkmcnt(0)
	v_mfma_f32_16x16x32_bf16 v[34:37], v[86:89], v[90:93], v[34:37]
	ds_read_b128 v[86:89], v77 offset:33344
	ds_read_b128 v[90:93], v85 offset:320
	s_waitcnt lgkmcnt(0)
	v_mfma_f32_16x16x32_bf16 v[38:41], v[86:89], v[90:93], v[38:41]
	ds_read_b128 v[86:89], v77 offset:33408
	ds_read_b128 v[90:93], v85 offset:384
	s_waitcnt lgkmcnt(0)
	v_mfma_f32_16x16x32_bf16 v[42:45], v[86:89], v[90:93], v[42:45]
	ds_read_b128 v[86:89], v77 offset:33472
	ds_read_b128 v[90:93], v85 offset:448
	s_waitcnt lgkmcnt(0)
	v_mfma_f32_16x16x32_bf16 v[46:49], v[86:89], v[90:93], v[46:49]
	ds_read_b128 v[86:89], v77 offset:33536
	ds_read_b128 v[90:93], v85 offset:512
	s_waitcnt lgkmcnt(0)
	v_mfma_f32_16x16x32_bf16 v[34:37], v[86:89], v[90:93], v[34:37]
	ds_read_b128 v[86:89], v77 offset:33600
	ds_read_b128 v[90:93], v85 offset:576
	s_waitcnt lgkmcnt(0)
	v_mfma_f32_16x16x32_bf16 v[38:41], v[86:89], v[90:93], v[38:41]
	ds_read_b128 v[86:89], v77 offset:33664
	ds_read_b128 v[90:93], v85 offset:640
	s_waitcnt lgkmcnt(0)
	v_mfma_f32_16x16x32_bf16 v[42:45], v[86:89], v[90:93], v[42:45]
	ds_read_b128 v[86:89], v77 offset:33728
	ds_read_b128 v[90:93], v85 offset:704
	s_waitcnt lgkmcnt(0)
	v_mfma_f32_16x16x32_bf16 v[46:49], v[86:89], v[90:93], v[46:49]
	ds_read_b128 v[86:89], v77 offset:33792
	ds_read_b128 v[90:93], v85 offset:768
	s_waitcnt lgkmcnt(0)
	v_mfma_f32_16x16x32_bf16 v[34:37], v[86:89], v[90:93], v[34:37]
	ds_read_b128 v[86:89], v77 offset:33856
	ds_read_b128 v[90:93], v85 offset:832
	s_waitcnt lgkmcnt(0)
	v_mfma_f32_16x16x32_bf16 v[38:41], v[86:89], v[90:93], v[38:41]
	ds_read_b128 v[86:89], v77 offset:33920
	ds_read_b128 v[90:93], v85 offset:896
	s_waitcnt lgkmcnt(0)
	v_mfma_f32_16x16x32_bf16 v[42:45], v[86:89], v[90:93], v[42:45]
	ds_read_b128 v[86:89], v77 offset:33984
	ds_read_b128 v[90:93], v85 offset:960
	s_waitcnt lgkmcnt(0)
	v_mfma_f32_16x16x32_bf16 v[46:49], v[86:89], v[90:93], v[46:49]
	ds_read_b128 v[86:89], v77 offset:34048
	ds_read_b128 v[90:93], v85 offset:1024
	s_waitcnt lgkmcnt(0)
	v_mfma_f32_16x16x32_bf16 v[34:37], v[86:89], v[90:93], v[34:37]
	ds_read_b128 v[86:89], v77 offset:34112
	ds_read_b128 v[90:93], v85 offset:1088
	s_waitcnt lgkmcnt(0)
	v_mfma_f32_16x16x32_bf16 v[38:41], v[86:89], v[90:93], v[38:41]
	ds_read_b128 v[86:89], v77 offset:34176
	ds_read_b128 v[90:93], v85 offset:1152
	s_waitcnt lgkmcnt(0)
	v_mfma_f32_16x16x32_bf16 v[42:45], v[86:89], v[90:93], v[42:45]
	ds_read_b128 v[86:89], v77 offset:34240
	ds_read_b128 v[90:93], v85 offset:1216
	s_waitcnt lgkmcnt(0)
	v_mfma_f32_16x16x32_bf16 v[46:49], v[86:89], v[90:93], v[46:49]
	ds_read_b128 v[86:89], v77 offset:34304
	ds_read_b128 v[90:93], v85 offset:1280
	s_waitcnt lgkmcnt(0)
	v_mfma_f32_16x16x32_bf16 v[34:37], v[86:89], v[90:93], v[34:37]
	ds_read_b128 v[86:89], v77 offset:34368
	ds_read_b128 v[90:93], v85 offset:1344
	s_waitcnt lgkmcnt(0)
	v_mfma_f32_16x16x32_bf16 v[38:41], v[86:89], v[90:93], v[38:41]
	ds_read_b128 v[86:89], v77 offset:34432
	ds_read_b128 v[90:93], v85 offset:1408
	s_waitcnt lgkmcnt(0)
	v_mfma_f32_16x16x32_bf16 v[42:45], v[86:89], v[90:93], v[42:45]
	ds_read_b128 v[86:89], v77 offset:34496
	ds_read_b128 v[90:93], v85 offset:1472
	s_waitcnt lgkmcnt(0)
	v_mfma_f32_16x16x32_bf16 v[46:49], v[86:89], v[90:93], v[46:49]
	ds_read_b128 v[86:89], v77 offset:34560
	ds_read_b128 v[90:93], v85 offset:1536
	s_waitcnt lgkmcnt(0)
	v_mfma_f32_16x16x32_bf16 v[34:37], v[86:89], v[90:93], v[34:37]
	ds_read_b128 v[86:89], v77 offset:34624
	ds_read_b128 v[90:93], v85 offset:1600
	s_waitcnt lgkmcnt(0)
	v_mfma_f32_16x16x32_bf16 v[38:41], v[86:89], v[90:93], v[38:41]
	ds_read_b128 v[86:89], v77 offset:34688
	ds_read_b128 v[90:93], v85 offset:1664
	s_waitcnt lgkmcnt(0)
	v_mfma_f32_16x16x32_bf16 v[42:45], v[86:89], v[90:93], v[42:45]
	ds_read_b128 v[86:89], v77 offset:34752
	ds_read_b128 v[90:93], v85 offset:1728
	s_waitcnt lgkmcnt(0)
	v_mfma_f32_16x16x32_bf16 v[46:49], v[86:89], v[90:93], v[46:49]
	ds_read_b128 v[86:89], v77 offset:34816
	ds_read_b128 v[90:93], v85 offset:1792
	s_waitcnt lgkmcnt(0)
	v_mfma_f32_16x16x32_bf16 v[34:37], v[86:89], v[90:93], v[34:37]
	ds_read_b128 v[86:89], v77 offset:34880
	ds_read_b128 v[90:93], v85 offset:1856
	s_waitcnt lgkmcnt(0)
	v_mfma_f32_16x16x32_bf16 v[38:41], v[86:89], v[90:93], v[38:41]
	ds_read_b128 v[86:89], v77 offset:34944
	ds_read_b128 v[90:93], v85 offset:1920
	s_waitcnt lgkmcnt(0)
	v_mfma_f32_16x16x32_bf16 v[42:45], v[86:89], v[90:93], v[42:45]
	ds_read_b128 v[86:89], v77 offset:35008
	ds_read_b128 v[90:93], v85 offset:1984
	s_nop 1
	v_pk_add_f32 v[34:35], v[34:35], v[38:39]
	v_ashrrev_i32_e32 v77, 31, v76
	s_waitcnt lgkmcnt(0)
	v_mfma_f32_16x16x32_bf16 v[46:49], v[86:89], v[90:93], v[46:49]
	s_nop 7
	v_pk_add_f32 v[38:39], v[42:43], v[46:47]
	s_nop 0
	v_pk_add_f32 v[38:39], v[34:35], v[38:39]
	v_lshlrev_b64 v[34:35], 13, v[76:77]
	v_lshl_add_u64 v[34:35], s[30:31], 0, v[34:35]
	v_mov_b32_dpp v42, v38 quad_perm:[1,0,3,2] row_mask:0xf bank_mask:0xf bound_ctrl:1
	v_max_f32_e32 v42, v42, v42
	v_max_f32_e32 v42, v38, v42
	s_nop 1
	v_mov_b32_dpp v43, v42 quad_perm:[2,3,0,1] row_mask:0xf bank_mask:0xf bound_ctrl:1
	v_max_f32_e32 v43, v43, v43
	v_max_f32_e32 v42, v42, v43
	s_nop 1
	v_mov_b32_dpp v43, v42 row_half_mirror row_mask:0xf bank_mask:0xf bound_ctrl:1
	v_max_f32_e32 v43, v43, v43
	v_max_f32_e32 v42, v42, v43
	s_nop 1
	v_mov_b32_dpp v43, v42 row_mirror row_mask:0xf bank_mask:0xf bound_ctrl:1
	v_max_f32_e32 v43, v43, v43
	v_max_f32_e32 v42, v42, v43
	v_sub_f32_e32 v38, v38, v42
	v_mul_f32_e32 v38, 0x3fb8aa3b, v38
	v_exp_f32_e32 v38, v38
	s_nop 1
	v_add_f32_dpp v42, v38, v38 quad_perm:[1,0,3,2] row_mask:0xf bank_mask:0xf bound_ctrl:1
	s_nop 1
	v_add_f32_dpp v42, v42, v42 quad_perm:[2,3,0,1] row_mask:0xf bank_mask:0xf bound_ctrl:1
	s_nop 1
	v_add_f32_dpp v42, v42, v42 row_half_mirror row_mask:0xf bank_mask:0xf bound_ctrl:1
	s_nop 1
	v_mov_b32_dpp v43, v42 row_mirror row_mask:0xf bank_mask:0xf bound_ctrl:1
	s_and_saveexec_b64 s[22:23], vcc
	s_cbranch_execz .LBB0_1074
	v_add_f32_e32 v42, v42, v43
	v_rcp_f32_e32 v42, v42
	s_sub_i32 s21, s20, 24
	s_ashr_i32 s0, s21, 11
	s_ashr_i32 s1, s0, 31
	s_and_b32 s21, s21, 0x7ff
	s_lshl_b64 s[0:1], s[0:1], 17
	v_mul_f32_e32 v38, v38, v42
	v_lshl_add_u64 v[42:43], v[34:35], 0, s[0:1]
	s_lshl_b32 s28, s21, 2
	v_lshl_add_u64 v[42:43], v[42:43], 0, s[28:29]
	global_store_dword v[42:43], v38, off

.Lpeel_exit_6:
	s_mov_b32 s98, 0x3b000000
	s_mov_b32 s99, 0xbcb8aa3b
	s_mov_b32 s100, 1.0
	v_pk_mul_f32 v[236:237], v[158:159], s[98:99] op_sel_hi:[1,0]
	v_pk_mul_f32 v[234:235], v[158:159], s[98:99] op_sel:[0,1] op_sel_hi:[1,1]
	v_exp_f32_e32 v234, v234
	v_exp_f32_e32 v235, v235
	s_nop 0
	v_pk_add_f32 v[234:235], v[234:235], s[100:101] op_sel_hi:[1,0]
	v_rcp_f32_e32 v234, v234
	v_rcp_f32_e32 v235, v235
	s_nop 0
	v_pk_mul_f32 v[236:237], v[236:237], v[234:235]
	v_pk_mul_f32 v[236:237], v[236:237], v[154:155]
	s_ashr_i32 s31, s30, 31
	s_ashr_i32 s29, s28, 31
	s_lshl_b64 s[12:13], s[30:31], 18
	s_lshl_b64 s[28:29], s[28:29], 15
	v_mov_b32_e32 v3, v195
	s_add_u32 s0, s6, s12
	v_med3_f32 v5, v236, s40, v190
	s_nop 15
	s_nop 15
	v_mov_b32_e32 v2, v196
	v_pk_mul_f32 v[238:239], v[160:161], s[98:99] op_sel_hi:[1,0]
	v_pk_mul_f32 v[234:235], v[160:161], s[98:99] op_sel:[0,1] op_sel_hi:[1,1]
	v_exp_f32_e32 v234, v234
	v_exp_f32_e32 v235, v235
	s_nop 0
	v_pk_add_f32 v[234:235], v[234:235], s[100:101] op_sel_hi:[1,0]
	v_rcp_f32_e32 v234, v234
	v_rcp_f32_e32 v235, v235
	s_nop 0
	v_pk_mul_f32 v[238:239], v[238:239], v[234:235]
	v_pk_mul_f32 v[238:239], v[238:239], v[156:157]
	v_add_u32_e32 v4, s49, v3
	s_addc_u32 s1, s7, s13
	s_add_u32 s12, s0, s28
	v_lshl_add_u32 v2, v2, 3, s50
	s_addc_u32 s13, s1, s29
	v_ashrrev_i32_e32 v3, 31, v2
	s_and_b64 vcc, exec, s[8:9]
	v_pk_mul_f32 v[240:241], v[150:151], s[98:99] op_sel_hi:[1,0]
	v_pk_mul_f32 v[234:235], v[150:151], s[98:99] op_sel:[0,1] op_sel_hi:[1,1]
	v_exp_f32_e32 v234, v234
	v_exp_f32_e32 v235, v235
	s_nop 0
	v_pk_add_f32 v[234:235], v[234:235], s[100:101] op_sel_hi:[1,0]
	v_rcp_f32_e32 v234, v234
	v_rcp_f32_e32 v235, v235
	s_nop 0
	v_pk_mul_f32 v[240:241], v[240:241], v[234:235]
	v_pk_mul_f32 v[240:241], v[240:241], v[146:147]
	v_mov_b32_e32 v174, v200
	v_mov_b32_e32 v172, v199
	v_mov_b32_e32 v170, v198
	v_mov_b32_e32 v168, v171
	s_mov_b32 s28, s26
	s_mov_b32 s30, s54
	s_mov_b64 s[34:35], s[14:15]
	v_pk_mul_f32 v[242:243], v[152:153], s[98:99] op_sel_hi:[1,0]
	v_pk_mul_f32 v[234:235], v[152:153], s[98:99] op_sel:[0,1] op_sel_hi:[1,1]
	v_exp_f32_e32 v234, v234
	v_exp_f32_e32 v235, v235
	s_nop 0
	v_pk_add_f32 v[234:235], v[234:235], s[100:101] op_sel_hi:[1,0]
	v_rcp_f32_e32 v234, v234
	v_rcp_f32_e32 v235, v235
	s_nop 0
	v_pk_mul_f32 v[242:243], v[242:243], v[234:235]
	v_pk_mul_f32 v[242:243], v[242:243], v[148:149]
	s_nop 0
	s_nop 0
	v_med3_f32 v13, v237, s40, v190
	v_cvt_pk_fp8_f32 v6, v5, v13
	v_med3_f32 v5, v238, s40, v190
	v_med3_f32 v7, v239, s40, v190
	v_med3_f32 v8, v241, s40, v190
	v_cvt_pk_fp8_f32 v6, v5, v7 op_sel:[0,0,1]
	v_med3_f32 v5, v240, s40, v190
	v_cvt_pk_fp8_f32 v7, v5, v8
	v_med3_f32 v5, v242, s40, v190
	v_med3_f32 v8, v243, s40, v190
	v_cvt_pk_fp8_f32 v7, v5, v8 op_sel:[0,0,1]
	v_ashrrev_i32_e32 v5, 31, v4
	v_lshlrev_b64 v[8:9], 7, v[4:5]
	v_lshl_add_u64 v[8:9], s[12:13], 0, v[8:9]
	v_lshl_add_u64 v[8:9], v[8:9], 0, v[2:3]
	v_pk_mul_f32 v[244:245], v[142:143], s[98:99] op_sel_hi:[1,0]
	v_pk_mul_f32 v[234:235], v[142:143], s[98:99] op_sel:[0,1] op_sel_hi:[1,1]
	v_exp_f32_e32 v234, v234
	v_exp_f32_e32 v235, v235
	s_nop 0
	v_pk_add_f32 v[234:235], v[234:235], s[100:101] op_sel_hi:[1,0]
	v_rcp_f32_e32 v234, v234
	v_rcp_f32_e32 v235, v235
	s_nop 0
	v_pk_mul_f32 v[244:245], v[244:245], v[234:235]
	v_pk_mul_f32 v[244:245], v[244:245], v[138:139]
	global_store_dwordx2 v[8:9], v[6:7], off
	s_nop 0
	s_nop 0
	v_med3_f32 v5, v244, s40, v190
	s_nop 0
	v_pk_mul_f32 v[246:247], v[144:145], s[98:99] op_sel_hi:[1,0]
	v_pk_mul_f32 v[234:235], v[144:145], s[98:99] op_sel:[0,1] op_sel_hi:[1,1]
	v_exp_f32_e32 v234, v234
	v_exp_f32_e32 v235, v235
	s_nop 0
	v_pk_add_f32 v[234:235], v[234:235], s[100:101] op_sel_hi:[1,0]
	v_rcp_f32_e32 v234, v234
	v_rcp_f32_e32 v235, v235
	s_nop 0
	v_pk_mul_f32 v[246:247], v[246:247], v[234:235]
	v_pk_mul_f32 v[246:247], v[246:247], v[140:141]
	v_med3_f32 v7, v245, s40, v190
	s_nop 0
	s_nop 0
	s_nop 0
	v_pk_mul_f32 v[248:249], v[134:135], s[98:99] op_sel_hi:[1,0]
	v_pk_mul_f32 v[234:235], v[134:135], s[98:99] op_sel:[0,1] op_sel_hi:[1,1]
	v_exp_f32_e32 v234, v234
	v_exp_f32_e32 v235, v235
	s_nop 0
	v_pk_add_f32 v[234:235], v[234:235], s[100:101] op_sel_hi:[1,0]
	v_rcp_f32_e32 v234, v234
	v_rcp_f32_e32 v235, v235
	s_nop 0
	v_pk_mul_f32 v[248:249], v[248:249], v[234:235]
	v_pk_mul_f32 v[248:249], v[248:249], v[130:131]
	s_nop 0
	s_nop 0
	s_nop 0
	s_nop 0
	v_pk_mul_f32 v[250:251], v[136:137], s[98:99] op_sel_hi:[1,0]
	v_pk_mul_f32 v[234:235], v[136:137], s[98:99] op_sel:[0,1] op_sel_hi:[1,1]
	v_exp_f32_e32 v234, v234
	v_exp_f32_e32 v235, v235
	s_nop 0
	v_pk_add_f32 v[234:235], v[234:235], s[100:101] op_sel_hi:[1,0]
	v_rcp_f32_e32 v234, v234
	v_rcp_f32_e32 v235, v235
	s_nop 0
	v_pk_mul_f32 v[250:251], v[250:251], v[234:235]
	v_pk_mul_f32 v[250:251], v[250:251], v[132:133]
	s_nop 0
	s_nop 0
	s_nop 0
	s_nop 0
	v_cvt_pk_fp8_f32 v8, v5, v7
	v_med3_f32 v5, v246, s40, v190
	v_med3_f32 v7, v247, s40, v190
	v_cvt_pk_fp8_f32 v8, v5, v7 op_sel:[0,0,1]
	v_med3_f32 v5, v248, s40, v190
	v_med3_f32 v7, v249, s40, v190
	v_cvt_pk_fp8_f32 v9, v5, v7
	v_add_u32_e32 v6, 16, v4
	v_med3_f32 v5, v250, s40, v190
	v_med3_f32 v7, v251, s40, v190
	v_cvt_pk_fp8_f32 v9, v5, v7 op_sel:[0,0,1]
	v_ashrrev_i32_e32 v7, 31, v6
	v_lshlrev_b64 v[6:7], 7, v[6:7]
	v_lshl_add_u64 v[6:7], s[12:13], 0, v[6:7]
	v_lshl_add_u64 v[6:7], v[6:7], 0, v[2:3]
	v_pk_mul_f32 v[236:237], v[126:127], s[98:99] op_sel_hi:[1,0]
	v_pk_mul_f32 v[234:235], v[126:127], s[98:99] op_sel:[0,1] op_sel_hi:[1,1]
	v_exp_f32_e32 v234, v234
	v_exp_f32_e32 v235, v235
	s_nop 0
	v_pk_add_f32 v[234:235], v[234:235], s[100:101] op_sel_hi:[1,0]
	v_rcp_f32_e32 v234, v234
	v_rcp_f32_e32 v235, v235
	s_nop 0
	v_pk_mul_f32 v[236:237], v[236:237], v[234:235]
	v_pk_mul_f32 v[236:237], v[236:237], v[122:123]
	global_store_dwordx2 v[6:7], v[8:9], off
	s_nop 0
	s_nop 0
	v_med3_f32 v5, v236, s40, v190
	s_nop 0
	v_pk_mul_f32 v[238:239], v[128:129], s[98:99] op_sel_hi:[1,0]
	v_pk_mul_f32 v[234:235], v[128:129], s[98:99] op_sel:[0,1] op_sel_hi:[1,1]
	v_exp_f32_e32 v234, v234
	v_exp_f32_e32 v235, v235
	s_nop 0
	v_pk_add_f32 v[234:235], v[234:235], s[100:101] op_sel_hi:[1,0]
	v_rcp_f32_e32 v234, v234
	v_rcp_f32_e32 v235, v235
	s_nop 0
	v_pk_mul_f32 v[238:239], v[238:239], v[234:235]
	v_pk_mul_f32 v[238:239], v[238:239], v[124:125]
	v_med3_f32 v7, v237, s40, v190
	s_nop 0
	s_nop 0
	s_nop 0
	v_pk_mul_f32 v[240:241], v[118:119], s[98:99] op_sel_hi:[1,0]
	v_pk_mul_f32 v[234:235], v[118:119], s[98:99] op_sel:[0,1] op_sel_hi:[1,1]
	v_exp_f32_e32 v234, v234
	v_exp_f32_e32 v235, v235
	s_nop 0
	v_pk_add_f32 v[234:235], v[234:235], s[100:101] op_sel_hi:[1,0]
	v_rcp_f32_e32 v234, v234
	v_rcp_f32_e32 v235, v235
	s_nop 0
	v_pk_mul_f32 v[240:241], v[240:241], v[234:235]
	v_pk_mul_f32 v[240:241], v[240:241], v[114:115]
	s_nop 0
	s_nop 0
	s_nop 0
	s_nop 0
	v_pk_mul_f32 v[242:243], v[120:121], s[98:99] op_sel_hi:[1,0]
	v_pk_mul_f32 v[234:235], v[120:121], s[98:99] op_sel:[0,1] op_sel_hi:[1,1]
	v_exp_f32_e32 v234, v234
	v_exp_f32_e32 v235, v235
	s_nop 0
	v_pk_add_f32 v[234:235], v[234:235], s[100:101] op_sel_hi:[1,0]
	v_rcp_f32_e32 v234, v234
	v_rcp_f32_e32 v235, v235
	s_nop 0
	v_pk_mul_f32 v[242:243], v[242:243], v[234:235]
	v_pk_mul_f32 v[242:243], v[242:243], v[116:117]
	s_nop 0
	s_nop 0
	s_nop 0
	s_nop 0
	v_cvt_pk_fp8_f32 v8, v5, v7
	v_med3_f32 v5, v238, s40, v190
	v_med3_f32 v7, v239, s40, v190
	v_cvt_pk_fp8_f32 v8, v5, v7 op_sel:[0,0,1]
	v_med3_f32 v5, v240, s40, v190
	v_med3_f32 v7, v241, s40, v190
	v_cvt_pk_fp8_f32 v9, v5, v7
	v_add_u32_e32 v6, 32, v4
	v_med3_f32 v5, v242, s40, v190
	v_med3_f32 v7, v243, s40, v190
	v_cvt_pk_fp8_f32 v9, v5, v7 op_sel:[0,0,1]
	v_ashrrev_i32_e32 v7, 31, v6
	v_lshlrev_b64 v[6:7], 7, v[6:7]
	v_lshl_add_u64 v[6:7], s[12:13], 0, v[6:7]
	v_lshl_add_u64 v[6:7], v[6:7], 0, v[2:3]
	v_pk_mul_f32 v[244:245], v[110:111], s[98:99] op_sel_hi:[1,0]
	v_pk_mul_f32 v[234:235], v[110:111], s[98:99] op_sel:[0,1] op_sel_hi:[1,1]
	v_exp_f32_e32 v234, v234
	v_exp_f32_e32 v235, v235
	s_nop 0
	v_pk_add_f32 v[234:235], v[234:235], s[100:101] op_sel_hi:[1,0]
	v_rcp_f32_e32 v234, v234
	v_rcp_f32_e32 v235, v235
	s_nop 0
	v_pk_mul_f32 v[244:245], v[244:245], v[234:235]
	v_pk_mul_f32 v[244:245], v[244:245], v[106:107]
	global_store_dwordx2 v[6:7], v[8:9], off
	s_nop 0
	s_nop 0
	v_med3_f32 v5, v244, s40, v190
	s_nop 0
	v_pk_mul_f32 v[246:247], v[112:113], s[98:99] op_sel_hi:[1,0]
	v_pk_mul_f32 v[234:235], v[112:113], s[98:99] op_sel:[0,1] op_sel_hi:[1,1]
	v_exp_f32_e32 v234, v234
	v_exp_f32_e32 v235, v235
	s_nop 0
	v_pk_add_f32 v[234:235], v[234:235], s[100:101] op_sel_hi:[1,0]
	v_rcp_f32_e32 v234, v234
	v_rcp_f32_e32 v235, v235
	s_nop 0
	v_pk_mul_f32 v[246:247], v[246:247], v[234:235]
	v_pk_mul_f32 v[246:247], v[246:247], v[108:109]
	v_med3_f32 v7, v245, s40, v190
	s_nop 0
	s_nop 0
	s_nop 0
	v_pk_mul_f32 v[248:249], v[102:103], s[98:99] op_sel_hi:[1,0]
	v_pk_mul_f32 v[234:235], v[102:103], s[98:99] op_sel:[0,1] op_sel_hi:[1,1]
	v_exp_f32_e32 v234, v234
	v_exp_f32_e32 v235, v235
	s_nop 0
	v_pk_add_f32 v[234:235], v[234:235], s[100:101] op_sel_hi:[1,0]
	v_rcp_f32_e32 v234, v234
	v_rcp_f32_e32 v235, v235
	s_nop 0
	v_pk_mul_f32 v[248:249], v[248:249], v[234:235]
	v_pk_mul_f32 v[248:249], v[248:249], v[98:99]
	s_nop 0
	s_nop 0
	s_nop 0
	s_nop 0
	v_pk_mul_f32 v[250:251], v[104:105], s[98:99] op_sel_hi:[1,0]
	v_pk_mul_f32 v[234:235], v[104:105], s[98:99] op_sel:[0,1] op_sel_hi:[1,1]
	v_exp_f32_e32 v234, v234
	v_exp_f32_e32 v235, v235
	s_nop 0
	v_pk_add_f32 v[234:235], v[234:235], s[100:101] op_sel_hi:[1,0]
	v_rcp_f32_e32 v234, v234
	v_rcp_f32_e32 v235, v235
	s_nop 0
	v_pk_mul_f32 v[250:251], v[250:251], v[234:235]
	v_pk_mul_f32 v[250:251], v[250:251], v[100:101]
	s_nop 0
	s_nop 0
	s_nop 0
	s_nop 0
	v_cvt_pk_fp8_f32 v8, v5, v7
	v_med3_f32 v5, v246, s40, v190
	v_med3_f32 v7, v247, s40, v190
	v_cvt_pk_fp8_f32 v8, v5, v7 op_sel:[0,0,1]
	v_med3_f32 v5, v248, s40, v190
	v_med3_f32 v7, v249, s40, v190
	v_cvt_pk_fp8_f32 v9, v5, v7
	v_add_u32_e32 v6, 48, v4
	v_med3_f32 v5, v250, s40, v190
	v_med3_f32 v7, v251, s40, v190
	v_cvt_pk_fp8_f32 v9, v5, v7 op_sel:[0,0,1]
	v_ashrrev_i32_e32 v7, 31, v6
	v_lshlrev_b64 v[6:7], 7, v[6:7]
	v_lshl_add_u64 v[6:7], s[12:13], 0, v[6:7]
	v_lshl_add_u64 v[6:7], v[6:7], 0, v[2:3]
	v_pk_mul_f32 v[236:237], v[94:95], s[98:99] op_sel_hi:[1,0]
	v_pk_mul_f32 v[234:235], v[94:95], s[98:99] op_sel:[0,1] op_sel_hi:[1,1]
	v_exp_f32_e32 v234, v234
	v_exp_f32_e32 v235, v235
	s_nop 0
	v_pk_add_f32 v[234:235], v[234:235], s[100:101] op_sel_hi:[1,0]
	v_rcp_f32_e32 v234, v234
	v_rcp_f32_e32 v235, v235
	s_nop 0
	v_pk_mul_f32 v[236:237], v[236:237], v[234:235]
	v_pk_mul_f32 v[236:237], v[236:237], v[90:91]
	global_store_dwordx2 v[6:7], v[8:9], off
	v_add_u32_e32 v6, 0x80, v4
	s_nop 0
	v_med3_f32 v5, v236, s40, v190
	s_nop 0
	v_pk_mul_f32 v[238:239], v[96:97], s[98:99] op_sel_hi:[1,0]
	v_pk_mul_f32 v[234:235], v[96:97], s[98:99] op_sel:[0,1] op_sel_hi:[1,1]
	v_exp_f32_e32 v234, v234
	v_exp_f32_e32 v235, v235
	s_nop 0
	v_pk_add_f32 v[234:235], v[234:235], s[100:101] op_sel_hi:[1,0]
	v_rcp_f32_e32 v234, v234
	v_rcp_f32_e32 v235, v235
	s_nop 0
	v_pk_mul_f32 v[238:239], v[238:239], v[234:235]
	v_pk_mul_f32 v[238:239], v[238:239], v[92:93]
	v_med3_f32 v7, v237, s40, v190
	s_nop 0
	s_nop 0
	s_nop 0
	v_pk_mul_f32 v[240:241], v[86:87], s[98:99] op_sel_hi:[1,0]
	v_pk_mul_f32 v[234:235], v[86:87], s[98:99] op_sel:[0,1] op_sel_hi:[1,1]
	v_exp_f32_e32 v234, v234
	v_exp_f32_e32 v235, v235
	s_nop 0
	v_pk_add_f32 v[234:235], v[234:235], s[100:101] op_sel_hi:[1,0]
	v_rcp_f32_e32 v234, v234
	v_rcp_f32_e32 v235, v235
	s_nop 0
	v_pk_mul_f32 v[240:241], v[240:241], v[234:235]
	v_pk_mul_f32 v[240:241], v[240:241], v[82:83]
	s_nop 0
	s_nop 0
	s_nop 0
	s_nop 0
	v_pk_mul_f32 v[242:243], v[88:89], s[98:99] op_sel_hi:[1,0]
	v_pk_mul_f32 v[234:235], v[88:89], s[98:99] op_sel:[0,1] op_sel_hi:[1,1]
	v_exp_f32_e32 v234, v234
	v_exp_f32_e32 v235, v235
	s_nop 0
	v_pk_add_f32 v[234:235], v[234:235], s[100:101] op_sel_hi:[1,0]
	v_rcp_f32_e32 v234, v234
	v_rcp_f32_e32 v235, v235
	s_nop 0
	v_pk_mul_f32 v[242:243], v[242:243], v[234:235]
	v_pk_mul_f32 v[242:243], v[242:243], v[84:85]
	s_nop 0
	s_nop 0
	s_nop 0
	s_nop 0
	v_cvt_pk_fp8_f32 v8, v5, v7
	v_med3_f32 v5, v238, s40, v190
	v_med3_f32 v7, v239, s40, v190
	v_cvt_pk_fp8_f32 v8, v5, v7 op_sel:[0,0,1]
	v_med3_f32 v5, v240, s40, v190
	v_med3_f32 v7, v241, s40, v190
	v_cvt_pk_fp8_f32 v9, v5, v7
	v_med3_f32 v5, v242, s40, v190
	v_med3_f32 v7, v243, s40, v190
	v_cvt_pk_fp8_f32 v9, v5, v7 op_sel:[0,0,1]
	v_ashrrev_i32_e32 v7, 31, v6
	v_lshlrev_b64 v[6:7], 7, v[6:7]
	v_lshl_add_u64 v[6:7], s[12:13], 0, v[6:7]
	v_lshl_add_u64 v[6:7], v[6:7], 0, v[2:3]
	v_pk_mul_f32 v[244:245], v[78:79], s[98:99] op_sel_hi:[1,0]
	v_pk_mul_f32 v[234:235], v[78:79], s[98:99] op_sel:[0,1] op_sel_hi:[1,1]
	v_exp_f32_e32 v234, v234
	v_exp_f32_e32 v235, v235
	s_nop 0
	v_pk_add_f32 v[234:235], v[234:235], s[100:101] op_sel_hi:[1,0]
	v_rcp_f32_e32 v234, v234
	v_rcp_f32_e32 v235, v235
	s_nop 0
	v_pk_mul_f32 v[244:245], v[244:245], v[234:235]
	v_pk_mul_f32 v[244:245], v[244:245], v[74:75]
	global_store_dwordx2 v[6:7], v[8:9], off
	s_nop 0
	s_nop 0
	v_med3_f32 v5, v244, s40, v190
	s_nop 0
	v_pk_mul_f32 v[246:247], v[80:81], s[98:99] op_sel_hi:[1,0]
	v_pk_mul_f32 v[234:235], v[80:81], s[98:99] op_sel:[0,1] op_sel_hi:[1,1]
	v_exp_f32_e32 v234, v234
	v_exp_f32_e32 v235, v235
	s_nop 0
	v_pk_add_f32 v[234:235], v[234:235], s[100:101] op_sel_hi:[1,0]
	v_rcp_f32_e32 v234, v234
	v_rcp_f32_e32 v235, v235
	s_nop 0
	v_pk_mul_f32 v[246:247], v[246:247], v[234:235]
	v_pk_mul_f32 v[246:247], v[246:247], v[76:77]
	v_med3_f32 v7, v245, s40, v190
	s_nop 0
	s_nop 0
	s_nop 0
	v_pk_mul_f32 v[248:249], v[70:71], s[98:99] op_sel_hi:[1,0]
	v_pk_mul_f32 v[234:235], v[70:71], s[98:99] op_sel:[0,1] op_sel_hi:[1,1]
	v_exp_f32_e32 v234, v234
	v_exp_f32_e32 v235, v235
	s_nop 0
	v_pk_add_f32 v[234:235], v[234:235], s[100:101] op_sel_hi:[1,0]
	v_rcp_f32_e32 v234, v234
	v_rcp_f32_e32 v235, v235
	s_nop 0
	v_pk_mul_f32 v[248:249], v[248:249], v[234:235]
	v_pk_mul_f32 v[248:249], v[248:249], v[66:67]
	s_nop 0
	s_nop 0
	s_nop 0
	s_nop 0
	v_pk_mul_f32 v[250:251], v[72:73], s[98:99] op_sel_hi:[1,0]
	v_pk_mul_f32 v[234:235], v[72:73], s[98:99] op_sel:[0,1] op_sel_hi:[1,1]
	v_exp_f32_e32 v234, v234
	v_exp_f32_e32 v235, v235
	s_nop 0
	v_pk_add_f32 v[234:235], v[234:235], s[100:101] op_sel_hi:[1,0]
	v_rcp_f32_e32 v234, v234
	v_rcp_f32_e32 v235, v235
	s_nop 0
	v_pk_mul_f32 v[250:251], v[250:251], v[234:235]
	v_pk_mul_f32 v[250:251], v[250:251], v[68:69]
	s_nop 0
	s_nop 0
	s_nop 0
	s_nop 0
	v_cvt_pk_fp8_f32 v8, v5, v7
	v_med3_f32 v5, v246, s40, v190
	v_med3_f32 v7, v247, s40, v190
	v_cvt_pk_fp8_f32 v8, v5, v7 op_sel:[0,0,1]
	v_med3_f32 v5, v248, s40, v190
	v_med3_f32 v7, v249, s40, v190
	v_cvt_pk_fp8_f32 v9, v5, v7
	v_add_u32_e32 v6, 0x90, v4
	v_med3_f32 v5, v250, s40, v190
	v_med3_f32 v7, v251, s40, v190
	v_cvt_pk_fp8_f32 v9, v5, v7 op_sel:[0,0,1]
	v_ashrrev_i32_e32 v7, 31, v6
	v_lshlrev_b64 v[6:7], 7, v[6:7]
	v_lshl_add_u64 v[6:7], s[12:13], 0, v[6:7]
	v_lshl_add_u64 v[6:7], v[6:7], 0, v[2:3]
	v_pk_mul_f32 v[236:237], v[62:63], s[98:99] op_sel_hi:[1,0]
	v_pk_mul_f32 v[234:235], v[62:63], s[98:99] op_sel:[0,1] op_sel_hi:[1,1]
	v_exp_f32_e32 v234, v234
	v_exp_f32_e32 v235, v235
	s_nop 0
	v_pk_add_f32 v[234:235], v[234:235], s[100:101] op_sel_hi:[1,0]
	v_rcp_f32_e32 v234, v234
	v_rcp_f32_e32 v235, v235
	s_nop 0
	v_pk_mul_f32 v[236:237], v[236:237], v[234:235]
	v_pk_mul_f32 v[236:237], v[236:237], v[58:59]
	global_store_dwordx2 v[6:7], v[8:9], off
	s_nop 0
	s_nop 0
	v_med3_f32 v5, v236, s40, v190
	s_nop 0
	v_pk_mul_f32 v[238:239], v[64:65], s[98:99] op_sel_hi:[1,0]
	v_pk_mul_f32 v[234:235], v[64:65], s[98:99] op_sel:[0,1] op_sel_hi:[1,1]
	v_exp_f32_e32 v234, v234
	v_exp_f32_e32 v235, v235
	s_nop 0
	v_pk_add_f32 v[234:235], v[234:235], s[100:101] op_sel_hi:[1,0]
	v_rcp_f32_e32 v234, v234
	v_rcp_f32_e32 v235, v235
	s_nop 0
	v_pk_mul_f32 v[238:239], v[238:239], v[234:235]
	v_pk_mul_f32 v[238:239], v[238:239], v[60:61]
	v_med3_f32 v7, v237, s40, v190
	s_nop 0
	s_nop 0
	s_nop 0
	v_pk_mul_f32 v[240:241], v[54:55], s[98:99] op_sel_hi:[1,0]
	v_pk_mul_f32 v[234:235], v[54:55], s[98:99] op_sel:[0,1] op_sel_hi:[1,1]
	v_exp_f32_e32 v234, v234
	v_exp_f32_e32 v235, v235
	s_nop 0
	v_pk_add_f32 v[234:235], v[234:235], s[100:101] op_sel_hi:[1,0]
	v_rcp_f32_e32 v234, v234
	v_rcp_f32_e32 v235, v235
	s_nop 0
	v_pk_mul_f32 v[240:241], v[240:241], v[234:235]
	v_pk_mul_f32 v[240:241], v[240:241], v[50:51]
	s_nop 0
	s_nop 0
	s_nop 0
	s_nop 0
	v_pk_mul_f32 v[242:243], v[56:57], s[98:99] op_sel_hi:[1,0]
	v_pk_mul_f32 v[234:235], v[56:57], s[98:99] op_sel:[0,1] op_sel_hi:[1,1]
	v_exp_f32_e32 v234, v234
	v_exp_f32_e32 v235, v235
	s_nop 0
	v_pk_add_f32 v[234:235], v[234:235], s[100:101] op_sel_hi:[1,0]
	v_rcp_f32_e32 v234, v234
	v_rcp_f32_e32 v235, v235
	s_nop 0
	v_pk_mul_f32 v[242:243], v[242:243], v[234:235]
	v_pk_mul_f32 v[242:243], v[242:243], v[52:53]
	s_nop 0
	s_nop 0
	s_nop 0
	s_nop 0
	v_cvt_pk_fp8_f32 v8, v5, v7
	v_med3_f32 v5, v238, s40, v190
	v_med3_f32 v7, v239, s40, v190
	v_cvt_pk_fp8_f32 v8, v5, v7 op_sel:[0,0,1]
	v_med3_f32 v5, v240, s40, v190
	v_med3_f32 v7, v241, s40, v190
	v_cvt_pk_fp8_f32 v9, v5, v7
	v_add_u32_e32 v6, 0xa0, v4
	v_med3_f32 v5, v242, s40, v190
	v_med3_f32 v7, v243, s40, v190
	v_cvt_pk_fp8_f32 v9, v5, v7 op_sel:[0,0,1]
	v_ashrrev_i32_e32 v7, 31, v6
	v_lshlrev_b64 v[6:7], 7, v[6:7]
	v_lshl_add_u64 v[6:7], s[12:13], 0, v[6:7]
	v_lshl_add_u64 v[6:7], v[6:7], 0, v[2:3]
	v_pk_mul_f32 v[244:245], v[46:47], s[98:99] op_sel_hi:[1,0]
	v_pk_mul_f32 v[234:235], v[46:47], s[98:99] op_sel:[0,1] op_sel_hi:[1,1]
	v_exp_f32_e32 v234, v234
	v_exp_f32_e32 v235, v235
	s_nop 0
	v_pk_add_f32 v[234:235], v[234:235], s[100:101] op_sel_hi:[1,0]
	v_rcp_f32_e32 v234, v234
	v_rcp_f32_e32 v235, v235
	s_nop 0
	v_pk_mul_f32 v[244:245], v[244:245], v[234:235]
	v_pk_mul_f32 v[244:245], v[244:245], v[42:43]
	global_store_dwordx2 v[6:7], v[8:9], off
	v_add_u32_e32 v4, 0xb0, v4
	s_nop 0
	v_med3_f32 v5, v244, s40, v190
	s_nop 0
	v_pk_mul_f32 v[246:247], v[48:49], s[98:99] op_sel_hi:[1,0]
	v_pk_mul_f32 v[234:235], v[48:49], s[98:99] op_sel:[0,1] op_sel_hi:[1,1]
	v_exp_f32_e32 v234, v234
	v_exp_f32_e32 v235, v235
	s_nop 0
	v_pk_add_f32 v[234:235], v[234:235], s[100:101] op_sel_hi:[1,0]
	v_rcp_f32_e32 v234, v234
	v_rcp_f32_e32 v235, v235
	s_nop 0
	v_pk_mul_f32 v[246:247], v[246:247], v[234:235]
	v_pk_mul_f32 v[246:247], v[246:247], v[44:45]
	s_nop 0
	s_nop 0
	v_pk_mul_f32 v[248:249], v[38:39], s[98:99] op_sel_hi:[1,0]
	v_pk_mul_f32 v[234:235], v[38:39], s[98:99] op_sel:[0,1] op_sel_hi:[1,1]
	v_exp_f32_e32 v234, v234
	v_exp_f32_e32 v235, v235
	s_nop 0
	v_pk_add_f32 v[234:235], v[234:235], s[100:101] op_sel_hi:[1,0]
	v_rcp_f32_e32 v234, v234
	v_rcp_f32_e32 v235, v235
	s_nop 0
	v_pk_mul_f32 v[248:249], v[248:249], v[234:235]
	v_pk_mul_f32 v[248:249], v[248:249], v[34:35]
	s_nop 0
	s_nop 0
	v_pk_mul_f32 v[250:251], v[40:41], s[98:99] op_sel_hi:[1,0]
	v_pk_mul_f32 v[234:235], v[40:41], s[98:99] op_sel:[0,1] op_sel_hi:[1,1]
	v_exp_f32_e32 v234, v234
	v_exp_f32_e32 v235, v235
	s_nop 0
	v_pk_add_f32 v[234:235], v[234:235], s[100:101] op_sel_hi:[1,0]
	v_rcp_f32_e32 v234, v234
	v_rcp_f32_e32 v235, v235
	s_nop 0
	v_pk_mul_f32 v[250:251], v[250:251], v[234:235]
	v_pk_mul_f32 v[250:251], v[250:251], v[36:37]
	s_nop 0
	s_nop 0
	v_med3_f32 v13, v245, s40, v190
	v_cvt_pk_fp8_f32 v6, v5, v13
	v_med3_f32 v5, v246, s40, v190
	v_med3_f32 v7, v247, s40, v190
	v_med3_f32 v8, v249, s40, v190
	v_cvt_pk_fp8_f32 v6, v5, v7 op_sel:[0,0,1]
	v_med3_f32 v5, v248, s40, v190
	v_cvt_pk_fp8_f32 v7, v5, v8
	v_med3_f32 v5, v250, s40, v190
	v_med3_f32 v8, v251, s40, v190
	v_cvt_pk_fp8_f32 v7, v5, v8 op_sel:[0,0,1]
	v_ashrrev_i32_e32 v5, 31, v4
	v_lshlrev_b64 v[4:5], 7, v[4:5]
	v_lshl_add_u64 v[4:5], s[12:13], 0, v[4:5]
	v_lshl_add_u64 v[2:3], v[4:5], 0, v[2:3]
	global_store_dwordx2 v[2:3], v[6:7], off
	s_cbranch_vccz .LBB0_1291
	s_waitcnt vmcnt(0)
	s_cmpk_gt_u32 s42, 0xff
	s_cbranch_scc1 .LBB0_1237
	s_barrier
	s_branch .LBB0_1237

.Lpeel_exit_7:
	v_pk_mul_f32 v[10:11], v[142:143], s[16:17] op_sel_hi:[1,0]
	v_pk_mul_f32 v[8:9], v[144:145], s[16:17] op_sel_hi:[1,0]
	v_med3_f32 v5, v10, s47, v173
	v_med3_f32 v11, v11, s47, v173
	v_cvt_pk_fp8_f32 v10, v5, v11
	v_mov_b32_e32 v3, v166
	v_mov_b32_e32 v2, v167
	s_lshl_b32 s0, s48, 8
	v_pk_mul_f32 v[14:15], v[138:139], s[16:17] op_sel_hi:[1,0]
	v_med3_f32 v5, v8, s47, v173
	v_med3_f32 v8, v9, s47, v173
	s_nop 15
	s_nop 15
	s_or_b32 s0, s0, s42
	v_cvt_pk_fp8_f32 v10, v5, v8 op_sel:[0,0,1]
	v_med3_f32 v5, v14, s47, v173
	v_med3_f32 v8, v15, s47, v173
	v_lshl_add_u32 v2, v2, 3, s0
	s_lshl_b32 s0, s26, 8
	v_cvt_pk_fp8_f32 v11, v5, v8
	s_add_i32 s0, s0, s41
	v_add_u32_e32 v4, s0, v3
	v_pk_mul_f32 v[12:13], v[140:141], s[16:17] op_sel_hi:[1,0]
	v_mov_b32_e32 v6, v4
	v_med3_f32 v5, v12, s47, v173
	v_med3_f32 v8, v13, s47, v173
	v_cvt_pk_fp8_f32 v11, v5, v8 op_sel:[0,0,1]
	v_ashrrev_i32_e32 v7, 31, v6
	v_lshlrev_b64 v[6:7], 10, v[6:7]
	v_ashrrev_i32_e32 v3, 31, v2
	v_lshl_add_u64 v[6:7], s[12:13], 0, v[6:7]
	v_lshl_add_u64 v[6:7], v[6:7], 0, v[2:3]
	global_store_dwordx2 v[6:7], v[10:11], off
	v_pk_mul_f32 v[10:11], v[134:135], s[16:17] op_sel_hi:[1,0]
	v_pk_mul_f32 v[8:9], v[136:137], s[16:17] op_sel_hi:[1,0]
	v_med3_f32 v5, v10, s47, v173
	v_med3_f32 v11, v11, s47, v173
	v_cvt_pk_fp8_f32 v10, v5, v11
	v_pk_mul_f32 v[14:15], v[130:131], s[16:17] op_sel_hi:[1,0]
	v_med3_f32 v5, v8, s47, v173
	v_med3_f32 v8, v9, s47, v173
	v_cvt_pk_fp8_f32 v10, v5, v8 op_sel:[0,0,1]
	v_med3_f32 v5, v14, s47, v173
	v_med3_f32 v8, v15, s47, v173
	v_cvt_pk_fp8_f32 v11, v5, v8
	v_pk_mul_f32 v[12:13], v[132:133], s[16:17] op_sel_hi:[1,0]
	v_pk_mul_f32 v[14:15], v[122:123], s[16:17] op_sel_hi:[1,0]
	v_med3_f32 v5, v12, s47, v173
	v_med3_f32 v8, v13, s47, v173
	v_cvt_pk_fp8_f32 v11, v5, v8 op_sel:[0,0,1]
	v_pk_mul_f32 v[8:9], v[128:129], s[16:17] op_sel_hi:[1,0]
	v_pk_mul_f32 v[12:13], v[124:125], s[16:17] op_sel_hi:[1,0]
	s_and_b64 vcc, exec, s[8:9]
	global_store_dwordx2 v[6:7], v[10:11], off offset:128
	v_pk_mul_f32 v[10:11], v[126:127], s[16:17] op_sel_hi:[1,0]
	v_add_u32_e32 v6, 16, v4
	v_med3_f32 v5, v10, s47, v173
	v_med3_f32 v11, v11, s47, v173
	v_cvt_pk_fp8_f32 v10, v5, v11
	v_med3_f32 v5, v8, s47, v173
	v_med3_f32 v8, v9, s47, v173
	v_cvt_pk_fp8_f32 v10, v5, v8 op_sel:[0,0,1]
	v_med3_f32 v5, v14, s47, v173
	v_med3_f32 v8, v15, s47, v173
	v_cvt_pk_fp8_f32 v11, v5, v8
	v_med3_f32 v5, v12, s47, v173
	v_med3_f32 v8, v13, s47, v173
	v_cvt_pk_fp8_f32 v11, v5, v8 op_sel:[0,0,1]
	v_ashrrev_i32_e32 v7, 31, v6
	v_lshlrev_b64 v[6:7], 10, v[6:7]
	v_lshl_add_u64 v[6:7], s[12:13], 0, v[6:7]
	v_lshl_add_u64 v[6:7], v[6:7], 0, v[2:3]
	global_store_dwordx2 v[6:7], v[10:11], off
	v_pk_mul_f32 v[10:11], v[118:119], s[16:17] op_sel_hi:[1,0]
	v_pk_mul_f32 v[8:9], v[120:121], s[16:17] op_sel_hi:[1,0]
	v_med3_f32 v5, v10, s47, v173
	v_med3_f32 v11, v11, s47, v173
	v_cvt_pk_fp8_f32 v10, v5, v11
	v_pk_mul_f32 v[14:15], v[114:115], s[16:17] op_sel_hi:[1,0]
	v_med3_f32 v5, v8, s47, v173
	v_med3_f32 v8, v9, s47, v173
	v_cvt_pk_fp8_f32 v10, v5, v8 op_sel:[0,0,1]
	v_med3_f32 v5, v14, s47, v173
	v_med3_f32 v8, v15, s47, v173
	v_cvt_pk_fp8_f32 v11, v5, v8
	v_pk_mul_f32 v[12:13], v[116:117], s[16:17] op_sel_hi:[1,0]
	v_pk_mul_f32 v[14:15], v[106:107], s[16:17] op_sel_hi:[1,0]
	v_med3_f32 v5, v12, s47, v173
	v_med3_f32 v8, v13, s47, v173
	v_cvt_pk_fp8_f32 v11, v5, v8 op_sel:[0,0,1]
	v_pk_mul_f32 v[8:9], v[112:113], s[16:17] op_sel_hi:[1,0]
	v_pk_mul_f32 v[12:13], v[108:109], s[16:17] op_sel_hi:[1,0]
	s_mov_b32 s48, s18
	global_store_dwordx2 v[6:7], v[10:11], off offset:128
	v_pk_mul_f32 v[10:11], v[110:111], s[16:17] op_sel_hi:[1,0]
	v_add_u32_e32 v6, 32, v4
	v_med3_f32 v5, v10, s47, v173
	v_med3_f32 v11, v11, s47, v173
	v_cvt_pk_fp8_f32 v10, v5, v11
	v_med3_f32 v5, v8, s47, v173
	v_med3_f32 v8, v9, s47, v173
	v_cvt_pk_fp8_f32 v10, v5, v8 op_sel:[0,0,1]
	v_med3_f32 v5, v14, s47, v173
	v_med3_f32 v8, v15, s47, v173
	v_cvt_pk_fp8_f32 v11, v5, v8
	v_med3_f32 v5, v12, s47, v173
	v_med3_f32 v8, v13, s47, v173
	v_cvt_pk_fp8_f32 v11, v5, v8 op_sel:[0,0,1]
	v_ashrrev_i32_e32 v7, 31, v6
	v_lshlrev_b64 v[6:7], 10, v[6:7]
	v_lshl_add_u64 v[6:7], s[12:13], 0, v[6:7]
	v_lshl_add_u64 v[6:7], v[6:7], 0, v[2:3]
	global_store_dwordx2 v[6:7], v[10:11], off
	v_pk_mul_f32 v[10:11], v[102:103], s[16:17] op_sel_hi:[1,0]
	v_pk_mul_f32 v[8:9], v[104:105], s[16:17] op_sel_hi:[1,0]
	v_med3_f32 v5, v10, s47, v173
	v_med3_f32 v11, v11, s47, v173
	v_cvt_pk_fp8_f32 v10, v5, v11
	v_pk_mul_f32 v[14:15], v[98:99], s[16:17] op_sel_hi:[1,0]
	v_med3_f32 v5, v8, s47, v173
	v_med3_f32 v8, v9, s47, v173
	v_cvt_pk_fp8_f32 v10, v5, v8 op_sel:[0,0,1]
	v_med3_f32 v5, v14, s47, v173
	v_med3_f32 v8, v15, s47, v173
	v_cvt_pk_fp8_f32 v11, v5, v8
	v_pk_mul_f32 v[12:13], v[100:101], s[16:17] op_sel_hi:[1,0]
	v_pk_mul_f32 v[14:15], v[90:91], s[16:17] op_sel_hi:[1,0]
	v_med3_f32 v5, v12, s47, v173
	v_med3_f32 v8, v13, s47, v173
	v_cvt_pk_fp8_f32 v11, v5, v8 op_sel:[0,0,1]
	v_pk_mul_f32 v[8:9], v[96:97], s[16:17] op_sel_hi:[1,0]
	v_pk_mul_f32 v[12:13], v[92:93], s[16:17] op_sel_hi:[1,0]
	s_mov_b32 s26, s20
	global_store_dwordx2 v[6:7], v[10:11], off offset:128
	v_pk_mul_f32 v[10:11], v[94:95], s[16:17] op_sel_hi:[1,0]
	v_add_u32_e32 v6, 48, v4
	v_med3_f32 v5, v10, s47, v173
	v_med3_f32 v11, v11, s47, v173
	v_cvt_pk_fp8_f32 v10, v5, v11
	v_med3_f32 v5, v8, s47, v173
	v_med3_f32 v8, v9, s47, v173
	v_cvt_pk_fp8_f32 v10, v5, v8 op_sel:[0,0,1]
	v_med3_f32 v5, v14, s47, v173
	v_med3_f32 v8, v15, s47, v173
	v_cvt_pk_fp8_f32 v11, v5, v8
	v_med3_f32 v5, v12, s47, v173
	v_med3_f32 v8, v13, s47, v173
	v_cvt_pk_fp8_f32 v11, v5, v8 op_sel:[0,0,1]
	v_ashrrev_i32_e32 v7, 31, v6
	v_lshlrev_b64 v[6:7], 10, v[6:7]
	v_lshl_add_u64 v[6:7], s[12:13], 0, v[6:7]
	v_lshl_add_u64 v[6:7], v[6:7], 0, v[2:3]
	global_store_dwordx2 v[6:7], v[10:11], off
	v_pk_mul_f32 v[10:11], v[86:87], s[16:17] op_sel_hi:[1,0]
	v_pk_mul_f32 v[8:9], v[88:89], s[16:17] op_sel_hi:[1,0]
	v_med3_f32 v5, v10, s47, v173
	v_med3_f32 v11, v11, s47, v173
	v_cvt_pk_fp8_f32 v10, v5, v11
	v_pk_mul_f32 v[14:15], v[82:83], s[16:17] op_sel_hi:[1,0]
	v_med3_f32 v5, v8, s47, v173
	v_med3_f32 v8, v9, s47, v173
	v_cvt_pk_fp8_f32 v10, v5, v8 op_sel:[0,0,1]
	v_med3_f32 v5, v14, s47, v173
	v_med3_f32 v8, v15, s47, v173
	v_cvt_pk_fp8_f32 v11, v5, v8
	v_pk_mul_f32 v[12:13], v[84:85], s[16:17] op_sel_hi:[1,0]
	v_pk_mul_f32 v[14:15], v[74:75], s[16:17] op_sel_hi:[1,0]
	v_med3_f32 v5, v12, s47, v173
	v_med3_f32 v8, v13, s47, v173
	v_cvt_pk_fp8_f32 v11, v5, v8 op_sel:[0,0,1]
	v_pk_mul_f32 v[8:9], v[80:81], s[16:17] op_sel_hi:[1,0]
	v_pk_mul_f32 v[12:13], v[76:77], s[16:17] op_sel_hi:[1,0]
	s_mov_b64 s[28:29], s[24:25]
	global_store_dwordx2 v[6:7], v[10:11], off offset:128
	v_pk_mul_f32 v[10:11], v[78:79], s[16:17] op_sel_hi:[1,0]
	v_add_u32_e32 v6, 0x80, v4
	v_med3_f32 v5, v10, s47, v173
	v_med3_f32 v11, v11, s47, v173
	v_cvt_pk_fp8_f32 v10, v5, v11
	v_med3_f32 v5, v8, s47, v173
	v_med3_f32 v8, v9, s47, v173
	v_cvt_pk_fp8_f32 v10, v5, v8 op_sel:[0,0,1]
	v_med3_f32 v5, v14, s47, v173
	v_med3_f32 v8, v15, s47, v173
	v_cvt_pk_fp8_f32 v11, v5, v8
	v_med3_f32 v5, v12, s47, v173
	v_med3_f32 v8, v13, s47, v173
	v_cvt_pk_fp8_f32 v11, v5, v8 op_sel:[0,0,1]
	v_ashrrev_i32_e32 v7, 31, v6
	v_lshlrev_b64 v[6:7], 10, v[6:7]
	v_lshl_add_u64 v[6:7], s[12:13], 0, v[6:7]
	v_lshl_add_u64 v[6:7], v[6:7], 0, v[2:3]
	global_store_dwordx2 v[6:7], v[10:11], off
	v_pk_mul_f32 v[10:11], v[70:71], s[16:17] op_sel_hi:[1,0]
	v_pk_mul_f32 v[8:9], v[72:73], s[16:17] op_sel_hi:[1,0]
	v_med3_f32 v5, v10, s47, v173
	v_med3_f32 v11, v11, s47, v173
	v_cvt_pk_fp8_f32 v10, v5, v11
	v_pk_mul_f32 v[14:15], v[66:67], s[16:17] op_sel_hi:[1,0]
	v_med3_f32 v5, v8, s47, v173
	v_med3_f32 v8, v9, s47, v173
	v_cvt_pk_fp8_f32 v10, v5, v8 op_sel:[0,0,1]
	v_med3_f32 v5, v14, s47, v173
	v_med3_f32 v8, v15, s47, v173
	v_cvt_pk_fp8_f32 v11, v5, v8
	v_pk_mul_f32 v[12:13], v[68:69], s[16:17] op_sel_hi:[1,0]
	v_pk_mul_f32 v[14:15], v[58:59], s[16:17] op_sel_hi:[1,0]
	v_med3_f32 v5, v12, s47, v173
	v_med3_f32 v8, v13, s47, v173
	v_cvt_pk_fp8_f32 v11, v5, v8 op_sel:[0,0,1]
	v_pk_mul_f32 v[8:9], v[64:65], s[16:17] op_sel_hi:[1,0]
	v_pk_mul_f32 v[12:13], v[60:61], s[16:17] op_sel_hi:[1,0]
	s_mov_b64 s[30:31], s[22:23]
	global_store_dwordx2 v[6:7], v[10:11], off offset:128
	v_pk_mul_f32 v[10:11], v[62:63], s[16:17] op_sel_hi:[1,0]
	v_add_u32_e32 v6, 0x90, v4
	v_med3_f32 v5, v10, s47, v173
	v_med3_f32 v11, v11, s47, v173
	v_cvt_pk_fp8_f32 v10, v5, v11
	v_med3_f32 v5, v8, s47, v173
	v_med3_f32 v8, v9, s47, v173
	v_cvt_pk_fp8_f32 v10, v5, v8 op_sel:[0,0,1]
	v_med3_f32 v5, v14, s47, v173
	v_med3_f32 v8, v15, s47, v173
	v_cvt_pk_fp8_f32 v11, v5, v8
	v_med3_f32 v5, v12, s47, v173
	v_med3_f32 v8, v13, s47, v173
	v_cvt_pk_fp8_f32 v11, v5, v8 op_sel:[0,0,1]
	v_ashrrev_i32_e32 v7, 31, v6
	v_lshlrev_b64 v[6:7], 10, v[6:7]
	v_lshl_add_u64 v[6:7], s[12:13], 0, v[6:7]
	v_lshl_add_u64 v[6:7], v[6:7], 0, v[2:3]
	global_store_dwordx2 v[6:7], v[10:11], off
	v_pk_mul_f32 v[10:11], v[54:55], s[16:17] op_sel_hi:[1,0]
	v_pk_mul_f32 v[8:9], v[56:57], s[16:17] op_sel_hi:[1,0]
	v_med3_f32 v5, v10, s47, v173
	v_med3_f32 v11, v11, s47, v173
	v_cvt_pk_fp8_f32 v10, v5, v11
	v_pk_mul_f32 v[14:15], v[50:51], s[16:17] op_sel_hi:[1,0]
	v_med3_f32 v5, v8, s47, v173
	v_med3_f32 v8, v9, s47, v173
	v_cvt_pk_fp8_f32 v10, v5, v8 op_sel:[0,0,1]
	v_med3_f32 v5, v14, s47, v173
	v_med3_f32 v8, v15, s47, v173
	v_cvt_pk_fp8_f32 v11, v5, v8
	v_pk_mul_f32 v[12:13], v[52:53], s[16:17] op_sel_hi:[1,0]
	v_pk_mul_f32 v[14:15], v[42:43], s[16:17] op_sel_hi:[1,0]
	v_med3_f32 v5, v12, s47, v173
	v_med3_f32 v8, v13, s47, v173
	v_cvt_pk_fp8_f32 v11, v5, v8 op_sel:[0,0,1]
	v_pk_mul_f32 v[8:9], v[48:49], s[16:17] op_sel_hi:[1,0]
	v_pk_mul_f32 v[12:13], v[44:45], s[16:17] op_sel_hi:[1,0]
	global_store_dwordx2 v[6:7], v[10:11], off offset:128
	v_pk_mul_f32 v[10:11], v[46:47], s[16:17] op_sel_hi:[1,0]
	v_add_u32_e32 v6, 0xa0, v4
	v_med3_f32 v5, v10, s47, v173
	v_med3_f32 v11, v11, s47, v173
	v_cvt_pk_fp8_f32 v10, v5, v11
	v_med3_f32 v5, v8, s47, v173
	v_med3_f32 v8, v9, s47, v173
	v_cvt_pk_fp8_f32 v10, v5, v8 op_sel:[0,0,1]
	v_med3_f32 v5, v14, s47, v173
	v_med3_f32 v8, v15, s47, v173
	v_cvt_pk_fp8_f32 v11, v5, v8
	v_med3_f32 v5, v12, s47, v173
	v_med3_f32 v8, v13, s47, v173
	v_cvt_pk_fp8_f32 v11, v5, v8 op_sel:[0,0,1]
	v_ashrrev_i32_e32 v7, 31, v6
	v_lshlrev_b64 v[6:7], 10, v[6:7]
	v_lshl_add_u64 v[6:7], s[12:13], 0, v[6:7]
	v_lshl_add_u64 v[6:7], v[6:7], 0, v[2:3]
	global_store_dwordx2 v[6:7], v[10:11], off
	v_pk_mul_f32 v[10:11], v[38:39], s[16:17] op_sel_hi:[1,0]
	v_pk_mul_f32 v[8:9], v[40:41], s[16:17] op_sel_hi:[1,0]
	v_med3_f32 v5, v10, s47, v173
	v_med3_f32 v11, v11, s47, v173
	v_cvt_pk_fp8_f32 v10, v5, v11
	v_pk_mul_f32 v[14:15], v[34:35], s[16:17] op_sel_hi:[1,0]
	v_med3_f32 v5, v8, s47, v173
	v_med3_f32 v8, v9, s47, v173
	v_cvt_pk_fp8_f32 v10, v5, v8 op_sel:[0,0,1]
	v_med3_f32 v5, v14, s47, v173
	v_med3_f32 v8, v15, s47, v173
	v_cvt_pk_fp8_f32 v11, v5, v8
	v_pk_mul_f32 v[12:13], v[36:37], s[16:17] op_sel_hi:[1,0]
	v_add_u32_e32 v4, 0xb0, v4
	v_med3_f32 v5, v12, s47, v173
	v_med3_f32 v8, v13, s47, v173
	v_cvt_pk_fp8_f32 v11, v5, v8 op_sel:[0,0,1]
	v_pk_mul_f32 v[8:9], v[28:29], s[16:17] op_sel_hi:[1,0]
	global_store_dwordx2 v[6:7], v[10:11], off offset:128
	v_pk_mul_f32 v[6:7], v[30:31], s[16:17] op_sel_hi:[1,0]
	v_pk_mul_f32 v[10:11], v[26:27], s[16:17] op_sel_hi:[1,0]
	v_ashrrev_i32_e32 v5, 31, v4
	v_med3_f32 v12, v6, s47, v173
	v_med3_f32 v7, v7, s47, v173
	v_lshlrev_b64 v[4:5], 10, v[4:5]
	v_cvt_pk_fp8_f32 v6, v12, v7
	v_lshl_add_u64 v[4:5], s[12:13], 0, v[4:5]
	v_lshl_add_u64 v[2:3], v[4:5], 0, v[2:3]
	v_pk_mul_f32 v[4:5], v[32:33], s[16:17] op_sel_hi:[1,0]
	v_med3_f32 v4, v4, s47, v173
	v_med3_f32 v5, v5, s47, v173
	v_cvt_pk_fp8_f32 v6, v4, v5 op_sel:[0,0,1]
	v_med3_f32 v4, v10, s47, v173
	v_med3_f32 v5, v11, s47, v173
	v_cvt_pk_fp8_f32 v7, v4, v5
	v_med3_f32 v4, v8, s47, v173
	v_med3_f32 v5, v9, s47, v173
	v_pk_mul_f32 v[10:11], v[18:19], s[16:17] op_sel_hi:[1,0]
	v_cvt_pk_fp8_f32 v7, v4, v5 op_sel:[0,0,1]
	v_pk_mul_f32 v[4:5], v[24:25], s[16:17] op_sel_hi:[1,0]
	v_pk_mul_f32 v[8:9], v[20:21], s[16:17] op_sel_hi:[1,0]
	v_med3_f32 v4, v4, s47, v173
	global_store_dwordx2 v[2:3], v[6:7], off
	v_pk_mul_f32 v[6:7], v[22:23], s[16:17] op_sel_hi:[1,0]
	v_med3_f32 v5, v5, s47, v173
	v_med3_f32 v12, v6, s47, v173
	v_med3_f32 v7, v7, s47, v173
	v_cvt_pk_fp8_f32 v6, v12, v7
	s_nop 0
	v_cvt_pk_fp8_f32 v6, v4, v5 op_sel:[0,0,1]
	v_med3_f32 v4, v10, s47, v173
	v_med3_f32 v5, v11, s47, v173
	v_cvt_pk_fp8_f32 v7, v4, v5
	v_med3_f32 v4, v8, s47, v173
	v_med3_f32 v5, v9, s47, v173
	v_cvt_pk_fp8_f32 v7, v4, v5 op_sel:[0,0,1]
	global_store_dwordx2 v[2:3], v[6:7], off offset:128
	s_cbranch_vccz .LBB0_1362
	s_waitcnt vmcnt(0)
	s_cmpk_gt_u32 s4, 0xff
	s_cbranch_scc1 .LBB0_1373
	s_barrier

.LBB0_1444:
	s_mul_hi_i32 s0, s11, 0x2aaaaaab
	s_lshr_b32 s1, s0, 31
	s_ashr_i32 s0, s0, 8
	s_add_i32 s14, s0, s1
	s_mul_i32 s0, s14, 0xfffffa00
	s_add_i32 s24, s11, s0
	s_lshr_b32 s0, s24, 22
	s_and_b32 s0, s0, 0x1ff
	s_add_i32 s25, s24, s0
	s_and_b32 s0, s25, 0xfe00
	s_sub_i32 s0, s24, s0
	s_sext_i32_i16 s1, s0
	s_bfe_u32 s1, s1, 0x5001a
	s_add_i32 s1, s0, s1
	s_sext_i32_i16 s12, s1
	s_and_b32 s1, s1, 0xffe0
	s_lshl_b32 s23, s12, 1
	s_sub_i32 s0, s0, s1
	s_andn2_b32 s23, s23, 63
	s_sext_i32_i16 s22, s0
	s_lshl_b32 s12, s22, 5
	v_or_b32_e32 v20, s23, v26
	s_mov_b64 s[20:21], -1
	s_cmpk_gt_i32 s24, 0x3ff
	v_ashrrev_i32_e32 v21, 31, v20
	v_or_b32_e32 v18, 8, v20
	v_or_b32_e32 v16, 16, v20
	v_or_b32_e32 v14, 24, v20
	v_or_b32_e32 v12, 32, v20
	v_or_b32_e32 v10, 40, v20
	v_or_b32_e32 v8, 48, v20
	v_or_b32_e32 v6, 56, v20
	s_cbranch_scc0 .LBB0_1446
	s_ashr_i32 s15, s14, 31
	s_lshl_b64 s[0:1], s[14:15], 20
	s_lshl_b64 s[20:21], s[14:15], 22
	s_add_u32 s15, s8, s20
	s_addc_u32 s20, s9, s21
	s_add_u32 s21, s6, s0
	s_addc_u32 s26, s7, s1
	s_ashr_i32 s13, s12, 31
	s_lshl_b64 s[0:1], s[12:13], 2
	s_add_u32 s0, s15, s0
	s_addc_u32 s1, s20, s1
	v_lshl_add_u64 v[72:73], s[0:1], 0, v[2:3]
	v_lshlrev_b64 v[22:23], 12, v[20:21]
	v_lshl_add_u64 v[22:23], v[72:73], 0, v[22:23]
	v_ashrrev_i32_e32 v19, 31, v18
	global_load_dwordx4 v[22:25], v[22:23], off nt
	v_lshlrev_b64 v[48:49], 12, v[18:19]
	v_lshl_add_u64 v[48:49], v[72:73], 0, v[48:49]
	v_ashrrev_i32_e32 v17, 31, v16
	global_load_dwordx4 v[48:51], v[48:49], off nt
	v_lshlrev_b64 v[52:53], 12, v[16:17]
	v_lshl_add_u64 v[52:53], v[72:73], 0, v[52:53]
	v_ashrrev_i32_e32 v15, 31, v14
	global_load_dwordx4 v[52:55], v[52:53], off nt
	v_lshlrev_b64 v[56:57], 12, v[14:15]
	v_lshl_add_u64 v[56:57], v[72:73], 0, v[56:57]
	v_ashrrev_i32_e32 v13, 31, v12
	global_load_dwordx4 v[56:59], v[56:57], off nt
	v_lshlrev_b64 v[60:61], 12, v[12:13]
	v_lshl_add_u64 v[60:61], v[72:73], 0, v[60:61]
	v_ashrrev_i32_e32 v11, 31, v10
	global_load_dwordx4 v[60:63], v[60:61], off nt
	v_lshlrev_b64 v[64:65], 12, v[10:11]
	v_lshl_add_u64 v[64:65], v[72:73], 0, v[64:65]
	v_ashrrev_i32_e32 v9, 31, v8
	global_load_dwordx4 v[64:67], v[64:65], off nt
	v_lshlrev_b64 v[68:69], 12, v[8:9]
	v_lshl_add_u64 v[68:69], v[72:73], 0, v[68:69]
	v_ashrrev_i32_e32 v7, 31, v6
	global_load_dwordx4 v[68:71], v[68:69], off nt
	v_lshlrev_b64 v[74:75], 12, v[6:7]
	v_lshl_add_u64 v[72:73], v[72:73], 0, v[74:75]
	global_load_dwordx4 v[72:75], v[72:73], off nt
	s_ashr_i32 s1, s23, 31
	s_add_u32 s0, s21, s23
	s_addc_u32 s1, s26, s1
	s_waitcnt vmcnt(0)
	ds_write2_b32 v31, v22, v23 offset1:1
	ds_write2_b32 v31, v24, v25 offset0:2 offset1:3
	s_waitcnt vmcnt(6)
	ds_write2_b32 v32, v48, v49 offset1:1
	ds_write2_b32 v33, v50, v51 offset1:1
	s_waitcnt vmcnt(5)
	ds_write2_b32 v34, v52, v53 offset1:1
	ds_write2_b32 v35, v54, v55 offset1:1
	s_waitcnt vmcnt(4)
	ds_write2_b32 v36, v56, v57 offset1:1
	ds_write2_b32 v37, v58, v59 offset1:1
	s_waitcnt vmcnt(3)
	ds_write2_b32 v38, v60, v61 offset1:1
	ds_write2_b32 v39, v62, v63 offset1:1
	s_waitcnt vmcnt(2)
	ds_write2_b32 v40, v64, v65 offset1:1
	ds_write2_b32 v41, v66, v67 offset1:1
	s_waitcnt vmcnt(1)
	ds_write2_b32 v42, v68, v69 offset1:1
	ds_write2_b32 v43, v70, v71 offset1:1
	s_waitcnt vmcnt(0)
	ds_write2_b32 v44, v72, v73 offset1:1
	ds_write2_b32 v45, v74, v75 offset1:1
	s_waitcnt lgkmcnt(0)
	ds_read_b32 v7, v30
	ds_read_b32 v9, v30 offset:132
	ds_read_b32 v11, v30 offset:264
	ds_read_b32 v13, v30 offset:396
	s_waitcnt lgkmcnt(0)
	v_mul_f32_e32 v7, 0x43000000, v7
	s_waitcnt lgkmcnt(2)
	v_mul_f32_e32 v9, 0x43000000, v9
	v_med3_f32 v7, v7, s10, v46
	v_med3_f32 v9, v9, s10, v46
	v_cvt_pk_fp8_f32 v24, v7, v9
	s_waitcnt lgkmcnt(1)
	v_mul_f32_e32 v11, 0x43000000, v11
	s_waitcnt lgkmcnt(0)
	v_mul_f32_e32 v13, 0x43000000, v13
	v_med3_f32 v7, v11, s10, v46
	v_med3_f32 v9, v13, s10, v46
	v_cvt_pk_fp8_f32 v24, v7, v9 op_sel:[0,0,1]
	ds_read_b32 v7, v30 offset:528
	ds_read_b32 v9, v30 offset:660
	ds_read_b32 v11, v30 offset:792
	ds_read_b32 v13, v30 offset:924
	s_waitcnt lgkmcnt(3)
	v_mul_f32_e32 v7, 0x43000000, v7
	s_waitcnt lgkmcnt(2)
	v_mul_f32_e32 v9, 0x43000000, v9
	v_med3_f32 v7, v7, s10, v46
	v_med3_f32 v9, v9, s10, v46
	v_cvt_pk_fp8_f32 v25, v7, v9
	s_waitcnt lgkmcnt(1)
	v_mul_f32_e32 v11, 0x43000000, v11
	s_waitcnt lgkmcnt(0)
	v_mul_f32_e32 v13, 0x43000000, v13
	v_med3_f32 v7, v11, s10, v46
	v_med3_f32 v9, v13, s10, v46
	v_cvt_pk_fp8_f32 v25, v7, v9 op_sel:[0,0,1]
	v_or_b32_e32 v48, s12, v26
	v_ashrrev_i32_e32 v49, 31, v48
	v_lshl_add_u64 v[22:23], s[0:1], 0, v[4:5]
	v_lshlrev_b64 v[48:49], 10, v[48:49]
	v_lshl_add_u64 v[48:49], v[22:23], 0, v[48:49]
	global_store_dwordx2 v[48:49], v[24:25], off nt
	ds_read_b32 v7, v30 offset:32
	ds_read_b32 v9, v30 offset:164
	ds_read_b32 v11, v30 offset:296
	ds_read_b32 v13, v30 offset:428
	s_waitcnt lgkmcnt(0)
	v_mul_f32_e32 v7, 0x43000000, v7
	v_mul_f32_e32 v9, 0x43000000, v9
	v_med3_f32 v7, v7, s10, v46
	v_med3_f32 v9, v9, s10, v46
	v_cvt_pk_fp8_f32 v24, v7, v9
	v_mul_f32_e32 v11, 0x43000000, v11
	v_mul_f32_e32 v13, 0x43000000, v13
	v_med3_f32 v7, v11, s10, v46
	v_med3_f32 v9, v13, s10, v46
	v_cvt_pk_fp8_f32 v24, v7, v9 op_sel:[0,0,1]
	ds_read_b32 v7, v30 offset:560
	ds_read_b32 v9, v30 offset:692
	ds_read_b32 v11, v30 offset:824
	ds_read_b32 v13, v30 offset:956
	s_waitcnt lgkmcnt(0)
	v_mul_f32_e32 v7, 0x43000000, v7
	v_mul_f32_e32 v9, 0x43000000, v9
	v_med3_f32 v7, v7, s10, v46
	v_med3_f32 v9, v9, s10, v46
	v_cvt_pk_fp8_f32 v25, v7, v9
	v_mul_f32_e32 v11, 0x43000000, v11
	v_mul_f32_e32 v13, 0x43000000, v13
	v_med3_f32 v7, v11, s10, v46
	v_med3_f32 v9, v13, s10, v46
	v_cvt_pk_fp8_f32 v25, v7, v9 op_sel:[0,0,1]
	v_or_b32_e32 v48, s12, v27
	v_ashrrev_i32_e32 v49, 31, v48
	v_lshlrev_b64 v[48:49], 10, v[48:49]
	v_lshl_add_u64 v[48:49], v[22:23], 0, v[48:49]
	global_store_dwordx2 v[48:49], v[24:25], off nt
	ds_read_b32 v7, v30 offset:64
	ds_read_b32 v9, v30 offset:196
	ds_read_b32 v11, v30 offset:328
	ds_read_b32 v13, v30 offset:460
	s_waitcnt lgkmcnt(0)
	v_mul_f32_e32 v7, 0x43000000, v7
	v_mul_f32_e32 v9, 0x43000000, v9
	v_med3_f32 v7, v7, s10, v46
	v_med3_f32 v9, v9, s10, v46
	v_cvt_pk_fp8_f32 v24, v7, v9
	v_mul_f32_e32 v11, 0x43000000, v11
	v_mul_f32_e32 v13, 0x43000000, v13
	v_med3_f32 v7, v11, s10, v46
	v_med3_f32 v9, v13, s10, v46
	v_cvt_pk_fp8_f32 v24, v7, v9 op_sel:[0,0,1]
	ds_read_b32 v7, v30 offset:592
	ds_read_b32 v9, v30 offset:724
	ds_read_b32 v11, v30 offset:856
	ds_read_b32 v13, v30 offset:988
	s_waitcnt lgkmcnt(0)
	v_mul_f32_e32 v7, 0x43000000, v7
	v_mul_f32_e32 v9, 0x43000000, v9
	v_med3_f32 v7, v7, s10, v46
	v_med3_f32 v9, v9, s10, v46
	v_cvt_pk_fp8_f32 v25, v7, v9
	v_mul_f32_e32 v11, 0x43000000, v11
	v_mul_f32_e32 v13, 0x43000000, v13
	v_med3_f32 v7, v11, s10, v46
	v_med3_f32 v9, v13, s10, v46
	v_cvt_pk_fp8_f32 v25, v7, v9 op_sel:[0,0,1]
	v_or_b32_e32 v48, s12, v28
	v_ashrrev_i32_e32 v49, 31, v48
	v_lshlrev_b64 v[48:49], 10, v[48:49]
	v_lshl_add_u64 v[48:49], v[22:23], 0, v[48:49]
	global_store_dwordx2 v[48:49], v[24:25], off nt
	ds_read_b32 v7, v30 offset:96
	ds_read_b32 v9, v30 offset:228
	ds_read_b32 v11, v30 offset:360
	ds_read_b32 v13, v30 offset:492
	s_waitcnt lgkmcnt(0)
	v_mul_f32_e32 v7, 0x43000000, v7
	v_mul_f32_e32 v9, 0x43000000, v9
	v_med3_f32 v7, v7, s10, v46
	v_med3_f32 v9, v9, s10, v46
	v_cvt_pk_fp8_f32 v24, v7, v9
	v_mul_f32_e32 v11, 0x43000000, v11
	v_mul_f32_e32 v13, 0x43000000, v13
	v_med3_f32 v7, v11, s10, v46
	v_med3_f32 v9, v13, s10, v46
	v_cvt_pk_fp8_f32 v24, v7, v9 op_sel:[0,0,1]
	ds_read_b32 v7, v30 offset:624
	ds_read_b32 v9, v30 offset:756
	ds_read_b32 v11, v30 offset:888
	ds_read_b32 v13, v30 offset:1020
	s_waitcnt lgkmcnt(0)
	v_mul_f32_e32 v7, 0x43000000, v7
	v_mul_f32_e32 v9, 0x43000000, v9
	v_med3_f32 v7, v7, s10, v46
	v_med3_f32 v9, v9, s10, v46
	v_cvt_pk_fp8_f32 v25, v7, v9
	v_mul_f32_e32 v11, 0x43000000, v11
	v_mul_f32_e32 v13, 0x43000000, v13
	v_med3_f32 v7, v11, s10, v46
	v_med3_f32 v9, v13, s10, v46
	v_cvt_pk_fp8_f32 v25, v7, v9 op_sel:[0,0,1]
	v_or_b32_e32 v48, s12, v29
	v_ashrrev_i32_e32 v49, 31, v48
	v_lshlrev_b64 v[48:49], 10, v[48:49]
	v_lshl_add_u64 v[22:23], v[22:23], 0, v[48:49]
	global_store_dwordx2 v[22:23], v[24:25], off nt
	s_waitcnt lgkmcnt(0)
	s_cbranch_execnz .LBB0_1443
	s_branch .LBB0_1447

.LBB0_1447:
	s_sext_i32_i16 s0, s25
	s_lshr_b32 s0, s0, 9
	s_addk_i32 s24, 0x1ff
	s_cmpk_lt_u32 s24, 0x3ff
	s_cselect_b32 s13, s17, s19
	s_cselect_b32 s21, s16, s18
	s_ashr_i32 s15, s14, 31
	s_sext_i32_i16 s20, s0
	s_lshl_b64 s[0:1], s[14:15], 22
	s_add_u32 s21, s21, s0
	s_addc_u32 s24, s13, s1
	s_lshl_b64 s[0:1], s[14:15], 21
	s_add_u32 s14, s4, s0
	s_addc_u32 s15, s5, s1
	s_ashr_i32 s13, s12, 31
	s_lshl_b64 s[0:1], s[12:13], 2
	s_add_u32 s0, s21, s0
	s_addc_u32 s1, s24, s1
	v_lshl_add_u64 v[22:23], s[0:1], 0, v[2:3]
	s_mov_b64 s[0:1], 0x8000000
	v_lshl_add_u64 v[24:25], v[22:23], 0, s[0:1]
	v_lshlrev_b64 v[20:21], 12, v[20:21]
	v_lshl_add_u64 v[20:21], v[24:25], 0, v[20:21]
	v_ashrrev_i32_e32 v19, 31, v18
	global_load_dwordx4 v[20:23], v[20:21], off nt
	v_lshlrev_b64 v[18:19], 12, v[18:19]
	v_lshl_add_u64 v[18:19], v[24:25], 0, v[18:19]
	v_ashrrev_i32_e32 v17, 31, v16
	global_load_dwordx4 v[48:51], v[18:19], off nt
	v_lshlrev_b64 v[16:17], 12, v[16:17]
	v_lshl_add_u64 v[16:17], v[24:25], 0, v[16:17]
	v_ashrrev_i32_e32 v15, 31, v14
	global_load_dwordx4 v[16:19], v[16:17], off nt
	v_lshlrev_b64 v[14:15], 12, v[14:15]
	v_lshl_add_u64 v[14:15], v[24:25], 0, v[14:15]
	v_ashrrev_i32_e32 v13, 31, v12
	global_load_dwordx4 v[52:55], v[14:15], off nt
	v_lshlrev_b64 v[12:13], 12, v[12:13]
	v_lshl_add_u64 v[12:13], v[24:25], 0, v[12:13]
	v_ashrrev_i32_e32 v11, 31, v10
	global_load_dwordx4 v[12:15], v[12:13], off nt
	v_lshlrev_b64 v[10:11], 12, v[10:11]
	v_lshl_add_u64 v[10:11], v[24:25], 0, v[10:11]
	v_ashrrev_i32_e32 v9, 31, v8
	global_load_dwordx4 v[56:59], v[10:11], off nt
	v_lshlrev_b64 v[8:9], 12, v[8:9]
	v_lshl_add_u64 v[8:9], v[24:25], 0, v[8:9]
	v_ashrrev_i32_e32 v7, 31, v6
	global_load_dwordx4 v[8:11], v[8:9], off nt
	v_lshlrev_b64 v[6:7], 12, v[6:7]
	v_lshl_add_u64 v[6:7], v[24:25], 0, v[6:7]
	global_load_dwordx4 v[60:63], v[6:7], off nt
	s_lshl_b32 s1, s20, 7
	s_ashr_i32 s0, s23, 31
	s_add_u32 s14, s14, s23
	s_addc_u32 s15, s15, s0
	s_lshl_b32 s0, s22, 6
	s_and_b32 s0, s0, 0xffffff00
	s_add_i32 s0, s0, s1
	s_and_b32 s1, s12, 0x60
	s_or_b32 s12, s0, s1
	v_lshl_add_u64 v[6:7], s[14:15], 0, v[4:5]
	s_waitcnt vmcnt(0)
	ds_write2_b32 v31, v20, v21 offset1:1
	ds_write2_b32 v31, v22, v23 offset0:2 offset1:3
	ds_write2_b32 v32, v48, v49 offset1:1
	ds_write2_b32 v33, v50, v51 offset1:1
	ds_write2_b32 v34, v16, v17 offset1:1
	ds_write2_b32 v35, v18, v19 offset1:1
	ds_write2_b32 v36, v52, v53 offset1:1
	ds_write2_b32 v37, v54, v55 offset1:1
	ds_write2_b32 v38, v12, v13 offset1:1
	ds_write2_b32 v39, v14, v15 offset1:1
	ds_write2_b32 v40, v56, v57 offset1:1
	ds_write2_b32 v41, v58, v59 offset1:1
	ds_write2_b32 v42, v8, v9 offset1:1
	ds_write2_b32 v43, v10, v11 offset1:1
	ds_write2_b32 v44, v60, v61 offset1:1
	ds_write2_b32 v45, v62, v63 offset1:1
	s_waitcnt lgkmcnt(0)
	ds_read_b32 v8, v30
	ds_read_b32 v9, v30 offset:132
	ds_read_b32 v10, v30 offset:264
	ds_read_b32 v11, v30 offset:396
	s_waitcnt lgkmcnt(0)
	v_mul_f32_e32 v8, 0x42800000, v8
	v_mul_f32_e32 v9, 0x42800000, v9
	v_med3_f32 v12, v8, s10, v46
	v_med3_f32 v9, v9, s10, v46
	v_cvt_pk_fp8_f32 v8, v12, v9
	v_mul_f32_e32 v10, 0x42800000, v10
	v_mul_f32_e32 v11, 0x42800000, v11
	v_med3_f32 v9, v10, s10, v46
	v_med3_f32 v10, v11, s10, v46
	v_cvt_pk_fp8_f32 v8, v9, v10 op_sel:[0,0,1]
	ds_read_b32 v9, v30 offset:528
	ds_read_b32 v10, v30 offset:660
	ds_read_b32 v11, v30 offset:792
	ds_read_b32 v12, v30 offset:924
	s_waitcnt lgkmcnt(3)
	v_mul_f32_e32 v9, 0x42800000, v9
	s_waitcnt lgkmcnt(2)
	v_mul_f32_e32 v10, 0x42800000, v10
	v_med3_f32 v13, v9, s10, v46
	v_med3_f32 v10, v10, s10, v46
	v_cvt_pk_fp8_f32 v9, v13, v10
	s_waitcnt lgkmcnt(1)
	v_mul_f32_e32 v11, 0x42800000, v11
	s_waitcnt lgkmcnt(0)
	v_mul_f32_e32 v12, 0x42800000, v12
	v_med3_f32 v10, v11, s10, v46
	v_med3_f32 v11, v12, s10, v46
	v_cvt_pk_fp8_f32 v9, v10, v11 op_sel:[0,0,1]
	v_or_b32_e32 v10, s12, v26
	v_ashrrev_i32_e32 v11, 31, v10
	v_lshlrev_b64 v[10:11], 10, v[10:11]
	v_lshl_add_u64 v[10:11], v[6:7], 0, v[10:11]
	global_store_dwordx2 v[10:11], v[8:9], off nt
	ds_read_b32 v8, v30 offset:32
	ds_read_b32 v9, v30 offset:164
	ds_read_b32 v10, v30 offset:296
	ds_read_b32 v11, v30 offset:428
	s_waitcnt lgkmcnt(0)
	v_mul_f32_e32 v8, 0x42800000, v8
	v_mul_f32_e32 v9, 0x42800000, v9
	v_med3_f32 v12, v8, s10, v46
	v_med3_f32 v9, v9, s10, v46
	v_cvt_pk_fp8_f32 v8, v12, v9
	v_mul_f32_e32 v10, 0x42800000, v10
	v_mul_f32_e32 v11, 0x42800000, v11
	v_med3_f32 v9, v10, s10, v46
	v_med3_f32 v10, v11, s10, v46
	v_cvt_pk_fp8_f32 v8, v9, v10 op_sel:[0,0,1]
	ds_read_b32 v9, v30 offset:560
	ds_read_b32 v10, v30 offset:692
	ds_read_b32 v11, v30 offset:824
	ds_read_b32 v12, v30 offset:956
	s_waitcnt lgkmcnt(0)
	v_mul_f32_e32 v9, 0x42800000, v9
	v_mul_f32_e32 v10, 0x42800000, v10
	v_med3_f32 v13, v9, s10, v46
	v_med3_f32 v10, v10, s10, v46
	v_cvt_pk_fp8_f32 v9, v13, v10
	v_mul_f32_e32 v11, 0x42800000, v11
	v_mul_f32_e32 v12, 0x42800000, v12
	v_med3_f32 v10, v11, s10, v46
	v_med3_f32 v11, v12, s10, v46
	v_cvt_pk_fp8_f32 v9, v10, v11 op_sel:[0,0,1]
	v_or_b32_e32 v10, s12, v27
	v_ashrrev_i32_e32 v11, 31, v10
	v_lshlrev_b64 v[10:11], 10, v[10:11]
	v_lshl_add_u64 v[10:11], v[6:7], 0, v[10:11]
	global_store_dwordx2 v[10:11], v[8:9], off nt
	ds_read_b32 v8, v30 offset:64
	ds_read_b32 v9, v30 offset:196
	ds_read_b32 v10, v30 offset:328
	ds_read_b32 v11, v30 offset:460
	s_waitcnt lgkmcnt(0)
	v_mul_f32_e32 v8, 0x42800000, v8
	v_mul_f32_e32 v9, 0x42800000, v9
	v_med3_f32 v12, v8, s10, v46
	v_med3_f32 v9, v9, s10, v46
	v_cvt_pk_fp8_f32 v8, v12, v9
	v_mul_f32_e32 v10, 0x42800000, v10
	v_mul_f32_e32 v11, 0x42800000, v11
	v_med3_f32 v9, v10, s10, v46
	v_med3_f32 v10, v11, s10, v46
	v_cvt_pk_fp8_f32 v8, v9, v10 op_sel:[0,0,1]
	ds_read_b32 v9, v30 offset:592
	ds_read_b32 v10, v30 offset:724
	ds_read_b32 v11, v30 offset:856
	ds_read_b32 v12, v30 offset:988
	s_waitcnt lgkmcnt(0)
	v_mul_f32_e32 v9, 0x42800000, v9
	v_mul_f32_e32 v10, 0x42800000, v10
	v_med3_f32 v13, v9, s10, v46
	v_med3_f32 v10, v10, s10, v46
	v_cvt_pk_fp8_f32 v9, v13, v10
	v_mul_f32_e32 v11, 0x42800000, v11
	v_mul_f32_e32 v12, 0x42800000, v12
	v_med3_f32 v10, v11, s10, v46
	v_med3_f32 v11, v12, s10, v46
	v_cvt_pk_fp8_f32 v9, v10, v11 op_sel:[0,0,1]
	v_or_b32_e32 v10, s12, v28
	v_ashrrev_i32_e32 v11, 31, v10
	v_lshlrev_b64 v[10:11], 10, v[10:11]
	v_lshl_add_u64 v[10:11], v[6:7], 0, v[10:11]
	global_store_dwordx2 v[10:11], v[8:9], off nt
	ds_read_b32 v8, v30 offset:96
	ds_read_b32 v9, v30 offset:228
	ds_read_b32 v10, v30 offset:360
	ds_read_b32 v11, v30 offset:492
	s_waitcnt lgkmcnt(0)
	v_mul_f32_e32 v8, 0x42800000, v8
	v_mul_f32_e32 v9, 0x42800000, v9
	v_med3_f32 v12, v8, s10, v46
	v_med3_f32 v9, v9, s10, v46
	v_cvt_pk_fp8_f32 v8, v12, v9
	v_mul_f32_e32 v10, 0x42800000, v10
	v_mul_f32_e32 v11, 0x42800000, v11
	v_med3_f32 v9, v10, s10, v46
	v_med3_f32 v10, v11, s10, v46
	v_cvt_pk_fp8_f32 v8, v9, v10 op_sel:[0,0,1]
	ds_read_b32 v9, v30 offset:624
	ds_read_b32 v10, v30 offset:756
	ds_read_b32 v11, v30 offset:888
	ds_read_b32 v12, v30 offset:1020
	s_waitcnt lgkmcnt(0)
	v_mul_f32_e32 v9, 0x42800000, v9
	v_mul_f32_e32 v10, 0x42800000, v10
	v_med3_f32 v13, v9, s10, v46
	v_med3_f32 v10, v10, s10, v46
	v_cvt_pk_fp8_f32 v9, v13, v10
	v_mul_f32_e32 v11, 0x42800000, v11
	v_mul_f32_e32 v12, 0x42800000, v12
	v_med3_f32 v10, v11, s10, v46
	v_med3_f32 v11, v12, s10, v46
	v_cvt_pk_fp8_f32 v9, v10, v11 op_sel:[0,0,1]
	v_or_b32_e32 v10, s12, v29
	v_ashrrev_i32_e32 v11, 31, v10
	v_lshlrev_b64 v[10:11], 10, v[10:11]
	v_lshl_add_u64 v[6:7], v[6:7], 0, v[10:11]
	global_store_dwordx2 v[6:7], v[8:9], off nt
	s_waitcnt lgkmcnt(0)
	s_branch .LBB0_1443

.LBB0_1645:
	s_add_u32 s57, s48, s56
	s_addc_u32 s58, s49, 0
	s_add_u32 s59, s57, 0x100
	s_addc_u32 s60, s58, 0
	s_and_b64 s[0:1], s[54:55], exec
	s_cselect_b32 s61, s43, s60
	s_cselect_b32 s60, s83, s59
	s_add_u32 s0, s14, s56
	s_addc_u32 s1, s15, 0
	s_add_u32 s56, s0, 0x100
	s_addc_u32 s59, s1, 0
	s_and_b64 s[0:1], s[54:55], exec
	s_cselect_b32 s63, s41, s59
	s_cselect_b32 s62, s94, s56
	s_add_u32 s64, s57, 0x40080
	s_addc_u32 s65, s58, 0
	s_add_i32 s0, s85, s37
	s_add_i32 m0, s39, 0xc000
	s_add_i32 s71, s39, 0xe000
	s_add_i32 s70, s0, 0x2000
	s_add_u32 s58, s62, 0x10000
	s_addc_u32 s59, s63, 0
	s_add_i32 s1, s4, s37
	ds_read_b128 v[26:29], v225
	ds_read_b128 v[30:33], v225 offset:1024
	ds_read_b128 v[42:45], v225 offset:2048
	ds_read_b128 v[46:49], v225 offset:3072
	s_add_i32 s96, s1, 0x2000
	s_add_i32 s81, 0, 0x18000
	s_add_u32 s56, s60, 0x40000
	s_addc_u32 s57, s61, 0
	s_add_i32 s78, s81, s37
	s_add_i32 s79, 0, 0x1c000
	s_add_i32 s80, s78, 0x2000
	s_add_u32 s54, s62, 0x10080
	s_addc_u32 s55, s63, 0
	s_add_i32 vcc_hi, s79, s37
	s_add_i32 vcc_lo, vcc_hi, 0x2000
	v_lshl_add_u64 v[190:191], s[64:65], 0, v[160:161]
	ds_read_b128 v[146:149], v226
	ds_read_b128 v[150:153], v226 offset:1024
	ds_read_b128 v[166:169], v226 offset:2048
	ds_read_b128 v[170:173], v226 offset:3072
	ds_read_b128 v[174:177], v226 offset:4096
	ds_read_b128 v[178:181], v226 offset:5120
	ds_read_b128 v[182:185], v226 offset:6144
	ds_read_b128 v[186:189], v226 offset:7168
	global_load_lds_dwordx4 v[190:191], off
	v_lshl_add_u64 v[190:191], s[64:65], 0, v[156:157]
	s_mov_b32 m0, s71
	s_nop 0
	global_load_lds_dwordx4 v[190:191], off
	s_waitcnt lgkmcnt(8)
	s_waitcnt vmcnt(10)
	s_barrier
	s_waitcnt lgkmcnt(0)
	s_waitcnt lgkmcnt(0)
	v_mfma_f32_16x16x32_bf16 v[142:145], v[26:29], v[146:149], v[142:145]
	v_mfma_f32_16x16x32_bf16 v[134:137], v[42:45], v[146:149], v[134:137]
	v_mfma_f32_16x16x32_bf16 v[126:129], v[26:29], v[166:169], v[126:129]
	v_mfma_f32_16x16x32_bf16 v[118:121], v[42:45], v[166:169], v[118:121]
	v_mfma_f32_16x16x32_bf16 v[110:113], v[26:29], v[174:177], v[110:113]
	v_mfma_f32_16x16x32_bf16 v[102:105], v[42:45], v[174:177], v[102:105]
	v_mfma_f32_16x16x32_bf16 v[94:97], v[26:29], v[182:185], v[94:97]
	v_mfma_f32_16x16x32_bf16 v[86:89], v[42:45], v[182:185], v[86:89]
	v_mfma_f32_16x16x32_bf16 v[142:145], v[30:33], v[150:153], v[142:145]
	v_mfma_f32_16x16x32_bf16 v[134:137], v[46:49], v[150:153], v[134:137]
	v_mfma_f32_16x16x32_bf16 v[126:129], v[30:33], v[170:173], v[126:129]
	v_mfma_f32_16x16x32_bf16 v[118:121], v[46:49], v[170:173], v[118:121]
	v_mfma_f32_16x16x32_bf16 v[110:113], v[30:33], v[178:181], v[110:113]
	v_mfma_f32_16x16x32_bf16 v[102:105], v[46:49], v[178:181], v[102:105]
	v_mfma_f32_16x16x32_bf16 v[94:97], v[30:33], v[186:189], v[94:97]
	v_mfma_f32_16x16x32_bf16 v[86:89], v[46:49], v[186:189], v[86:89]
	s_barrier
	s_mov_b32 m0, s0
	v_lshl_add_u64 v[206:207], s[62:63], 0, v[158:159]
	ds_read_b128 v[190:193], v227
	ds_read_b128 v[194:197], v227 offset:1024
	ds_read_b128 v[198:201], v227 offset:2048
	ds_read_b128 v[202:205], v227 offset:3072
	global_load_lds_dwordx4 v[206:207], off
	v_lshl_add_u64 v[208:209], s[62:63], 0, v[154:155]
	s_mov_b32 m0, s70
	s_nop 0
	global_load_lds_dwordx4 v[208:209], off
	s_waitcnt vmcnt(10)
	s_barrier
	s_waitcnt lgkmcnt(0)
	s_waitcnt lgkmcnt(0)
	v_mfma_f32_16x16x32_bf16 v[138:141], v[190:193], v[146:149], v[138:141]
	v_mfma_f32_16x16x32_bf16 v[130:133], v[198:201], v[146:149], v[130:133]
	v_mfma_f32_16x16x32_bf16 v[122:125], v[190:193], v[166:169], v[122:125]
	v_mfma_f32_16x16x32_bf16 v[114:117], v[198:201], v[166:169], v[114:117]
	v_mfma_f32_16x16x32_bf16 v[106:109], v[190:193], v[174:177], v[106:109]
	v_mfma_f32_16x16x32_bf16 v[98:101], v[198:201], v[174:177], v[98:101]
	v_mfma_f32_16x16x32_bf16 v[90:93], v[190:193], v[182:185], v[90:93]
	v_mfma_f32_16x16x32_bf16 v[82:85], v[198:201], v[182:185], v[82:85]
	v_mfma_f32_16x16x32_bf16 v[138:141], v[194:197], v[150:153], v[138:141]
	v_mfma_f32_16x16x32_bf16 v[130:133], v[202:205], v[150:153], v[130:133]
	v_mfma_f32_16x16x32_bf16 v[122:125], v[194:197], v[170:173], v[122:125]
	v_mfma_f32_16x16x32_bf16 v[114:117], v[202:205], v[170:173], v[114:117]
	v_mfma_f32_16x16x32_bf16 v[106:109], v[194:197], v[178:181], v[106:109]
	v_mfma_f32_16x16x32_bf16 v[98:101], v[202:205], v[178:181], v[98:101]
	v_mfma_f32_16x16x32_bf16 v[90:93], v[194:197], v[186:189], v[90:93]
	v_mfma_f32_16x16x32_bf16 v[82:85], v[202:205], v[186:189], v[82:85]
	s_mov_b32 m0, s39
	v_lshl_add_u64 v[210:211], s[60:61], 0, v[160:161]
	s_barrier
	ds_read_b128 v[146:149], v226 offset:16384
	ds_read_b128 v[150:153], v226 offset:17408
	ds_read_b128 v[166:169], v226 offset:18432
	ds_read_b128 v[170:173], v226 offset:19456
	ds_read_b128 v[174:177], v226 offset:20480
	ds_read_b128 v[178:181], v226 offset:21504
	ds_read_b128 v[182:185], v226 offset:22528
	ds_read_b128 v[186:189], v226 offset:23552
	global_load_lds_dwordx4 v[210:211], off
	v_lshl_add_u64 v[212:213], s[60:61], 0, v[156:157]
	s_mov_b32 m0, s53
	s_nop 0
	global_load_lds_dwordx4 v[212:213], off
	s_waitcnt vmcnt(10)
	s_barrier
	s_waitcnt lgkmcnt(0)
	s_waitcnt lgkmcnt(0)
	v_mfma_f32_16x16x32_bf16 v[78:81], v[26:29], v[146:149], v[78:81]
	v_mfma_f32_16x16x32_bf16 v[70:73], v[42:45], v[146:149], v[70:73]
	v_mfma_f32_16x16x32_bf16 v[62:65], v[26:29], v[166:169], v[62:65]
	v_mfma_f32_16x16x32_bf16 v[54:57], v[42:45], v[166:169], v[54:57]
	v_mfma_f32_16x16x32_bf16 v[38:41], v[26:29], v[174:177], v[38:41]
	v_mfma_f32_16x16x32_bf16 v[22:25], v[42:45], v[174:177], v[22:25]
	v_mfma_f32_16x16x32_bf16 v[14:17], v[26:29], v[182:185], v[14:17]
	v_mfma_f32_16x16x32_bf16 v[6:9], v[42:45], v[182:185], v[6:9]
	v_mfma_f32_16x16x32_bf16 v[78:81], v[30:33], v[150:153], v[78:81]
	v_mfma_f32_16x16x32_bf16 v[70:73], v[46:49], v[150:153], v[70:73]
	v_mfma_f32_16x16x32_bf16 v[62:65], v[30:33], v[170:173], v[62:65]
	v_mfma_f32_16x16x32_bf16 v[54:57], v[46:49], v[170:173], v[54:57]
	v_mfma_f32_16x16x32_bf16 v[38:41], v[30:33], v[178:181], v[38:41]
	v_mfma_f32_16x16x32_bf16 v[22:25], v[46:49], v[178:181], v[22:25]
	v_mfma_f32_16x16x32_bf16 v[14:17], v[30:33], v[186:189], v[14:17]
	v_mfma_f32_16x16x32_bf16 v[6:9], v[46:49], v[186:189], v[6:9]
	s_barrier
	s_mov_b32 m0, s1
	v_lshl_add_u64 v[26:27], s[58:59], 0, v[158:159]
	global_load_lds_dwordx4 v[26:27], off
	v_lshl_add_u64 v[26:27], s[58:59], 0, v[154:155]
	s_mov_b32 m0, s96
	s_nop 0
	global_load_lds_dwordx4 v[26:27], off
	s_waitcnt vmcnt(10)
	s_barrier
	v_mfma_f32_16x16x32_bf16 v[34:37], v[190:193], v[174:177], v[34:37]
	v_mfma_f32_16x16x32_bf16 v[18:21], v[198:201], v[174:177], v[18:21]
	v_mfma_f32_16x16x32_bf16 v[10:13], v[190:193], v[182:185], v[10:13]
	v_mfma_f32_16x16x32_bf16 v[2:5], v[198:201], v[182:185], v[2:5]
	v_mfma_f32_16x16x32_bf16 v[26:29], v[190:193], v[146:149], v[74:77]
	v_mfma_f32_16x16x32_bf16 v[30:33], v[198:201], v[146:149], v[66:69]
	v_mfma_f32_16x16x32_bf16 v[42:45], v[190:193], v[166:169], v[58:61]
	v_mfma_f32_16x16x32_bf16 v[46:49], v[198:201], v[166:169], v[50:53]
	v_mfma_f32_16x16x32_bf16 v[34:37], v[194:197], v[178:181], v[34:37]
	v_mfma_f32_16x16x32_bf16 v[18:21], v[202:205], v[178:181], v[18:21]
	v_mfma_f32_16x16x32_bf16 v[10:13], v[194:197], v[186:189], v[10:13]
	v_mfma_f32_16x16x32_bf16 v[2:5], v[202:205], v[186:189], v[2:5]
	v_mfma_f32_16x16x32_bf16 v[26:29], v[194:197], v[150:153], v[26:29]
	v_mfma_f32_16x16x32_bf16 v[30:33], v[202:205], v[150:153], v[30:33]
	v_mfma_f32_16x16x32_bf16 v[42:45], v[194:197], v[170:173], v[42:45]
	v_mfma_f32_16x16x32_bf16 v[46:49], v[202:205], v[170:173], v[46:49]
	v_add_u32_e32 v74, s81, v224
	s_barrier
	ds_read_b128 v[50:53], v74
	ds_read_b128 v[58:61], v74 offset:1024
	ds_read_b128 v[66:69], v74 offset:2048
	ds_read_b128 v[74:77], v74 offset:3072
	s_mov_b32 m0, s66
	v_lshl_add_u64 v[190:191], s[56:57], 0, v[160:161]
	ds_read_b128 v[146:149], v226 offset:32768
	ds_read_b128 v[150:153], v226 offset:33792
	ds_read_b128 v[166:169], v226 offset:34816
	ds_read_b128 v[170:173], v226 offset:35840
	ds_read_b128 v[174:177], v226 offset:36864
	ds_read_b128 v[178:181], v226 offset:37888
	ds_read_b128 v[182:185], v226 offset:38912
	ds_read_b128 v[186:189], v226 offset:39936
	global_load_lds_dwordx4 v[190:191], off
	v_lshl_add_u64 v[190:191], s[56:57], 0, v[156:157]
	s_mov_b32 m0, s67
	s_nop 0
	global_load_lds_dwordx4 v[190:191], off
	s_waitcnt lgkmcnt(8)
	s_waitcnt vmcnt(10)
	s_barrier
	s_waitcnt lgkmcnt(0)
	s_waitcnt lgkmcnt(0)
	v_mfma_f32_16x16x32_bf16 v[142:145], v[50:53], v[146:149], v[142:145]
	v_mfma_f32_16x16x32_bf16 v[134:137], v[66:69], v[146:149], v[134:137]
	v_mfma_f32_16x16x32_bf16 v[126:129], v[50:53], v[166:169], v[126:129]
	v_mfma_f32_16x16x32_bf16 v[118:121], v[66:69], v[166:169], v[118:121]
	v_mfma_f32_16x16x32_bf16 v[110:113], v[50:53], v[174:177], v[110:113]
	v_mfma_f32_16x16x32_bf16 v[102:105], v[66:69], v[174:177], v[102:105]
	v_mfma_f32_16x16x32_bf16 v[94:97], v[50:53], v[182:185], v[94:97]
	v_mfma_f32_16x16x32_bf16 v[86:89], v[66:69], v[182:185], v[86:89]
	v_mfma_f32_16x16x32_bf16 v[142:145], v[58:61], v[150:153], v[142:145]
	v_mfma_f32_16x16x32_bf16 v[134:137], v[74:77], v[150:153], v[134:137]
	v_mfma_f32_16x16x32_bf16 v[126:129], v[58:61], v[170:173], v[126:129]
	v_mfma_f32_16x16x32_bf16 v[118:121], v[74:77], v[170:173], v[118:121]
	v_mfma_f32_16x16x32_bf16 v[110:113], v[58:61], v[178:181], v[110:113]
	v_mfma_f32_16x16x32_bf16 v[102:105], v[74:77], v[178:181], v[102:105]
	v_mfma_f32_16x16x32_bf16 v[94:97], v[58:61], v[186:189], v[94:97]
	v_mfma_f32_16x16x32_bf16 v[86:89], v[74:77], v[186:189], v[86:89]
	s_barrier
	s_mov_b32 m0, s78
	v_add_u32_e32 v202, s79, v224
	v_lshl_add_u64 v[206:207], v[206:207], 0, s[26:27]
	ds_read_b128 v[190:193], v202
	ds_read_b128 v[194:197], v202 offset:1024
	ds_read_b128 v[198:201], v202 offset:2048
	ds_read_b128 v[202:205], v202 offset:3072
	global_load_lds_dwordx4 v[206:207], off
	v_lshl_add_u64 v[206:207], v[208:209], 0, s[26:27]
	s_mov_b32 m0, s80
	s_nop 0
	global_load_lds_dwordx4 v[206:207], off
	s_waitcnt vmcnt(10)
	s_barrier
	s_waitcnt lgkmcnt(0)
	s_waitcnt lgkmcnt(0)
	v_mfma_f32_16x16x32_bf16 v[138:141], v[190:193], v[146:149], v[138:141]
	v_mfma_f32_16x16x32_bf16 v[130:133], v[198:201], v[146:149], v[130:133]
	v_mfma_f32_16x16x32_bf16 v[122:125], v[190:193], v[166:169], v[122:125]
	v_mfma_f32_16x16x32_bf16 v[114:117], v[198:201], v[166:169], v[114:117]
	v_mfma_f32_16x16x32_bf16 v[106:109], v[190:193], v[174:177], v[106:109]
	v_mfma_f32_16x16x32_bf16 v[98:101], v[198:201], v[174:177], v[98:101]
	v_mfma_f32_16x16x32_bf16 v[90:93], v[190:193], v[182:185], v[90:93]
	v_mfma_f32_16x16x32_bf16 v[82:85], v[198:201], v[182:185], v[82:85]
	v_mfma_f32_16x16x32_bf16 v[138:141], v[194:197], v[150:153], v[138:141]
	v_mfma_f32_16x16x32_bf16 v[130:133], v[202:205], v[150:153], v[130:133]
	v_mfma_f32_16x16x32_bf16 v[122:125], v[194:197], v[170:173], v[122:125]
	v_mfma_f32_16x16x32_bf16 v[114:117], v[202:205], v[170:173], v[114:117]
	v_mfma_f32_16x16x32_bf16 v[106:109], v[194:197], v[178:181], v[106:109]
	v_mfma_f32_16x16x32_bf16 v[98:101], v[202:205], v[178:181], v[98:101]
	v_mfma_f32_16x16x32_bf16 v[90:93], v[194:197], v[186:189], v[90:93]
	v_mfma_f32_16x16x32_bf16 v[82:85], v[202:205], v[186:189], v[82:85]
	s_mov_b32 m0, s6
	v_lshl_add_u64 v[206:207], v[210:211], 0, s[26:27]
	s_barrier
	ds_read_b128 v[146:149], v226 offset:49152
	ds_read_b128 v[150:153], v226 offset:50176
	ds_read_b128 v[166:169], v226 offset:51200
	ds_read_b128 v[170:173], v226 offset:52224
	ds_read_b128 v[174:177], v226 offset:53248
	ds_read_b128 v[178:181], v226 offset:54272
	ds_read_b128 v[182:185], v226 offset:55296
	ds_read_b128 v[186:189], v226 offset:56320
	global_load_lds_dwordx4 v[206:207], off
	v_lshl_add_u64 v[206:207], v[212:213], 0, s[26:27]
	s_mov_b32 m0, s7
	s_nop 0
	global_load_lds_dwordx4 v[206:207], off
	s_waitcnt vmcnt(10)
	s_barrier
	s_waitcnt lgkmcnt(0)
	s_waitcnt lgkmcnt(0)
	v_mfma_f32_16x16x32_bf16 v[78:81], v[50:53], v[146:149], v[78:81]
	v_mfma_f32_16x16x32_bf16 v[70:73], v[66:69], v[146:149], v[70:73]
	v_mfma_f32_16x16x32_bf16 v[62:65], v[50:53], v[166:169], v[62:65]
	v_mfma_f32_16x16x32_bf16 v[54:57], v[66:69], v[166:169], v[54:57]
	v_mfma_f32_16x16x32_bf16 v[38:41], v[50:53], v[174:177], v[38:41]
	v_mfma_f32_16x16x32_bf16 v[22:25], v[66:69], v[174:177], v[22:25]
	v_mfma_f32_16x16x32_bf16 v[14:17], v[50:53], v[182:185], v[14:17]
	v_mfma_f32_16x16x32_bf16 v[6:9], v[66:69], v[182:185], v[6:9]
	v_mfma_f32_16x16x32_bf16 v[78:81], v[58:61], v[150:153], v[78:81]
	v_mfma_f32_16x16x32_bf16 v[70:73], v[74:77], v[150:153], v[70:73]
	v_mfma_f32_16x16x32_bf16 v[62:65], v[58:61], v[170:173], v[62:65]
	v_mfma_f32_16x16x32_bf16 v[54:57], v[74:77], v[170:173], v[54:57]
	v_mfma_f32_16x16x32_bf16 v[38:41], v[58:61], v[178:181], v[38:41]
	v_mfma_f32_16x16x32_bf16 v[22:25], v[74:77], v[178:181], v[22:25]
	v_mfma_f32_16x16x32_bf16 v[14:17], v[58:61], v[186:189], v[14:17]
	v_mfma_f32_16x16x32_bf16 v[6:9], v[74:77], v[186:189], v[6:9]
	s_barrier
	s_mov_b32 m0, vcc_hi
	v_lshl_add_u64 v[50:51], s[54:55], 0, v[158:159]
	global_load_lds_dwordx4 v[50:51], off
	v_lshl_add_u64 v[50:51], s[54:55], 0, v[154:155]
	s_mov_b32 m0, vcc_lo
	s_nop 0
	global_load_lds_dwordx4 v[50:51], off
	s_waitcnt vmcnt(10)
	s_barrier
	v_mfma_f32_16x16x32_bf16 v[26:29], v[190:193], v[146:149], v[26:29]
	v_mfma_f32_16x16x32_bf16 v[74:77], v[194:197], v[150:153], v[26:29]
	v_mfma_f32_16x16x32_bf16 v[26:29], v[198:201], v[146:149], v[30:33]
	v_mfma_f32_16x16x32_bf16 v[66:69], v[202:205], v[150:153], v[26:29]
	v_mfma_f32_16x16x32_bf16 v[26:29], v[190:193], v[166:169], v[42:45]
	v_mfma_f32_16x16x32_bf16 v[58:61], v[194:197], v[170:173], v[26:29]
	v_mfma_f32_16x16x32_bf16 v[26:29], v[198:201], v[166:169], v[46:49]
	v_mfma_f32_16x16x32_bf16 v[50:53], v[202:205], v[170:173], v[26:29]
	v_mfma_f32_16x16x32_bf16 v[26:29], v[190:193], v[174:177], v[34:37]
	v_mfma_f32_16x16x32_bf16 v[18:21], v[198:201], v[174:177], v[18:21]
	v_mfma_f32_16x16x32_bf16 v[10:13], v[190:193], v[182:185], v[10:13]
	v_mfma_f32_16x16x32_bf16 v[2:5], v[198:201], v[182:185], v[2:5]
	v_mfma_f32_16x16x32_bf16 v[34:37], v[194:197], v[178:181], v[26:29]
	v_mfma_f32_16x16x32_bf16 v[18:21], v[202:205], v[178:181], v[18:21]
	v_mfma_f32_16x16x32_bf16 v[10:13], v[194:197], v[186:189], v[10:13]
	v_mfma_f32_16x16x32_bf16 v[2:5], v[202:205], v[186:189], v[2:5]
	s_movk_i32 s56, 0x100
	s_andn2_b64 vcc, exec, s[50:51]
	s_mov_b64 s[54:55], -1
	s_mov_b64 s[50:51], 0
	s_barrier
	s_cbranch_vccz .LBB0_1645
	s_lshl_b32 s0, s82, 7
	s_and_b32 s1, s0, 0x380
	v_mov_b32_e32 v167, v222
	v_mov_b32_e32 v26, v223
	s_or_b32 s1, s1, s11
	s_cmp_lt_u32 s82, 8
	v_lshl_add_u32 v166, v26, 3, s1
	s_mov_b32 s1, 0x32100000
	s_cselect_b32 s1, s1, 0x1a100000
	s_cselect_b32 s49, s9, s17
	s_cselect_b32 s48, s8, s16
	s_add_u32 s50, s18, s1
	s_addc_u32 s51, s19, 0
	s_and_b32 s0, s0, 0xfffffc00
	v_add_u32_e32 v26, s0, v166
	s_load_dwordx2 s[0:1], s[20:21], 0x78
	v_ashrrev_i32_e32 v27, 31, v26
	v_readlane_b32 s56, v254, 5
	v_lshlrev_b64 v[146:147], 2, v[26:27]
	v_readlane_b32 s57, v254, 6
	v_readlane_b32 s58, v254, 7
	v_readlane_b32 s59, v254, 8
	s_waitcnt lgkmcnt(0)
	v_lshl_add_u64 v[26:27], s[0:1], 0, v[146:147]
	v_lshl_add_u64 v[42:43], s[56:57], 0, v[146:147]
	v_lshl_add_u64 v[150:151], s[58:59], 0, v[146:147]
	global_load_dwordx4 v[30:33], v[26:27], off offset:16
	global_load_dwordx4 v[46:49], v[26:27], off
	s_nop 0
	global_load_dwordx4 v[26:29], v[42:43], off offset:16
	s_nop 0
	global_load_dwordx4 v[42:45], v[42:43], off
	s_nop 0
	global_load_dwordx4 v[146:149], v[150:151], off offset:16
	s_nop 0
	global_load_dwordx4 v[150:153], v[150:151], off
	s_lshl_b32 s0, s52, 8
	s_add_i32 s0, s0, s10
	s_waitcnt vmcnt(0)
	v_add_f32_e32 v134, v134, v30
	v_add_f32_e32 v142, v142, v46
	v_add_f32_e32 v138, v138, v42
	v_max_f32_e32 v168, v150, v150
	v_mul_f32_e64 v150, |v150|, s5
	v_exp_f32_e32 v232, v150
	v_mul_f32_e32 v138, 0xbfb8aa3b, v138
	v_exp_f32_e32 v138, v138
	v_mul_f32_e32 v142, 0xbfb8aa3b, v142
	v_add_f32_e32 v172, 1.0, v232
	v_add_f32_e32 v150, -1.0, v172
	v_sub_f32_e32 v169, v150, v172
	v_add_f32_e32 v169, 1.0, v169
	v_sub_f32_e32 v150, v232, v150
	v_add_f32_e32 v174, v150, v169
	v_max_f32_e32 v150, v151, v151
	v_min_f32_e32 v169, 0, v150
	v_mul_f32_e64 v150, |v151|, s5
	v_exp_f32_e32 v233, v150
	v_cvt_f64_f32_e32 v[170:171], v172
	v_frexp_exp_i32_f64_e32 v170, v[170:171]
	v_frexp_mant_f32_e32 v173, v172
	v_add_f32_e32 v171, 1.0, v233
	v_add_f32_e32 v150, -1.0, v171
	v_sub_f32_e32 v151, v150, v171
	v_add_f32_e32 v151, 1.0, v151
	v_sub_f32_e32 v150, v233, v150
	v_add_f32_e32 v175, v150, v151
	v_frexp_mant_f32_e32 v176, v171
	v_cvt_f64_f32_e32 v[150:151], v171
	v_cmp_gt_f32_e32 vcc, s72, v173
	v_frexp_exp_i32_f64_e32 v150, v[150:151]
	v_cmp_gt_f32_e64 s[14:15], s72, v176
	v_subbrev_co_u32_e32 v176, vcc, 0, v170, vcc
	s_nop 0
	v_subbrev_co_u32_e64 v173, s[14:15], 0, v150, s[14:15]
	v_sub_u32_e32 v151, 0, v176
	v_ldexp_f32 v150, v172, v151
	v_sub_u32_e32 v172, 0, v173
	v_ldexp_f32 v170, v174, v151
	v_ldexp_f32 v151, v171, v172
	v_ldexp_f32 v171, v175, v172
	v_pk_add_f32 v[174:175], v[150:151], 1.0 op_sel_hi:[1,0]
	v_pk_add_f32 v[184:185], v[150:151], -1.0 op_sel_hi:[1,0]
	v_pk_add_f32 v[178:179], v[174:175], -1.0 op_sel_hi:[1,0]
	v_pk_add_f32 v[186:187], v[184:185], 1.0 op_sel_hi:[1,0]
	v_pk_add_f32 v[178:179], v[150:151], v[178:179] neg_lo:[0,1] neg_hi:[0,1]
	v_pk_add_f32 v[150:151], v[150:151], v[186:187] neg_lo:[0,1] neg_hi:[0,1]
	v_pk_add_f32 v[178:179], v[170:171], v[178:179]
	v_pk_add_f32 v[150:151], v[170:171], v[150:151]
	v_pk_add_f32 v[180:181], v[174:175], v[178:179]
	v_pk_add_f32 v[170:171], v[184:185], v[150:151]
	v_rcp_f32_e32 v182, v180
	v_rcp_f32_e32 v183, v181
	v_pk_add_f32 v[174:175], v[180:181], v[174:175] neg_lo:[0,1] neg_hi:[0,1]
	v_pk_add_f32 v[184:185], v[170:171], v[184:185] neg_lo:[0,1] neg_hi:[0,1]
	v_pk_add_f32 v[174:175], v[178:179], v[174:175] neg_lo:[0,1] neg_hi:[0,1]
	v_pk_mul_f32 v[186:187], v[170:171], v[182:183]
	v_pk_add_f32 v[150:151], v[150:151], v[184:185] neg_lo:[0,1] neg_hi:[0,1]
	v_pk_mul_f32 v[178:179], v[180:181], v[186:187]
	s_mov_b32 s14, 0x3ecc95a3
	v_pk_fma_f32 v[184:185], v[186:187], v[180:181], v[178:179] neg_lo:[0,0,1] neg_hi:[0,0,1]
	v_cvt_f32_i32_e32 v177, v173
	v_pk_fma_f32 v[184:185], v[186:187], v[174:175], v[184:185]
	v_cvt_f32_i32_e32 v176, v176
	v_pk_add_f32 v[188:189], v[178:179], v[184:185]
	v_add_f32_e32 v138, 1.0, v138
	v_pk_add_f32 v[190:191], v[170:171], v[188:189] neg_lo:[0,1] neg_hi:[0,1]
	v_pk_add_f32 v[178:179], v[188:189], v[178:179] neg_lo:[0,1] neg_hi:[0,1]
	v_pk_add_f32 v[170:171], v[170:171], v[190:191] neg_lo:[0,1] neg_hi:[0,1]
	v_rcp_f32_e32 v249, v138
	v_pk_add_f32 v[170:171], v[170:171], v[188:189] neg_lo:[0,1] neg_hi:[0,1]
	v_add_f32_e32 v138, v143, v47
	v_pk_add_f32 v[150:151], v[150:151], v[170:171]
	v_pk_add_f32 v[170:171], v[178:179], v[184:185] neg_lo:[0,1] neg_hi:[0,1]
	v_mul_f32_e32 v138, 0xbfb8aa3b, v138
	v_pk_add_f32 v[150:151], v[170:171], v[150:151]
	v_exp_f32_e32 v138, v138
	v_pk_add_f32 v[170:171], v[190:191], v[150:151]
	v_exp_f32_e32 v142, v142
	v_pk_mul_f32 v[178:179], v[182:183], v[170:171]
	v_pk_add_f32 v[190:191], v[190:191], v[170:171] neg_lo:[0,1] neg_hi:[0,1]
	v_pk_mul_f32 v[184:185], v[180:181], v[178:179]
	v_pk_add_f32 v[150:151], v[150:151], v[190:191]
	v_pk_fma_f32 v[180:181], v[178:179], v[180:181], v[184:185] neg_lo:[0,0,1] neg_hi:[0,0,1]
	v_pk_add_f32 v[196:197], v[186:187], v[178:179]
	v_pk_fma_f32 v[174:175], v[178:179], v[174:175], v[180:181]
	v_add_f32_e32 v138, 1.0, v138
	v_pk_add_f32 v[180:181], v[184:185], v[174:175]
	v_rcp_f32_e32 v143, v138
	v_pk_add_f32 v[192:193], v[170:171], v[180:181] neg_lo:[0,1] neg_hi:[0,1]
	v_pk_add_f32 v[188:189], v[180:181], v[184:185] neg_lo:[0,1] neg_hi:[0,1]
	v_pk_add_f32 v[194:195], v[170:171], v[192:193] neg_lo:[0,1] neg_hi:[0,1]
	v_mov_b32_e32 v170, v181
	v_mov_b32_e32 v184, v185
	v_mov_b32_e32 v185, v193
	v_pk_add_f32 v[194:195], v[194:195], v[180:181] neg_lo:[0,1] neg_hi:[0,1]
	v_pk_add_f32 v[170:171], v[170:171], v[184:185] neg_lo:[0,1] neg_hi:[0,1]
	v_mov_b32_e32 v180, v175
	v_pk_add_f32 v[170:171], v[170:171], v[180:181] neg_lo:[0,1] neg_hi:[0,1]
	v_pk_add_f32 v[188:189], v[188:189], v[174:175] neg_lo:[0,1] neg_hi:[0,1]
	v_mov_b32_e32 v195, v171
	v_pk_add_f32 v[150:151], v[150:151], v[194:195]
	v_mov_b32_e32 v189, v170
	v_pk_add_f32 v[150:151], v[188:189], v[150:151]
	v_pk_add_f32 v[170:171], v[196:197], v[186:187] neg_lo:[0,1] neg_hi:[0,1]
	v_pk_add_f32 v[150:151], v[192:193], v[150:151]
	v_pk_add_f32 v[170:171], v[178:179], v[170:171] neg_lo:[0,1] neg_hi:[0,1]
	v_pk_mul_f32 v[150:151], v[182:183], v[150:151]
	v_pk_mul_f32 v[182:183], v[176:177], s[34:35] op_sel_hi:[1,0]
	v_pk_add_f32 v[150:151], v[170:171], v[150:151]
	v_pk_fma_f32 v[184:185], v[176:177], s[34:35], v[182:183] op_sel_hi:[1,0,1] neg_lo:[0,0,1] neg_hi:[0,0,1]
	v_pk_add_f32 v[174:175], v[196:197], v[150:151]
	v_pk_fma_f32 v[184:185], v[176:177], s[36:37], v[184:185] op_sel_hi:[1,0,1]
	v_pk_add_f32 v[170:171], v[174:175], v[196:197] neg_lo:[0,1] neg_hi:[0,1]
	v_pk_mul_f32 v[178:179], v[174:175], v[174:175]
	v_pk_add_f32 v[170:171], v[150:151], v[170:171] neg_lo:[0,1] neg_hi:[0,1]
	v_mov_b64_e32 v[150:151], s[14:15]
	v_pk_fma_f32 v[180:181], v[178:179], s[28:29], v[150:151] op_sel_hi:[1,0,0]
	v_ldexp_f32 v172, v174, 1
	v_pk_fma_f32 v[180:181], v[178:179], v[180:181], s[30:31] op_sel_hi:[1,1,0]
	v_ldexp_f32 v173, v175, 1
	v_pk_mul_f32 v[174:175], v[174:175], v[178:179]
	v_ldexp_f32 v170, v170, 1
	v_pk_mul_f32 v[174:175], v[174:175], v[180:181]
	v_ldexp_f32 v171, v171, 1
	v_pk_add_f32 v[178:179], v[172:173], v[174:175]
	v_pk_add_f32 v[176:177], v[182:183], v[184:185]
	v_pk_add_f32 v[172:173], v[178:179], v[172:173] neg_lo:[0,1] neg_hi:[0,1]
	v_pk_add_f32 v[182:183], v[176:177], v[182:183] neg_lo:[0,1] neg_hi:[0,1]
	v_pk_add_f32 v[172:173], v[174:175], v[172:173] neg_lo:[0,1] neg_hi:[0,1]
	v_pk_add_f32 v[182:183], v[184:185], v[182:183] neg_lo:[0,1] neg_hi:[0,1]
	v_pk_add_f32 v[170:171], v[170:171], v[172:173]
	v_add_f32_e32 v138, v139, v43
	v_pk_add_f32 v[190:191], v[178:179], v[170:171]
	v_mul_f32_e32 v138, 0xbfb8aa3b, v138
	v_pk_add_f32 v[172:173], v[190:191], v[178:179] neg_lo:[0,1] neg_hi:[0,1]
	v_exp_f32_e32 v138, v138
	v_pk_add_f32 v[170:171], v[170:171], v[172:173] neg_lo:[0,1] neg_hi:[0,1]
	v_add_f32_e32 v142, 1.0, v142
	v_pk_add_f32 v[184:185], v[182:183], v[170:171]
	v_add_f32_e32 v138, 1.0, v138
	v_pk_add_f32 v[172:173], v[184:185], v[182:183] neg_lo:[0,1] neg_hi:[0,1]
	v_rcp_f32_e32 v250, v138
	v_pk_add_f32 v[188:189], v[170:171], v[172:173] neg_lo:[0,1] neg_hi:[0,1]
	v_max_f32_e32 v170, v152, v152
	v_mul_f32_e64 v152, |v152|, s5
	v_exp_f32_e32 v236, v152
	v_pk_add_f32 v[174:175], v[184:185], v[172:173] neg_lo:[0,1] neg_hi:[0,1]
	v_min_f32_e32 v180, 0, v170
	v_pk_add_f32 v[186:187], v[182:183], v[174:175] neg_lo:[0,1] neg_hi:[0,1]
	v_add_f32_e32 v172, 1.0, v236
	v_add_f32_e32 v152, -1.0, v172
	v_sub_f32_e32 v170, v152, v172
	v_add_f32_e32 v170, 1.0, v170
	v_sub_f32_e32 v152, v236, v152
	v_add_f32_e32 v173, v152, v170
	v_max_f32_e32 v152, v153, v153
	v_min_f32_e32 v181, 0, v152
	v_mul_f32_e64 v152, |v153|, s5
	v_exp_f32_e32 v238, v152
	v_cvt_f64_f32_e32 v[170:171], v172
	v_frexp_exp_i32_f64_e32 v170, v[170:171]
	v_frexp_mant_f32_e32 v174, v172
	v_add_f32_e32 v171, 1.0, v238
	v_add_f32_e32 v152, -1.0, v171
	v_sub_f32_e32 v153, v152, v171
	v_add_f32_e32 v153, 1.0, v153
	v_sub_f32_e32 v152, v238, v152
	v_add_f32_e32 v175, v152, v153
	v_frexp_mant_f32_e32 v178, v171
	v_cvt_f64_f32_e32 v[152:153], v171
	v_cmp_gt_f32_e32 vcc, s72, v174
	v_frexp_exp_i32_f64_e32 v152, v[152:153]
	v_cmp_gt_f32_e64 s[14:15], s72, v178
	v_subbrev_co_u32_e32 v207, vcc, 0, v170, vcc
	s_nop 0
	v_subbrev_co_u32_e64 v206, s[14:15], 0, v152, s[14:15]
	v_sub_u32_e32 v153, 0, v207
	v_ldexp_f32 v152, v172, v153
	v_sub_u32_e32 v172, 0, v206
	v_ldexp_f32 v170, v173, v153
	v_ldexp_f32 v153, v171, v172
	v_ldexp_f32 v171, v175, v172
	v_pk_add_f32 v[172:173], v[152:153], 1.0 op_sel_hi:[1,0]
	v_pk_add_f32 v[192:193], v[152:153], -1.0 op_sel_hi:[1,0]
	v_pk_add_f32 v[174:175], v[172:173], -1.0 op_sel_hi:[1,0]
	v_pk_add_f32 v[194:195], v[192:193], 1.0 op_sel_hi:[1,0]
	v_pk_add_f32 v[174:175], v[152:153], v[174:175] neg_lo:[0,1] neg_hi:[0,1]
	v_pk_add_f32 v[152:153], v[152:153], v[194:195] neg_lo:[0,1] neg_hi:[0,1]
	v_pk_add_f32 v[174:175], v[170:171], v[174:175]
	v_pk_add_f32 v[152:153], v[170:171], v[152:153]
	v_pk_add_f32 v[178:179], v[172:173], v[174:175]
	v_pk_add_f32 v[170:171], v[192:193], v[152:153]
	v_rcp_f32_e32 v182, v178
	v_rcp_f32_e32 v183, v179
	v_pk_add_f32 v[172:173], v[178:179], v[172:173] neg_lo:[0,1] neg_hi:[0,1]
	v_pk_add_f32 v[192:193], v[170:171], v[192:193] neg_lo:[0,1] neg_hi:[0,1]
	v_pk_add_f32 v[172:173], v[174:175], v[172:173] neg_lo:[0,1] neg_hi:[0,1]
	v_pk_mul_f32 v[194:195], v[170:171], v[182:183]
	v_pk_add_f32 v[152:153], v[152:153], v[192:193] neg_lo:[0,1] neg_hi:[0,1]
	v_pk_mul_f32 v[174:175], v[178:179], v[194:195]
	v_add_f32_e32 v138, v144, v48
	v_pk_fma_f32 v[192:193], v[194:195], v[178:179], v[174:175] neg_lo:[0,0,1] neg_hi:[0,0,1]
	v_mul_f32_e32 v138, 0xbfb8aa3b, v138
	v_pk_fma_f32 v[192:193], v[194:195], v[172:173], v[192:193]
	v_exp_f32_e32 v138, v138
	v_pk_add_f32 v[196:197], v[174:175], v[192:193]
	v_rcp_f32_e32 v142, v142
	v_pk_add_f32 v[198:199], v[170:171], v[196:197] neg_lo:[0,1] neg_hi:[0,1]
	v_pk_add_f32 v[174:175], v[196:197], v[174:175] neg_lo:[0,1] neg_hi:[0,1]
	v_pk_add_f32 v[170:171], v[170:171], v[198:199] neg_lo:[0,1] neg_hi:[0,1]
	v_add_f32_e32 v138, 1.0, v138
	v_pk_add_f32 v[170:171], v[170:171], v[196:197] neg_lo:[0,1] neg_hi:[0,1]
	v_min_f32_e32 v168, 0, v168
	v_pk_add_f32 v[152:153], v[152:153], v[170:171]
	v_pk_add_f32 v[170:171], v[174:175], v[192:193] neg_lo:[0,1] neg_hi:[0,1]
	v_add_f32_e32 v130, v130, v26
	v_pk_add_f32 v[152:153], v[170:171], v[152:153]
	v_mul_f32_e32 v130, 0xbfb8aa3b, v130
	v_pk_add_f32 v[170:171], v[198:199], v[152:153]
	v_exp_f32_e32 v130, v130
	v_pk_mul_f32 v[174:175], v[182:183], v[170:171]
	v_pk_add_f32 v[198:199], v[198:199], v[170:171] neg_lo:[0,1] neg_hi:[0,1]
	v_pk_mul_f32 v[192:193], v[178:179], v[174:175]
	v_pk_add_f32 v[152:153], v[152:153], v[198:199]
	v_pk_fma_f32 v[178:179], v[174:175], v[178:179], v[192:193] neg_lo:[0,0,1] neg_hi:[0,0,1]
	v_pk_add_f32 v[204:205], v[194:195], v[174:175]
	v_pk_fma_f32 v[172:173], v[174:175], v[172:173], v[178:179]
	v_add_f32_e32 v130, 1.0, v130
	v_pk_add_f32 v[178:179], v[192:193], v[172:173]
	v_mul_f32_e32 v134, 0xbfb8aa3b, v134
	v_pk_add_f32 v[200:201], v[170:171], v[178:179] neg_lo:[0,1] neg_hi:[0,1]
	v_pk_add_f32 v[196:197], v[178:179], v[192:193] neg_lo:[0,1] neg_hi:[0,1]
	v_pk_add_f32 v[202:203], v[170:171], v[200:201] neg_lo:[0,1] neg_hi:[0,1]
	v_mov_b32_e32 v170, v179
	v_mov_b32_e32 v192, v193
	v_mov_b32_e32 v193, v201
	v_pk_add_f32 v[202:203], v[202:203], v[178:179] neg_lo:[0,1] neg_hi:[0,1]
	v_pk_add_f32 v[170:171], v[170:171], v[192:193] neg_lo:[0,1] neg_hi:[0,1]
	v_mov_b32_e32 v178, v173
	v_pk_add_f32 v[170:171], v[170:171], v[178:179] neg_lo:[0,1] neg_hi:[0,1]
	v_pk_add_f32 v[196:197], v[196:197], v[172:173] neg_lo:[0,1] neg_hi:[0,1]
	v_mov_b32_e32 v203, v171
	v_pk_add_f32 v[152:153], v[152:153], v[202:203]
	v_mov_b32_e32 v197, v170
	v_pk_add_f32 v[152:153], v[196:197], v[152:153]
	v_pk_add_f32 v[170:171], v[204:205], v[194:195] neg_lo:[0,1] neg_hi:[0,1]
	v_pk_add_f32 v[152:153], v[200:201], v[152:153]
	v_pk_add_f32 v[170:171], v[174:175], v[170:171] neg_lo:[0,1] neg_hi:[0,1]
	v_pk_mul_f32 v[152:153], v[182:183], v[152:153]
	v_cvt_f32_i32_e32 v183, v206
	v_pk_add_f32 v[152:153], v[170:171], v[152:153]
	v_cvt_f32_i32_e32 v182, v207
	v_pk_add_f32 v[170:171], v[204:205], v[152:153]
	v_exp_f32_e32 v134, v134
	v_pk_mul_f32 v[174:175], v[170:171], v[170:171]
	v_pk_add_f32 v[172:173], v[170:171], v[204:205] neg_lo:[0,1] neg_hi:[0,1]
	v_pk_fma_f32 v[178:179], v[174:175], s[28:29], v[150:151] op_sel_hi:[1,0,0]
	v_pk_add_f32 v[152:153], v[152:153], v[172:173] neg_lo:[0,1] neg_hi:[0,1]
	v_ldexp_f32 v172, v170, 1
	v_pk_fma_f32 v[178:179], v[174:175], v[178:179], s[30:31] op_sel_hi:[1,1,0]
	v_ldexp_f32 v173, v171, 1
	v_pk_mul_f32 v[170:171], v[170:171], v[174:175]
	v_pk_mul_f32 v[192:193], v[182:183], s[34:35] op_sel_hi:[1,0]
	v_pk_mul_f32 v[170:171], v[170:171], v[178:179]
	v_ldexp_f32 v152, v152, 1
	v_pk_add_f32 v[174:175], v[172:173], v[170:171]
	v_pk_fma_f32 v[194:195], v[182:183], s[34:35], v[192:193] op_sel_hi:[1,0,1] neg_lo:[0,0,1] neg_hi:[0,0,1]
	v_pk_add_f32 v[172:173], v[174:175], v[172:173] neg_lo:[0,1] neg_hi:[0,1]
	v_ldexp_f32 v153, v153, 1
	v_pk_add_f32 v[170:171], v[170:171], v[172:173] neg_lo:[0,1] neg_hi:[0,1]
	v_pk_fma_f32 v[182:183], v[182:183], s[36:37], v[194:195] op_sel_hi:[1,0,1]
	v_pk_add_f32 v[152:153], v[152:153], v[170:171]
	v_pk_add_f32 v[202:203], v[192:193], v[182:183]
	v_pk_add_f32 v[210:211], v[174:175], v[152:153]
	v_pk_add_f32 v[192:193], v[202:203], v[192:193] neg_lo:[0,1] neg_hi:[0,1]
	v_pk_add_f32 v[170:171], v[210:211], v[174:175] neg_lo:[0,1] neg_hi:[0,1]
	v_pk_add_f32 v[182:183], v[182:183], v[192:193] neg_lo:[0,1] neg_hi:[0,1]
	v_pk_add_f32 v[152:153], v[152:153], v[170:171] neg_lo:[0,1] neg_hi:[0,1]
	v_add_f32_e32 v134, 1.0, v134
	v_pk_add_f32 v[204:205], v[182:183], v[152:153]
	v_rcp_f32_e32 v134, v134
	v_pk_add_f32 v[170:171], v[204:205], v[182:183] neg_lo:[0,1] neg_hi:[0,1]
	v_add_f32_e32 v126, v126, v46
	v_pk_add_f32 v[208:209], v[152:153], v[170:171] neg_lo:[0,1] neg_hi:[0,1]
	v_max_f32_e32 v152, v146, v146
	v_mul_f32_e64 v146, |v146|, s5
	v_exp_f32_e32 v235, v146
	v_pk_add_f32 v[172:173], v[204:205], v[170:171] neg_lo:[0,1] neg_hi:[0,1]
	v_min_f32_e32 v178, 0, v152
	v_pk_add_f32 v[206:207], v[182:183], v[172:173] neg_lo:[0,1] neg_hi:[0,1]
	v_add_f32_e32 v170, 1.0, v235
	v_add_f32_e32 v146, -1.0, v170
	v_sub_f32_e32 v152, v146, v170
	v_add_f32_e32 v152, 1.0, v152
	v_sub_f32_e32 v146, v235, v146
	v_add_f32_e32 v171, v146, v152
	v_max_f32_e32 v146, v147, v147
	v_min_f32_e32 v179, 0, v146
	v_mul_f32_e64 v146, |v147|, s5
	v_exp_f32_e32 v237, v146
	v_cvt_f64_f32_e32 v[152:153], v170
	v_frexp_exp_i32_f64_e32 v152, v[152:153]
	v_frexp_mant_f32_e32 v172, v170
	v_add_f32_e32 v153, 1.0, v237
	v_add_f32_e32 v146, -1.0, v153
	v_sub_f32_e32 v147, v146, v153
	v_add_f32_e32 v147, 1.0, v147
	v_sub_f32_e32 v146, v237, v146
	v_add_f32_e32 v173, v146, v147
	v_frexp_mant_f32_e32 v174, v153
	v_cvt_f64_f32_e32 v[146:147], v153
	v_cmp_gt_f32_e32 vcc, s72, v172
	v_frexp_exp_i32_f64_e32 v146, v[146:147]
	v_cmp_gt_f32_e64 s[14:15], s72, v174
	v_subbrev_co_u32_e32 v217, vcc, 0, v152, vcc
	s_nop 0
	v_subbrev_co_u32_e64 v216, s[14:15], 0, v146, s[14:15]
	v_sub_u32_e32 v147, 0, v217
	v_ldexp_f32 v146, v170, v147
	v_sub_u32_e32 v170, 0, v216
	v_ldexp_f32 v152, v171, v147
	v_ldexp_f32 v147, v153, v170
	v_ldexp_f32 v153, v173, v170
	v_pk_add_f32 v[170:171], v[146:147], 1.0 op_sel_hi:[1,0]
	v_pk_add_f32 v[192:193], v[146:147], -1.0 op_sel_hi:[1,0]
	v_pk_add_f32 v[172:173], v[170:171], -1.0 op_sel_hi:[1,0]
	v_pk_add_f32 v[194:195], v[192:193], 1.0 op_sel_hi:[1,0]
	v_pk_add_f32 v[172:173], v[146:147], v[172:173] neg_lo:[0,1] neg_hi:[0,1]
	v_pk_add_f32 v[146:147], v[146:147], v[194:195] neg_lo:[0,1] neg_hi:[0,1]
	v_pk_add_f32 v[172:173], v[152:153], v[172:173]
	v_pk_add_f32 v[146:147], v[152:153], v[146:147]
	v_pk_add_f32 v[174:175], v[170:171], v[172:173]
	v_pk_add_f32 v[152:153], v[192:193], v[146:147]
	v_rcp_f32_e32 v182, v174
	v_rcp_f32_e32 v183, v175
	v_pk_add_f32 v[170:171], v[174:175], v[170:171] neg_lo:[0,1] neg_hi:[0,1]
	v_pk_add_f32 v[192:193], v[152:153], v[192:193] neg_lo:[0,1] neg_hi:[0,1]
	v_pk_add_f32 v[170:171], v[172:173], v[170:171] neg_lo:[0,1] neg_hi:[0,1]
	v_pk_mul_f32 v[194:195], v[152:153], v[182:183]
	v_pk_add_f32 v[146:147], v[146:147], v[192:193] neg_lo:[0,1] neg_hi:[0,1]
	v_pk_mul_f32 v[172:173], v[174:175], v[194:195]
	v_mul_f32_e32 v126, 0xbfb8aa3b, v126
	v_pk_fma_f32 v[192:193], v[194:195], v[174:175], v[172:173] neg_lo:[0,0,1] neg_hi:[0,0,1]
	v_exp_f32_e32 v126, v126
	v_pk_fma_f32 v[192:193], v[194:195], v[170:171], v[192:193]
	v_add_f32_e32 v122, v122, v42
	v_pk_add_f32 v[196:197], v[172:173], v[192:193]
	v_add_f32_e32 v126, 1.0, v126
	v_pk_add_f32 v[198:199], v[152:153], v[196:197] neg_lo:[0,1] neg_hi:[0,1]
	v_pk_add_f32 v[172:173], v[196:197], v[172:173] neg_lo:[0,1] neg_hi:[0,1]
	v_pk_add_f32 v[152:153], v[152:153], v[198:199] neg_lo:[0,1] neg_hi:[0,1]
	v_rcp_f32_e32 v126, v126
	v_pk_add_f32 v[152:153], v[152:153], v[196:197] neg_lo:[0,1] neg_hi:[0,1]
	v_mul_f32_e32 v122, 0xbfb8aa3b, v122
	v_pk_add_f32 v[146:147], v[146:147], v[152:153]
	v_pk_add_f32 v[152:153], v[172:173], v[192:193] neg_lo:[0,1] neg_hi:[0,1]
	v_exp_f32_e32 v122, v122
	v_pk_add_f32 v[146:147], v[152:153], v[146:147]
	v_add_f32_e32 v123, v123, v43
	v_pk_add_f32 v[152:153], v[198:199], v[146:147]
	v_add_f32_e32 v122, 1.0, v122
	v_pk_mul_f32 v[172:173], v[182:183], v[152:153]
	v_pk_add_f32 v[198:199], v[198:199], v[152:153] neg_lo:[0,1] neg_hi:[0,1]
	v_pk_mul_f32 v[192:193], v[174:175], v[172:173]
	v_pk_add_f32 v[146:147], v[146:147], v[198:199]
	v_pk_fma_f32 v[174:175], v[172:173], v[174:175], v[192:193] neg_lo:[0,0,1] neg_hi:[0,0,1]
	v_pk_add_f32 v[214:215], v[194:195], v[172:173]
	v_pk_fma_f32 v[170:171], v[172:173], v[170:171], v[174:175]
	v_rcp_f32_e32 v122, v122
	v_pk_add_f32 v[174:175], v[192:193], v[170:171]
	v_mul_f32_e32 v123, 0xbfb8aa3b, v123
	v_pk_add_f32 v[200:201], v[152:153], v[174:175] neg_lo:[0,1] neg_hi:[0,1]
	v_pk_add_f32 v[196:197], v[174:175], v[192:193] neg_lo:[0,1] neg_hi:[0,1]
	v_pk_add_f32 v[212:213], v[152:153], v[200:201] neg_lo:[0,1] neg_hi:[0,1]
	v_mov_b32_e32 v152, v175
	v_mov_b32_e32 v192, v193
	v_mov_b32_e32 v193, v201
	v_pk_add_f32 v[212:213], v[212:213], v[174:175] neg_lo:[0,1] neg_hi:[0,1]
	v_pk_add_f32 v[152:153], v[152:153], v[192:193] neg_lo:[0,1] neg_hi:[0,1]
	v_mov_b32_e32 v174, v171
	v_pk_add_f32 v[152:153], v[152:153], v[174:175] neg_lo:[0,1] neg_hi:[0,1]
	v_pk_add_f32 v[196:197], v[196:197], v[170:171] neg_lo:[0,1] neg_hi:[0,1]
	v_mov_b32_e32 v213, v153
	v_pk_add_f32 v[146:147], v[146:147], v[212:213]
	v_mov_b32_e32 v197, v152
	v_pk_add_f32 v[146:147], v[196:197], v[146:147]
	v_pk_add_f32 v[152:153], v[214:215], v[194:195] neg_lo:[0,1] neg_hi:[0,1]
	v_pk_add_f32 v[146:147], v[200:201], v[146:147]
	v_pk_add_f32 v[152:153], v[172:173], v[152:153] neg_lo:[0,1] neg_hi:[0,1]
	v_pk_mul_f32 v[146:147], v[182:183], v[146:147]
	v_cvt_f32_i32_e32 v183, v216
	v_pk_add_f32 v[146:147], v[152:153], v[146:147]
	v_cvt_f32_i32_e32 v182, v217
	v_pk_add_f32 v[152:153], v[214:215], v[146:147]
	v_exp_f32_e32 v123, v123
	v_pk_mul_f32 v[172:173], v[152:153], v[152:153]
	v_pk_add_f32 v[170:171], v[152:153], v[214:215] neg_lo:[0,1] neg_hi:[0,1]
	v_pk_fma_f32 v[174:175], v[172:173], s[28:29], v[150:151] op_sel_hi:[1,0,0]
	v_pk_add_f32 v[146:147], v[146:147], v[170:171] neg_lo:[0,1] neg_hi:[0,1]
	v_ldexp_f32 v170, v152, 1
	v_pk_fma_f32 v[174:175], v[172:173], v[174:175], s[30:31] op_sel_hi:[1,1,0]
	v_ldexp_f32 v171, v153, 1
	v_pk_mul_f32 v[152:153], v[152:153], v[172:173]
	v_pk_mul_f32 v[194:195], v[182:183], s[34:35] op_sel_hi:[1,0]
	v_pk_mul_f32 v[152:153], v[152:153], v[174:175]
	v_ldexp_f32 v146, v146, 1
	v_pk_add_f32 v[172:173], v[170:171], v[152:153]
	v_pk_fma_f32 v[192:193], v[182:183], s[34:35], v[194:195] op_sel_hi:[1,0,1] neg_lo:[0,0,1] neg_hi:[0,0,1]
	v_pk_add_f32 v[170:171], v[172:173], v[170:171] neg_lo:[0,1] neg_hi:[0,1]
	v_ldexp_f32 v147, v147, 1
	v_pk_add_f32 v[152:153], v[152:153], v[170:171] neg_lo:[0,1] neg_hi:[0,1]
	v_pk_fma_f32 v[182:183], v[182:183], s[36:37], v[192:193] op_sel_hi:[1,0,1]
	v_pk_add_f32 v[146:147], v[146:147], v[152:153]
	v_pk_add_f32 v[192:193], v[194:195], v[182:183]
	v_pk_add_f32 v[200:201], v[172:173], v[146:147]
	v_pk_add_f32 v[194:195], v[192:193], v[194:195] neg_lo:[0,1] neg_hi:[0,1]
	v_pk_add_f32 v[152:153], v[200:201], v[172:173] neg_lo:[0,1] neg_hi:[0,1]
	v_pk_add_f32 v[182:183], v[182:183], v[194:195] neg_lo:[0,1] neg_hi:[0,1]
	v_pk_add_f32 v[146:147], v[146:147], v[152:153] neg_lo:[0,1] neg_hi:[0,1]
	v_add_f32_e32 v123, 1.0, v123
	v_pk_add_f32 v[194:195], v[182:183], v[146:147]
	v_rcp_f32_e32 v123, v123
	v_pk_add_f32 v[152:153], v[194:195], v[182:183] neg_lo:[0,1] neg_hi:[0,1]
	v_add_f32_e32 v124, v124, v44
	v_pk_add_f32 v[170:171], v[194:195], v[152:153] neg_lo:[0,1] neg_hi:[0,1]
	v_pk_add_f32 v[198:199], v[146:147], v[152:153] neg_lo:[0,1] neg_hi:[0,1]
	v_max_f32_e32 v146, v148, v148
	v_pk_add_f32 v[196:197], v[182:183], v[170:171] neg_lo:[0,1] neg_hi:[0,1]
	v_min_f32_e32 v182, 0, v146
	v_mul_f32_e64 v146, |v148|, s5
	v_exp_f32_e32 v239, v146
	v_mul_f32_e32 v124, 0xbfb8aa3b, v124
	v_exp_f32_e32 v124, v124
	v_add_f32_e32 v118, v118, v30
	v_add_f32_e32 v148, 1.0, v239
	v_add_f32_e32 v146, -1.0, v148
	v_sub_f32_e32 v147, v146, v148
	v_add_f32_e32 v147, 1.0, v147
	v_sub_f32_e32 v146, v239, v146
	v_add_f32_e32 v152, v146, v147
	v_cvt_f64_f32_e32 v[146:147], v148
	v_frexp_exp_i32_f64_e32 v170, v[146:147]
	v_max_f32_e32 v146, v149, v149
	v_min_f32_e32 v183, 0, v146
	v_mul_f32_e64 v146, |v149|, s5
	v_exp_f32_e32 v240, v146
	v_frexp_mant_f32_e32 v153, v148
	v_cmp_gt_f32_e32 vcc, s72, v153
	v_add_f32_e32 v124, 1.0, v124
	v_add_f32_e32 v149, 1.0, v240
	v_add_f32_e32 v146, -1.0, v149
	v_sub_f32_e32 v147, v146, v149
	v_add_f32_e32 v147, 1.0, v147
	v_sub_f32_e32 v146, v240, v146
	v_add_f32_e32 v171, v146, v147
	v_frexp_mant_f32_e32 v172, v149
	v_cvt_f64_f32_e32 v[146:147], v149
	v_frexp_exp_i32_f64_e32 v146, v[146:147]
	v_cmp_gt_f32_e64 s[14:15], s72, v172
	v_subbrev_co_u32_e32 v241, vcc, 0, v170, vcc
	s_nop 0
	v_subbrev_co_u32_e64 v234, s[14:15], 0, v146, s[14:15]
	v_sub_u32_e32 v147, 0, v241
	v_ldexp_f32 v146, v148, v147
	v_ldexp_f32 v148, v152, v147
	v_sub_u32_e32 v152, 0, v234
	v_ldexp_f32 v147, v149, v152
	v_ldexp_f32 v149, v171, v152
	v_pk_add_f32 v[152:153], v[146:147], 1.0 op_sel_hi:[1,0]
	v_pk_add_f32 v[212:213], v[146:147], -1.0 op_sel_hi:[1,0]
	v_pk_add_f32 v[170:171], v[152:153], -1.0 op_sel_hi:[1,0]
	v_pk_add_f32 v[214:215], v[212:213], 1.0 op_sel_hi:[1,0]
	v_pk_add_f32 v[170:171], v[146:147], v[170:171] neg_lo:[0,1] neg_hi:[0,1]
	v_pk_add_f32 v[146:147], v[146:147], v[214:215] neg_lo:[0,1] neg_hi:[0,1]
	v_pk_add_f32 v[170:171], v[148:149], v[170:171]
	v_pk_add_f32 v[146:147], v[148:149], v[146:147]
	v_pk_add_f32 v[172:173], v[152:153], v[170:171]
	v_pk_add_f32 v[148:149], v[212:213], v[146:147]
	v_rcp_f32_e32 v174, v172
	v_rcp_f32_e32 v175, v173
	v_pk_add_f32 v[152:153], v[172:173], v[152:153] neg_lo:[0,1] neg_hi:[0,1]
	v_pk_add_f32 v[212:213], v[148:149], v[212:213] neg_lo:[0,1] neg_hi:[0,1]
	v_pk_add_f32 v[152:153], v[170:171], v[152:153] neg_lo:[0,1] neg_hi:[0,1]
	v_pk_mul_f32 v[214:215], v[148:149], v[174:175]
	v_pk_add_f32 v[146:147], v[146:147], v[212:213] neg_lo:[0,1] neg_hi:[0,1]
	v_pk_mul_f32 v[170:171], v[172:173], v[214:215]
	v_cmp_lt_f32_e64 s[14:15], |v233|, s77
	v_pk_fma_f32 v[212:213], v[214:215], v[172:173], v[170:171] neg_lo:[0,0,1] neg_hi:[0,0,1]
	v_rcp_f32_e32 v124, v124
	v_pk_fma_f32 v[212:213], v[214:215], v[152:153], v[212:213]
	v_add_f32_e32 v125, v125, v45
	v_pk_add_f32 v[216:217], v[170:171], v[212:213]
	v_mul_f32_e32 v118, 0xbfb8aa3b, v118
	v_pk_add_f32 v[218:219], v[148:149], v[216:217] neg_lo:[0,1] neg_hi:[0,1]
	v_pk_add_f32 v[170:171], v[216:217], v[170:171] neg_lo:[0,1] neg_hi:[0,1]
	v_pk_add_f32 v[148:149], v[148:149], v[218:219] neg_lo:[0,1] neg_hi:[0,1]
	v_mul_f32_e32 v125, 0xbfb8aa3b, v125
	v_pk_add_f32 v[148:149], v[148:149], v[216:217] neg_lo:[0,1] neg_hi:[0,1]
	v_exp_f32_e32 v118, v118
	v_pk_add_f32 v[146:147], v[146:147], v[148:149]
	v_pk_add_f32 v[148:149], v[170:171], v[212:213] neg_lo:[0,1] neg_hi:[0,1]
	v_exp_f32_e32 v125, v125
	v_pk_add_f32 v[146:147], v[148:149], v[146:147]
	v_add_f32_e32 v118, 1.0, v118
	v_pk_add_f32 v[148:149], v[218:219], v[146:147]
	v_add_f32_e32 v125, 1.0, v125
	v_pk_mul_f32 v[170:171], v[174:175], v[148:149]
	v_pk_add_f32 v[218:219], v[218:219], v[148:149] neg_lo:[0,1] neg_hi:[0,1]
	v_pk_mul_f32 v[212:213], v[172:173], v[170:171]
	v_pk_add_f32 v[146:147], v[146:147], v[218:219]
	v_pk_fma_f32 v[172:173], v[170:171], v[172:173], v[212:213] neg_lo:[0,0,1] neg_hi:[0,0,1]
	v_pk_add_f32 v[244:245], v[214:215], v[170:171]
	v_pk_fma_f32 v[152:153], v[170:171], v[152:153], v[172:173]
	v_rcp_f32_e32 v118, v118
	v_pk_add_f32 v[172:173], v[212:213], v[152:153]
	v_rcp_f32_e32 v125, v125
	v_pk_add_f32 v[220:221], v[148:149], v[172:173] neg_lo:[0,1] neg_hi:[0,1]
	v_pk_add_f32 v[216:217], v[172:173], v[212:213] neg_lo:[0,1] neg_hi:[0,1]
	v_pk_add_f32 v[242:243], v[148:149], v[220:221] neg_lo:[0,1] neg_hi:[0,1]
	v_mov_b32_e32 v148, v173
	v_mov_b32_e32 v212, v213
	v_mov_b32_e32 v213, v221
	v_pk_add_f32 v[242:243], v[242:243], v[172:173] neg_lo:[0,1] neg_hi:[0,1]
	v_pk_add_f32 v[148:149], v[148:149], v[212:213] neg_lo:[0,1] neg_hi:[0,1]
	v_mov_b32_e32 v172, v153
	v_pk_add_f32 v[148:149], v[148:149], v[172:173] neg_lo:[0,1] neg_hi:[0,1]
	v_pk_add_f32 v[216:217], v[216:217], v[152:153] neg_lo:[0,1] neg_hi:[0,1]
	v_mov_b32_e32 v243, v149
	v_pk_add_f32 v[146:147], v[146:147], v[242:243]
	v_mov_b32_e32 v217, v148
	v_pk_add_f32 v[146:147], v[216:217], v[146:147]
	v_pk_add_f32 v[148:149], v[244:245], v[214:215] neg_lo:[0,1] neg_hi:[0,1]
	v_pk_add_f32 v[146:147], v[220:221], v[146:147]
	v_pk_add_f32 v[148:149], v[170:171], v[148:149] neg_lo:[0,1] neg_hi:[0,1]
	v_pk_mul_f32 v[146:147], v[174:175], v[146:147]
	v_cvt_f32_i32_e32 v173, v234
	v_pk_add_f32 v[146:147], v[148:149], v[146:147]
	v_cvt_f32_i32_e32 v172, v241
	v_pk_add_f32 v[148:149], v[244:245], v[146:147]
	v_add_u32_e32 v234, s0, v167
	v_pk_mul_f32 v[170:171], v[148:149], v[148:149]
	v_pk_add_f32 v[152:153], v[148:149], v[244:245] neg_lo:[0,1] neg_hi:[0,1]
	v_pk_fma_f32 v[150:151], v[170:171], s[28:29], v[150:151] op_sel_hi:[1,0,0]
	v_pk_add_f32 v[146:147], v[146:147], v[152:153] neg_lo:[0,1] neg_hi:[0,1]
	v_ldexp_f32 v152, v148, 1
	v_pk_fma_f32 v[150:151], v[170:171], v[150:151], s[30:31] op_sel_hi:[1,1,0]
	v_ldexp_f32 v153, v149, 1
	v_pk_mul_f32 v[148:149], v[148:149], v[170:171]
	v_pk_mul_f32 v[174:175], v[172:173], s[34:35] op_sel_hi:[1,0]
	v_pk_mul_f32 v[148:149], v[148:149], v[150:151]
	v_ldexp_f32 v146, v146, 1
	v_pk_add_f32 v[150:151], v[152:153], v[148:149]
	v_pk_fma_f32 v[212:213], v[172:173], s[34:35], v[174:175] op_sel_hi:[1,0,1] neg_lo:[0,0,1] neg_hi:[0,0,1]
	v_pk_add_f32 v[152:153], v[150:151], v[152:153] neg_lo:[0,1] neg_hi:[0,1]
	v_ldexp_f32 v147, v147, 1
	v_pk_add_f32 v[148:149], v[148:149], v[152:153] neg_lo:[0,1] neg_hi:[0,1]
	v_pk_fma_f32 v[172:173], v[172:173], s[36:37], v[212:213] op_sel_hi:[1,0,1]
	v_pk_add_f32 v[146:147], v[146:147], v[148:149]
	v_pk_add_f32 v[212:213], v[174:175], v[172:173]
	v_pk_add_f32 v[220:221], v[150:151], v[146:147]
	v_pk_add_f32 v[174:175], v[212:213], v[174:175] neg_lo:[0,1] neg_hi:[0,1]
	v_pk_add_f32 v[148:149], v[220:221], v[150:151] neg_lo:[0,1] neg_hi:[0,1]
	v_pk_add_f32 v[172:173], v[172:173], v[174:175] neg_lo:[0,1] neg_hi:[0,1]
	v_pk_add_f32 v[146:147], v[146:147], v[148:149] neg_lo:[0,1] neg_hi:[0,1]
	v_ashrrev_i32_e32 v167, 31, v166
	v_pk_add_f32 v[214:215], v[172:173], v[146:147]
	v_mov_b32_e32 v242, v190
	v_pk_add_f32 v[148:149], v[214:215], v[172:173] neg_lo:[0,1] neg_hi:[0,1]
	v_mov_b32_e32 v243, v176
	v_pk_add_f32 v[218:219], v[146:147], v[148:149] neg_lo:[0,1] neg_hi:[0,1]
	v_mov_b32_e32 v146, v234
	v_pk_add_f32 v[150:151], v[214:215], v[148:149] neg_lo:[0,1] neg_hi:[0,1]
	v_ashrrev_i32_e32 v147, 31, v146
	v_lshlrev_b64 v[146:147], 10, v[146:147]
	v_lshl_add_u64 v[146:147], v[146:147], 0, v[166:167]
	v_lshlrev_b64 v[148:149], 1, v[146:147]
	v_lshl_add_u64 v[174:175], s[24:25], 0, v[148:149]
	v_pk_add_f32 v[216:217], v[172:173], v[150:151] neg_lo:[0,1] neg_hi:[0,1]
	global_load_dwordx4 v[150:153], v[174:175], off
	v_lshl_add_u64 v[170:171], s[50:51], 0, v[146:147]
	v_add_co_u32_e32 v146, vcc, s84, v174
	v_lshl_add_u64 v[172:173], s[48:49], 0, v[148:149]
	s_nop 0
	v_addc_co_u32_e32 v147, vcc, 0, v175, vcc
	global_load_dwordx4 v[146:149], v[146:147], off
	v_cmp_neq_f32_e32 vcc, s73, v232
	v_add_f32_e32 v114, v114, v26
	v_add_f32_e32 v119, v119, v31
	v_mul_f32_e32 v114, 0xbfb8aa3b, v114
	v_mul_f32_e32 v119, 0xbfb8aa3b, v119
	v_exp_f32_e32 v114, v114
	v_exp_f32_e32 v119, v119
	v_add_f32_e32 v120, v120, v32
	v_add_f32_e32 v115, v115, v27
	v_add_f32_e32 v114, 1.0, v114
	v_add_f32_e32 v119, 1.0, v119
	v_rcp_f32_e32 v114, v114
	v_rcp_f32_e32 v119, v119
	v_mul_f32_e32 v120, 0xbfb8aa3b, v120
	v_mul_f32_e32 v115, 0xbfb8aa3b, v115
	v_exp_f32_e32 v120, v120
	v_exp_f32_e32 v115, v115
	v_add_f32_e32 v121, v121, v33
	v_add_f32_e32 v116, v116, v28
	v_add_f32_e32 v120, 1.0, v120
	v_add_f32_e32 v115, 1.0, v115
	v_rcp_f32_e32 v120, v120
	v_rcp_f32_e32 v115, v115
	v_mul_f32_e32 v121, 0xbfb8aa3b, v121
	v_mul_f32_e32 v116, 0xbfb8aa3b, v116
	v_exp_f32_e32 v121, v121
	v_exp_f32_e32 v116, v116
	v_add_f32_e32 v117, v117, v29
	v_mul_f32_e32 v117, 0xbfb8aa3b, v117
	v_add_f32_e32 v121, 1.0, v121
	v_add_f32_e32 v116, 1.0, v116
	v_rcp_f32_e32 v121, v121
	v_rcp_f32_e32 v116, v116
	v_exp_f32_e32 v117, v117
	s_waitcnt vmcnt(0) lgkmcnt(0)
	v_lshlrev_b32_e32 v241, 16, v150
	v_and_b32_e32 v246, 0xffff0000, v150
	v_rcp_f32_e32 v150, v138
	v_add_f32_e32 v138, v140, v44
	v_mul_f32_e32 v138, 0xbfb8aa3b, v138
	v_exp_f32_e32 v138, v138
	v_lshlrev_b32_e32 v247, 16, v151
	v_and_b32_e32 v248, 0xffff0000, v151
	v_add_f32_e32 v117, 1.0, v117
	v_add_f32_e32 v138, 1.0, v138
	v_rcp_f32_e32 v251, v138
	v_add_f32_e32 v138, v145, v49
	v_mul_f32_e32 v138, 0xbfb8aa3b, v138
	v_exp_f32_e32 v138, v138
	v_rcp_f32_e32 v117, v117
	v_add_f32_e32 v138, 1.0, v138
	v_rcp_f32_e32 v151, v138
	v_add_f32_e32 v138, v141, v45
	v_mul_f32_e32 v138, 0xbfb8aa3b, v138
	v_exp_f32_e32 v138, v138
	s_nop 0
	v_add_f32_e32 v138, 1.0, v138
	v_rcp_f32_e32 v252, v138
	v_pk_add_f32 v[138:139], v[176:177], v[190:191]
	s_nop 0
	v_pk_add_f32 v[140:141], v[138:139], v[176:177] neg_lo:[0,1] neg_hi:[0,1]
	v_mov_b32_e32 v176, v191
	v_pk_add_f32 v[144:145], v[138:139], v[140:141] neg_lo:[0,1] neg_hi:[0,1]
	v_mov_b32_e32 v244, v140
	v_mov_b32_e32 v245, v144
	v_mov_b32_e32 v144, v141
	v_pk_add_f32 v[242:243], v[242:243], v[244:245] neg_lo:[0,1] neg_hi:[0,1]
	v_pk_add_f32 v[140:141], v[176:177], v[144:145] neg_lo:[0,1] neg_hi:[0,1]
	v_pk_add_f32 v[242:243], v[242:243], v[242:243] op_sel:[0,1] op_sel_hi:[1,0]
	v_pk_add_f32 v[140:141], v[140:141], v[140:141] op_sel_hi:[0,1]
	v_mov_b32_e32 v243, v185
	v_mov_b32_e32 v185, v141
	v_pk_add_f32 v[140:141], v[242:243], v[184:185]
	v_pk_add_f32 v[176:177], v[188:189], v[186:187]
	v_pk_add_f32 v[144:145], v[138:139], v[140:141]
	s_nop 0
	v_pk_add_f32 v[138:139], v[144:145], v[138:139] neg_lo:[0,1] neg_hi:[0,1]
	s_nop 0
	v_pk_add_f32 v[138:139], v[140:141], v[138:139] neg_lo:[0,1] neg_hi:[0,1]
	s_nop 0
	v_pk_add_f32 v[138:139], v[176:177], v[138:139]
	v_mov_b32_e32 v176, v210
	v_pk_add_f32 v[138:139], v[144:145], v[138:139]
	v_mov_b32_e32 v177, v202
	v_cndmask_b32_e32 v138, v228, v138, vcc
	v_cmp_neq_f32_e32 vcc, s73, v233
	s_nop 1
	v_cndmask_b32_e32 v139, v228, v139, vcc
	v_cmp_ngt_f32_e32 vcc, -1.0, v233
	s_nop 1
	v_cndmask_b32_e32 v139, v229, v139, vcc
	v_cmp_ngt_f32_e32 vcc, -1.0, v232
	s_nop 1
	v_cndmask_b32_e32 v138, v229, v138, vcc
	v_cmp_neq_f32_e32 vcc, -1.0, v232
	s_nop 1
	v_cndmask_b32_e32 v138, v230, v138, vcc
	v_cmp_neq_f32_e32 vcc, -1.0, v233
	s_nop 1
	v_cndmask_b32_e32 v139, v230, v139, vcc
	v_cmp_lt_f32_e64 vcc, |v232|, s77
	v_cndmask_b32_e64 v139, v139, v233, s[14:15]
	v_cmp_lt_f32_e64 s[14:15], |v238|, s77
	v_cndmask_b32_e32 v138, v138, v232, vcc
	v_pk_add_f32 v[138:139], v[168:169], v[138:139] neg_lo:[0,1] neg_hi:[0,1]
	v_cmp_neq_f32_e32 vcc, s73, v236
	v_pk_mul_f32 v[144:145], v[138:139], s[38:39] op_sel_hi:[1,0]
	s_nop 0
	v_pk_mul_f32 v[138:139], v[142:143], v[144:145]
	v_mul_f32_e32 v126, v126, v144
	v_add_f32_e32 v140, v138, v138
	v_mul_f32_e32 v140, 0x3fb8aa3b, v140
	v_exp_f32_e32 v140, v140
	v_cvt_pk_bf16_f32 v138, v138, v139
	v_sub_f32_e32 v140, 1.0, v140
	v_max_f32_e32 v140, 0, v140
	v_sqrt_f32_e32 v140, v140
	s_nop 0
	v_mul_f32_e32 v140, v249, v140
	v_mul_f32_e32 v186, v140, v241
	v_add_f32_e32 v140, v139, v139
	v_mul_f32_e32 v140, 0x3fb8aa3b, v140
	v_exp_f32_e32 v140, v140
	s_nop 0
	v_sub_f32_e32 v140, 1.0, v140
	v_max_f32_e32 v140, 0, v140
	v_sqrt_f32_e32 v140, v140
	s_nop 0
	v_mul_f32_e32 v140, v250, v140
	v_mul_f32_e32 v187, v140, v246
	v_pk_add_f32 v[140:141], v[202:203], v[210:211]
	s_nop 0
	v_pk_add_f32 v[142:143], v[140:141], v[202:203] neg_lo:[0,1] neg_hi:[0,1]
	v_mov_b32_e32 v202, v211
	v_pk_add_f32 v[168:169], v[140:141], v[142:143] neg_lo:[0,1] neg_hi:[0,1]
	v_mov_b32_e32 v184, v142
	v_mov_b32_e32 v185, v168
	v_mov_b32_e32 v168, v143
	v_pk_add_f32 v[176:177], v[176:177], v[184:185] neg_lo:[0,1] neg_hi:[0,1]
	v_pk_add_f32 v[142:143], v[202:203], v[168:169] neg_lo:[0,1] neg_hi:[0,1]
	v_pk_add_f32 v[176:177], v[176:177], v[176:177] op_sel:[0,1] op_sel_hi:[1,0]
	v_pk_add_f32 v[142:143], v[142:143], v[142:143] op_sel_hi:[0,1]
	v_mov_b32_e32 v177, v205
	v_mov_b32_e32 v205, v143
	v_pk_add_f32 v[142:143], v[176:177], v[204:205]
	v_pk_add_f32 v[176:177], v[208:209], v[206:207]
	v_pk_add_f32 v[168:169], v[140:141], v[142:143]
	s_nop 0
	v_pk_add_f32 v[140:141], v[168:169], v[140:141] neg_lo:[0,1] neg_hi:[0,1]
	s_nop 0
	v_pk_add_f32 v[140:141], v[142:143], v[140:141] neg_lo:[0,1] neg_hi:[0,1]
	s_nop 0
	v_pk_add_f32 v[140:141], v[176:177], v[140:141]
	v_rcp_f32_e32 v177, v130
	v_add_f32_e32 v130, v135, v31
	v_pk_add_f32 v[140:141], v[168:169], v[140:141]
	v_mul_f32_e32 v130, 0xbfb8aa3b, v130
	v_cndmask_b32_e32 v139, v228, v140, vcc
	v_cmp_neq_f32_e32 vcc, s73, v238
	v_exp_f32_e32 v130, v130
	v_and_b32_e32 v176, 0xffff0000, v152
	v_cndmask_b32_e32 v140, v228, v141, vcc
	v_cmp_ngt_f32_e32 vcc, -1.0, v238
	v_add_f32_e32 v130, 1.0, v130
	v_rcp_f32_e32 v135, v130
	v_cndmask_b32_e32 v140, v229, v140, vcc
	v_cmp_ngt_f32_e32 vcc, -1.0, v236
	v_add_f32_e32 v130, v131, v27
	v_mul_f32_e32 v130, 0xbfb8aa3b, v130
	v_cndmask_b32_e32 v139, v229, v139, vcc
	v_cmp_neq_f32_e32 vcc, -1.0, v236
	v_exp_f32_e32 v130, v130
	s_nop 0
	v_cndmask_b32_e32 v139, v230, v139, vcc
	v_cmp_neq_f32_e32 vcc, -1.0, v238
	v_add_f32_e32 v130, 1.0, v130
	v_rcp_f32_e32 v184, v130
	v_cndmask_b32_e32 v140, v230, v140, vcc
	v_cmp_lt_f32_e64 vcc, |v236|, s77
	v_cndmask_b32_e64 v141, v140, v238, s[14:15]
	v_add_f32_e32 v130, v136, v32
	v_cndmask_b32_e32 v140, v139, v236, vcc
	v_pk_add_f32 v[140:141], v[180:181], v[140:141] neg_lo:[0,1] neg_hi:[0,1]
	v_mul_f32_e32 v130, 0xbfb8aa3b, v130
	v_pk_mul_f32 v[142:143], v[140:141], s[38:39] op_sel_hi:[1,0]
	v_exp_f32_e32 v130, v130
	v_pk_mul_f32 v[140:141], v[150:151], v[142:143]
	v_lshlrev_b32_e32 v180, 16, v153
	v_add_f32_e32 v139, v140, v140
	v_mul_f32_e32 v139, 0x3fb8aa3b, v139
	v_exp_f32_e32 v139, v139
	v_add_f32_e32 v130, 1.0, v130
	v_rcp_f32_e32 v136, v130
	v_add_f32_e32 v130, v132, v28
	v_sub_f32_e32 v139, 1.0, v139
	v_max_f32_e32 v139, 0, v139
	v_sqrt_f32_e32 v139, v139
	v_mul_f32_e32 v130, 0xbfb8aa3b, v130
	v_exp_f32_e32 v130, v130
	v_and_b32_e32 v181, 0xffff0000, v153
	v_mul_f32_e32 v139, v251, v139
	v_mul_f32_e32 v150, v139, v247
	v_add_f32_e32 v139, v141, v141
	v_mul_f32_e32 v139, 0x3fb8aa3b, v139
	v_exp_f32_e32 v139, v139
	v_add_f32_e32 v130, 1.0, v130
	v_rcp_f32_e32 v185, v130
	v_add_f32_e32 v130, v137, v33
	v_mul_f32_e32 v130, 0xbfb8aa3b, v130
	v_exp_f32_e32 v130, v130
	v_sub_f32_e32 v139, 1.0, v139
	v_max_f32_e32 v139, 0, v139
	v_sqrt_f32_e32 v139, v139
	v_add_f32_e32 v130, 1.0, v130
	v_rcp_f32_e32 v137, v130
	v_add_f32_e32 v130, v133, v29
	v_mul_f32_e32 v130, 0xbfb8aa3b, v130
	v_mul_f32_e32 v139, v252, v139
	v_exp_f32_e32 v130, v130
	v_mul_f32_e32 v151, v139, v248
	v_cvt_pk_bf16_f32 v139, v140, v141
	v_mul_f32_e32 v140, 0x42000000, v186
	v_mul_f32_e32 v141, 0x42000000, v187
	v_mul_f32_e32 v168, 0x42000000, v150
	v_med3_f32 v140, v140, s29, v231
	v_med3_f32 v141, v141, s29, v231
	v_cvt_pk_fp8_f32 v150, v140, v141
	v_add_f32_e32 v130, 1.0, v130
	v_mul_f32_e32 v151, 0x42000000, v151
	v_rcp_f32_e32 v186, v130
	v_pk_add_f32 v[130:131], v[192:193], v[200:201]
	v_med3_f32 v140, v168, s29, v231
	v_med3_f32 v141, v151, s29, v231
	v_pk_add_f32 v[132:133], v[130:131], v[192:193] neg_lo:[0,1] neg_hi:[0,1]
	v_cvt_pk_fp8_f32 v150, v140, v141 op_sel:[0,0,1]
	v_pk_add_f32 v[140:141], v[130:131], v[132:133] neg_lo:[0,1] neg_hi:[0,1]
	v_lshlrev_b32_e32 v151, 16, v152
	v_mov_b32_e32 v152, v200
	v_mov_b32_e32 v153, v192
	v_mov_b32_e32 v168, v132
	v_mov_b32_e32 v169, v140
	v_mov_b32_e32 v192, v201
	v_mov_b32_e32 v140, v133
	v_pk_add_f32 v[152:153], v[152:153], v[168:169] neg_lo:[0,1] neg_hi:[0,1]
	v_pk_add_f32 v[132:133], v[192:193], v[140:141] neg_lo:[0,1] neg_hi:[0,1]
	v_pk_add_f32 v[152:153], v[152:153], v[152:153] op_sel:[0,1] op_sel_hi:[1,0]
	v_pk_add_f32 v[132:133], v[132:133], v[132:133] op_sel_hi:[0,1]
	v_mov_b32_e32 v153, v195
	v_mov_b32_e32 v195, v133
	v_pk_add_f32 v[132:133], v[152:153], v[194:195]
	v_pk_add_f32 v[152:153], v[198:199], v[196:197]
	v_pk_add_f32 v[140:141], v[130:131], v[132:133]
	v_cmp_neq_f32_e32 vcc, s73, v235
	v_pk_add_f32 v[130:131], v[140:141], v[130:131] neg_lo:[0,1] neg_hi:[0,1]
	v_cmp_lt_f32_e64 s[14:15], |v237|, s77
	v_pk_add_f32 v[130:131], v[132:133], v[130:131] neg_lo:[0,1] neg_hi:[0,1]
	v_mov_b32_e32 v168, v220
	v_pk_add_f32 v[130:131], v[152:153], v[130:131]
	v_mov_b32_e32 v169, v212
	v_pk_add_f32 v[130:131], v[140:141], v[130:131]
	s_nop 0
	v_cndmask_b32_e32 v130, v228, v130, vcc
	v_cmp_neq_f32_e32 vcc, s73, v237
	s_nop 1
	v_cndmask_b32_e32 v131, v228, v131, vcc
	v_cmp_ngt_f32_e32 vcc, -1.0, v237
	s_nop 1
	v_cndmask_b32_e32 v131, v229, v131, vcc
	v_cmp_ngt_f32_e32 vcc, -1.0, v235
	s_nop 1
	v_cndmask_b32_e32 v130, v229, v130, vcc
	v_cmp_neq_f32_e32 vcc, -1.0, v235
	s_nop 1
	v_cndmask_b32_e32 v130, v230, v130, vcc
	v_cmp_neq_f32_e32 vcc, -1.0, v237
	s_nop 1
	v_cndmask_b32_e32 v131, v230, v131, vcc
	v_cmp_lt_f32_e64 vcc, |v235|, s77
	v_cndmask_b32_e64 v131, v131, v237, s[14:15]
	v_cmp_lt_f32_e64 s[14:15], |v240|, s77
	v_cndmask_b32_e32 v130, v130, v235, vcc
	v_pk_add_f32 v[130:131], v[178:179], v[130:131] neg_lo:[0,1] neg_hi:[0,1]
	v_cmp_neq_f32_e32 vcc, s73, v239
	v_pk_mul_f32 v[130:131], v[130:131], s[38:39] op_sel_hi:[1,0]
	s_nop 0
	v_pk_mul_f32 v[132:133], v[134:135], v[130:131]
	v_mul_f32_e32 v118, v118, v130
	v_add_f32_e32 v134, v132, v132
	v_mul_f32_e32 v134, 0x3fb8aa3b, v134
	v_exp_f32_e32 v134, v134
	v_cvt_pk_bf16_f32 v140, v132, v133
	v_mul_f32_e32 v119, v119, v131
	v_sub_f32_e32 v134, 1.0, v134
	v_max_f32_e32 v134, 0, v134
	v_sqrt_f32_e32 v134, v134
	s_nop 0
	v_mul_f32_e32 v134, v177, v134
	v_mul_f32_e32 v151, v134, v151
	v_add_f32_e32 v134, v133, v133
	v_mul_f32_e32 v134, 0x3fb8aa3b, v134
	v_exp_f32_e32 v134, v134
	v_pk_add_f32 v[132:133], v[212:213], v[220:221]
	v_sub_f32_e32 v134, 1.0, v134
	v_max_f32_e32 v134, 0, v134
	v_sqrt_f32_e32 v134, v134
	s_nop 0
	v_mul_f32_e32 v134, v184, v134
	v_mul_f32_e32 v178, v134, v176
	v_pk_add_f32 v[134:135], v[132:133], v[212:213] neg_lo:[0,1] neg_hi:[0,1]
	v_mov_b32_e32 v212, v221
	v_pk_add_f32 v[152:153], v[132:133], v[134:135] neg_lo:[0,1] neg_hi:[0,1]
	v_mov_b32_e32 v176, v134
	v_mov_b32_e32 v177, v152
	v_mov_b32_e32 v152, v135
	v_pk_add_f32 v[168:169], v[168:169], v[176:177] neg_lo:[0,1] neg_hi:[0,1]
	v_pk_add_f32 v[134:135], v[212:213], v[152:153] neg_lo:[0,1] neg_hi:[0,1]
	v_pk_add_f32 v[168:169], v[168:169], v[168:169] op_sel:[0,1] op_sel_hi:[1,0]
	v_pk_add_f32 v[134:135], v[134:135], v[134:135] op_sel_hi:[0,1]
	v_mov_b32_e32 v169, v215
	v_mov_b32_e32 v215, v135
	v_pk_add_f32 v[134:135], v[168:169], v[214:215]
	v_pk_add_f32 v[168:169], v[218:219], v[216:217]
	v_pk_add_f32 v[152:153], v[132:133], v[134:135]
	s_nop 0
	v_pk_add_f32 v[132:133], v[152:153], v[132:133] neg_lo:[0,1] neg_hi:[0,1]
	s_nop 0
	v_pk_add_f32 v[132:133], v[134:135], v[132:133] neg_lo:[0,1] neg_hi:[0,1]
	s_nop 0
	v_pk_add_f32 v[132:133], v[168:169], v[132:133]
	s_nop 0
	v_pk_add_f32 v[132:133], v[152:153], v[132:133]
	s_nop 0
	v_cndmask_b32_e32 v132, v228, v132, vcc
	v_cmp_neq_f32_e32 vcc, s73, v240
	s_nop 1
	v_cndmask_b32_e32 v133, v228, v133, vcc
	v_cmp_ngt_f32_e32 vcc, -1.0, v240
	s_nop 1
	v_cndmask_b32_e32 v133, v229, v133, vcc
	v_cmp_ngt_f32_e32 vcc, -1.0, v239
	s_nop 1
	v_cndmask_b32_e32 v132, v229, v132, vcc
	v_cmp_neq_f32_e32 vcc, -1.0, v239
	s_nop 1
	v_cndmask_b32_e32 v132, v230, v132, vcc
	v_cmp_neq_f32_e32 vcc, -1.0, v240
	s_nop 1
	v_cndmask_b32_e32 v133, v230, v133, vcc
	v_cmp_lt_f32_e64 vcc, |v239|, s77
	v_cndmask_b32_e64 v133, v133, v240, s[14:15]
	s_nop 0
	v_cndmask_b32_e32 v132, v132, v239, vcc
	v_pk_add_f32 v[132:133], v[182:183], v[132:133] neg_lo:[0,1] neg_hi:[0,1]
	s_nop 0
	v_pk_mul_f32 v[132:133], v[132:133], s[38:39] op_sel_hi:[1,0]
	s_nop 0
	v_pk_mul_f32 v[134:135], v[136:137], v[132:133]
	v_mul_f32_e32 v120, v120, v132
	v_add_f32_e32 v136, v134, v134
	v_add_f32_e32 v137, v135, v135
	v_mul_f32_e32 v136, 0x3fb8aa3b, v136
	v_mul_f32_e32 v137, 0x3fb8aa3b, v137
	v_exp_f32_e32 v136, v136
	v_exp_f32_e32 v137, v137
	v_cvt_pk_bf16_f32 v141, v134, v135
	v_mul_f32_e32 v134, 0x42000000, v151
	v_sub_f32_e32 v136, 1.0, v136
	v_sub_f32_e32 v137, 1.0, v137
	v_max_f32_e32 v136, 0, v136
	v_max_f32_e32 v137, 0, v137
	v_sqrt_f32_e32 v136, v136
	v_sqrt_f32_e32 v137, v137
	v_mul_f32_e32 v135, 0x42000000, v178
	v_med3_f32 v134, v134, s29, v231
	v_med3_f32 v135, v135, s29, v231
	v_mul_f32_e32 v136, v185, v136
	v_mul_f32_e32 v137, v186, v137
	v_cvt_pk_fp8_f32 v151, v134, v135
	v_mul_f32_e32 v136, v136, v180
	v_mul_f32_e32 v137, v137, v181
	v_mul_f32_e32 v136, 0x42000000, v136
	v_mul_f32_e32 v137, 0x42000000, v137
	v_med3_f32 v134, v136, s29, v231
	v_med3_f32 v135, v137, s29, v231
	v_cvt_pk_fp8_f32 v151, v134, v135 op_sel:[0,0,1]
	global_store_dwordx4 v[172:173], v[138:141], off
	global_store_dwordx2 v[170:171], v[150:151], off
	s_nop 0
	v_add_f32_e32 v138, v126, v126
	v_mul_f32_e32 v138, 0x3fb8aa3b, v138
	v_exp_f32_e32 v138, v138
	v_lshlrev_b32_e32 v134, 16, v146
	v_and_b32_e32 v135, 0xffff0000, v146
	v_lshlrev_b32_e32 v136, 16, v147
	v_sub_f32_e32 v138, 1.0, v138
	v_max_f32_e32 v138, 0, v138
	v_sqrt_f32_e32 v138, v138
	v_and_b32_e32 v137, 0xffff0000, v147
	v_mul_f32_e32 v121, v121, v133
	v_mul_f32_e32 v122, v122, v138
	v_mul_f32_e32 v134, v122, v134
	v_add_f32_e32 v122, v127, v47
	v_mul_f32_e32 v122, 0xbfb8aa3b, v122
	v_exp_f32_e32 v122, v122
	s_nop 0
	v_add_f32_e32 v122, 1.0, v122
	v_rcp_f32_e32 v122, v122
	s_nop 0
	v_mul_f32_e32 v122, v122, v145
	v_add_f32_e32 v127, v122, v122
	v_mul_f32_e32 v127, 0x3fb8aa3b, v127
	v_exp_f32_e32 v127, v127
	v_cvt_pk_bf16_f32 v122, v126, v122
	v_mul_f32_e32 v126, 0x42000000, v134
	v_sub_f32_e32 v127, 1.0, v127
	v_max_f32_e32 v127, 0, v127
	v_sqrt_f32_e32 v127, v127
	s_nop 0
	v_mul_f32_e32 v123, v123, v127
	v_mul_f32_e32 v127, v123, v135
	v_add_f32_e32 v123, v128, v48
	v_mul_f32_e32 v123, 0xbfb8aa3b, v123
	v_exp_f32_e32 v123, v123
	v_mul_f32_e32 v127, 0x42000000, v127
	v_med3_f32 v127, v127, s29, v231
	v_add_f32_e32 v123, 1.0, v123
	v_rcp_f32_e32 v123, v123
	s_nop 0
	v_mul_f32_e32 v123, v123, v142
	v_add_f32_e32 v128, v123, v123
	v_mul_f32_e32 v128, 0x3fb8aa3b, v128
	v_exp_f32_e32 v128, v128
	s_nop 0
	v_sub_f32_e32 v128, 1.0, v128
	v_max_f32_e32 v128, 0, v128
	v_sqrt_f32_e32 v128, v128
	s_nop 0
	v_mul_f32_e32 v124, v124, v128
	v_add_f32_e32 v128, v129, v49
	v_mul_f32_e32 v128, 0xbfb8aa3b, v128
	v_exp_f32_e32 v128, v128
	v_mul_f32_e32 v124, v124, v136
	v_mul_f32_e32 v124, 0x42000000, v124
	v_med3_f32 v124, v124, s29, v231
	v_add_f32_e32 v128, 1.0, v128
	v_rcp_f32_e32 v128, v128
	s_nop 0
	v_mul_f32_e32 v128, v128, v143
	v_add_f32_e32 v129, v128, v128
	v_mul_f32_e32 v129, 0x3fb8aa3b, v129
	v_exp_f32_e32 v129, v129
	v_cvt_pk_bf16_f32 v123, v123, v128
	v_med3_f32 v128, v126, s29, v231
	v_sub_f32_e32 v129, 1.0, v129
	v_max_f32_e32 v129, 0, v129
	v_sqrt_f32_e32 v129, v129
	v_cvt_pk_fp8_f32 v126, v128, v127
	v_lshlrev_b32_e32 v127, 16, v149
	v_and_b32_e32 v128, 0xffff0000, v149
	v_mul_f32_e32 v125, v125, v129
	v_add_f32_e32 v129, v118, v118
	v_mul_f32_e32 v129, 0x3fb8aa3b, v129
	v_exp_f32_e32 v129, v129
	v_mul_f32_e32 v125, v125, v137
	v_mul_f32_e32 v125, 0x42000000, v125
	v_med3_f32 v125, v125, s29, v231
	v_sub_f32_e32 v129, 1.0, v129
	v_max_f32_e32 v129, 0, v129
	v_sqrt_f32_e32 v129, v129
	v_cvt_pk_fp8_f32 v126, v124, v125 op_sel:[0,0,1]
	v_lshlrev_b32_e32 v124, 16, v148
	v_and_b32_e32 v125, 0xffff0000, v148
	v_mul_f32_e32 v114, v114, v129
	v_mul_f32_e32 v114, v114, v124
	v_add_f32_e32 v124, v119, v119
	v_mul_f32_e32 v124, 0x3fb8aa3b, v124
	v_exp_f32_e32 v124, v124
	v_mul_f32_e32 v114, 0x42000000, v114
	v_med3_f32 v114, v114, s29, v231
	v_sub_f32_e32 v124, 1.0, v124
	v_max_f32_e32 v124, 0, v124
	v_sqrt_f32_e32 v124, v124
	s_nop 0
	v_mul_f32_e32 v115, v115, v124
	v_add_f32_e32 v124, v120, v120
	v_mul_f32_e32 v124, 0x3fb8aa3b, v124
	v_exp_f32_e32 v124, v124
	v_mul_f32_e32 v115, v115, v125
	v_mul_f32_e32 v115, 0x42000000, v115
	v_med3_f32 v115, v115, s29, v231
	v_sub_f32_e32 v124, 1.0, v124
	v_max_f32_e32 v124, 0, v124
	v_sqrt_f32_e32 v124, v124
	v_cvt_pk_bf16_f32 v125, v120, v121
	v_mul_f32_e32 v116, v116, v124
	v_add_f32_e32 v124, v121, v121
	v_mul_f32_e32 v124, 0x3fb8aa3b, v124
	v_exp_f32_e32 v124, v124
	v_mul_f32_e32 v116, v116, v127
	v_cvt_pk_fp8_f32 v127, v114, v115
	v_sub_f32_e32 v124, 1.0, v124
	v_max_f32_e32 v124, 0, v124
	v_sqrt_f32_e32 v124, v124
	v_mul_f32_e32 v116, 0x42000000, v116
	v_med3_f32 v114, v116, s29, v231
	v_mul_f32_e32 v117, v117, v124
	v_mul_f32_e32 v117, v117, v128
	v_mul_f32_e32 v117, 0x42000000, v117
	v_med3_f32 v115, v117, s29, v231
	v_cvt_pk_fp8_f32 v127, v114, v115 op_sel:[0,0,1]
	v_add_co_u32_e32 v114, vcc, s84, v172
	v_cvt_pk_bf16_f32 v124, v118, v119
	s_nop 0
	v_addc_co_u32_e32 v115, vcc, 0, v173, vcc
	global_store_dwordx4 v[114:115], v[122:125], off
	v_add_co_u32_e32 v114, vcc, s93, v170
	s_nop 1
	v_addc_co_u32_e32 v115, vcc, 0, v171, vcc
	global_store_dwordx2 v[114:115], v[126:127], off
	v_add_co_u32_e32 v114, vcc, s92, v174
	v_add_f32_e32 v110, v110, v46
	s_nop 0
	v_addc_co_u32_e32 v115, vcc, 0, v175, vcc
	global_load_dwordx4 v[114:117], v[114:115], off
	v_mul_f32_e32 v110, 0xbfb8aa3b, v110
	v_add_f32_e32 v111, v111, v47
	v_exp_f32_e32 v110, v110
	v_mul_f32_e32 v111, 0xbfb8aa3b, v111
	v_exp_f32_e32 v111, v111
	v_add_f32_e32 v112, v112, v48
	v_add_f32_e32 v113, v113, v49
	v_add_f32_e32 v110, 1.0, v110
	v_mul_f32_e32 v112, 0xbfb8aa3b, v112
	v_mul_f32_e32 v113, 0xbfb8aa3b, v113
	v_rcp_f32_e32 v110, v110
	v_exp_f32_e32 v112, v112
	v_exp_f32_e32 v113, v113
	v_add_f32_e32 v111, 1.0, v111
	v_rcp_f32_e32 v111, v111
	v_add_co_u32_e32 v118, vcc, s89, v174
	v_add_f32_e32 v120, v106, v42
	s_nop 0
	v_addc_co_u32_e32 v119, vcc, 0, v175, vcc
	v_add_f32_e32 v122, v108, v44
	v_mul_f32_e32 v110, v110, v144
	v_add_f32_e32 v121, v107, v43
	v_add_f32_e32 v123, v109, v45
	global_load_dwordx4 v[106:109], v[118:119], off
	v_mul_f32_e32 v118, 0xbfb8aa3b, v120
	v_mul_f32_e32 v120, 0xbfb8aa3b, v122
	v_add_f32_e32 v112, 1.0, v112
	v_add_f32_e32 v113, 1.0, v113
	v_add_f32_e32 v122, v110, v110
	v_rcp_f32_e32 v112, v112
	v_rcp_f32_e32 v113, v113
	v_mul_f32_e32 v111, v111, v145
	v_mul_f32_e32 v122, 0x3fb8aa3b, v122
	v_mul_f32_e32 v119, 0xbfb8aa3b, v121
	v_mul_f32_e32 v121, 0xbfb8aa3b, v123
	v_add_f32_e32 v123, v111, v111
	v_exp_f32_e32 v122, v122
	v_exp_f32_e32 v118, v118
	v_mul_f32_e32 v123, 0x3fb8aa3b, v123
	v_exp_f32_e32 v123, v123
	v_exp_f32_e32 v119, v119
	v_mul_f32_e32 v112, v112, v142
	v_mul_f32_e32 v113, v113, v143
	v_add_f32_e32 v124, v112, v112
	v_add_f32_e32 v125, v113, v113
	v_sub_f32_e32 v122, 1.0, v122
	v_add_f32_e32 v118, 1.0, v118
	v_mul_f32_e32 v124, 0x3fb8aa3b, v124
	v_mul_f32_e32 v125, 0x3fb8aa3b, v125
	v_max_f32_e32 v122, 0, v122
	v_rcp_f32_e32 v118, v118
	v_exp_f32_e32 v124, v124
	v_exp_f32_e32 v125, v125
	v_sub_f32_e32 v123, 1.0, v123
	v_sqrt_f32_e32 v122, v122
	v_exp_f32_e32 v120, v120
	v_exp_f32_e32 v121, v121
	v_add_f32_e32 v119, 1.0, v119
	v_max_f32_e32 v123, 0, v123
	v_rcp_f32_e32 v119, v119
	v_sqrt_f32_e32 v123, v123
	v_add_f32_e32 v102, v102, v30
	v_mul_f32_e32 v102, 0xbfb8aa3b, v102
	v_sub_f32_e32 v124, 1.0, v124
	v_sub_f32_e32 v125, 1.0, v125
	v_mul_f32_e32 v118, v118, v122
	v_exp_f32_e32 v102, v102
	v_add_f32_e32 v120, 1.0, v120
	v_add_f32_e32 v121, 1.0, v121
	v_max_f32_e32 v124, 0, v124
	v_rcp_f32_e32 v120, v120
	v_rcp_f32_e32 v121, v121
	v_sqrt_f32_e32 v124, v124
	v_mul_f32_e32 v119, v119, v123
	v_cvt_pk_bf16_f32 v110, v110, v111
	v_cvt_pk_bf16_f32 v111, v112, v113
	v_add_f32_e32 v102, 1.0, v102
	v_rcp_f32_e32 v102, v102
	s_waitcnt vmcnt(0) lgkmcnt(0)
	v_lshlrev_b32_e32 v122, 16, v114
	v_mul_f32_e32 v118, v118, v122
	v_max_f32_e32 v122, 0, v125
	v_and_b32_e32 v114, 0xffff0000, v114
	v_sqrt_f32_e32 v122, v122
	v_mul_f32_e32 v114, v119, v114
	v_mul_f32_e32 v112, 0x42000000, v118
	v_mul_f32_e32 v113, 0x42000000, v114
	v_med3_f32 v112, v112, s29, v231
	v_med3_f32 v113, v113, s29, v231
	v_lshlrev_b32_e32 v123, 16, v115
	v_and_b32_e32 v115, 0xffff0000, v115
	v_mul_f32_e32 v119, v120, v124
	v_mul_f32_e32 v120, v121, v122
	v_cvt_pk_fp8_f32 v114, v112, v113
	v_mul_f32_e32 v119, v119, v123
	v_mul_f32_e32 v115, v120, v115
	v_mul_f32_e32 v118, 0x42000000, v119
	v_mul_f32_e32 v112, 0x42000000, v115
	v_med3_f32 v113, v118, s29, v231
	v_med3_f32 v112, v112, s29, v231
	v_mul_f32_e32 v102, v102, v130
	v_cvt_pk_fp8_f32 v114, v113, v112 op_sel:[0,0,1]
	v_lshlrev_b32_e32 v112, 16, v116
	v_and_b32_e32 v113, 0xffff0000, v116
	v_add_f32_e32 v116, v102, v102
	v_add_f32_e32 v103, v103, v31
	v_add_f32_e32 v98, v98, v26
	v_mul_f32_e32 v116, 0x3fb8aa3b, v116
	v_mul_f32_e32 v103, 0xbfb8aa3b, v103
	v_mul_f32_e32 v98, 0xbfb8aa3b, v98
	v_exp_f32_e32 v116, v116
	v_exp_f32_e32 v103, v103
	v_exp_f32_e32 v98, v98
	v_add_f32_e32 v104, v104, v32
	v_sub_f32_e32 v116, 1.0, v116
	v_add_f32_e32 v103, 1.0, v103
	v_add_f32_e32 v98, 1.0, v98
	v_max_f32_e32 v116, 0, v116
	v_rcp_f32_e32 v103, v103
	v_rcp_f32_e32 v98, v98
	v_sqrt_f32_e32 v116, v116
	v_add_f32_e32 v105, v105, v33
	v_mul_f32_e32 v103, v103, v131
	v_add_f32_e32 v99, v99, v27
	v_mul_f32_e32 v98, v98, v116
	v_add_f32_e32 v116, v103, v103
	v_mul_f32_e32 v116, 0x3fb8aa3b, v116
	v_mul_f32_e32 v104, 0xbfb8aa3b, v104
	v_mul_f32_e32 v105, 0xbfb8aa3b, v105
	v_mul_f32_e32 v99, 0xbfb8aa3b, v99
	v_exp_f32_e32 v116, v116
	v_exp_f32_e32 v104, v104
	v_exp_f32_e32 v105, v105
	v_exp_f32_e32 v99, v99
	v_sub_f32_e32 v116, 1.0, v116
	v_add_f32_e32 v104, 1.0, v104
	v_add_f32_e32 v105, 1.0, v105
	v_add_f32_e32 v99, 1.0, v99
	v_max_f32_e32 v116, 0, v116
	v_rcp_f32_e32 v104, v104
	v_rcp_f32_e32 v105, v105
	v_rcp_f32_e32 v99, v99
	v_sqrt_f32_e32 v116, v116
	v_mul_f32_e32 v104, v104, v132
	v_mul_f32_e32 v105, v105, v133
	v_mul_f32_e32 v98, v98, v112
	v_mul_f32_e32 v99, v99, v116
	v_add_f32_e32 v112, v104, v104
	v_add_f32_e32 v116, v105, v105
	v_add_f32_e32 v100, v100, v28
	v_mul_f32_e32 v112, 0x3fb8aa3b, v112
	v_add_f32_e32 v101, v101, v29
	v_mul_f32_e32 v116, 0x3fb8aa3b, v116
	v_mul_f32_e32 v100, 0xbfb8aa3b, v100
	v_exp_f32_e32 v112, v112
	v_mul_f32_e32 v101, 0xbfb8aa3b, v101
	v_exp_f32_e32 v116, v116
	v_add_f32_e32 v94, v94, v46
	v_exp_f32_e32 v100, v100
	v_exp_f32_e32 v101, v101
	v_mul_f32_e32 v94, 0xbfb8aa3b, v94
	v_exp_f32_e32 v94, v94
	v_sub_f32_e32 v112, 1.0, v112
	v_sub_f32_e32 v116, 1.0, v116
	v_add_f32_e32 v100, 1.0, v100
	v_max_f32_e32 v112, 0, v112
	v_add_f32_e32 v101, 1.0, v101
	v_max_f32_e32 v116, 0, v116
	v_rcp_f32_e32 v100, v100
	v_sqrt_f32_e32 v112, v112
	v_rcp_f32_e32 v101, v101
	v_sqrt_f32_e32 v116, v116
	v_add_f32_e32 v94, 1.0, v94
	v_rcp_f32_e32 v94, v94
	v_mul_f32_e32 v99, v99, v113
	v_lshlrev_b32_e32 v115, 16, v117
	v_and_b32_e32 v117, 0xffff0000, v117
	v_mul_f32_e32 v100, v100, v112
	v_mul_f32_e32 v101, v101, v116
	v_mul_f32_e32 v98, 0x42000000, v98
	v_mul_f32_e32 v99, 0x42000000, v99
	v_mul_f32_e32 v100, v100, v115
	v_mul_f32_e32 v101, v101, v117
	v_med3_f32 v98, v98, s29, v231
	v_med3_f32 v99, v99, s29, v231
	v_mul_f32_e32 v94, v94, v144
	v_cvt_pk_fp8_f32 v115, v98, v99
	v_mul_f32_e32 v98, 0x42000000, v101
	v_add_f32_e32 v101, v94, v94
	v_add_f32_e32 v95, v95, v47
	v_add_f32_e32 v90, v90, v42
	v_mul_f32_e32 v101, 0x3fb8aa3b, v101
	v_mul_f32_e32 v95, 0xbfb8aa3b, v95
	v_mul_f32_e32 v90, 0xbfb8aa3b, v90
	v_exp_f32_e32 v101, v101
	v_exp_f32_e32 v95, v95
	v_exp_f32_e32 v90, v90
	v_add_f32_e32 v91, v91, v43
	v_sub_f32_e32 v101, 1.0, v101
	v_add_f32_e32 v95, 1.0, v95
	v_add_f32_e32 v90, 1.0, v90
	v_max_f32_e32 v101, 0, v101
	v_rcp_f32_e32 v95, v95
	v_rcp_f32_e32 v90, v90
	v_sqrt_f32_e32 v101, v101
	v_add_f32_e32 v96, v96, v48
	v_mul_f32_e32 v95, v95, v145
	v_mul_f32_e32 v91, 0xbfb8aa3b, v91
	v_mul_f32_e32 v90, v90, v101
	v_add_f32_e32 v101, v95, v95
	v_mul_f32_e32 v101, 0x3fb8aa3b, v101
	v_exp_f32_e32 v101, v101
	v_mul_f32_e32 v96, 0xbfb8aa3b, v96
	v_add_f32_e32 v97, v97, v49
	v_exp_f32_e32 v91, v91
	v_exp_f32_e32 v96, v96
	v_mul_f32_e32 v97, 0xbfb8aa3b, v97
	v_exp_f32_e32 v97, v97
	v_mul_f32_e32 v100, 0x42000000, v100
	v_med3_f32 v99, v100, s29, v231
	v_med3_f32 v98, v98, s29, v231
	v_sub_f32_e32 v101, 1.0, v101
	v_add_f32_e32 v92, v92, v44
	v_cvt_pk_fp8_f32 v115, v99, v98 op_sel:[0,0,1]
	v_add_co_u32_e32 v98, vcc, s92, v172
	v_add_f32_e32 v91, 1.0, v91
	v_max_f32_e32 v101, 0, v101
	v_add_f32_e32 v96, 1.0, v96
	v_mul_f32_e32 v92, 0xbfb8aa3b, v92
	v_cvt_pk_bf16_f32 v112, v102, v103
	v_cvt_pk_bf16_f32 v113, v104, v105
	v_addc_co_u32_e32 v99, vcc, 0, v173, vcc
	v_rcp_f32_e32 v91, v91
	v_sqrt_f32_e32 v101, v101
	v_exp_f32_e32 v92, v92
	v_rcp_f32_e32 v96, v96
	v_add_f32_e32 v97, 1.0, v97
	global_store_dwordx4 v[98:99], v[110:113], off
	v_add_co_u32_e32 v98, vcc, s84, v170
	v_rcp_f32_e32 v97, v97
	s_nop 0
	v_addc_co_u32_e32 v99, vcc, 0, v171, vcc
	global_store_dwordx2 v[98:99], v[114:115], off
	v_lshlrev_b32_e32 v98, 16, v106
	v_mul_f32_e32 v98, v90, v98
	v_mul_f32_e32 v90, v91, v101
	v_add_f32_e32 v91, 1.0, v92
	v_mul_f32_e32 v92, v96, v142
	v_add_f32_e32 v96, v92, v92
	v_mul_f32_e32 v97, v97, v143
	v_mul_f32_e32 v96, 0x3fb8aa3b, v96
	v_add_f32_e32 v101, v97, v97
	v_exp_f32_e32 v96, v96
	v_add_f32_e32 v93, v93, v45
	v_mul_f32_e32 v101, 0x3fb8aa3b, v101
	v_mul_f32_e32 v93, 0xbfb8aa3b, v93
	v_exp_f32_e32 v101, v101
	v_exp_f32_e32 v93, v93
	v_add_f32_e32 v86, v86, v30
	v_mul_f32_e32 v86, 0xbfb8aa3b, v86
	v_sub_f32_e32 v96, 1.0, v96
	v_exp_f32_e32 v86, v86
	v_max_f32_e32 v96, 0, v96
	v_sub_f32_e32 v101, 1.0, v101
	v_rcp_f32_e32 v91, v91
	v_sqrt_f32_e32 v96, v96
	v_add_f32_e32 v93, 1.0, v93
	v_max_f32_e32 v101, 0, v101
	v_rcp_f32_e32 v93, v93
	v_sqrt_f32_e32 v101, v101
	v_add_f32_e32 v86, 1.0, v86
	v_and_b32_e32 v99, 0xffff0000, v106
	v_rcp_f32_e32 v86, v86
	v_lshlrev_b32_e32 v100, 16, v107
	v_mul_f32_e32 v99, v90, v99
	v_mul_f32_e32 v90, v91, v96
	v_and_b32_e32 v102, 0xffff0000, v107
	v_mul_f32_e32 v96, v90, v100
	v_mul_f32_e32 v90, v93, v101
	v_mul_f32_e32 v93, v90, v102
	v_cvt_pk_bf16_f32 v90, v94, v95
	v_cvt_pk_bf16_f32 v91, v92, v97
	v_mul_f32_e32 v92, 0x42000000, v98
	v_mul_f32_e32 v94, 0x42000000, v99
	v_mul_f32_e32 v95, 0x42000000, v96
	v_med3_f32 v92, v92, s29, v231
	v_med3_f32 v96, v94, s29, v231
	v_mul_f32_e32 v86, v86, v130
	v_cvt_pk_fp8_f32 v94, v92, v96
	v_add_f32_e32 v96, v86, v86
	v_add_f32_e32 v87, v87, v31
	v_add_f32_e32 v82, v82, v26
	v_mul_f32_e32 v96, 0x3fb8aa3b, v96
	v_mul_f32_e32 v87, 0xbfb8aa3b, v87
	v_mul_f32_e32 v82, 0xbfb8aa3b, v82
	v_exp_f32_e32 v96, v96
	v_exp_f32_e32 v87, v87
	v_exp_f32_e32 v82, v82
	v_add_f32_e32 v88, v88, v32
	v_sub_f32_e32 v96, 1.0, v96
	v_add_f32_e32 v87, 1.0, v87
	v_add_f32_e32 v82, 1.0, v82
	v_max_f32_e32 v96, 0, v96
	v_rcp_f32_e32 v87, v87
	v_rcp_f32_e32 v82, v82
	v_sqrt_f32_e32 v96, v96
	v_mul_f32_e32 v88, 0xbfb8aa3b, v88
	v_mul_f32_e32 v87, v87, v131
	v_exp_f32_e32 v88, v88
	v_mul_f32_e32 v82, v82, v96
	v_add_f32_e32 v96, v87, v87
	v_add_f32_e32 v89, v89, v33
	v_add_f32_e32 v83, v83, v27
	v_mul_f32_e32 v96, 0x3fb8aa3b, v96
	v_mul_f32_e32 v89, 0xbfb8aa3b, v89
	v_mul_f32_e32 v83, 0xbfb8aa3b, v83
	v_exp_f32_e32 v96, v96
	v_exp_f32_e32 v89, v89
	v_exp_f32_e32 v83, v83
	v_add_f32_e32 v88, 1.0, v88
	v_rcp_f32_e32 v88, v88
	v_sub_f32_e32 v96, 1.0, v96
	v_add_f32_e32 v89, 1.0, v89
	v_mul_f32_e32 v92, 0x42000000, v93
	v_add_f32_e32 v83, 1.0, v83
	v_max_f32_e32 v96, 0, v96
	v_rcp_f32_e32 v89, v89
	v_med3_f32 v93, v95, s29, v231
	v_med3_f32 v92, v92, s29, v231
	v_rcp_f32_e32 v83, v83
	v_sqrt_f32_e32 v96, v96
	v_cvt_pk_fp8_f32 v94, v93, v92 op_sel:[0,0,1]
	v_lshlrev_b32_e32 v92, 16, v108
	v_mul_f32_e32 v88, v88, v132
	v_mul_f32_e32 v82, v82, v92
	v_add_f32_e32 v92, v88, v88
	v_add_f32_e32 v84, v84, v28
	v_mul_f32_e32 v92, 0x3fb8aa3b, v92
	v_mul_f32_e32 v89, v89, v133
	v_mul_f32_e32 v84, 0xbfb8aa3b, v84
	v_mul_f32_e32 v83, v83, v96
	v_exp_f32_e32 v92, v92
	v_add_f32_e32 v96, v89, v89
	v_exp_f32_e32 v84, v84
	v_add_f32_e32 v85, v85, v29
	v_mul_f32_e32 v96, 0x3fb8aa3b, v96
	v_mul_f32_e32 v85, 0xbfb8aa3b, v85
	v_exp_f32_e32 v96, v96
	v_exp_f32_e32 v85, v85
	v_sub_f32_e32 v92, 1.0, v92
	v_add_f32_e32 v84, 1.0, v84
	v_max_f32_e32 v92, 0, v92
	v_rcp_f32_e32 v84, v84
	v_sqrt_f32_e32 v92, v92
	v_sub_f32_e32 v96, 1.0, v96
	v_add_f32_e32 v85, 1.0, v85
	v_max_f32_e32 v96, 0, v96
	v_and_b32_e32 v93, 0xffff0000, v108
	v_rcp_f32_e32 v85, v85
	v_sqrt_f32_e32 v96, v96
	v_mul_f32_e32 v83, v83, v93
	v_lshlrev_b32_e32 v95, 16, v109
	v_mul_f32_e32 v84, v84, v92
	v_mul_f32_e32 v82, 0x42000000, v82
	v_mul_f32_e32 v83, 0x42000000, v83
	v_mul_f32_e32 v84, v84, v95
	v_med3_f32 v82, v82, s29, v231
	v_med3_f32 v83, v83, s29, v231
	v_and_b32_e32 v97, 0xffff0000, v109
	v_mul_f32_e32 v85, v85, v96
	v_cvt_pk_fp8_f32 v95, v82, v83
	v_mul_f32_e32 v85, v85, v97
	v_mul_f32_e32 v84, 0x42000000, v84
	v_mul_f32_e32 v82, 0x42000000, v85
	v_med3_f32 v83, v84, s29, v231
	v_med3_f32 v82, v82, s29, v231
	v_cvt_pk_fp8_f32 v95, v83, v82 op_sel:[0,0,1]
	v_add_co_u32_e32 v82, vcc, s89, v172
	v_cvt_pk_bf16_f32 v92, v86, v87
	v_cvt_pk_bf16_f32 v93, v88, v89
	v_addc_co_u32_e32 v83, vcc, 0, v173, vcc
	s_mov_b32 s0, 0xc000
	global_store_dwordx4 v[82:83], v[90:93], off
	v_add_co_u32_e32 v82, vcc, s0, v170
	s_nop 1
	v_addc_co_u32_e32 v83, vcc, 0, v171, vcc
	global_store_dwordx2 v[82:83], v[94:95], off
	v_add_u32_e32 v82, 0x80, v234
	v_add_f32_e32 v78, v78, v46
	v_ashrrev_i32_e32 v83, 31, v82
	v_lshlrev_b64 v[82:83], 10, v[82:83]
	v_lshl_add_u64 v[88:89], v[82:83], 0, v[166:167]
	v_lshlrev_b64 v[90:91], 1, v[88:89]
	v_lshl_add_u64 v[82:83], s[24:25], 0, v[90:91]
	global_load_dwordx4 v[84:87], v[82:83], off
	v_mul_f32_e32 v78, 0xbfb8aa3b, v78
	v_exp_f32_e32 v92, v78
	v_add_f32_e32 v79, v79, v47
	v_add_f32_e32 v80, v80, v48
	v_mul_f32_e32 v79, 0xbfb8aa3b, v79
	v_add_f32_e32 v74, v74, v42
	v_add_f32_e32 v81, v81, v49
	v_mul_f32_e32 v80, 0xbfb8aa3b, v80
	v_exp_f32_e32 v93, v79
	v_add_f32_e32 v75, v75, v43
	v_add_f32_e32 v76, v76, v44
	v_add_f32_e32 v77, v77, v45
	v_mul_f32_e32 v74, 0xbfb8aa3b, v74
	v_mul_f32_e32 v81, 0xbfb8aa3b, v81
	v_exp_f32_e32 v94, v80
	v_lshl_add_u64 v[78:79], s[50:51], 0, v[88:89]
	v_add_f32_e32 v88, 1.0, v92
	v_mul_f32_e32 v75, 0xbfb8aa3b, v75
	v_mul_f32_e32 v76, 0xbfb8aa3b, v76
	v_mul_f32_e32 v77, 0xbfb8aa3b, v77
	v_exp_f32_e32 v74, v74
	v_exp_f32_e32 v95, v81
	v_rcp_f32_e32 v88, v88
	v_exp_f32_e32 v75, v75
	v_exp_f32_e32 v76, v76
	v_exp_f32_e32 v77, v77
	v_lshl_add_u64 v[80:81], s[48:49], 0, v[90:91]
	v_add_f32_e32 v90, 1.0, v93
	v_add_f32_e32 v92, 1.0, v94
	v_rcp_f32_e32 v90, v90
	v_add_f32_e32 v89, 1.0, v74
	v_add_f32_e32 v93, 1.0, v95
	v_add_co_u32_e32 v74, vcc, s84, v82
	v_rcp_f32_e32 v92, v92
	v_mul_f32_e32 v88, v88, v144
	v_add_f32_e32 v91, 1.0, v75
	v_add_f32_e32 v76, 1.0, v76
	v_add_f32_e32 v77, 1.0, v77
	v_addc_co_u32_e32 v75, vcc, 0, v83, vcc
	v_rcp_f32_e32 v93, v93
	v_add_f32_e32 v96, v88, v88
	v_rcp_f32_e32 v94, v76
	v_rcp_f32_e32 v95, v77
	global_load_dwordx4 v[74:77], v[74:75], off
	v_mul_f32_e32 v96, 0x3fb8aa3b, v96
	v_mul_f32_e32 v90, v90, v145
	v_exp_f32_e32 v96, v96
	v_mul_f32_e32 v92, v92, v142
	v_add_f32_e32 v97, v90, v90
	v_mul_f32_e32 v93, v93, v143
	v_add_f32_e32 v98, v92, v92
	v_mul_f32_e32 v97, 0x3fb8aa3b, v97
	v_add_f32_e32 v99, v93, v93
	v_mul_f32_e32 v98, 0x3fb8aa3b, v98
	v_exp_f32_e32 v97, v97
	v_mul_f32_e32 v99, 0x3fb8aa3b, v99
	v_exp_f32_e32 v98, v98
	v_sub_f32_e32 v96, 1.0, v96
	v_exp_f32_e32 v99, v99
	v_max_f32_e32 v96, 0, v96
	v_rcp_f32_e32 v89, v89
	v_sqrt_f32_e32 v96, v96
	v_add_f32_e32 v70, v70, v30
	v_sub_f32_e32 v97, 1.0, v97
	v_mul_f32_e32 v70, 0xbfb8aa3b, v70
	v_sub_f32_e32 v98, 1.0, v98
	v_max_f32_e32 v97, 0, v97
	v_exp_f32_e32 v70, v70
	v_rcp_f32_e32 v91, v91
	v_sub_f32_e32 v99, 1.0, v99
	v_max_f32_e32 v98, 0, v98
	v_sqrt_f32_e32 v97, v97
	v_max_f32_e32 v99, 0, v99
	v_sqrt_f32_e32 v98, v98
	v_mul_f32_e32 v89, v89, v96
	v_add_f32_e32 v70, 1.0, v70
	v_mul_f32_e32 v91, v91, v97
	s_waitcnt vmcnt(0) lgkmcnt(0)
	v_lshlrev_b32_e32 v96, 16, v84
	v_mul_f32_e32 v89, v89, v96
	v_sqrt_f32_e32 v96, v99
	v_and_b32_e32 v84, 0xffff0000, v84
	v_rcp_f32_e32 v70, v70
	v_lshlrev_b32_e32 v97, 16, v85
	v_mul_f32_e32 v91, v91, v84
	v_mul_f32_e32 v84, v94, v98
	v_and_b32_e32 v85, 0xffff0000, v85
	v_mul_f32_e32 v94, v84, v97
	v_mul_f32_e32 v84, v95, v96
	v_mul_f32_e32 v95, v84, v85
	v_cvt_pk_bf16_f32 v84, v88, v90
	v_mul_f32_e32 v88, 0x42000000, v89
	v_mul_f32_e32 v89, 0x42000000, v91
	v_med3_f32 v91, v88, s29, v231
	v_med3_f32 v89, v89, s29, v231
	v_mul_f32_e32 v70, v70, v130
	v_cvt_pk_fp8_f32 v88, v91, v89
	v_add_f32_e32 v91, v70, v70
	v_add_f32_e32 v71, v71, v31
	v_add_f32_e32 v66, v66, v26
	v_mul_f32_e32 v91, 0x3fb8aa3b, v91
	v_mul_f32_e32 v71, 0xbfb8aa3b, v71
	v_mul_f32_e32 v66, 0xbfb8aa3b, v66
	v_exp_f32_e32 v91, v91
	v_exp_f32_e32 v71, v71
	v_exp_f32_e32 v66, v66
	v_add_f32_e32 v73, v73, v33
	v_sub_f32_e32 v91, 1.0, v91
	v_add_f32_e32 v71, 1.0, v71
	v_add_f32_e32 v66, 1.0, v66
	v_max_f32_e32 v91, 0, v91
	v_rcp_f32_e32 v71, v71
	v_rcp_f32_e32 v66, v66
	v_sqrt_f32_e32 v91, v91
	v_add_f32_e32 v67, v67, v27
	v_mul_f32_e32 v71, v71, v131
	v_add_f32_e32 v72, v72, v32
	v_mul_f32_e32 v66, v66, v91
	v_add_f32_e32 v91, v71, v71
	v_mul_f32_e32 v91, 0x3fb8aa3b, v91
	v_mul_f32_e32 v73, 0xbfb8aa3b, v73
	v_mul_f32_e32 v67, 0xbfb8aa3b, v67
	v_exp_f32_e32 v91, v91
	v_mul_f32_e32 v72, 0xbfb8aa3b, v72
	v_exp_f32_e32 v73, v73
	v_exp_f32_e32 v67, v67
	v_exp_f32_e32 v72, v72
	v_sub_f32_e32 v91, 1.0, v91
	v_add_f32_e32 v73, 1.0, v73
	v_add_f32_e32 v67, 1.0, v67
	v_max_f32_e32 v91, 0, v91
	v_add_f32_e32 v72, 1.0, v72
	v_rcp_f32_e32 v73, v73
	v_rcp_f32_e32 v67, v67
	v_sqrt_f32_e32 v91, v91
	v_rcp_f32_e32 v72, v72
	v_mul_f32_e32 v90, 0x42000000, v94
	v_mul_f32_e32 v89, 0x42000000, v95
	v_med3_f32 v90, v90, s29, v231
	v_med3_f32 v89, v89, s29, v231
	v_mul_f32_e32 v73, v73, v133
	v_cvt_pk_fp8_f32 v88, v90, v89 op_sel:[0,0,1]
	v_lshlrev_b32_e32 v89, 16, v86
	v_mul_f32_e32 v67, v67, v91
	v_mul_f32_e32 v72, v72, v132
	v_add_f32_e32 v91, v73, v73
	v_mul_f32_e32 v66, v66, v89
	v_add_f32_e32 v89, v72, v72
	v_add_f32_e32 v69, v69, v29
	v_mul_f32_e32 v91, 0x3fb8aa3b, v91
	v_add_f32_e32 v68, v68, v28
	v_mul_f32_e32 v89, 0x3fb8aa3b, v89
	v_mul_f32_e32 v69, 0xbfb8aa3b, v69
	v_exp_f32_e32 v91, v91
	v_add_f32_e32 v62, v62, v46
	v_mul_f32_e32 v68, 0xbfb8aa3b, v68
	v_exp_f32_e32 v89, v89
	v_exp_f32_e32 v69, v69
	v_mul_f32_e32 v62, 0xbfb8aa3b, v62
	v_exp_f32_e32 v68, v68
	v_exp_f32_e32 v62, v62
	v_sub_f32_e32 v91, 1.0, v91
	v_sub_f32_e32 v89, 1.0, v89
	v_add_f32_e32 v69, 1.0, v69
	v_max_f32_e32 v91, 0, v91
	v_add_f32_e32 v68, 1.0, v68
	v_max_f32_e32 v89, 0, v89
	v_rcp_f32_e32 v69, v69
	v_sqrt_f32_e32 v91, v91
	v_add_f32_e32 v62, 1.0, v62
	v_rcp_f32_e32 v68, v68
	v_sqrt_f32_e32 v89, v89
	v_rcp_f32_e32 v62, v62
	v_and_b32_e32 v86, 0xffff0000, v86
	v_mul_f32_e32 v67, v67, v86
	v_lshlrev_b32_e32 v90, 16, v87
	v_and_b32_e32 v87, 0xffff0000, v87
	v_mul_f32_e32 v69, v69, v91
	v_mul_f32_e32 v66, 0x42000000, v66
	v_mul_f32_e32 v67, 0x42000000, v67
	v_mul_f32_e32 v68, v68, v89
	v_mul_f32_e32 v69, v69, v87
	v_med3_f32 v66, v66, s29, v231
	v_med3_f32 v67, v67, s29, v231
	v_mul_f32_e32 v62, v62, v144
	v_cvt_pk_fp8_f32 v89, v66, v67
	v_mul_f32_e32 v66, 0x42000000, v69
	v_add_f32_e32 v69, v62, v62
	v_add_f32_e32 v63, v63, v47
	v_add_f32_e32 v58, v58, v42
	v_mul_f32_e32 v69, 0x3fb8aa3b, v69
	v_mul_f32_e32 v63, 0xbfb8aa3b, v63
	v_mul_f32_e32 v58, 0xbfb8aa3b, v58
	v_exp_f32_e32 v69, v69
	v_exp_f32_e32 v63, v63
	v_exp_f32_e32 v58, v58
	v_add_f32_e32 v59, v59, v43
	v_sub_f32_e32 v69, 1.0, v69
	v_add_f32_e32 v63, 1.0, v63
	v_add_f32_e32 v58, 1.0, v58
	v_max_f32_e32 v69, 0, v69
	v_rcp_f32_e32 v63, v63
	v_rcp_f32_e32 v58, v58
	v_sqrt_f32_e32 v69, v69
	v_add_f32_e32 v64, v64, v48
	v_mul_f32_e32 v63, v63, v145
	v_mul_f32_e32 v59, 0xbfb8aa3b, v59
	v_mul_f32_e32 v58, v58, v69
	v_add_f32_e32 v69, v63, v63
	v_mul_f32_e32 v69, 0x3fb8aa3b, v69
	v_exp_f32_e32 v69, v69
	v_mul_f32_e32 v64, 0xbfb8aa3b, v64
	v_add_f32_e32 v65, v65, v49
	v_exp_f32_e32 v59, v59
	v_exp_f32_e32 v64, v64
	v_mul_f32_e32 v65, 0xbfb8aa3b, v65
	v_exp_f32_e32 v65, v65
	v_sub_f32_e32 v69, 1.0, v69
	v_add_f32_e32 v60, v60, v44
	v_add_f32_e32 v59, 1.0, v59
	v_max_f32_e32 v69, 0, v69
	v_add_f32_e32 v64, 1.0, v64
	v_mul_f32_e32 v60, 0xbfb8aa3b, v60
	v_mul_f32_e32 v68, v68, v90
	v_rcp_f32_e32 v59, v59
	v_sqrt_f32_e32 v69, v69
	v_exp_f32_e32 v60, v60
	v_rcp_f32_e32 v64, v64
	v_add_f32_e32 v65, 1.0, v65
	v_mul_f32_e32 v68, 0x42000000, v68
	v_rcp_f32_e32 v65, v65
	v_med3_f32 v67, v68, s29, v231
	v_med3_f32 v66, v66, s29, v231
	v_cvt_pk_fp8_f32 v89, v67, v66 op_sel:[0,0,1]
	v_lshlrev_b32_e32 v66, 16, v74
	v_mul_f32_e32 v66, v58, v66
	v_mul_f32_e32 v58, v59, v69
	v_add_f32_e32 v59, 1.0, v60
	v_mul_f32_e32 v60, v64, v142
	v_add_f32_e32 v64, v60, v60
	v_mul_f32_e32 v65, v65, v143
	v_mul_f32_e32 v64, 0x3fb8aa3b, v64
	v_add_f32_e32 v69, v65, v65
	v_exp_f32_e32 v64, v64
	v_add_f32_e32 v61, v61, v45
	v_mul_f32_e32 v69, 0x3fb8aa3b, v69
	v_mul_f32_e32 v61, 0xbfb8aa3b, v61
	v_exp_f32_e32 v69, v69
	v_exp_f32_e32 v61, v61
	v_add_f32_e32 v54, v54, v30
	v_mul_f32_e32 v54, 0xbfb8aa3b, v54
	v_sub_f32_e32 v64, 1.0, v64
	v_exp_f32_e32 v54, v54
	v_max_f32_e32 v64, 0, v64
	v_sub_f32_e32 v69, 1.0, v69
	v_rcp_f32_e32 v59, v59
	v_sqrt_f32_e32 v64, v64
	v_add_f32_e32 v61, 1.0, v61
	v_max_f32_e32 v69, 0, v69
	v_rcp_f32_e32 v61, v61
	v_sqrt_f32_e32 v69, v69
	v_add_f32_e32 v54, 1.0, v54
	v_and_b32_e32 v67, 0xffff0000, v74
	v_rcp_f32_e32 v54, v54
	v_lshlrev_b32_e32 v68, 16, v75
	v_mul_f32_e32 v67, v58, v67
	v_mul_f32_e32 v58, v59, v64
	v_cvt_pk_bf16_f32 v86, v70, v71
	v_and_b32_e32 v70, 0xffff0000, v75
	v_mul_f32_e32 v64, v58, v68
	v_mul_f32_e32 v58, v61, v69
	v_mul_f32_e32 v61, v58, v70
	v_cvt_pk_bf16_f32 v58, v62, v63
	v_cvt_pk_bf16_f32 v59, v60, v65
	v_mul_f32_e32 v60, 0x42000000, v66
	v_mul_f32_e32 v62, 0x42000000, v67
	v_mul_f32_e32 v63, 0x42000000, v64
	v_med3_f32 v60, v60, s29, v231
	v_med3_f32 v64, v62, s29, v231
	v_mul_f32_e32 v54, v54, v130
	v_cvt_pk_fp8_f32 v62, v60, v64
	v_add_f32_e32 v64, v54, v54
	v_add_f32_e32 v55, v55, v31
	v_add_f32_e32 v50, v50, v26
	v_mul_f32_e32 v64, 0x3fb8aa3b, v64
	v_mul_f32_e32 v55, 0xbfb8aa3b, v55
	v_mul_f32_e32 v50, 0xbfb8aa3b, v50
	v_exp_f32_e32 v64, v64
	v_exp_f32_e32 v55, v55
	v_exp_f32_e32 v50, v50
	v_add_f32_e32 v56, v56, v32
	v_sub_f32_e32 v64, 1.0, v64
	v_add_f32_e32 v55, 1.0, v55
	v_add_f32_e32 v50, 1.0, v50
	v_max_f32_e32 v64, 0, v64
	v_rcp_f32_e32 v55, v55
	v_rcp_f32_e32 v50, v50
	v_sqrt_f32_e32 v64, v64
	v_mul_f32_e32 v56, 0xbfb8aa3b, v56
	v_mul_f32_e32 v55, v55, v131
	v_exp_f32_e32 v56, v56
	v_mul_f32_e32 v50, v50, v64
	v_add_f32_e32 v64, v55, v55
	v_add_f32_e32 v57, v57, v33
	v_add_f32_e32 v51, v51, v27
	v_mul_f32_e32 v64, 0x3fb8aa3b, v64
	v_mul_f32_e32 v57, 0xbfb8aa3b, v57
	v_mul_f32_e32 v51, 0xbfb8aa3b, v51
	v_exp_f32_e32 v64, v64
	v_exp_f32_e32 v57, v57
	v_exp_f32_e32 v51, v51
	v_add_f32_e32 v56, 1.0, v56
	v_rcp_f32_e32 v56, v56
	v_sub_f32_e32 v64, 1.0, v64
	v_add_f32_e32 v57, 1.0, v57
	v_mul_f32_e32 v60, 0x42000000, v61
	v_add_f32_e32 v51, 1.0, v51
	v_max_f32_e32 v64, 0, v64
	v_rcp_f32_e32 v57, v57
	v_med3_f32 v61, v63, s29, v231
	v_med3_f32 v60, v60, s29, v231
	v_rcp_f32_e32 v51, v51
	v_sqrt_f32_e32 v64, v64
	v_cvt_pk_fp8_f32 v62, v61, v60 op_sel:[0,0,1]
	v_lshlrev_b32_e32 v60, 16, v76
	v_mul_f32_e32 v56, v56, v132
	v_mul_f32_e32 v50, v50, v60
	v_add_f32_e32 v60, v56, v56
	v_add_f32_e32 v52, v52, v28
	v_mul_f32_e32 v60, 0x3fb8aa3b, v60
	v_mul_f32_e32 v57, v57, v133
	v_mul_f32_e32 v52, 0xbfb8aa3b, v52
	v_mul_f32_e32 v51, v51, v64
	v_exp_f32_e32 v60, v60
	v_add_f32_e32 v64, v57, v57
	v_exp_f32_e32 v52, v52
	v_add_f32_e32 v53, v53, v29
	v_mul_f32_e32 v64, 0x3fb8aa3b, v64
	v_mul_f32_e32 v53, 0xbfb8aa3b, v53
	v_exp_f32_e32 v64, v64
	v_exp_f32_e32 v53, v53
	v_sub_f32_e32 v60, 1.0, v60
	v_add_f32_e32 v52, 1.0, v52
	v_max_f32_e32 v60, 0, v60
	v_rcp_f32_e32 v52, v52
	v_sqrt_f32_e32 v60, v60
	v_sub_f32_e32 v64, 1.0, v64
	v_add_f32_e32 v53, 1.0, v53
	v_max_f32_e32 v64, 0, v64
	v_and_b32_e32 v61, 0xffff0000, v76
	v_rcp_f32_e32 v53, v53
	v_sqrt_f32_e32 v64, v64
	v_mul_f32_e32 v51, v51, v61
	v_lshlrev_b32_e32 v63, 16, v77
	v_mul_f32_e32 v52, v52, v60
	v_mul_f32_e32 v50, 0x42000000, v50
	v_mul_f32_e32 v51, 0x42000000, v51
	v_mul_f32_e32 v52, v52, v63
	v_med3_f32 v50, v50, s29, v231
	v_med3_f32 v51, v51, s29, v231
	v_and_b32_e32 v65, 0xffff0000, v77
	v_mul_f32_e32 v53, v53, v64
	v_cvt_pk_fp8_f32 v63, v50, v51
	v_mul_f32_e32 v53, v53, v65
	v_mul_f32_e32 v52, 0x42000000, v52
	v_mul_f32_e32 v50, 0x42000000, v53
	v_med3_f32 v51, v52, s29, v231
	v_med3_f32 v50, v50, s29, v231
	v_cvt_pk_fp8_f32 v63, v51, v50 op_sel:[0,0,1]
	v_add_co_u32_e32 v50, vcc, s84, v80
	v_cvt_pk_bf16_f32 v85, v92, v93
	v_cvt_pk_bf16_f32 v87, v72, v73
	v_cvt_pk_bf16_f32 v60, v54, v55
	v_cvt_pk_bf16_f32 v61, v56, v57
	v_addc_co_u32_e32 v51, vcc, 0, v81, vcc
	global_store_dwordx4 v[80:81], v[84:87], off
	global_store_dwordx2 v[78:79], v[88:89], off
	global_store_dwordx4 v[50:51], v[58:61], off
	v_add_co_u32_e32 v50, vcc, s93, v78
	s_nop 1
	v_addc_co_u32_e32 v51, vcc, 0, v79, vcc
	global_store_dwordx2 v[50:51], v[62:63], off
	v_add_co_u32_e32 v50, vcc, s92, v82
	v_add_f32_e32 v38, v38, v46
	s_nop 0
	v_addc_co_u32_e32 v51, vcc, 0, v83, vcc
	global_load_dwordx4 v[54:57], v[50:51], off
	v_mul_f32_e32 v38, 0xbfb8aa3b, v38
	v_exp_f32_e32 v38, v38
	v_add_f32_e32 v34, v34, v42
	v_mul_f32_e32 v34, 0xbfb8aa3b, v34
	v_exp_f32_e32 v34, v34
	v_add_f32_e32 v38, 1.0, v38
	v_rcp_f32_e32 v38, v38
	v_add_f32_e32 v39, v39, v47
	v_add_f32_e32 v34, 1.0, v34
	v_mul_f32_e32 v39, 0xbfb8aa3b, v39
	v_exp_f32_e32 v39, v39
	v_add_f32_e32 v35, v35, v43
	v_mul_f32_e32 v35, 0xbfb8aa3b, v35
	v_exp_f32_e32 v35, v35
	v_add_f32_e32 v39, 1.0, v39
	v_rcp_f32_e32 v39, v39
	v_add_f32_e32 v36, v36, v44
	v_add_f32_e32 v35, 1.0, v35
	v_rcp_f32_e32 v35, v35
	v_mul_f32_e32 v39, v39, v145
	v_mul_f32_e32 v36, 0xbfb8aa3b, v36
	v_exp_f32_e32 v36, v36
	v_add_co_u32_e32 v50, vcc, s89, v82
	v_add_f32_e32 v22, v22, v30
	v_add_f32_e32 v36, 1.0, v36
	v_rcp_f32_e32 v36, v36
	v_addc_co_u32_e32 v51, vcc, 0, v83, vcc
	global_load_dwordx4 v[50:53], v[50:51], off
	v_add_f32_e32 v37, v37, v45
	v_mul_f32_e32 v22, 0xbfb8aa3b, v22
	v_mul_f32_e32 v37, 0xbfb8aa3b, v37
	v_exp_f32_e32 v22, v22
	v_exp_f32_e32 v37, v37
	v_add_f32_e32 v18, v18, v26
	v_add_f32_e32 v23, v23, v31
	v_add_f32_e32 v22, 1.0, v22
	v_add_f32_e32 v37, 1.0, v37
	v_rcp_f32_e32 v22, v22
	v_rcp_f32_e32 v37, v37
	v_mul_f32_e32 v18, 0xbfb8aa3b, v18
	v_mul_f32_e32 v23, 0xbfb8aa3b, v23
	v_mul_f32_e32 v22, v22, v130
	v_exp_f32_e32 v18, v18
	v_exp_f32_e32 v23, v23
	v_add_f32_e32 v24, v24, v32
	v_add_f32_e32 v19, v19, v27
	v_add_f32_e32 v18, 1.0, v18
	v_add_f32_e32 v23, 1.0, v23
	v_rcp_f32_e32 v18, v18
	v_rcp_f32_e32 v23, v23
	v_mul_f32_e32 v24, 0xbfb8aa3b, v24
	v_mul_f32_e32 v19, 0xbfb8aa3b, v19
	v_exp_f32_e32 v24, v24
	v_mul_f32_e32 v23, v23, v131
	v_exp_f32_e32 v19, v19
	v_add_f32_e32 v25, v25, v33
	v_add_f32_e32 v24, 1.0, v24
	v_rcp_f32_e32 v24, v24
	v_add_f32_e32 v19, 1.0, v19
	v_rcp_f32_e32 v19, v19
	v_add_f32_e32 v20, v20, v28
	v_mul_f32_e32 v24, v24, v132
	v_mul_f32_e32 v25, 0xbfb8aa3b, v25
	v_mul_f32_e32 v20, 0xbfb8aa3b, v20
	v_exp_f32_e32 v25, v25
	v_exp_f32_e32 v20, v20
	v_add_f32_e32 v14, v14, v46
	v_add_f32_e32 v21, v21, v29
	v_add_f32_e32 v25, 1.0, v25
	v_add_f32_e32 v20, 1.0, v20
	v_rcp_f32_e32 v25, v25
	v_rcp_f32_e32 v20, v20
	v_mul_f32_e32 v14, 0xbfb8aa3b, v14
	v_mul_f32_e32 v21, 0xbfb8aa3b, v21
	v_mul_f32_e32 v25, v25, v133
	v_exp_f32_e32 v14, v14
	v_exp_f32_e32 v21, v21
	s_waitcnt vmcnt(0) lgkmcnt(0)
	v_lshlrev_b32_e32 v58, 16, v54
	v_and_b32_e32 v59, 0xffff0000, v54
	v_lshlrev_b32_e32 v60, 16, v55
	v_and_b32_e32 v54, 0xffff0000, v55
	v_rcp_f32_e32 v55, v34
	v_mul_f32_e32 v34, v38, v144
	v_add_f32_e32 v38, v34, v34
	v_mul_f32_e32 v38, 0x3fb8aa3b, v38
	v_exp_f32_e32 v38, v38
	v_cvt_pk_bf16_f32 v34, v34, v39
	v_add_f32_e32 v14, 1.0, v14
	v_add_f32_e32 v21, 1.0, v21
	v_sub_f32_e32 v38, 1.0, v38
	v_max_f32_e32 v38, 0, v38
	v_sqrt_f32_e32 v38, v38
	v_rcp_f32_e32 v14, v14
	v_rcp_f32_e32 v21, v21
	v_add_f32_e32 v10, v10, v42
	v_mul_f32_e32 v38, v55, v38
	v_add_f32_e32 v55, v39, v39
	v_mul_f32_e32 v55, 0x3fb8aa3b, v55
	v_exp_f32_e32 v55, v55
	v_mul_f32_e32 v38, v38, v58
	v_mul_f32_e32 v38, 0x42000000, v38
	v_mul_f32_e32 v14, v14, v144
	v_sub_f32_e32 v55, 1.0, v55
	v_max_f32_e32 v55, 0, v55
	v_sqrt_f32_e32 v55, v55
	v_mul_f32_e32 v10, 0xbfb8aa3b, v10
	v_exp_f32_e32 v10, v10
	v_add_f32_e32 v11, v11, v43
	v_mul_f32_e32 v35, v35, v55
	v_mul_f32_e32 v55, v35, v59
	v_add_f32_e32 v35, v40, v48
	v_mul_f32_e32 v35, 0xbfb8aa3b, v35
	v_exp_f32_e32 v35, v35
	v_mul_f32_e32 v39, 0x42000000, v55
	v_med3_f32 v39, v39, s29, v231
	v_add_f32_e32 v10, 1.0, v10
	v_add_f32_e32 v35, 1.0, v35
	v_rcp_f32_e32 v35, v35
	v_rcp_f32_e32 v10, v10
	v_mul_f32_e32 v11, 0xbfb8aa3b, v11
	v_exp_f32_e32 v11, v11
	v_mul_f32_e32 v35, v35, v142
	v_add_f32_e32 v40, v35, v35
	v_mul_f32_e32 v40, 0x3fb8aa3b, v40
	v_exp_f32_e32 v40, v40
	v_add_f32_e32 v11, 1.0, v11
	v_rcp_f32_e32 v11, v11
	v_add_f32_e32 v12, v12, v44
	v_sub_f32_e32 v40, 1.0, v40
	v_max_f32_e32 v40, 0, v40
	v_sqrt_f32_e32 v40, v40
	v_mul_f32_e32 v12, 0xbfb8aa3b, v12
	v_exp_f32_e32 v12, v12
	v_add_f32_e32 v6, v6, v30
	v_mul_f32_e32 v36, v36, v40
	v_add_f32_e32 v40, v41, v49
	v_mul_f32_e32 v40, 0xbfb8aa3b, v40
	v_exp_f32_e32 v40, v40
	v_mul_f32_e32 v36, v36, v60
	v_mul_f32_e32 v36, 0x42000000, v36
	v_med3_f32 v36, v36, s29, v231
	v_add_f32_e32 v40, 1.0, v40
	v_rcp_f32_e32 v40, v40
	v_add_f32_e32 v12, 1.0, v12
	v_rcp_f32_e32 v12, v12
	v_add_f32_e32 v13, v13, v45
	v_mul_f32_e32 v40, v40, v143
	v_add_f32_e32 v41, v40, v40
	v_mul_f32_e32 v41, 0x3fb8aa3b, v41
	v_exp_f32_e32 v41, v41
	v_cvt_pk_bf16_f32 v35, v35, v40
	v_med3_f32 v40, v38, s29, v231
	v_sub_f32_e32 v41, 1.0, v41
	v_max_f32_e32 v41, 0, v41
	v_sqrt_f32_e32 v41, v41
	v_cvt_pk_fp8_f32 v38, v40, v39
	v_lshlrev_b32_e32 v39, 16, v57
	v_and_b32_e32 v40, 0xffff0000, v57
	v_mul_f32_e32 v37, v37, v41
	v_add_f32_e32 v41, v22, v22
	v_mul_f32_e32 v41, 0x3fb8aa3b, v41
	v_exp_f32_e32 v41, v41
	v_mul_f32_e32 v37, v37, v54
	v_mul_f32_e32 v37, 0x42000000, v37
	v_med3_f32 v37, v37, s29, v231
	v_sub_f32_e32 v41, 1.0, v41
	v_max_f32_e32 v41, 0, v41
	v_sqrt_f32_e32 v41, v41
	v_cvt_pk_fp8_f32 v38, v36, v37 op_sel:[0,0,1]
	v_lshlrev_b32_e32 v36, 16, v56
	v_and_b32_e32 v37, 0xffff0000, v56
	v_mul_f32_e32 v18, v18, v41
	v_mul_f32_e32 v18, v18, v36
	v_add_f32_e32 v36, v23, v23
	v_mul_f32_e32 v36, 0x3fb8aa3b, v36
	v_exp_f32_e32 v36, v36
	v_mul_f32_e32 v18, 0x42000000, v18
	v_med3_f32 v18, v18, s29, v231
	v_mul_f32_e32 v6, 0xbfb8aa3b, v6
	v_sub_f32_e32 v36, 1.0, v36
	v_max_f32_e32 v36, 0, v36
	v_sqrt_f32_e32 v36, v36
	v_mul_f32_e32 v13, 0xbfb8aa3b, v13
	v_exp_f32_e32 v6, v6
	v_exp_f32_e32 v13, v13
	v_mul_f32_e32 v19, v19, v36
	v_add_f32_e32 v36, v24, v24
	v_mul_f32_e32 v36, 0x3fb8aa3b, v36
	v_exp_f32_e32 v36, v36
	v_mul_f32_e32 v19, v19, v37
	v_mul_f32_e32 v19, 0x42000000, v19
	v_med3_f32 v19, v19, s29, v231
	v_sub_f32_e32 v36, 1.0, v36
	v_max_f32_e32 v36, 0, v36
	v_sqrt_f32_e32 v36, v36
	v_cvt_pk_bf16_f32 v37, v24, v25
	v_add_f32_e32 v6, 1.0, v6
	v_add_f32_e32 v13, 1.0, v13
	v_mul_f32_e32 v20, v20, v36
	v_add_f32_e32 v36, v25, v25
	v_mul_f32_e32 v36, 0x3fb8aa3b, v36
	v_exp_f32_e32 v36, v36
	v_mul_f32_e32 v20, v20, v39
	v_cvt_pk_fp8_f32 v39, v18, v19
	v_sub_f32_e32 v36, 1.0, v36
	v_max_f32_e32 v36, 0, v36
	v_sqrt_f32_e32 v36, v36
	v_mul_f32_e32 v20, 0x42000000, v20
	v_med3_f32 v18, v20, s29, v231
	v_rcp_f32_e32 v6, v6
	v_mul_f32_e32 v21, v21, v36
	v_cvt_pk_bf16_f32 v36, v22, v23
	v_add_f32_e32 v22, v14, v14
	v_mul_f32_e32 v22, 0x3fb8aa3b, v22
	v_exp_f32_e32 v22, v22
	v_mul_f32_e32 v21, v21, v40
	v_mul_f32_e32 v21, 0x42000000, v21
	v_med3_f32 v19, v21, s29, v231
	v_sub_f32_e32 v22, 1.0, v22
	v_max_f32_e32 v22, 0, v22
	v_cvt_pk_fp8_f32 v39, v18, v19 op_sel:[0,0,1]
	v_add_co_u32_e32 v18, vcc, s92, v80
	v_sqrt_f32_e32 v22, v22
	s_nop 0
	v_addc_co_u32_e32 v19, vcc, 0, v81, vcc
	global_store_dwordx4 v[18:19], v[34:37], off
	v_add_co_u32_e32 v18, vcc, s84, v78
	v_mul_f32_e32 v10, v10, v22
	s_nop 0
	v_addc_co_u32_e32 v19, vcc, 0, v79, vcc
	global_store_dwordx2 v[18:19], v[38:39], off
	v_lshlrev_b32_e32 v18, 16, v50
	v_mul_f32_e32 v18, v10, v18
	v_add_f32_e32 v10, v15, v47
	v_mul_f32_e32 v10, 0xbfb8aa3b, v10
	v_exp_f32_e32 v10, v10
	v_and_b32_e32 v19, 0xffff0000, v50
	v_rcp_f32_e32 v13, v13
	v_mul_f32_e32 v6, v6, v130
	v_add_f32_e32 v10, 1.0, v10
	v_rcp_f32_e32 v10, v10
	v_add_f32_e32 v2, v2, v26
	v_add_f32_e32 v7, v7, v31
	v_mul_f32_e32 v2, 0xbfb8aa3b, v2
	v_mul_f32_e32 v10, v10, v145
	v_add_f32_e32 v15, v10, v10
	v_mul_f32_e32 v15, 0x3fb8aa3b, v15
	v_exp_f32_e32 v15, v15
	v_mul_f32_e32 v7, 0xbfb8aa3b, v7
	v_exp_f32_e32 v2, v2
	v_exp_f32_e32 v7, v7
	v_sub_f32_e32 v15, 1.0, v15
	v_max_f32_e32 v15, 0, v15
	v_sqrt_f32_e32 v15, v15
	v_cvt_pk_bf16_f32 v10, v14, v10
	v_mul_f32_e32 v14, 0x42000000, v18
	v_add_f32_e32 v2, 1.0, v2
	v_mul_f32_e32 v11, v11, v15
	v_mul_f32_e32 v15, v11, v19
	v_add_f32_e32 v11, v16, v48
	v_mul_f32_e32 v11, 0xbfb8aa3b, v11
	v_exp_f32_e32 v11, v11
	v_mul_f32_e32 v15, 0x42000000, v15
	v_med3_f32 v15, v15, s29, v231
	v_add_f32_e32 v7, 1.0, v7
	v_add_f32_e32 v11, 1.0, v11
	v_rcp_f32_e32 v11, v11
	v_lshlrev_b32_e32 v20, 16, v51
	v_and_b32_e32 v21, 0xffff0000, v51
	v_rcp_f32_e32 v2, v2
	v_mul_f32_e32 v11, v11, v142
	v_add_f32_e32 v16, v11, v11
	v_mul_f32_e32 v16, 0x3fb8aa3b, v16
	v_exp_f32_e32 v16, v16
	v_rcp_f32_e32 v7, v7
	v_add_f32_e32 v8, v8, v32
	v_add_f32_e32 v3, v3, v27
	v_sub_f32_e32 v16, 1.0, v16
	v_max_f32_e32 v16, 0, v16
	v_sqrt_f32_e32 v16, v16
	v_mul_f32_e32 v7, v7, v131
	v_mul_f32_e32 v8, 0xbfb8aa3b, v8
	v_mul_f32_e32 v3, 0xbfb8aa3b, v3
	v_mul_f32_e32 v12, v12, v16
	v_add_f32_e32 v16, v17, v49
	v_mul_f32_e32 v16, 0xbfb8aa3b, v16
	v_exp_f32_e32 v16, v16
	v_mul_f32_e32 v12, v12, v20
	v_mul_f32_e32 v12, 0x42000000, v12
	v_med3_f32 v12, v12, s29, v231
	v_add_f32_e32 v16, 1.0, v16
	v_rcp_f32_e32 v16, v16
	v_exp_f32_e32 v8, v8
	v_exp_f32_e32 v3, v3
	v_add_f32_e32 v9, v9, v33
	v_mul_f32_e32 v16, v16, v143
	v_add_f32_e32 v17, v16, v16
	v_mul_f32_e32 v17, 0x3fb8aa3b, v17
	v_exp_f32_e32 v17, v17
	v_cvt_pk_bf16_f32 v11, v11, v16
	v_med3_f32 v16, v14, s29, v231
	v_sub_f32_e32 v17, 1.0, v17
	v_max_f32_e32 v17, 0, v17
	v_sqrt_f32_e32 v17, v17
	v_cvt_pk_fp8_f32 v14, v16, v15
	v_add_f32_e32 v8, 1.0, v8
	v_add_f32_e32 v3, 1.0, v3
	v_mul_f32_e32 v13, v13, v17
	v_add_f32_e32 v17, v6, v6
	v_mul_f32_e32 v17, 0x3fb8aa3b, v17
	v_exp_f32_e32 v17, v17
	v_mul_f32_e32 v13, v13, v21
	v_mul_f32_e32 v13, 0x42000000, v13
	v_med3_f32 v13, v13, s29, v231
	v_sub_f32_e32 v17, 1.0, v17
	v_max_f32_e32 v17, 0, v17
	v_sqrt_f32_e32 v17, v17
	v_cvt_pk_fp8_f32 v14, v12, v13 op_sel:[0,0,1]
	v_lshlrev_b32_e32 v12, 16, v52
	v_rcp_f32_e32 v8, v8
	v_mul_f32_e32 v2, v2, v17
	v_mul_f32_e32 v2, v2, v12
	v_add_f32_e32 v12, v7, v7
	v_mul_f32_e32 v12, 0x3fb8aa3b, v12
	v_exp_f32_e32 v12, v12
	v_rcp_f32_e32 v3, v3
	v_mul_f32_e32 v8, v8, v132
	v_add_f32_e32 v4, v4, v28
	v_sub_f32_e32 v12, 1.0, v12
	v_max_f32_e32 v12, 0, v12
	v_sqrt_f32_e32 v12, v12
	v_mul_f32_e32 v9, 0xbfb8aa3b, v9
	v_mul_f32_e32 v4, 0xbfb8aa3b, v4
	v_exp_f32_e32 v9, v9
	v_mul_f32_e32 v3, v3, v12
	v_add_f32_e32 v12, v8, v8
	v_mul_f32_e32 v12, 0x3fb8aa3b, v12
	v_exp_f32_e32 v12, v12
	v_exp_f32_e32 v4, v4
	v_add_f32_e32 v9, 1.0, v9
	v_rcp_f32_e32 v9, v9
	v_sub_f32_e32 v12, 1.0, v12
	v_add_f32_e32 v4, 1.0, v4
	v_max_f32_e32 v12, 0, v12
	v_rcp_f32_e32 v4, v4
	v_sqrt_f32_e32 v12, v12
	v_mul_f32_e32 v9, v9, v133
	v_add_f32_e32 v5, v5, v29
	v_mul_f32_e32 v5, 0xbfb8aa3b, v5
	v_mul_f32_e32 v4, v4, v12
	v_add_f32_e32 v12, v9, v9
	v_mul_f32_e32 v12, 0x3fb8aa3b, v12
	v_exp_f32_e32 v12, v12
	v_exp_f32_e32 v5, v5
	v_and_b32_e32 v13, 0xffff0000, v52
	v_mul_f32_e32 v3, v3, v13
	v_sub_f32_e32 v12, 1.0, v12
	v_add_f32_e32 v5, 1.0, v5
	v_max_f32_e32 v12, 0, v12
	v_rcp_f32_e32 v5, v5
	v_sqrt_f32_e32 v12, v12
	v_lshlrev_b32_e32 v15, 16, v53
	v_mul_f32_e32 v2, 0x42000000, v2
	v_mul_f32_e32 v3, 0x42000000, v3
	v_mul_f32_e32 v4, v4, v15
	v_med3_f32 v2, v2, s29, v231
	v_med3_f32 v3, v3, s29, v231
	v_and_b32_e32 v16, 0xffff0000, v53
	v_mul_f32_e32 v5, v5, v12
	v_cvt_pk_fp8_f32 v15, v2, v3
	v_mul_f32_e32 v5, v5, v16
	v_mul_f32_e32 v4, 0x42000000, v4
	v_mul_f32_e32 v5, 0x42000000, v5
	v_med3_f32 v2, v4, s29, v231
	v_med3_f32 v3, v5, s29, v231
	v_cvt_pk_fp8_f32 v15, v2, v3 op_sel:[0,0,1]
	v_add_co_u32_e32 v2, vcc, 0x18000, v80
	v_cvt_pk_bf16_f32 v12, v6, v7
	v_cvt_pk_bf16_f32 v13, v8, v9
	v_addc_co_u32_e32 v3, vcc, 0, v81, vcc
	global_store_dwordx4 v[2:3], v[10:13], off
	v_add_co_u32_e32 v2, vcc, 0xc000, v78
	s_nop 1
	v_addc_co_u32_e32 v3, vcc, 0, v79, vcc
	global_store_dwordx2 v[2:3], v[14:15], off
	s_and_b64 vcc, exec, s[12:13]
	s_mov_b32 s82, s40
	s_mov_b32 s52, s42
	s_mov_b64 s[14:15], s[46:47]
	s_mov_b64 s[48:49], s[44:45]
	s_mov_b32 s94, s23
	s_cbranch_vccz .LBB0_1638
	s_waitcnt vmcnt(0)
	s_cmpk_gt_u32 s22, 0xff
	v_readlane_b32 s81, v253, 46
	v_readlane_b32 s80, v253, 45
	v_readlane_b32 s89, v253, 44
	s_cbranch_scc1 .LBB0_1649
	s_barrier

.LBB0_1810:
	s_waitcnt vmcnt(0) lgkmcnt(0)
	v_lshlrev_b32_e32 v77, 16, v37
	v_lshlrev_b32_e32 v76, 16, v36
	v_and_b32_e32 v37, 0xffff0000, v37
	v_and_b32_e32 v36, 0xffff0000, v36
	v_pk_add_f32 v[68:69], v[76:77], v[36:37]
	v_lshlrev_b32_e32 v87, 16, v35
	v_lshlrev_b32_e32 v86, 16, v34
	v_and_b32_e32 v35, 0xffff0000, v35
	v_and_b32_e32 v34, 0xffff0000, v34
	v_lshlrev_b32_e32 v46, 16, v39
	v_and_b32_e32 v48, 0xffff0000, v39
	v_add_f32_e32 v39, v68, v69
	v_pk_add_f32 v[68:69], v[86:87], v[34:35]
	v_lshlrev_b32_e32 v42, 16, v40
	v_and_b32_e32 v43, 0xffff0000, v40
	v_lshlrev_b32_e32 v40, 16, v41
	v_and_b32_e32 v41, 0xffff0000, v41
	v_pk_add_f32 v[68:69], v[68:69], v[68:69] op_sel_hi:[0,1]
	v_lshlrev_b32_e32 v44, 16, v38
	v_and_b32_e32 v38, 0xffff0000, v38
	v_add_f32_e32 v49, 0, v39
	v_add_f32_e32 v45, v42, v43
	v_add_f32_e32 v39, v40, v41
	v_mov_b32_e32 v47, v69
	v_pk_add_f32 v[70:71], v[44:45], v[38:39]
	v_pk_add_f32 v[68:69], v[46:47], v[48:49]
	s_min_u32 s0, s10, 29
	v_pk_add_f32 v[68:69], v[70:71], v[68:69]
	s_lshl_b32 s0, s0, 3
	v_add_f32_e32 v39, v68, v69
	s_add_i32 s22, s9, s0
	s_nop 0
	v_add_f32_dpp v39, v39, v39 quad_perm:[1,0,3,2] row_mask:0xf bank_mask:0xf bound_ctrl:1
	s_nop 1
	v_add_f32_dpp v39, v39, v39 quad_perm:[2,3,0,1] row_mask:0xf bank_mask:0xf bound_ctrl:1
	s_nop 1
	v_add_f32_dpp v39, v39, v39 row_half_mirror row_mask:0xf bank_mask:0xf bound_ctrl:1
	s_nop 1
	v_add_f32_dpp v39, v39, v39 row_mirror row_mask:0xf bank_mask:0xf bound_ctrl:1
	s_nop 0
	v_readlane_b32 s11, v39, 16
	v_readlane_b32 s23, v39, 48
	v_readlane_b32 s0, v39, 0
	v_readlane_b32 s1, v39, 32
	v_mov_b32_e32 v68, s11
	v_mov_b32_e32 v69, s23
	v_pk_add_f32 v[68:69], s[0:1], v[68:69]
	s_nop 0
	v_add_f32_e32 v39, v68, v69
	v_fmac_f32_e32 v36, 0xba800000, v39
	v_fmac_f32_e32 v37, 0xba800000, v39
	v_fmac_f32_e32 v77, 0xba800000, v39
	v_fmac_f32_e32 v76, 0xba800000, v39
	v_mov_b32_e32 v88, v77
	v_mov_b32_e32 v89, v37
	v_mov_b32_e32 v77, v36
	v_fmac_f32_e32 v34, 0xba800000, v39
	v_fmac_f32_e32 v35, 0xba800000, v39
	v_fmac_f32_e32 v87, 0xba800000, v39
	v_pk_mul_f32 v[68:69], v[88:89], v[88:89]
	v_pk_mul_f32 v[36:37], v[76:77], v[76:77]
	v_fmac_f32_e32 v86, 0xba800000, v39
	v_mov_b32_e32 v90, v87
	v_mov_b32_e32 v91, v35
	v_mov_b32_e32 v87, v34
	v_pk_mov_b32 v[70:71], v[36:37], v[68:69] op_sel:[1,0]
	v_mov_b32_e32 v37, v69
	v_pk_mul_f32 v[68:69], v[90:91], v[90:91]
	v_pk_mul_f32 v[34:35], v[86:87], v[86:87]
	v_pk_add_f32 v[36:37], v[70:71], v[36:37]
	v_pk_mov_b32 v[70:71], v[34:35], v[68:69] op_sel:[1,0]
	v_mov_b32_e32 v35, v69
	v_pk_add_f32 v[34:35], v[70:71], v[34:35]
	v_fmac_f32_e32 v42, 0xba800000, v39
	v_pk_add_f32 v[34:35], v[34:35], v[34:35] op_sel_hi:[0,1]
	v_fmac_f32_e32 v43, 0xba800000, v39
	v_fmac_f32_e32 v40, 0xba800000, v39
	v_mul_f32_e32 v34, v42, v42
	v_fmac_f32_e32 v41, 0xba800000, v39
	v_pk_fma_f32 v[68:69], v[42:43], v[42:43], v[34:35] op_sel_hi:[1,1,0]
	v_mul_f32_e32 v34, v40, v40
	v_pk_add_f32 v[36:37], v[36:37], v[36:37] op_sel_hi:[0,1]
	v_pk_fma_f32 v[70:71], v[40:41], v[40:41], v[34:35] op_sel_hi:[1,1,0]
	v_fmac_f32_e32 v48, 0xba800000, v39
	v_fmac_f32_e32 v46, 0xba800000, v39
	v_fmac_f32_e32 v38, 0xba800000, v39
	v_fmac_f32_e32 v44, 0xba800000, v39
	v_mul_f32_e32 v68, v44, v44
	v_mul_f32_e32 v70, v38, v38
	v_mul_f32_e32 v36, v46, v46
	v_mul_f32_e32 v34, v48, v48
	v_pk_add_f32 v[68:69], v[68:69], v[70:71]
	v_pk_add_f32 v[34:35], v[36:37], v[34:35]
	v_mov_b32_e32 v47, v48
	v_pk_add_f32 v[34:35], v[68:69], v[34:35]
	s_nop 0
	v_add_f32_e32 v34, v34, v35
	s_nop 1
	v_add_f32_dpp v34, v34, v34 quad_perm:[1,0,3,2] row_mask:0xf bank_mask:0xf bound_ctrl:1
	s_nop 1
	v_add_f32_dpp v34, v34, v34 quad_perm:[2,3,0,1] row_mask:0xf bank_mask:0xf bound_ctrl:1
	s_nop 1
	v_add_f32_dpp v34, v34, v34 row_half_mirror row_mask:0xf bank_mask:0xf bound_ctrl:1
	s_nop 1
	v_add_f32_dpp v34, v34, v34 row_mirror row_mask:0xf bank_mask:0xf bound_ctrl:1
	s_nop 0
	v_readlane_b32 s11, v34, 16
	v_readlane_b32 s23, v34, 48
	v_readlane_b32 s0, v34, 0
	v_readlane_b32 s1, v34, 32
	v_mov_b32_e32 v34, s11
	v_mov_b32_e32 v35, s23
	v_pk_add_f32 v[34:35], s[0:1], v[34:35]
	s_mov_b32 s0, 0xf800000
	v_add_f32_e32 v34, v34, v35
	v_fmamk_f32 v34, v34, 0x3a800000, v83
	s_ashr_i32 s23, s22, 31
	v_mul_f32_e32 v35, 0x4f800000, v34
	v_cmp_gt_f32_e32 vcc, s0, v34
	s_lshl_b64 s[0:1], s[22:23], 11
	s_and_b32 s11, s10, 3
	v_cndmask_b32_e32 v36, v34, v35, vcc
	v_lshl_add_u64 v[34:35], v[54:55], 0, s[0:1]
	global_load_dwordx2 v[68:69], v[34:35], off
	global_load_dwordx2 v[70:71], v[34:35], off offset:512
	global_load_dwordx2 v[72:73], v[34:35], off offset:1024
	global_load_dwordx2 v[74:75], v[34:35], off offset:1536
	v_sqrt_f32_e32 v37, v36
	s_mul_i32 s26, s11, 0x810
	s_add_i32 s26, s87, s26
	v_add_u32_e32 v39, -1, v37
	v_fma_f32 v45, -v39, v37, v36
	v_cmp_ge_f32_e64 s[22:23], 0, v45
	v_add_u32_e32 v45, 1, v37
	s_nop 0
	v_cndmask_b32_e64 v39, v37, v39, s[22:23]
	v_fma_f32 v37, -v45, v37, v36
	v_cmp_lt_f32_e64 s[22:23], 0, v37
	s_nop 1
	v_cndmask_b32_e64 v37, v39, v45, s[22:23]
	v_mul_f32_e32 v39, 0x37800000, v37
	v_cndmask_b32_e32 v37, v37, v39, vcc
	v_cmp_class_f32_e32 vcc, v36, v84
	s_add_i32 s22, s4, s8
	s_ashr_i32 s23, s22, 31
	v_cndmask_b32_e32 v36, v37, v36, vcc
	v_div_scale_f32 v37, s[0:1], v36, v36, 1.0
	v_rcp_f32_e32 v39, v37
	s_lshl_b64 s[0:1], s[22:23], 11
	v_fma_f32 v34, -v37, v39, 1.0
	v_fmac_f32_e32 v39, v34, v39
	v_div_scale_f32 v34, vcc, 1.0, v36, 1.0
	v_mul_f32_e32 v35, v34, v39
	v_fma_f32 v45, -v37, v35, v34
	v_fmac_f32_e32 v35, v45, v39
	v_fma_f32 v34, -v37, v35, v34
	v_div_fmas_f32 v34, v34, v39, v35
	v_div_fixup_f32 v34, v34, v36, 1.0
	v_mov_b32_e32 v45, v38
	v_pk_mul_f32 v[36:37], v[76:77], v[34:35] op_sel_hi:[1,0]
	v_pk_mul_f32 v[76:77], v[88:89], v[34:35] op_sel_hi:[1,0]
	v_pk_mul_f32 v[38:39], v[44:45], v[34:35] op_sel_hi:[1,0]
	v_mov_b32_e32 v44, v78
	v_pk_fma_f32 v[76:77], v[4:5], v[76:77], v[12:13]
	v_pk_fma_f32 v[36:37], v[2:3], v[36:37], v[10:11]
	v_pk_mul_f32 v[86:87], v[86:87], v[34:35] op_sel_hi:[1,0]
	v_pk_mul_f32 v[88:89], v[90:91], v[34:35] op_sel_hi:[1,0]
	v_pk_fma_f32 v[86:87], v[6:7], v[86:87], v[14:15]
	v_pk_fma_f32 v[88:89], v[8:9], v[88:89], v[16:17]
	v_pk_mul_f32 v[42:43], v[42:43], v[34:35] op_sel_hi:[1,0]
	v_pk_mul_f32 v[40:41], v[40:41], v[34:35] op_sel_hi:[1,0]
	v_pk_mul_f32 v[34:35], v[46:47], v[34:35] op_sel_hi:[1,0]
	v_lshl_add_u32 v48, v44, 3, s26
	v_cvt_pk_bf16_f32 v44, v36, v37
	v_cvt_pk_bf16_f32 v45, v76, v77
	v_lshl_add_u64 v[46:47], v[56:57], 0, s[0:1]
	v_pk_fma_f32 v[40:41], v[20:21], v[40:41], v[28:29]
	v_pk_fma_f32 v[42:43], v[18:19], v[42:43], v[26:27]
	global_store_dwordx2 v[46:47], v[44:45], off nt
	ds_write_b64 v48, v[44:45] offset:33024
	v_cvt_pk_bf16_f32 v44, v86, v87
	v_cvt_pk_bf16_f32 v45, v88, v89
	v_pk_fma_f32 v[34:35], v[24:25], v[34:35], v[32:33]
	v_pk_fma_f32 v[38:39], v[22:23], v[38:39], v[30:31]
	global_store_dwordx2 v[46:47], v[44:45], off offset:512 nt
	ds_write_b64 v48, v[44:45] offset:33536
	v_cvt_pk_bf16_f32 v44, v42, v43
	v_cvt_pk_bf16_f32 v45, v40, v41
	global_store_dwordx2 v[46:47], v[44:45], off offset:1024 nt
	ds_write_b64 v48, v[44:45] offset:34048
	v_cvt_pk_bf16_f32 v44, v38, v39
	v_cvt_pk_bf16_f32 v45, v34, v35
	global_store_dwordx2 v[46:47], v[44:45], off offset:1536 nt
	ds_write_b64 v48, v[44:45] offset:34560
	v_med3_f32 v36, v36, s6, v85
	v_med3_f32 v37, v37, s6, v85
	v_cvt_pk_fp8_f32 v44, v36, v37
	v_med3_f32 v36, v76, s6, v85
	v_med3_f32 v37, v77, s6, v85
	v_med3_f32 v45, v86, s6, v85
	v_cvt_pk_fp8_f32 v44, v36, v37 op_sel:[0,0,1]
	v_med3_f32 v46, v87, s6, v85
	v_cvt_pk_fp8_f32 v47, v45, v46
	s_lshl_b64 s[0:1], s[22:23], 10
	v_lshl_add_u64 v[36:37], v[58:59], 0, s[0:1]
	global_store_dword v[36:37], v44, off
	v_med3_f32 v44, v88, s6, v85
	v_med3_f32 v45, v89, s6, v85
	v_cvt_pk_fp8_f32 v47, v44, v45 op_sel:[0,0,1]
	v_med3_f32 v42, v42, s6, v85
	v_med3_f32 v43, v43, s6, v85
	v_cvt_pk_fp8_f32 v44, v42, v43
	v_med3_f32 v38, v38, s6, v85
	v_med3_f32 v39, v39, s6, v85
	v_cvt_pk_fp8_f32 v42, v38, v39
	v_med3_f32 v34, v34, s6, v85
	v_med3_f32 v35, v35, s6, v85
	v_med3_f32 v40, v40, s6, v85
	v_med3_f32 v41, v41, s6, v85
	v_cvt_pk_fp8_f32 v42, v34, v35 op_sel:[0,0,1]
	v_cvt_pk_fp8_f32 v44, v40, v41 op_sel:[0,0,1]
	s_cmp_lg_u32 s11, 3
	global_store_dword v[36:37], v47, off offset:256
	global_store_dword v[36:37], v44, off offset:512
	global_store_dword v[36:37], v42, off offset:768
	s_cbranch_scc1 .LBB0_1809
	v_mov_b32_e32 v76, v78
	s_nop 0
	v_and_b32_e32 v34, 3, v76
	v_mul_u32_u24_e32 v34, 0x810, v34
	v_and_b32_e32 v35, -16, v76
	v_add3_u32 v77, s87, v34, v35
	v_and_b32_e32 v34, 15, v76
	v_mul_u32_u24_e32 v34, 0x810, v34
	v_add3_u32 v94, 0, v34, v35
	ds_read_b128 v[34:37], v77 offset:33024
	ds_read_b128 v[38:41], v94
	s_waitcnt lgkmcnt(0)
	v_mfma_f32_16x16x32_bf16 v[34:37], v[34:37], v[38:41], 0
	ds_read_b128 v[38:41], v77 offset:33088
	ds_read_b128 v[42:45], v94 offset:64
	v_cmp_gt_i32_e32 vcc, 16, v76
	s_waitcnt lgkmcnt(0)
	v_mfma_f32_16x16x32_bf16 v[38:41], v[38:41], v[42:45], 0
	ds_read_b128 v[42:45], v77 offset:33152
	ds_read_b128 v[46:49], v94 offset:128
	s_waitcnt lgkmcnt(0)
	v_mfma_f32_16x16x32_bf16 v[42:45], v[42:45], v[46:49], 0
	ds_read_b128 v[46:49], v77 offset:33216
	ds_read_b128 v[86:89], v94 offset:192
	s_waitcnt lgkmcnt(0)
	v_mfma_f32_16x16x32_bf16 v[46:49], v[46:49], v[86:89], 0
	ds_read_b128 v[86:89], v77 offset:33280
	ds_read_b128 v[90:93], v94 offset:256
	s_waitcnt lgkmcnt(0)
	v_mfma_f32_16x16x32_bf16 v[34:37], v[86:89], v[90:93], v[34:37]
	ds_read_b128 v[86:89], v77 offset:33344
	ds_read_b128 v[90:93], v94 offset:320
	s_waitcnt lgkmcnt(0)
	v_mfma_f32_16x16x32_bf16 v[38:41], v[86:89], v[90:93], v[38:41]
	ds_read_b128 v[86:89], v77 offset:33408
	ds_read_b128 v[90:93], v94 offset:384
	s_waitcnt lgkmcnt(0)
	v_mfma_f32_16x16x32_bf16 v[42:45], v[86:89], v[90:93], v[42:45]
	ds_read_b128 v[86:89], v77 offset:33472
	ds_read_b128 v[90:93], v94 offset:448
	s_waitcnt lgkmcnt(0)
	v_mfma_f32_16x16x32_bf16 v[46:49], v[86:89], v[90:93], v[46:49]
	ds_read_b128 v[86:89], v77 offset:33536
	ds_read_b128 v[90:93], v94 offset:512
	s_waitcnt lgkmcnt(0)
	v_mfma_f32_16x16x32_bf16 v[34:37], v[86:89], v[90:93], v[34:37]
	ds_read_b128 v[86:89], v77 offset:33600
	ds_read_b128 v[90:93], v94 offset:576
	s_waitcnt lgkmcnt(0)
	v_mfma_f32_16x16x32_bf16 v[38:41], v[86:89], v[90:93], v[38:41]
	ds_read_b128 v[86:89], v77 offset:33664
	ds_read_b128 v[90:93], v94 offset:640
	s_waitcnt lgkmcnt(0)
	v_mfma_f32_16x16x32_bf16 v[42:45], v[86:89], v[90:93], v[42:45]
	ds_read_b128 v[86:89], v77 offset:33728
	ds_read_b128 v[90:93], v94 offset:704
	s_waitcnt lgkmcnt(0)
	v_mfma_f32_16x16x32_bf16 v[46:49], v[86:89], v[90:93], v[46:49]
	ds_read_b128 v[86:89], v77 offset:33792
	ds_read_b128 v[90:93], v94 offset:768
	s_waitcnt lgkmcnt(0)
	v_mfma_f32_16x16x32_bf16 v[34:37], v[86:89], v[90:93], v[34:37]
	ds_read_b128 v[86:89], v77 offset:33856
	ds_read_b128 v[90:93], v94 offset:832
	s_waitcnt lgkmcnt(0)
	v_mfma_f32_16x16x32_bf16 v[38:41], v[86:89], v[90:93], v[38:41]
	ds_read_b128 v[86:89], v77 offset:33920
	ds_read_b128 v[90:93], v94 offset:896
	s_waitcnt lgkmcnt(0)
	v_mfma_f32_16x16x32_bf16 v[42:45], v[86:89], v[90:93], v[42:45]
	ds_read_b128 v[86:89], v77 offset:33984
	ds_read_b128 v[90:93], v94 offset:960
	s_waitcnt lgkmcnt(0)
	v_mfma_f32_16x16x32_bf16 v[46:49], v[86:89], v[90:93], v[46:49]
	ds_read_b128 v[86:89], v77 offset:34048
	ds_read_b128 v[90:93], v94 offset:1024
	s_waitcnt lgkmcnt(0)
	v_mfma_f32_16x16x32_bf16 v[34:37], v[86:89], v[90:93], v[34:37]
	ds_read_b128 v[86:89], v77 offset:34112
	ds_read_b128 v[90:93], v94 offset:1088
	s_waitcnt lgkmcnt(0)
	v_mfma_f32_16x16x32_bf16 v[38:41], v[86:89], v[90:93], v[38:41]
	ds_read_b128 v[86:89], v77 offset:34176
	ds_read_b128 v[90:93], v94 offset:1152
	s_waitcnt lgkmcnt(0)
	v_mfma_f32_16x16x32_bf16 v[42:45], v[86:89], v[90:93], v[42:45]
	ds_read_b128 v[86:89], v77 offset:34240
	ds_read_b128 v[90:93], v94 offset:1216
	s_waitcnt lgkmcnt(0)
	v_mfma_f32_16x16x32_bf16 v[46:49], v[86:89], v[90:93], v[46:49]
	ds_read_b128 v[86:89], v77 offset:34304
	ds_read_b128 v[90:93], v94 offset:1280
	s_waitcnt lgkmcnt(0)
	v_mfma_f32_16x16x32_bf16 v[34:37], v[86:89], v[90:93], v[34:37]
	ds_read_b128 v[86:89], v77 offset:34368
	ds_read_b128 v[90:93], v94 offset:1344
	s_waitcnt lgkmcnt(0)
	v_mfma_f32_16x16x32_bf16 v[38:41], v[86:89], v[90:93], v[38:41]
	ds_read_b128 v[86:89], v77 offset:34432
	ds_read_b128 v[90:93], v94 offset:1408
	s_waitcnt lgkmcnt(0)
	v_mfma_f32_16x16x32_bf16 v[42:45], v[86:89], v[90:93], v[42:45]
	ds_read_b128 v[86:89], v77 offset:34496
	ds_read_b128 v[90:93], v94 offset:1472
	s_waitcnt lgkmcnt(0)
	v_mfma_f32_16x16x32_bf16 v[46:49], v[86:89], v[90:93], v[46:49]
	ds_read_b128 v[86:89], v77 offset:34560
	ds_read_b128 v[90:93], v94 offset:1536
	s_waitcnt lgkmcnt(0)
	v_mfma_f32_16x16x32_bf16 v[34:37], v[86:89], v[90:93], v[34:37]
	ds_read_b128 v[86:89], v77 offset:34624
	ds_read_b128 v[90:93], v94 offset:1600
	s_waitcnt lgkmcnt(0)
	v_mfma_f32_16x16x32_bf16 v[38:41], v[86:89], v[90:93], v[38:41]
	ds_read_b128 v[86:89], v77 offset:34688
	ds_read_b128 v[90:93], v94 offset:1664
	s_waitcnt lgkmcnt(0)
	v_mfma_f32_16x16x32_bf16 v[42:45], v[86:89], v[90:93], v[42:45]
	ds_read_b128 v[86:89], v77 offset:34752
	ds_read_b128 v[90:93], v94 offset:1728
	s_waitcnt lgkmcnt(0)
	v_mfma_f32_16x16x32_bf16 v[46:49], v[86:89], v[90:93], v[46:49]
	ds_read_b128 v[86:89], v77 offset:34816
	ds_read_b128 v[90:93], v94 offset:1792
	s_waitcnt lgkmcnt(0)
	v_mfma_f32_16x16x32_bf16 v[34:37], v[86:89], v[90:93], v[34:37]
	ds_read_b128 v[86:89], v77 offset:34880
	ds_read_b128 v[90:93], v94 offset:1856
	s_waitcnt lgkmcnt(0)
	v_mfma_f32_16x16x32_bf16 v[38:41], v[86:89], v[90:93], v[38:41]
	ds_read_b128 v[86:89], v77 offset:34944
	ds_read_b128 v[90:93], v94 offset:1920
	s_waitcnt lgkmcnt(0)
	v_mfma_f32_16x16x32_bf16 v[42:45], v[86:89], v[90:93], v[42:45]
	ds_read_b128 v[86:89], v77 offset:35008
	ds_read_b128 v[90:93], v94 offset:1984
	s_nop 1
	v_pk_add_f32 v[34:35], v[34:35], v[38:39]
	v_ashrrev_i32_e32 v77, 31, v76
	s_waitcnt lgkmcnt(0)
	v_mfma_f32_16x16x32_bf16 v[46:49], v[86:89], v[90:93], v[46:49]
	s_nop 7
	v_pk_add_f32 v[38:39], v[42:43], v[46:47]
	s_nop 0
	v_pk_add_f32 v[38:39], v[34:35], v[38:39]
	v_lshlrev_b64 v[34:35], 13, v[76:77]
	v_lshl_add_u64 v[34:35], s[30:31], 0, v[34:35]
	v_mov_b32_dpp v42, v38 quad_perm:[1,0,3,2] row_mask:0xf bank_mask:0xf bound_ctrl:1
	v_max_f32_e32 v42, v42, v42
	v_max_f32_e32 v42, v38, v42
	s_nop 1
	v_mov_b32_dpp v43, v42 quad_perm:[2,3,0,1] row_mask:0xf bank_mask:0xf bound_ctrl:1
	v_max_f32_e32 v43, v43, v43
	v_max_f32_e32 v42, v42, v43
	s_nop 1
	v_mov_b32_dpp v43, v42 row_half_mirror row_mask:0xf bank_mask:0xf bound_ctrl:1
	v_max_f32_e32 v43, v43, v43
	v_max_f32_e32 v42, v42, v43
	s_nop 1
	v_mov_b32_dpp v43, v42 row_mirror row_mask:0xf bank_mask:0xf bound_ctrl:1
	v_max_f32_e32 v43, v43, v43
	v_max_f32_e32 v42, v42, v43
	v_sub_f32_e32 v38, v38, v42
	v_mul_f32_e32 v38, 0x3fb8aa3b, v38
	v_exp_f32_e32 v38, v38
	s_nop 1
	v_add_f32_dpp v42, v38, v38 quad_perm:[1,0,3,2] row_mask:0xf bank_mask:0xf bound_ctrl:1
	s_nop 1
	v_add_f32_dpp v42, v42, v42 quad_perm:[2,3,0,1] row_mask:0xf bank_mask:0xf bound_ctrl:1
	s_nop 1
	v_add_f32_dpp v42, v42, v42 row_half_mirror row_mask:0xf bank_mask:0xf bound_ctrl:1
	s_nop 1
	v_mov_b32_dpp v43, v42 row_mirror row_mask:0xf bank_mask:0xf bound_ctrl:1
	s_and_saveexec_b64 s[34:35], vcc
	s_cbranch_execz .LBB0_1813
	v_add_f32_e32 v42, v42, v43
	v_rcp_f32_e32 v42, v42
	s_sub_i32 s11, s22, 24
	s_ashr_i32 s0, s11, 11
	s_ashr_i32 s1, s0, 31
	s_and_b32 s11, s11, 0x7ff
	s_lshl_b64 s[0:1], s[0:1], 17
	v_mul_f32_e32 v38, v38, v42
	v_lshl_add_u64 v[42:43], v[34:35], 0, s[0:1]
	s_lshl_b32 s26, s11, 2
	v_lshl_add_u64 v[42:43], v[42:43], 0, s[26:27]
	global_store_dword v[42:43], v38, off

.Lpeel_exit_11:
	s_mov_b32 s98, 0x3b000000
	s_mov_b32 s99, 0xbcb8aa3b
	s_mov_b32 s100, 1.0
	v_pk_mul_f32 v[236:237], v[158:159], s[98:99] op_sel_hi:[1,0]
	v_pk_mul_f32 v[234:235], v[158:159], s[98:99] op_sel:[0,1] op_sel_hi:[1,1]
	v_exp_f32_e32 v234, v234
	v_exp_f32_e32 v235, v235
	s_nop 0
	v_pk_add_f32 v[234:235], v[234:235], s[100:101] op_sel_hi:[1,0]
	v_rcp_f32_e32 v234, v234
	v_rcp_f32_e32 v235, v235
	s_nop 0
	v_pk_mul_f32 v[236:237], v[236:237], v[234:235]
	v_pk_mul_f32 v[236:237], v[236:237], v[154:155]
	s_ashr_i32 s35, s34, 31
	s_ashr_i32 s31, s30, 31
	s_lshl_b64 s[14:15], s[34:35], 18
	s_lshl_b64 s[30:31], s[30:31], 15
	v_mov_b32_e32 v3, v195
	s_add_u32 s0, s6, s14
	v_med3_f32 v5, v236, s10, v190
	s_nop 15
	s_nop 15
	v_mov_b32_e32 v2, v196
	v_pk_mul_f32 v[238:239], v[160:161], s[98:99] op_sel_hi:[1,0]
	v_pk_mul_f32 v[234:235], v[160:161], s[98:99] op_sel:[0,1] op_sel_hi:[1,1]
	v_exp_f32_e32 v234, v234
	v_exp_f32_e32 v235, v235
	s_nop 0
	v_pk_add_f32 v[234:235], v[234:235], s[100:101] op_sel_hi:[1,0]
	v_rcp_f32_e32 v234, v234
	v_rcp_f32_e32 v235, v235
	s_nop 0
	v_pk_mul_f32 v[238:239], v[238:239], v[234:235]
	v_pk_mul_f32 v[238:239], v[238:239], v[156:157]
	v_add_u32_e32 v4, s49, v3
	s_addc_u32 s1, s7, s15
	s_add_u32 s14, s0, s30
	v_lshl_add_u32 v2, v2, 3, s50
	s_addc_u32 s15, s1, s31
	v_ashrrev_i32_e32 v3, 31, v2
	s_and_b64 vcc, exec, s[12:13]
	v_pk_mul_f32 v[240:241], v[150:151], s[98:99] op_sel_hi:[1,0]
	v_pk_mul_f32 v[234:235], v[150:151], s[98:99] op_sel:[0,1] op_sel_hi:[1,1]
	v_exp_f32_e32 v234, v234
	v_exp_f32_e32 v235, v235
	s_nop 0
	v_pk_add_f32 v[234:235], v[234:235], s[100:101] op_sel_hi:[1,0]
	v_rcp_f32_e32 v234, v234
	v_rcp_f32_e32 v235, v235
	s_nop 0
	v_pk_mul_f32 v[240:241], v[240:241], v[234:235]
	v_pk_mul_f32 v[240:241], v[240:241], v[146:147]
	v_mov_b32_e32 v174, v200
	v_mov_b32_e32 v172, v199
	v_mov_b32_e32 v170, v198
	v_mov_b32_e32 v168, v171
	s_mov_b32 s30, s28
	s_mov_b32 s34, s54
	s_mov_b64 s[36:37], s[16:17]
	v_pk_mul_f32 v[242:243], v[152:153], s[98:99] op_sel_hi:[1,0]
	v_pk_mul_f32 v[234:235], v[152:153], s[98:99] op_sel:[0,1] op_sel_hi:[1,1]
	v_exp_f32_e32 v234, v234
	v_exp_f32_e32 v235, v235
	s_nop 0
	v_pk_add_f32 v[234:235], v[234:235], s[100:101] op_sel_hi:[1,0]
	v_rcp_f32_e32 v234, v234
	v_rcp_f32_e32 v235, v235
	s_nop 0
	v_pk_mul_f32 v[242:243], v[242:243], v[234:235]
	v_pk_mul_f32 v[242:243], v[242:243], v[148:149]
	s_nop 0
	s_nop 0
	v_med3_f32 v13, v237, s10, v190
	v_cvt_pk_fp8_f32 v6, v5, v13
	v_med3_f32 v5, v238, s10, v190
	v_med3_f32 v7, v239, s10, v190
	v_med3_f32 v8, v241, s10, v190
	v_cvt_pk_fp8_f32 v6, v5, v7 op_sel:[0,0,1]
	v_med3_f32 v5, v240, s10, v190
	v_cvt_pk_fp8_f32 v7, v5, v8
	v_med3_f32 v5, v242, s10, v190
	v_med3_f32 v8, v243, s10, v190
	v_cvt_pk_fp8_f32 v7, v5, v8 op_sel:[0,0,1]
	v_ashrrev_i32_e32 v5, 31, v4
	v_lshlrev_b64 v[8:9], 7, v[4:5]
	v_lshl_add_u64 v[8:9], s[14:15], 0, v[8:9]
	v_lshl_add_u64 v[8:9], v[8:9], 0, v[2:3]
	v_pk_mul_f32 v[244:245], v[142:143], s[98:99] op_sel_hi:[1,0]
	v_pk_mul_f32 v[234:235], v[142:143], s[98:99] op_sel:[0,1] op_sel_hi:[1,1]
	v_exp_f32_e32 v234, v234
	v_exp_f32_e32 v235, v235
	s_nop 0
	v_pk_add_f32 v[234:235], v[234:235], s[100:101] op_sel_hi:[1,0]
	v_rcp_f32_e32 v234, v234
	v_rcp_f32_e32 v235, v235
	s_nop 0
	v_pk_mul_f32 v[244:245], v[244:245], v[234:235]
	v_pk_mul_f32 v[244:245], v[244:245], v[138:139]
	global_store_dwordx2 v[8:9], v[6:7], off
	s_nop 0
	s_nop 0
	v_med3_f32 v5, v244, s10, v190
	s_nop 0
	v_pk_mul_f32 v[246:247], v[144:145], s[98:99] op_sel_hi:[1,0]
	v_pk_mul_f32 v[234:235], v[144:145], s[98:99] op_sel:[0,1] op_sel_hi:[1,1]
	v_exp_f32_e32 v234, v234
	v_exp_f32_e32 v235, v235
	s_nop 0
	v_pk_add_f32 v[234:235], v[234:235], s[100:101] op_sel_hi:[1,0]
	v_rcp_f32_e32 v234, v234
	v_rcp_f32_e32 v235, v235
	s_nop 0
	v_pk_mul_f32 v[246:247], v[246:247], v[234:235]
	v_pk_mul_f32 v[246:247], v[246:247], v[140:141]
	v_med3_f32 v7, v245, s10, v190
	s_nop 0
	s_nop 0
	s_nop 0
	v_pk_mul_f32 v[248:249], v[134:135], s[98:99] op_sel_hi:[1,0]
	v_pk_mul_f32 v[234:235], v[134:135], s[98:99] op_sel:[0,1] op_sel_hi:[1,1]
	v_exp_f32_e32 v234, v234
	v_exp_f32_e32 v235, v235
	s_nop 0
	v_pk_add_f32 v[234:235], v[234:235], s[100:101] op_sel_hi:[1,0]
	v_rcp_f32_e32 v234, v234
	v_rcp_f32_e32 v235, v235
	s_nop 0
	v_pk_mul_f32 v[248:249], v[248:249], v[234:235]
	v_pk_mul_f32 v[248:249], v[248:249], v[130:131]
	s_nop 0
	s_nop 0
	s_nop 0
	s_nop 0
	v_pk_mul_f32 v[250:251], v[136:137], s[98:99] op_sel_hi:[1,0]
	v_pk_mul_f32 v[234:235], v[136:137], s[98:99] op_sel:[0,1] op_sel_hi:[1,1]
	v_exp_f32_e32 v234, v234
	v_exp_f32_e32 v235, v235
	s_nop 0
	v_pk_add_f32 v[234:235], v[234:235], s[100:101] op_sel_hi:[1,0]
	v_rcp_f32_e32 v234, v234
	v_rcp_f32_e32 v235, v235
	s_nop 0
	v_pk_mul_f32 v[250:251], v[250:251], v[234:235]
	v_pk_mul_f32 v[250:251], v[250:251], v[132:133]
	s_nop 0
	s_nop 0
	s_nop 0
	s_nop 0
	v_cvt_pk_fp8_f32 v8, v5, v7
	v_med3_f32 v5, v246, s10, v190
	v_med3_f32 v7, v247, s10, v190
	v_cvt_pk_fp8_f32 v8, v5, v7 op_sel:[0,0,1]
	v_med3_f32 v5, v248, s10, v190
	v_med3_f32 v7, v249, s10, v190
	v_cvt_pk_fp8_f32 v9, v5, v7
	v_add_u32_e32 v6, 16, v4
	v_med3_f32 v5, v250, s10, v190
	v_med3_f32 v7, v251, s10, v190
	v_cvt_pk_fp8_f32 v9, v5, v7 op_sel:[0,0,1]
	v_ashrrev_i32_e32 v7, 31, v6
	v_lshlrev_b64 v[6:7], 7, v[6:7]
	v_lshl_add_u64 v[6:7], s[14:15], 0, v[6:7]
	v_lshl_add_u64 v[6:7], v[6:7], 0, v[2:3]
	v_pk_mul_f32 v[236:237], v[126:127], s[98:99] op_sel_hi:[1,0]
	v_pk_mul_f32 v[234:235], v[126:127], s[98:99] op_sel:[0,1] op_sel_hi:[1,1]
	v_exp_f32_e32 v234, v234
	v_exp_f32_e32 v235, v235
	s_nop 0
	v_pk_add_f32 v[234:235], v[234:235], s[100:101] op_sel_hi:[1,0]
	v_rcp_f32_e32 v234, v234
	v_rcp_f32_e32 v235, v235
	s_nop 0
	v_pk_mul_f32 v[236:237], v[236:237], v[234:235]
	v_pk_mul_f32 v[236:237], v[236:237], v[122:123]
	global_store_dwordx2 v[6:7], v[8:9], off
	s_nop 0
	s_nop 0
	v_med3_f32 v5, v236, s10, v190
	s_nop 0
	v_pk_mul_f32 v[238:239], v[128:129], s[98:99] op_sel_hi:[1,0]
	v_pk_mul_f32 v[234:235], v[128:129], s[98:99] op_sel:[0,1] op_sel_hi:[1,1]
	v_exp_f32_e32 v234, v234
	v_exp_f32_e32 v235, v235
	s_nop 0
	v_pk_add_f32 v[234:235], v[234:235], s[100:101] op_sel_hi:[1,0]
	v_rcp_f32_e32 v234, v234
	v_rcp_f32_e32 v235, v235
	s_nop 0
	v_pk_mul_f32 v[238:239], v[238:239], v[234:235]
	v_pk_mul_f32 v[238:239], v[238:239], v[124:125]
	v_med3_f32 v7, v237, s10, v190
	s_nop 0
	s_nop 0
	s_nop 0
	v_pk_mul_f32 v[240:241], v[118:119], s[98:99] op_sel_hi:[1,0]
	v_pk_mul_f32 v[234:235], v[118:119], s[98:99] op_sel:[0,1] op_sel_hi:[1,1]
	v_exp_f32_e32 v234, v234
	v_exp_f32_e32 v235, v235
	s_nop 0
	v_pk_add_f32 v[234:235], v[234:235], s[100:101] op_sel_hi:[1,0]
	v_rcp_f32_e32 v234, v234
	v_rcp_f32_e32 v235, v235
	s_nop 0
	v_pk_mul_f32 v[240:241], v[240:241], v[234:235]
	v_pk_mul_f32 v[240:241], v[240:241], v[114:115]
	s_nop 0
	s_nop 0
	s_nop 0
	s_nop 0
	v_pk_mul_f32 v[242:243], v[120:121], s[98:99] op_sel_hi:[1,0]
	v_pk_mul_f32 v[234:235], v[120:121], s[98:99] op_sel:[0,1] op_sel_hi:[1,1]
	v_exp_f32_e32 v234, v234
	v_exp_f32_e32 v235, v235
	s_nop 0
	v_pk_add_f32 v[234:235], v[234:235], s[100:101] op_sel_hi:[1,0]
	v_rcp_f32_e32 v234, v234
	v_rcp_f32_e32 v235, v235
	s_nop 0
	v_pk_mul_f32 v[242:243], v[242:243], v[234:235]
	v_pk_mul_f32 v[242:243], v[242:243], v[116:117]
	s_nop 0
	s_nop 0
	s_nop 0
	s_nop 0
	v_cvt_pk_fp8_f32 v8, v5, v7
	v_med3_f32 v5, v238, s10, v190
	v_med3_f32 v7, v239, s10, v190
	v_cvt_pk_fp8_f32 v8, v5, v7 op_sel:[0,0,1]
	v_med3_f32 v5, v240, s10, v190
	v_med3_f32 v7, v241, s10, v190
	v_cvt_pk_fp8_f32 v9, v5, v7
	v_add_u32_e32 v6, 32, v4
	v_med3_f32 v5, v242, s10, v190
	v_med3_f32 v7, v243, s10, v190
	v_cvt_pk_fp8_f32 v9, v5, v7 op_sel:[0,0,1]
	v_ashrrev_i32_e32 v7, 31, v6
	v_lshlrev_b64 v[6:7], 7, v[6:7]
	v_lshl_add_u64 v[6:7], s[14:15], 0, v[6:7]
	v_lshl_add_u64 v[6:7], v[6:7], 0, v[2:3]
	v_pk_mul_f32 v[244:245], v[110:111], s[98:99] op_sel_hi:[1,0]
	v_pk_mul_f32 v[234:235], v[110:111], s[98:99] op_sel:[0,1] op_sel_hi:[1,1]
	v_exp_f32_e32 v234, v234
	v_exp_f32_e32 v235, v235
	s_nop 0
	v_pk_add_f32 v[234:235], v[234:235], s[100:101] op_sel_hi:[1,0]
	v_rcp_f32_e32 v234, v234
	v_rcp_f32_e32 v235, v235
	s_nop 0
	v_pk_mul_f32 v[244:245], v[244:245], v[234:235]
	v_pk_mul_f32 v[244:245], v[244:245], v[106:107]
	global_store_dwordx2 v[6:7], v[8:9], off
	s_nop 0
	s_nop 0
	v_med3_f32 v5, v244, s10, v190
	s_nop 0
	v_pk_mul_f32 v[246:247], v[112:113], s[98:99] op_sel_hi:[1,0]
	v_pk_mul_f32 v[234:235], v[112:113], s[98:99] op_sel:[0,1] op_sel_hi:[1,1]
	v_exp_f32_e32 v234, v234
	v_exp_f32_e32 v235, v235
	s_nop 0
	v_pk_add_f32 v[234:235], v[234:235], s[100:101] op_sel_hi:[1,0]
	v_rcp_f32_e32 v234, v234
	v_rcp_f32_e32 v235, v235
	s_nop 0
	v_pk_mul_f32 v[246:247], v[246:247], v[234:235]
	v_pk_mul_f32 v[246:247], v[246:247], v[108:109]
	v_med3_f32 v7, v245, s10, v190
	s_nop 0
	s_nop 0
	s_nop 0
	v_pk_mul_f32 v[248:249], v[102:103], s[98:99] op_sel_hi:[1,0]
	v_pk_mul_f32 v[234:235], v[102:103], s[98:99] op_sel:[0,1] op_sel_hi:[1,1]
	v_exp_f32_e32 v234, v234
	v_exp_f32_e32 v235, v235
	s_nop 0
	v_pk_add_f32 v[234:235], v[234:235], s[100:101] op_sel_hi:[1,0]
	v_rcp_f32_e32 v234, v234
	v_rcp_f32_e32 v235, v235
	s_nop 0
	v_pk_mul_f32 v[248:249], v[248:249], v[234:235]
	v_pk_mul_f32 v[248:249], v[248:249], v[98:99]
	s_nop 0
	s_nop 0
	s_nop 0
	s_nop 0
	v_pk_mul_f32 v[250:251], v[104:105], s[98:99] op_sel_hi:[1,0]
	v_pk_mul_f32 v[234:235], v[104:105], s[98:99] op_sel:[0,1] op_sel_hi:[1,1]
	v_exp_f32_e32 v234, v234
	v_exp_f32_e32 v235, v235
	s_nop 0
	v_pk_add_f32 v[234:235], v[234:235], s[100:101] op_sel_hi:[1,0]
	v_rcp_f32_e32 v234, v234
	v_rcp_f32_e32 v235, v235
	s_nop 0
	v_pk_mul_f32 v[250:251], v[250:251], v[234:235]
	v_pk_mul_f32 v[250:251], v[250:251], v[100:101]
	s_nop 0
	s_nop 0
	s_nop 0
	s_nop 0
	v_cvt_pk_fp8_f32 v8, v5, v7
	v_med3_f32 v5, v246, s10, v190
	v_med3_f32 v7, v247, s10, v190
	v_cvt_pk_fp8_f32 v8, v5, v7 op_sel:[0,0,1]
	v_med3_f32 v5, v248, s10, v190
	v_med3_f32 v7, v249, s10, v190
	v_cvt_pk_fp8_f32 v9, v5, v7
	v_add_u32_e32 v6, 48, v4
	v_med3_f32 v5, v250, s10, v190
	v_med3_f32 v7, v251, s10, v190
	v_cvt_pk_fp8_f32 v9, v5, v7 op_sel:[0,0,1]
	v_ashrrev_i32_e32 v7, 31, v6
	v_lshlrev_b64 v[6:7], 7, v[6:7]
	v_lshl_add_u64 v[6:7], s[14:15], 0, v[6:7]
	v_lshl_add_u64 v[6:7], v[6:7], 0, v[2:3]
	v_pk_mul_f32 v[236:237], v[94:95], s[98:99] op_sel_hi:[1,0]
	v_pk_mul_f32 v[234:235], v[94:95], s[98:99] op_sel:[0,1] op_sel_hi:[1,1]
	v_exp_f32_e32 v234, v234
	v_exp_f32_e32 v235, v235
	s_nop 0
	v_pk_add_f32 v[234:235], v[234:235], s[100:101] op_sel_hi:[1,0]
	v_rcp_f32_e32 v234, v234
	v_rcp_f32_e32 v235, v235
	s_nop 0
	v_pk_mul_f32 v[236:237], v[236:237], v[234:235]
	v_pk_mul_f32 v[236:237], v[236:237], v[90:91]
	global_store_dwordx2 v[6:7], v[8:9], off
	v_add_u32_e32 v6, 0x80, v4
	s_nop 0
	v_med3_f32 v5, v236, s10, v190
	s_nop 0
	v_pk_mul_f32 v[238:239], v[96:97], s[98:99] op_sel_hi:[1,0]
	v_pk_mul_f32 v[234:235], v[96:97], s[98:99] op_sel:[0,1] op_sel_hi:[1,1]
	v_exp_f32_e32 v234, v234
	v_exp_f32_e32 v235, v235
	s_nop 0
	v_pk_add_f32 v[234:235], v[234:235], s[100:101] op_sel_hi:[1,0]
	v_rcp_f32_e32 v234, v234
	v_rcp_f32_e32 v235, v235
	s_nop 0
	v_pk_mul_f32 v[238:239], v[238:239], v[234:235]
	v_pk_mul_f32 v[238:239], v[238:239], v[92:93]
	v_med3_f32 v7, v237, s10, v190
	s_nop 0
	s_nop 0
	s_nop 0
	v_pk_mul_f32 v[240:241], v[86:87], s[98:99] op_sel_hi:[1,0]
	v_pk_mul_f32 v[234:235], v[86:87], s[98:99] op_sel:[0,1] op_sel_hi:[1,1]
	v_exp_f32_e32 v234, v234
	v_exp_f32_e32 v235, v235
	s_nop 0
	v_pk_add_f32 v[234:235], v[234:235], s[100:101] op_sel_hi:[1,0]
	v_rcp_f32_e32 v234, v234
	v_rcp_f32_e32 v235, v235
	s_nop 0
	v_pk_mul_f32 v[240:241], v[240:241], v[234:235]
	v_pk_mul_f32 v[240:241], v[240:241], v[82:83]
	s_nop 0
	s_nop 0
	s_nop 0
	s_nop 0
	v_pk_mul_f32 v[242:243], v[88:89], s[98:99] op_sel_hi:[1,0]
	v_pk_mul_f32 v[234:235], v[88:89], s[98:99] op_sel:[0,1] op_sel_hi:[1,1]
	v_exp_f32_e32 v234, v234
	v_exp_f32_e32 v235, v235
	s_nop 0
	v_pk_add_f32 v[234:235], v[234:235], s[100:101] op_sel_hi:[1,0]
	v_rcp_f32_e32 v234, v234
	v_rcp_f32_e32 v235, v235
	s_nop 0
	v_pk_mul_f32 v[242:243], v[242:243], v[234:235]
	v_pk_mul_f32 v[242:243], v[242:243], v[84:85]
	s_nop 0
	s_nop 0
	s_nop 0
	s_nop 0
	v_cvt_pk_fp8_f32 v8, v5, v7
	v_med3_f32 v5, v238, s10, v190
	v_med3_f32 v7, v239, s10, v190
	v_cvt_pk_fp8_f32 v8, v5, v7 op_sel:[0,0,1]
	v_med3_f32 v5, v240, s10, v190
	v_med3_f32 v7, v241, s10, v190
	v_cvt_pk_fp8_f32 v9, v5, v7
	v_med3_f32 v5, v242, s10, v190
	v_med3_f32 v7, v243, s10, v190
	v_cvt_pk_fp8_f32 v9, v5, v7 op_sel:[0,0,1]
	v_ashrrev_i32_e32 v7, 31, v6
	v_lshlrev_b64 v[6:7], 7, v[6:7]
	v_lshl_add_u64 v[6:7], s[14:15], 0, v[6:7]
	v_lshl_add_u64 v[6:7], v[6:7], 0, v[2:3]
	v_pk_mul_f32 v[244:245], v[78:79], s[98:99] op_sel_hi:[1,0]
	v_pk_mul_f32 v[234:235], v[78:79], s[98:99] op_sel:[0,1] op_sel_hi:[1,1]
	v_exp_f32_e32 v234, v234
	v_exp_f32_e32 v235, v235
	s_nop 0
	v_pk_add_f32 v[234:235], v[234:235], s[100:101] op_sel_hi:[1,0]
	v_rcp_f32_e32 v234, v234
	v_rcp_f32_e32 v235, v235
	s_nop 0
	v_pk_mul_f32 v[244:245], v[244:245], v[234:235]
	v_pk_mul_f32 v[244:245], v[244:245], v[74:75]
	global_store_dwordx2 v[6:7], v[8:9], off
	s_nop 0
	s_nop 0
	v_med3_f32 v5, v244, s10, v190
	s_nop 0
	v_pk_mul_f32 v[246:247], v[80:81], s[98:99] op_sel_hi:[1,0]
	v_pk_mul_f32 v[234:235], v[80:81], s[98:99] op_sel:[0,1] op_sel_hi:[1,1]
	v_exp_f32_e32 v234, v234
	v_exp_f32_e32 v235, v235
	s_nop 0
	v_pk_add_f32 v[234:235], v[234:235], s[100:101] op_sel_hi:[1,0]
	v_rcp_f32_e32 v234, v234
	v_rcp_f32_e32 v235, v235
	s_nop 0
	v_pk_mul_f32 v[246:247], v[246:247], v[234:235]
	v_pk_mul_f32 v[246:247], v[246:247], v[76:77]
	v_med3_f32 v7, v245, s10, v190
	s_nop 0
	s_nop 0
	s_nop 0
	v_pk_mul_f32 v[248:249], v[70:71], s[98:99] op_sel_hi:[1,0]
	v_pk_mul_f32 v[234:235], v[70:71], s[98:99] op_sel:[0,1] op_sel_hi:[1,1]
	v_exp_f32_e32 v234, v234
	v_exp_f32_e32 v235, v235
	s_nop 0
	v_pk_add_f32 v[234:235], v[234:235], s[100:101] op_sel_hi:[1,0]
	v_rcp_f32_e32 v234, v234
	v_rcp_f32_e32 v235, v235
	s_nop 0
	v_pk_mul_f32 v[248:249], v[248:249], v[234:235]
	v_pk_mul_f32 v[248:249], v[248:249], v[66:67]
	s_nop 0
	s_nop 0
	s_nop 0
	s_nop 0
	v_pk_mul_f32 v[250:251], v[72:73], s[98:99] op_sel_hi:[1,0]
	v_pk_mul_f32 v[234:235], v[72:73], s[98:99] op_sel:[0,1] op_sel_hi:[1,1]
	v_exp_f32_e32 v234, v234
	v_exp_f32_e32 v235, v235
	s_nop 0
	v_pk_add_f32 v[234:235], v[234:235], s[100:101] op_sel_hi:[1,0]
	v_rcp_f32_e32 v234, v234
	v_rcp_f32_e32 v235, v235
	s_nop 0
	v_pk_mul_f32 v[250:251], v[250:251], v[234:235]
	v_pk_mul_f32 v[250:251], v[250:251], v[68:69]
	s_nop 0
	s_nop 0
	s_nop 0
	s_nop 0
	v_cvt_pk_fp8_f32 v8, v5, v7
	v_med3_f32 v5, v246, s10, v190
	v_med3_f32 v7, v247, s10, v190
	v_cvt_pk_fp8_f32 v8, v5, v7 op_sel:[0,0,1]
	v_med3_f32 v5, v248, s10, v190
	v_med3_f32 v7, v249, s10, v190
	v_cvt_pk_fp8_f32 v9, v5, v7
	v_add_u32_e32 v6, 0x90, v4
	v_med3_f32 v5, v250, s10, v190
	v_med3_f32 v7, v251, s10, v190
	v_cvt_pk_fp8_f32 v9, v5, v7 op_sel:[0,0,1]
	v_ashrrev_i32_e32 v7, 31, v6
	v_lshlrev_b64 v[6:7], 7, v[6:7]
	v_lshl_add_u64 v[6:7], s[14:15], 0, v[6:7]
	v_lshl_add_u64 v[6:7], v[6:7], 0, v[2:3]
	v_pk_mul_f32 v[236:237], v[62:63], s[98:99] op_sel_hi:[1,0]
	v_pk_mul_f32 v[234:235], v[62:63], s[98:99] op_sel:[0,1] op_sel_hi:[1,1]
	v_exp_f32_e32 v234, v234
	v_exp_f32_e32 v235, v235
	s_nop 0
	v_pk_add_f32 v[234:235], v[234:235], s[100:101] op_sel_hi:[1,0]
	v_rcp_f32_e32 v234, v234
	v_rcp_f32_e32 v235, v235
	s_nop 0
	v_pk_mul_f32 v[236:237], v[236:237], v[234:235]
	v_pk_mul_f32 v[236:237], v[236:237], v[58:59]
	global_store_dwordx2 v[6:7], v[8:9], off
	s_nop 0
	s_nop 0
	v_med3_f32 v5, v236, s10, v190
	s_nop 0
	v_pk_mul_f32 v[238:239], v[64:65], s[98:99] op_sel_hi:[1,0]
	v_pk_mul_f32 v[234:235], v[64:65], s[98:99] op_sel:[0,1] op_sel_hi:[1,1]
	v_exp_f32_e32 v234, v234
	v_exp_f32_e32 v235, v235
	s_nop 0
	v_pk_add_f32 v[234:235], v[234:235], s[100:101] op_sel_hi:[1,0]
	v_rcp_f32_e32 v234, v234
	v_rcp_f32_e32 v235, v235
	s_nop 0
	v_pk_mul_f32 v[238:239], v[238:239], v[234:235]
	v_pk_mul_f32 v[238:239], v[238:239], v[60:61]
	v_med3_f32 v7, v237, s10, v190
	s_nop 0
	s_nop 0
	s_nop 0
	v_pk_mul_f32 v[240:241], v[54:55], s[98:99] op_sel_hi:[1,0]
	v_pk_mul_f32 v[234:235], v[54:55], s[98:99] op_sel:[0,1] op_sel_hi:[1,1]
	v_exp_f32_e32 v234, v234
	v_exp_f32_e32 v235, v235
	s_nop 0
	v_pk_add_f32 v[234:235], v[234:235], s[100:101] op_sel_hi:[1,0]
	v_rcp_f32_e32 v234, v234
	v_rcp_f32_e32 v235, v235
	s_nop 0
	v_pk_mul_f32 v[240:241], v[240:241], v[234:235]
	v_pk_mul_f32 v[240:241], v[240:241], v[50:51]
	s_nop 0
	s_nop 0
	s_nop 0
	s_nop 0
	v_pk_mul_f32 v[242:243], v[56:57], s[98:99] op_sel_hi:[1,0]
	v_pk_mul_f32 v[234:235], v[56:57], s[98:99] op_sel:[0,1] op_sel_hi:[1,1]
	v_exp_f32_e32 v234, v234
	v_exp_f32_e32 v235, v235
	s_nop 0
	v_pk_add_f32 v[234:235], v[234:235], s[100:101] op_sel_hi:[1,0]
	v_rcp_f32_e32 v234, v234
	v_rcp_f32_e32 v235, v235
	s_nop 0
	v_pk_mul_f32 v[242:243], v[242:243], v[234:235]
	v_pk_mul_f32 v[242:243], v[242:243], v[52:53]
	s_nop 0
	s_nop 0
	s_nop 0
	s_nop 0
	v_cvt_pk_fp8_f32 v8, v5, v7
	v_med3_f32 v5, v238, s10, v190
	v_med3_f32 v7, v239, s10, v190
	v_cvt_pk_fp8_f32 v8, v5, v7 op_sel:[0,0,1]
	v_med3_f32 v5, v240, s10, v190
	v_med3_f32 v7, v241, s10, v190
	v_cvt_pk_fp8_f32 v9, v5, v7
	v_add_u32_e32 v6, 0xa0, v4
	v_med3_f32 v5, v242, s10, v190
	v_med3_f32 v7, v243, s10, v190
	v_cvt_pk_fp8_f32 v9, v5, v7 op_sel:[0,0,1]
	v_ashrrev_i32_e32 v7, 31, v6
	v_lshlrev_b64 v[6:7], 7, v[6:7]
	v_lshl_add_u64 v[6:7], s[14:15], 0, v[6:7]
	v_lshl_add_u64 v[6:7], v[6:7], 0, v[2:3]
	v_pk_mul_f32 v[244:245], v[46:47], s[98:99] op_sel_hi:[1,0]
	v_pk_mul_f32 v[234:235], v[46:47], s[98:99] op_sel:[0,1] op_sel_hi:[1,1]
	v_exp_f32_e32 v234, v234
	v_exp_f32_e32 v235, v235
	s_nop 0
	v_pk_add_f32 v[234:235], v[234:235], s[100:101] op_sel_hi:[1,0]
	v_rcp_f32_e32 v234, v234
	v_rcp_f32_e32 v235, v235
	s_nop 0
	v_pk_mul_f32 v[244:245], v[244:245], v[234:235]
	v_pk_mul_f32 v[244:245], v[244:245], v[42:43]
	global_store_dwordx2 v[6:7], v[8:9], off
	v_add_u32_e32 v4, 0xb0, v4
	s_nop 0
	v_med3_f32 v5, v244, s10, v190
	s_nop 0
	v_pk_mul_f32 v[246:247], v[48:49], s[98:99] op_sel_hi:[1,0]
	v_pk_mul_f32 v[234:235], v[48:49], s[98:99] op_sel:[0,1] op_sel_hi:[1,1]
	v_exp_f32_e32 v234, v234
	v_exp_f32_e32 v235, v235
	s_nop 0
	v_pk_add_f32 v[234:235], v[234:235], s[100:101] op_sel_hi:[1,0]
	v_rcp_f32_e32 v234, v234
	v_rcp_f32_e32 v235, v235
	s_nop 0
	v_pk_mul_f32 v[246:247], v[246:247], v[234:235]
	v_pk_mul_f32 v[246:247], v[246:247], v[44:45]
	s_nop 0
	s_nop 0
	v_pk_mul_f32 v[248:249], v[38:39], s[98:99] op_sel_hi:[1,0]
	v_pk_mul_f32 v[234:235], v[38:39], s[98:99] op_sel:[0,1] op_sel_hi:[1,1]
	v_exp_f32_e32 v234, v234
	v_exp_f32_e32 v235, v235
	s_nop 0
	v_pk_add_f32 v[234:235], v[234:235], s[100:101] op_sel_hi:[1,0]
	v_rcp_f32_e32 v234, v234
	v_rcp_f32_e32 v235, v235
	s_nop 0
	v_pk_mul_f32 v[248:249], v[248:249], v[234:235]
	v_pk_mul_f32 v[248:249], v[248:249], v[34:35]
	s_nop 0
	s_nop 0
	v_pk_mul_f32 v[250:251], v[40:41], s[98:99] op_sel_hi:[1,0]
	v_pk_mul_f32 v[234:235], v[40:41], s[98:99] op_sel:[0,1] op_sel_hi:[1,1]
	v_exp_f32_e32 v234, v234
	v_exp_f32_e32 v235, v235
	s_nop 0
	v_pk_add_f32 v[234:235], v[234:235], s[100:101] op_sel_hi:[1,0]
	v_rcp_f32_e32 v234, v234
	v_rcp_f32_e32 v235, v235
	s_nop 0
	v_pk_mul_f32 v[250:251], v[250:251], v[234:235]
	v_pk_mul_f32 v[250:251], v[250:251], v[36:37]
	s_nop 0
	s_nop 0
	v_med3_f32 v13, v245, s10, v190
	v_cvt_pk_fp8_f32 v6, v5, v13
	v_med3_f32 v5, v246, s10, v190
	v_med3_f32 v7, v247, s10, v190
	v_med3_f32 v8, v249, s10, v190
	v_cvt_pk_fp8_f32 v6, v5, v7 op_sel:[0,0,1]
	v_med3_f32 v5, v248, s10, v190
	v_cvt_pk_fp8_f32 v7, v5, v8
	v_med3_f32 v5, v250, s10, v190
	v_med3_f32 v8, v251, s10, v190
	v_cvt_pk_fp8_f32 v7, v5, v8 op_sel:[0,0,1]
	v_ashrrev_i32_e32 v5, 31, v4
	v_lshlrev_b64 v[4:5], 7, v[4:5]
	v_lshl_add_u64 v[4:5], s[14:15], 0, v[4:5]
	v_lshl_add_u64 v[2:3], v[4:5], 0, v[2:3]
	global_store_dwordx2 v[2:3], v[6:7], off
	s_cbranch_vccz .LBB0_2030
	s_waitcnt vmcnt(0)
	s_cmpk_gt_u32 s42, 0xff
	s_cbranch_scc1 .LBB0_1976
	s_barrier
	s_branch .LBB0_1976

.Lpeel_exit_12:
	v_pk_mul_f32 v[10:11], v[142:143], s[18:19] op_sel_hi:[1,0]
	v_pk_mul_f32 v[8:9], v[144:145], s[18:19] op_sel_hi:[1,0]
	v_med3_f32 v5, v10, s47, v173
	v_med3_f32 v11, v11, s47, v173
	v_cvt_pk_fp8_f32 v10, v5, v11
	v_mov_b32_e32 v3, v166
	v_mov_b32_e32 v2, v167
	s_lshl_b32 s0, s48, 8
	v_pk_mul_f32 v[14:15], v[138:139], s[18:19] op_sel_hi:[1,0]
	v_med3_f32 v5, v8, s47, v173
	v_med3_f32 v8, v9, s47, v173
	s_nop 15
	s_nop 15
	s_or_b32 s0, s0, s42
	v_cvt_pk_fp8_f32 v10, v5, v8 op_sel:[0,0,1]
	v_med3_f32 v5, v14, s47, v173
	v_med3_f32 v8, v15, s47, v173
	v_lshl_add_u32 v2, v2, 3, s0
	s_lshl_b32 s0, s28, 8
	v_cvt_pk_fp8_f32 v11, v5, v8
	s_add_i32 s0, s0, s41
	v_add_u32_e32 v4, s0, v3
	v_pk_mul_f32 v[12:13], v[140:141], s[18:19] op_sel_hi:[1,0]
	v_mov_b32_e32 v6, v4
	v_med3_f32 v5, v12, s47, v173
	v_med3_f32 v8, v13, s47, v173
	v_cvt_pk_fp8_f32 v11, v5, v8 op_sel:[0,0,1]
	v_ashrrev_i32_e32 v7, 31, v6
	v_lshlrev_b64 v[6:7], 10, v[6:7]
	v_ashrrev_i32_e32 v3, 31, v2
	v_lshl_add_u64 v[6:7], s[14:15], 0, v[6:7]
	v_lshl_add_u64 v[6:7], v[6:7], 0, v[2:3]
	global_store_dwordx2 v[6:7], v[10:11], off
	v_pk_mul_f32 v[10:11], v[134:135], s[18:19] op_sel_hi:[1,0]
	v_pk_mul_f32 v[8:9], v[136:137], s[18:19] op_sel_hi:[1,0]
	v_med3_f32 v5, v10, s47, v173
	v_med3_f32 v11, v11, s47, v173
	v_cvt_pk_fp8_f32 v10, v5, v11
	v_pk_mul_f32 v[14:15], v[130:131], s[18:19] op_sel_hi:[1,0]
	v_med3_f32 v5, v8, s47, v173
	v_med3_f32 v8, v9, s47, v173
	v_cvt_pk_fp8_f32 v10, v5, v8 op_sel:[0,0,1]
	v_med3_f32 v5, v14, s47, v173
	v_med3_f32 v8, v15, s47, v173
	v_cvt_pk_fp8_f32 v11, v5, v8
	v_pk_mul_f32 v[12:13], v[132:133], s[18:19] op_sel_hi:[1,0]
	v_pk_mul_f32 v[14:15], v[122:123], s[18:19] op_sel_hi:[1,0]
	v_med3_f32 v5, v12, s47, v173
	v_med3_f32 v8, v13, s47, v173
	v_cvt_pk_fp8_f32 v11, v5, v8 op_sel:[0,0,1]
	v_pk_mul_f32 v[8:9], v[128:129], s[18:19] op_sel_hi:[1,0]
	v_pk_mul_f32 v[12:13], v[124:125], s[18:19] op_sel_hi:[1,0]
	s_and_b64 vcc, exec, s[12:13]
	global_store_dwordx2 v[6:7], v[10:11], off offset:128
	v_pk_mul_f32 v[10:11], v[126:127], s[18:19] op_sel_hi:[1,0]
	v_add_u32_e32 v6, 16, v4
	v_med3_f32 v5, v10, s47, v173
	v_med3_f32 v11, v11, s47, v173
	v_cvt_pk_fp8_f32 v10, v5, v11
	v_med3_f32 v5, v8, s47, v173
	v_med3_f32 v8, v9, s47, v173
	v_cvt_pk_fp8_f32 v10, v5, v8 op_sel:[0,0,1]
	v_med3_f32 v5, v14, s47, v173
	v_med3_f32 v8, v15, s47, v173
	v_cvt_pk_fp8_f32 v11, v5, v8
	v_med3_f32 v5, v12, s47, v173
	v_med3_f32 v8, v13, s47, v173
	v_cvt_pk_fp8_f32 v11, v5, v8 op_sel:[0,0,1]
	v_ashrrev_i32_e32 v7, 31, v6
	v_lshlrev_b64 v[6:7], 10, v[6:7]
	v_lshl_add_u64 v[6:7], s[14:15], 0, v[6:7]
	v_lshl_add_u64 v[6:7], v[6:7], 0, v[2:3]
	global_store_dwordx2 v[6:7], v[10:11], off
	v_pk_mul_f32 v[10:11], v[118:119], s[18:19] op_sel_hi:[1,0]
	v_pk_mul_f32 v[8:9], v[120:121], s[18:19] op_sel_hi:[1,0]
	v_med3_f32 v5, v10, s47, v173
	v_med3_f32 v11, v11, s47, v173
	v_cvt_pk_fp8_f32 v10, v5, v11
	v_pk_mul_f32 v[14:15], v[114:115], s[18:19] op_sel_hi:[1,0]
	v_med3_f32 v5, v8, s47, v173
	v_med3_f32 v8, v9, s47, v173
	v_cvt_pk_fp8_f32 v10, v5, v8 op_sel:[0,0,1]
	v_med3_f32 v5, v14, s47, v173
	v_med3_f32 v8, v15, s47, v173
	v_cvt_pk_fp8_f32 v11, v5, v8
	v_pk_mul_f32 v[12:13], v[116:117], s[18:19] op_sel_hi:[1,0]
	v_pk_mul_f32 v[14:15], v[106:107], s[18:19] op_sel_hi:[1,0]
	v_med3_f32 v5, v12, s47, v173
	v_med3_f32 v8, v13, s47, v173
	v_cvt_pk_fp8_f32 v11, v5, v8 op_sel:[0,0,1]
	v_pk_mul_f32 v[8:9], v[112:113], s[18:19] op_sel_hi:[1,0]
	v_pk_mul_f32 v[12:13], v[108:109], s[18:19] op_sel_hi:[1,0]
	s_mov_b32 s48, s20
	global_store_dwordx2 v[6:7], v[10:11], off offset:128
	v_pk_mul_f32 v[10:11], v[110:111], s[18:19] op_sel_hi:[1,0]
	v_add_u32_e32 v6, 32, v4
	v_med3_f32 v5, v10, s47, v173
	v_med3_f32 v11, v11, s47, v173
	v_cvt_pk_fp8_f32 v10, v5, v11
	v_med3_f32 v5, v8, s47, v173
	v_med3_f32 v8, v9, s47, v173
	v_cvt_pk_fp8_f32 v10, v5, v8 op_sel:[0,0,1]
	v_med3_f32 v5, v14, s47, v173
	v_med3_f32 v8, v15, s47, v173
	v_cvt_pk_fp8_f32 v11, v5, v8
	v_med3_f32 v5, v12, s47, v173
	v_med3_f32 v8, v13, s47, v173
	v_cvt_pk_fp8_f32 v11, v5, v8 op_sel:[0,0,1]
	v_ashrrev_i32_e32 v7, 31, v6
	v_lshlrev_b64 v[6:7], 10, v[6:7]
	v_lshl_add_u64 v[6:7], s[14:15], 0, v[6:7]
	v_lshl_add_u64 v[6:7], v[6:7], 0, v[2:3]
	global_store_dwordx2 v[6:7], v[10:11], off
	v_pk_mul_f32 v[10:11], v[102:103], s[18:19] op_sel_hi:[1,0]
	v_pk_mul_f32 v[8:9], v[104:105], s[18:19] op_sel_hi:[1,0]
	v_med3_f32 v5, v10, s47, v173
	v_med3_f32 v11, v11, s47, v173
	v_cvt_pk_fp8_f32 v10, v5, v11
	v_pk_mul_f32 v[14:15], v[98:99], s[18:19] op_sel_hi:[1,0]
	v_med3_f32 v5, v8, s47, v173
	v_med3_f32 v8, v9, s47, v173
	v_cvt_pk_fp8_f32 v10, v5, v8 op_sel:[0,0,1]
	v_med3_f32 v5, v14, s47, v173
	v_med3_f32 v8, v15, s47, v173
	v_cvt_pk_fp8_f32 v11, v5, v8
	v_pk_mul_f32 v[12:13], v[100:101], s[18:19] op_sel_hi:[1,0]
	v_pk_mul_f32 v[14:15], v[90:91], s[18:19] op_sel_hi:[1,0]
	v_med3_f32 v5, v12, s47, v173
	v_med3_f32 v8, v13, s47, v173
	v_cvt_pk_fp8_f32 v11, v5, v8 op_sel:[0,0,1]
	v_pk_mul_f32 v[8:9], v[96:97], s[18:19] op_sel_hi:[1,0]
	v_pk_mul_f32 v[12:13], v[92:93], s[18:19] op_sel_hi:[1,0]
	s_mov_b32 s28, s22
	global_store_dwordx2 v[6:7], v[10:11], off offset:128
	v_pk_mul_f32 v[10:11], v[94:95], s[18:19] op_sel_hi:[1,0]
	v_add_u32_e32 v6, 48, v4
	v_med3_f32 v5, v10, s47, v173
	v_med3_f32 v11, v11, s47, v173
	v_cvt_pk_fp8_f32 v10, v5, v11
	v_med3_f32 v5, v8, s47, v173
	v_med3_f32 v8, v9, s47, v173
	v_cvt_pk_fp8_f32 v10, v5, v8 op_sel:[0,0,1]
	v_med3_f32 v5, v14, s47, v173
	v_med3_f32 v8, v15, s47, v173
	v_cvt_pk_fp8_f32 v11, v5, v8
	v_med3_f32 v5, v12, s47, v173
	v_med3_f32 v8, v13, s47, v173
	v_cvt_pk_fp8_f32 v11, v5, v8 op_sel:[0,0,1]
	v_ashrrev_i32_e32 v7, 31, v6
	v_lshlrev_b64 v[6:7], 10, v[6:7]
	v_lshl_add_u64 v[6:7], s[14:15], 0, v[6:7]
	v_lshl_add_u64 v[6:7], v[6:7], 0, v[2:3]
	global_store_dwordx2 v[6:7], v[10:11], off
	v_pk_mul_f32 v[10:11], v[86:87], s[18:19] op_sel_hi:[1,0]
	v_pk_mul_f32 v[8:9], v[88:89], s[18:19] op_sel_hi:[1,0]
	v_med3_f32 v5, v10, s47, v173
	v_med3_f32 v11, v11, s47, v173
	v_cvt_pk_fp8_f32 v10, v5, v11
	v_pk_mul_f32 v[14:15], v[82:83], s[18:19] op_sel_hi:[1,0]
	v_med3_f32 v5, v8, s47, v173
	v_med3_f32 v8, v9, s47, v173
	v_cvt_pk_fp8_f32 v10, v5, v8 op_sel:[0,0,1]
	v_med3_f32 v5, v14, s47, v173
	v_med3_f32 v8, v15, s47, v173
	v_cvt_pk_fp8_f32 v11, v5, v8
	v_pk_mul_f32 v[12:13], v[84:85], s[18:19] op_sel_hi:[1,0]
	v_pk_mul_f32 v[14:15], v[74:75], s[18:19] op_sel_hi:[1,0]
	v_med3_f32 v5, v12, s47, v173
	v_med3_f32 v8, v13, s47, v173
	v_cvt_pk_fp8_f32 v11, v5, v8 op_sel:[0,0,1]
	v_pk_mul_f32 v[8:9], v[80:81], s[18:19] op_sel_hi:[1,0]
	v_pk_mul_f32 v[12:13], v[76:77], s[18:19] op_sel_hi:[1,0]
	s_mov_b64 s[30:31], s[26:27]
	global_store_dwordx2 v[6:7], v[10:11], off offset:128
	v_pk_mul_f32 v[10:11], v[78:79], s[18:19] op_sel_hi:[1,0]
	v_add_u32_e32 v6, 0x80, v4
	v_med3_f32 v5, v10, s47, v173
	v_med3_f32 v11, v11, s47, v173
	v_cvt_pk_fp8_f32 v10, v5, v11
	v_med3_f32 v5, v8, s47, v173
	v_med3_f32 v8, v9, s47, v173
	v_cvt_pk_fp8_f32 v10, v5, v8 op_sel:[0,0,1]
	v_med3_f32 v5, v14, s47, v173
	v_med3_f32 v8, v15, s47, v173
	v_cvt_pk_fp8_f32 v11, v5, v8
	v_med3_f32 v5, v12, s47, v173
	v_med3_f32 v8, v13, s47, v173
	v_cvt_pk_fp8_f32 v11, v5, v8 op_sel:[0,0,1]
	v_ashrrev_i32_e32 v7, 31, v6
	v_lshlrev_b64 v[6:7], 10, v[6:7]
	v_lshl_add_u64 v[6:7], s[14:15], 0, v[6:7]
	v_lshl_add_u64 v[6:7], v[6:7], 0, v[2:3]
	global_store_dwordx2 v[6:7], v[10:11], off
	v_pk_mul_f32 v[10:11], v[70:71], s[18:19] op_sel_hi:[1,0]
	v_pk_mul_f32 v[8:9], v[72:73], s[18:19] op_sel_hi:[1,0]
	v_med3_f32 v5, v10, s47, v173
	v_med3_f32 v11, v11, s47, v173
	v_cvt_pk_fp8_f32 v10, v5, v11
	v_pk_mul_f32 v[14:15], v[66:67], s[18:19] op_sel_hi:[1,0]
	v_med3_f32 v5, v8, s47, v173
	v_med3_f32 v8, v9, s47, v173
	v_cvt_pk_fp8_f32 v10, v5, v8 op_sel:[0,0,1]
	v_med3_f32 v5, v14, s47, v173
	v_med3_f32 v8, v15, s47, v173
	v_cvt_pk_fp8_f32 v11, v5, v8
	v_pk_mul_f32 v[12:13], v[68:69], s[18:19] op_sel_hi:[1,0]
	v_pk_mul_f32 v[14:15], v[58:59], s[18:19] op_sel_hi:[1,0]
	v_med3_f32 v5, v12, s47, v173
	v_med3_f32 v8, v13, s47, v173
	v_cvt_pk_fp8_f32 v11, v5, v8 op_sel:[0,0,1]
	v_pk_mul_f32 v[8:9], v[64:65], s[18:19] op_sel_hi:[1,0]
	v_pk_mul_f32 v[12:13], v[60:61], s[18:19] op_sel_hi:[1,0]
	s_mov_b64 s[34:35], s[24:25]
	global_store_dwordx2 v[6:7], v[10:11], off offset:128
	v_pk_mul_f32 v[10:11], v[62:63], s[18:19] op_sel_hi:[1,0]
	v_add_u32_e32 v6, 0x90, v4
	v_med3_f32 v5, v10, s47, v173
	v_med3_f32 v11, v11, s47, v173
	v_cvt_pk_fp8_f32 v10, v5, v11
	v_med3_f32 v5, v8, s47, v173
	v_med3_f32 v8, v9, s47, v173
	v_cvt_pk_fp8_f32 v10, v5, v8 op_sel:[0,0,1]
	v_med3_f32 v5, v14, s47, v173
	v_med3_f32 v8, v15, s47, v173
	v_cvt_pk_fp8_f32 v11, v5, v8
	v_med3_f32 v5, v12, s47, v173
	v_med3_f32 v8, v13, s47, v173
	v_cvt_pk_fp8_f32 v11, v5, v8 op_sel:[0,0,1]
	v_ashrrev_i32_e32 v7, 31, v6
	v_lshlrev_b64 v[6:7], 10, v[6:7]
	v_lshl_add_u64 v[6:7], s[14:15], 0, v[6:7]
	v_lshl_add_u64 v[6:7], v[6:7], 0, v[2:3]
	global_store_dwordx2 v[6:7], v[10:11], off
	v_pk_mul_f32 v[10:11], v[54:55], s[18:19] op_sel_hi:[1,0]
	v_pk_mul_f32 v[8:9], v[56:57], s[18:19] op_sel_hi:[1,0]
	v_med3_f32 v5, v10, s47, v173
	v_med3_f32 v11, v11, s47, v173
	v_cvt_pk_fp8_f32 v10, v5, v11
	v_pk_mul_f32 v[14:15], v[50:51], s[18:19] op_sel_hi:[1,0]
	v_med3_f32 v5, v8, s47, v173
	v_med3_f32 v8, v9, s47, v173
	v_cvt_pk_fp8_f32 v10, v5, v8 op_sel:[0,0,1]
	v_med3_f32 v5, v14, s47, v173
	v_med3_f32 v8, v15, s47, v173
	v_cvt_pk_fp8_f32 v11, v5, v8
	v_pk_mul_f32 v[12:13], v[52:53], s[18:19] op_sel_hi:[1,0]
	v_pk_mul_f32 v[14:15], v[42:43], s[18:19] op_sel_hi:[1,0]
	v_med3_f32 v5, v12, s47, v173
	v_med3_f32 v8, v13, s47, v173
	v_cvt_pk_fp8_f32 v11, v5, v8 op_sel:[0,0,1]
	v_pk_mul_f32 v[8:9], v[48:49], s[18:19] op_sel_hi:[1,0]
	v_pk_mul_f32 v[12:13], v[44:45], s[18:19] op_sel_hi:[1,0]
	global_store_dwordx2 v[6:7], v[10:11], off offset:128
	v_pk_mul_f32 v[10:11], v[46:47], s[18:19] op_sel_hi:[1,0]
	v_add_u32_e32 v6, 0xa0, v4
	v_med3_f32 v5, v10, s47, v173
	v_med3_f32 v11, v11, s47, v173
	v_cvt_pk_fp8_f32 v10, v5, v11
	v_med3_f32 v5, v8, s47, v173
	v_med3_f32 v8, v9, s47, v173
	v_cvt_pk_fp8_f32 v10, v5, v8 op_sel:[0,0,1]
	v_med3_f32 v5, v14, s47, v173
	v_med3_f32 v8, v15, s47, v173
	v_cvt_pk_fp8_f32 v11, v5, v8
	v_med3_f32 v5, v12, s47, v173
	v_med3_f32 v8, v13, s47, v173
	v_cvt_pk_fp8_f32 v11, v5, v8 op_sel:[0,0,1]
	v_ashrrev_i32_e32 v7, 31, v6
	v_lshlrev_b64 v[6:7], 10, v[6:7]
	v_lshl_add_u64 v[6:7], s[14:15], 0, v[6:7]
	v_lshl_add_u64 v[6:7], v[6:7], 0, v[2:3]
	global_store_dwordx2 v[6:7], v[10:11], off
	v_pk_mul_f32 v[10:11], v[38:39], s[18:19] op_sel_hi:[1,0]
	v_pk_mul_f32 v[8:9], v[40:41], s[18:19] op_sel_hi:[1,0]
	v_med3_f32 v5, v10, s47, v173
	v_med3_f32 v11, v11, s47, v173
	v_cvt_pk_fp8_f32 v10, v5, v11
	v_pk_mul_f32 v[14:15], v[34:35], s[18:19] op_sel_hi:[1,0]
	v_med3_f32 v5, v8, s47, v173
	v_med3_f32 v8, v9, s47, v173
	v_cvt_pk_fp8_f32 v10, v5, v8 op_sel:[0,0,1]
	v_med3_f32 v5, v14, s47, v173
	v_med3_f32 v8, v15, s47, v173
	v_cvt_pk_fp8_f32 v11, v5, v8
	v_pk_mul_f32 v[12:13], v[36:37], s[18:19] op_sel_hi:[1,0]
	v_add_u32_e32 v4, 0xb0, v4
	v_med3_f32 v5, v12, s47, v173
	v_med3_f32 v8, v13, s47, v173
	v_cvt_pk_fp8_f32 v11, v5, v8 op_sel:[0,0,1]
	v_pk_mul_f32 v[8:9], v[28:29], s[18:19] op_sel_hi:[1,0]
	global_store_dwordx2 v[6:7], v[10:11], off offset:128
	v_pk_mul_f32 v[6:7], v[30:31], s[18:19] op_sel_hi:[1,0]
	v_pk_mul_f32 v[10:11], v[26:27], s[18:19] op_sel_hi:[1,0]
	v_ashrrev_i32_e32 v5, 31, v4
	v_med3_f32 v12, v6, s47, v173
	v_med3_f32 v7, v7, s47, v173
	v_lshlrev_b64 v[4:5], 10, v[4:5]
	v_cvt_pk_fp8_f32 v6, v12, v7
	v_lshl_add_u64 v[4:5], s[14:15], 0, v[4:5]
	v_lshl_add_u64 v[2:3], v[4:5], 0, v[2:3]
	v_pk_mul_f32 v[4:5], v[32:33], s[18:19] op_sel_hi:[1,0]
	v_med3_f32 v4, v4, s47, v173
	v_med3_f32 v5, v5, s47, v173
	v_cvt_pk_fp8_f32 v6, v4, v5 op_sel:[0,0,1]
	v_med3_f32 v4, v10, s47, v173
	v_med3_f32 v5, v11, s47, v173
	v_cvt_pk_fp8_f32 v7, v4, v5
	v_med3_f32 v4, v8, s47, v173
	v_med3_f32 v5, v9, s47, v173
	v_pk_mul_f32 v[10:11], v[18:19], s[18:19] op_sel_hi:[1,0]
	v_cvt_pk_fp8_f32 v7, v4, v5 op_sel:[0,0,1]
	v_pk_mul_f32 v[4:5], v[24:25], s[18:19] op_sel_hi:[1,0]
	v_pk_mul_f32 v[8:9], v[20:21], s[18:19] op_sel_hi:[1,0]
	v_med3_f32 v4, v4, s47, v173
	global_store_dwordx2 v[2:3], v[6:7], off
	v_pk_mul_f32 v[6:7], v[22:23], s[18:19] op_sel_hi:[1,0]
	v_med3_f32 v5, v5, s47, v173
	v_med3_f32 v12, v6, s47, v173
	v_med3_f32 v7, v7, s47, v173
	v_cvt_pk_fp8_f32 v6, v12, v7
	s_nop 0
	v_cvt_pk_fp8_f32 v6, v4, v5 op_sel:[0,0,1]
	v_med3_f32 v4, v10, s47, v173
	v_med3_f32 v5, v11, s47, v173
	v_cvt_pk_fp8_f32 v7, v4, v5
	v_med3_f32 v4, v8, s47, v173
	v_med3_f32 v5, v9, s47, v173
	v_cvt_pk_fp8_f32 v7, v4, v5 op_sel:[0,0,1]
	global_store_dwordx2 v[2:3], v[6:7], off offset:128
	s_cbranch_vccz .LBB0_2101
	s_waitcnt vmcnt(0)
	s_cmpk_gt_u32 s4, 0xff
	s_cbranch_scc1 .LBB0_2112
	s_barrier

.LBB0_2183:
	s_mul_hi_i32 s0, s21, 0x2aaaaaab
	s_lshr_b32 s1, s0, 31
	s_ashr_i32 s0, s0, 8
	s_add_i32 s12, s0, s1
	s_mul_i32 s0, s12, 0xfffffa00
	s_add_i32 s24, s21, s0
	s_lshr_b32 s0, s24, 22
	s_and_b32 s0, s0, 0x1ff
	s_add_i32 s25, s24, s0
	s_and_b32 s0, s25, 0xfe00
	s_sub_i32 s0, s24, s0
	s_sext_i32_i16 s1, s0
	s_bfe_u32 s1, s1, 0x5001a
	s_add_i32 s1, s0, s1
	s_sext_i32_i16 s10, s1
	s_and_b32 s1, s1, 0xffe0
	s_lshl_b32 s23, s10, 1
	s_sub_i32 s0, s0, s1
	s_andn2_b32 s23, s23, 63
	s_sext_i32_i16 s22, s0
	s_lshl_b32 s10, s22, 5
	v_or_b32_e32 v20, s23, v26
	s_mov_b64 s[14:15], -1
	s_cmpk_gt_i32 s24, 0x3ff
	v_ashrrev_i32_e32 v21, 31, v20
	v_or_b32_e32 v18, 8, v20
	v_or_b32_e32 v16, 16, v20
	v_or_b32_e32 v14, 24, v20
	v_or_b32_e32 v12, 32, v20
	v_or_b32_e32 v10, 40, v20
	v_or_b32_e32 v8, 48, v20
	v_or_b32_e32 v6, 56, v20
	s_cbranch_scc0 .LBB0_2185
	s_ashr_i32 s13, s12, 31
	s_lshl_b64 s[0:1], s[12:13], 20
	s_lshl_b64 s[14:15], s[12:13], 22
	s_add_u32 s13, s8, s14
	s_addc_u32 s14, s9, s15
	s_add_u32 s15, s6, s0
	s_addc_u32 s26, s7, s1
	s_ashr_i32 s11, s10, 31
	s_lshl_b64 s[0:1], s[10:11], 2
	s_add_u32 s0, s13, s0
	s_addc_u32 s1, s14, s1
	v_lshl_add_u64 v[72:73], s[0:1], 0, v[2:3]
	v_lshlrev_b64 v[22:23], 12, v[20:21]
	v_lshl_add_u64 v[22:23], v[72:73], 0, v[22:23]
	v_ashrrev_i32_e32 v19, 31, v18
	global_load_dwordx4 v[22:25], v[22:23], off nt
	v_lshlrev_b64 v[48:49], 12, v[18:19]
	v_lshl_add_u64 v[48:49], v[72:73], 0, v[48:49]
	v_ashrrev_i32_e32 v17, 31, v16
	global_load_dwordx4 v[48:51], v[48:49], off nt
	v_lshlrev_b64 v[52:53], 12, v[16:17]
	v_lshl_add_u64 v[52:53], v[72:73], 0, v[52:53]
	v_ashrrev_i32_e32 v15, 31, v14
	global_load_dwordx4 v[52:55], v[52:53], off nt
	v_lshlrev_b64 v[56:57], 12, v[14:15]
	v_lshl_add_u64 v[56:57], v[72:73], 0, v[56:57]
	v_ashrrev_i32_e32 v13, 31, v12
	global_load_dwordx4 v[56:59], v[56:57], off nt
	v_lshlrev_b64 v[60:61], 12, v[12:13]
	v_lshl_add_u64 v[60:61], v[72:73], 0, v[60:61]
	v_ashrrev_i32_e32 v11, 31, v10
	global_load_dwordx4 v[60:63], v[60:61], off nt
	v_lshlrev_b64 v[64:65], 12, v[10:11]
	v_lshl_add_u64 v[64:65], v[72:73], 0, v[64:65]
	v_ashrrev_i32_e32 v9, 31, v8
	global_load_dwordx4 v[64:67], v[64:65], off nt
	v_lshlrev_b64 v[68:69], 12, v[8:9]
	v_lshl_add_u64 v[68:69], v[72:73], 0, v[68:69]
	v_ashrrev_i32_e32 v7, 31, v6
	global_load_dwordx4 v[68:71], v[68:69], off nt
	v_lshlrev_b64 v[74:75], 12, v[6:7]
	v_lshl_add_u64 v[72:73], v[72:73], 0, v[74:75]
	global_load_dwordx4 v[72:75], v[72:73], off nt
	s_ashr_i32 s1, s23, 31
	s_add_u32 s0, s15, s23
	s_addc_u32 s1, s26, s1
	s_waitcnt vmcnt(0)
	ds_write2_b32 v31, v22, v23 offset1:1
	ds_write2_b32 v31, v24, v25 offset0:2 offset1:3
	s_waitcnt vmcnt(6)
	ds_write2_b32 v32, v48, v49 offset1:1
	ds_write2_b32 v33, v50, v51 offset1:1
	s_waitcnt vmcnt(5)
	ds_write2_b32 v34, v52, v53 offset1:1
	ds_write2_b32 v35, v54, v55 offset1:1
	s_waitcnt vmcnt(4)
	ds_write2_b32 v36, v56, v57 offset1:1
	ds_write2_b32 v37, v58, v59 offset1:1
	s_waitcnt vmcnt(3)
	ds_write2_b32 v38, v60, v61 offset1:1
	ds_write2_b32 v39, v62, v63 offset1:1
	s_waitcnt vmcnt(2)
	ds_write2_b32 v40, v64, v65 offset1:1
	ds_write2_b32 v41, v66, v67 offset1:1
	s_waitcnt vmcnt(1)
	ds_write2_b32 v42, v68, v69 offset1:1
	ds_write2_b32 v43, v70, v71 offset1:1
	s_waitcnt vmcnt(0)
	ds_write2_b32 v44, v72, v73 offset1:1
	ds_write2_b32 v45, v74, v75 offset1:1
	s_waitcnt lgkmcnt(0)
	ds_read_b32 v7, v30
	ds_read_b32 v9, v30 offset:132
	ds_read_b32 v11, v30 offset:264
	ds_read_b32 v13, v30 offset:396
	s_waitcnt lgkmcnt(0)
	v_mul_f32_e32 v7, 0x43000000, v7
	s_waitcnt lgkmcnt(2)
	v_mul_f32_e32 v9, 0x43000000, v9
	v_med3_f32 v7, v7, s20, v46
	v_med3_f32 v9, v9, s20, v46
	v_cvt_pk_fp8_f32 v24, v7, v9
	s_waitcnt lgkmcnt(1)
	v_mul_f32_e32 v11, 0x43000000, v11
	s_waitcnt lgkmcnt(0)
	v_mul_f32_e32 v13, 0x43000000, v13
	v_med3_f32 v7, v11, s20, v46
	v_med3_f32 v9, v13, s20, v46
	v_cvt_pk_fp8_f32 v24, v7, v9 op_sel:[0,0,1]
	ds_read_b32 v7, v30 offset:528
	ds_read_b32 v9, v30 offset:660
	ds_read_b32 v11, v30 offset:792
	ds_read_b32 v13, v30 offset:924
	s_waitcnt lgkmcnt(3)
	v_mul_f32_e32 v7, 0x43000000, v7
	s_waitcnt lgkmcnt(2)
	v_mul_f32_e32 v9, 0x43000000, v9
	v_med3_f32 v7, v7, s20, v46
	v_med3_f32 v9, v9, s20, v46
	v_cvt_pk_fp8_f32 v25, v7, v9
	s_waitcnt lgkmcnt(1)
	v_mul_f32_e32 v11, 0x43000000, v11
	s_waitcnt lgkmcnt(0)
	v_mul_f32_e32 v13, 0x43000000, v13
	v_med3_f32 v7, v11, s20, v46
	v_med3_f32 v9, v13, s20, v46
	v_cvt_pk_fp8_f32 v25, v7, v9 op_sel:[0,0,1]
	v_or_b32_e32 v48, s10, v26
	v_ashrrev_i32_e32 v49, 31, v48
	v_lshl_add_u64 v[22:23], s[0:1], 0, v[4:5]
	v_lshlrev_b64 v[48:49], 10, v[48:49]
	v_lshl_add_u64 v[48:49], v[22:23], 0, v[48:49]
	global_store_dwordx2 v[48:49], v[24:25], off nt
	ds_read_b32 v7, v30 offset:32
	ds_read_b32 v9, v30 offset:164
	ds_read_b32 v11, v30 offset:296
	ds_read_b32 v13, v30 offset:428
	s_waitcnt lgkmcnt(0)
	v_mul_f32_e32 v7, 0x43000000, v7
	v_mul_f32_e32 v9, 0x43000000, v9
	v_med3_f32 v7, v7, s20, v46
	v_med3_f32 v9, v9, s20, v46
	v_cvt_pk_fp8_f32 v24, v7, v9
	v_mul_f32_e32 v11, 0x43000000, v11
	v_mul_f32_e32 v13, 0x43000000, v13
	v_med3_f32 v7, v11, s20, v46
	v_med3_f32 v9, v13, s20, v46
	v_cvt_pk_fp8_f32 v24, v7, v9 op_sel:[0,0,1]
	ds_read_b32 v7, v30 offset:560
	ds_read_b32 v9, v30 offset:692
	ds_read_b32 v11, v30 offset:824
	ds_read_b32 v13, v30 offset:956
	s_waitcnt lgkmcnt(0)
	v_mul_f32_e32 v7, 0x43000000, v7
	v_mul_f32_e32 v9, 0x43000000, v9
	v_med3_f32 v7, v7, s20, v46
	v_med3_f32 v9, v9, s20, v46
	v_cvt_pk_fp8_f32 v25, v7, v9
	v_mul_f32_e32 v11, 0x43000000, v11
	v_mul_f32_e32 v13, 0x43000000, v13
	v_med3_f32 v7, v11, s20, v46
	v_med3_f32 v9, v13, s20, v46
	v_cvt_pk_fp8_f32 v25, v7, v9 op_sel:[0,0,1]
	v_or_b32_e32 v48, s10, v27
	v_ashrrev_i32_e32 v49, 31, v48
	v_lshlrev_b64 v[48:49], 10, v[48:49]
	v_lshl_add_u64 v[48:49], v[22:23], 0, v[48:49]
	global_store_dwordx2 v[48:49], v[24:25], off nt
	ds_read_b32 v7, v30 offset:64
	ds_read_b32 v9, v30 offset:196
	ds_read_b32 v11, v30 offset:328
	ds_read_b32 v13, v30 offset:460
	s_waitcnt lgkmcnt(0)
	v_mul_f32_e32 v7, 0x43000000, v7
	v_mul_f32_e32 v9, 0x43000000, v9
	v_med3_f32 v7, v7, s20, v46
	v_med3_f32 v9, v9, s20, v46
	v_cvt_pk_fp8_f32 v24, v7, v9
	v_mul_f32_e32 v11, 0x43000000, v11
	v_mul_f32_e32 v13, 0x43000000, v13
	v_med3_f32 v7, v11, s20, v46
	v_med3_f32 v9, v13, s20, v46
	v_cvt_pk_fp8_f32 v24, v7, v9 op_sel:[0,0,1]
	ds_read_b32 v7, v30 offset:592
	ds_read_b32 v9, v30 offset:724
	ds_read_b32 v11, v30 offset:856
	ds_read_b32 v13, v30 offset:988
	s_waitcnt lgkmcnt(0)
	v_mul_f32_e32 v7, 0x43000000, v7
	v_mul_f32_e32 v9, 0x43000000, v9
	v_med3_f32 v7, v7, s20, v46
	v_med3_f32 v9, v9, s20, v46
	v_cvt_pk_fp8_f32 v25, v7, v9
	v_mul_f32_e32 v11, 0x43000000, v11
	v_mul_f32_e32 v13, 0x43000000, v13
	v_med3_f32 v7, v11, s20, v46
	v_med3_f32 v9, v13, s20, v46
	v_cvt_pk_fp8_f32 v25, v7, v9 op_sel:[0,0,1]
	v_or_b32_e32 v48, s10, v28
	v_ashrrev_i32_e32 v49, 31, v48
	v_lshlrev_b64 v[48:49], 10, v[48:49]
	v_lshl_add_u64 v[48:49], v[22:23], 0, v[48:49]
	global_store_dwordx2 v[48:49], v[24:25], off nt
	ds_read_b32 v7, v30 offset:96
	ds_read_b32 v9, v30 offset:228
	ds_read_b32 v11, v30 offset:360
	ds_read_b32 v13, v30 offset:492
	s_waitcnt lgkmcnt(0)
	v_mul_f32_e32 v7, 0x43000000, v7
	v_mul_f32_e32 v9, 0x43000000, v9
	v_med3_f32 v7, v7, s20, v46
	v_med3_f32 v9, v9, s20, v46
	v_cvt_pk_fp8_f32 v24, v7, v9
	v_mul_f32_e32 v11, 0x43000000, v11
	v_mul_f32_e32 v13, 0x43000000, v13
	v_med3_f32 v7, v11, s20, v46
	v_med3_f32 v9, v13, s20, v46
	v_cvt_pk_fp8_f32 v24, v7, v9 op_sel:[0,0,1]
	ds_read_b32 v7, v30 offset:624
	ds_read_b32 v9, v30 offset:756
	ds_read_b32 v11, v30 offset:888
	ds_read_b32 v13, v30 offset:1020
	s_waitcnt lgkmcnt(0)
	v_mul_f32_e32 v7, 0x43000000, v7
	v_mul_f32_e32 v9, 0x43000000, v9
	v_med3_f32 v7, v7, s20, v46
	v_med3_f32 v9, v9, s20, v46
	v_cvt_pk_fp8_f32 v25, v7, v9
	v_mul_f32_e32 v11, 0x43000000, v11
	v_mul_f32_e32 v13, 0x43000000, v13
	v_med3_f32 v7, v11, s20, v46
	v_med3_f32 v9, v13, s20, v46
	v_cvt_pk_fp8_f32 v25, v7, v9 op_sel:[0,0,1]
	v_or_b32_e32 v48, s10, v29
	v_ashrrev_i32_e32 v49, 31, v48
	v_lshlrev_b64 v[48:49], 10, v[48:49]
	v_lshl_add_u64 v[22:23], v[22:23], 0, v[48:49]
	global_store_dwordx2 v[22:23], v[24:25], off nt
	s_waitcnt lgkmcnt(0)
	s_cbranch_execnz .LBB0_2182
	s_branch .LBB0_2186

.LBB0_2186:
	s_sext_i32_i16 s0, s25
	s_lshr_b32 s0, s0, 9
	s_addk_i32 s24, 0x1ff
	s_cmpk_lt_u32 s24, 0x3ff
	s_cselect_b32 s11, s17, s19
	s_cselect_b32 s15, s16, s18
	s_ashr_i32 s13, s12, 31
	s_sext_i32_i16 s14, s0
	s_lshl_b64 s[0:1], s[12:13], 22
	s_add_u32 s15, s15, s0
	s_addc_u32 s24, s11, s1
	s_lshl_b64 s[0:1], s[12:13], 21
	s_add_u32 s12, s4, s0
	s_addc_u32 s13, s5, s1
	s_ashr_i32 s11, s10, 31
	s_lshl_b64 s[0:1], s[10:11], 2
	s_add_u32 s0, s15, s0
	s_addc_u32 s1, s24, s1
	v_lshl_add_u64 v[22:23], s[0:1], 0, v[2:3]
	s_mov_b64 s[0:1], 0xc000000
	v_lshl_add_u64 v[24:25], v[22:23], 0, s[0:1]
	v_lshlrev_b64 v[20:21], 12, v[20:21]
	v_lshl_add_u64 v[20:21], v[24:25], 0, v[20:21]
	v_ashrrev_i32_e32 v19, 31, v18
	global_load_dwordx4 v[20:23], v[20:21], off nt
	v_lshlrev_b64 v[18:19], 12, v[18:19]
	v_lshl_add_u64 v[18:19], v[24:25], 0, v[18:19]
	v_ashrrev_i32_e32 v17, 31, v16
	global_load_dwordx4 v[48:51], v[18:19], off nt
	v_lshlrev_b64 v[16:17], 12, v[16:17]
	v_lshl_add_u64 v[16:17], v[24:25], 0, v[16:17]
	v_ashrrev_i32_e32 v15, 31, v14
	global_load_dwordx4 v[16:19], v[16:17], off nt
	v_lshlrev_b64 v[14:15], 12, v[14:15]
	v_lshl_add_u64 v[14:15], v[24:25], 0, v[14:15]
	v_ashrrev_i32_e32 v13, 31, v12
	global_load_dwordx4 v[52:55], v[14:15], off nt
	v_lshlrev_b64 v[12:13], 12, v[12:13]
	v_lshl_add_u64 v[12:13], v[24:25], 0, v[12:13]
	v_ashrrev_i32_e32 v11, 31, v10
	global_load_dwordx4 v[12:15], v[12:13], off nt
	v_lshlrev_b64 v[10:11], 12, v[10:11]
	v_lshl_add_u64 v[10:11], v[24:25], 0, v[10:11]
	v_ashrrev_i32_e32 v9, 31, v8
	global_load_dwordx4 v[56:59], v[10:11], off nt
	v_lshlrev_b64 v[8:9], 12, v[8:9]
	v_lshl_add_u64 v[8:9], v[24:25], 0, v[8:9]
	v_ashrrev_i32_e32 v7, 31, v6
	global_load_dwordx4 v[8:11], v[8:9], off nt
	v_lshlrev_b64 v[6:7], 12, v[6:7]
	v_lshl_add_u64 v[6:7], v[24:25], 0, v[6:7]
	global_load_dwordx4 v[60:63], v[6:7], off nt
	s_lshl_b32 s1, s14, 7
	s_ashr_i32 s0, s23, 31
	s_add_u32 s12, s12, s23
	s_addc_u32 s13, s13, s0
	s_lshl_b32 s0, s22, 6
	s_and_b32 s0, s0, 0xffffff00
	s_add_i32 s0, s0, s1
	s_and_b32 s1, s10, 0x60
	s_or_b32 s10, s0, s1
	v_lshl_add_u64 v[6:7], s[12:13], 0, v[4:5]
	s_waitcnt vmcnt(0)
	ds_write2_b32 v31, v20, v21 offset1:1
	ds_write2_b32 v31, v22, v23 offset0:2 offset1:3
	ds_write2_b32 v32, v48, v49 offset1:1
	ds_write2_b32 v33, v50, v51 offset1:1
	ds_write2_b32 v34, v16, v17 offset1:1
	ds_write2_b32 v35, v18, v19 offset1:1
	ds_write2_b32 v36, v52, v53 offset1:1
	ds_write2_b32 v37, v54, v55 offset1:1
	ds_write2_b32 v38, v12, v13 offset1:1
	ds_write2_b32 v39, v14, v15 offset1:1
	ds_write2_b32 v40, v56, v57 offset1:1
	ds_write2_b32 v41, v58, v59 offset1:1
	ds_write2_b32 v42, v8, v9 offset1:1
	ds_write2_b32 v43, v10, v11 offset1:1
	ds_write2_b32 v44, v60, v61 offset1:1
	ds_write2_b32 v45, v62, v63 offset1:1
	s_waitcnt lgkmcnt(0)
	ds_read_b32 v8, v30
	ds_read_b32 v9, v30 offset:132
	ds_read_b32 v10, v30 offset:264
	ds_read_b32 v11, v30 offset:396
	s_waitcnt lgkmcnt(0)
	v_mul_f32_e32 v8, 0x42800000, v8
	v_mul_f32_e32 v9, 0x42800000, v9
	v_med3_f32 v12, v8, s20, v46
	v_med3_f32 v9, v9, s20, v46
	v_cvt_pk_fp8_f32 v8, v12, v9
	v_mul_f32_e32 v10, 0x42800000, v10
	v_mul_f32_e32 v11, 0x42800000, v11
	v_med3_f32 v9, v10, s20, v46
	v_med3_f32 v10, v11, s20, v46
	v_cvt_pk_fp8_f32 v8, v9, v10 op_sel:[0,0,1]
	ds_read_b32 v9, v30 offset:528
	ds_read_b32 v10, v30 offset:660
	ds_read_b32 v11, v30 offset:792
	ds_read_b32 v12, v30 offset:924
	s_waitcnt lgkmcnt(3)
	v_mul_f32_e32 v9, 0x42800000, v9
	s_waitcnt lgkmcnt(2)
	v_mul_f32_e32 v10, 0x42800000, v10
	v_med3_f32 v13, v9, s20, v46
	v_med3_f32 v10, v10, s20, v46
	v_cvt_pk_fp8_f32 v9, v13, v10
	s_waitcnt lgkmcnt(1)
	v_mul_f32_e32 v11, 0x42800000, v11
	s_waitcnt lgkmcnt(0)
	v_mul_f32_e32 v12, 0x42800000, v12
	v_med3_f32 v10, v11, s20, v46
	v_med3_f32 v11, v12, s20, v46
	v_cvt_pk_fp8_f32 v9, v10, v11 op_sel:[0,0,1]
	v_or_b32_e32 v10, s10, v26
	v_ashrrev_i32_e32 v11, 31, v10
	v_lshlrev_b64 v[10:11], 10, v[10:11]
	v_lshl_add_u64 v[10:11], v[6:7], 0, v[10:11]
	global_store_dwordx2 v[10:11], v[8:9], off nt
	ds_read_b32 v8, v30 offset:32
	ds_read_b32 v9, v30 offset:164
	ds_read_b32 v10, v30 offset:296
	ds_read_b32 v11, v30 offset:428
	s_waitcnt lgkmcnt(0)
	v_mul_f32_e32 v8, 0x42800000, v8
	v_mul_f32_e32 v9, 0x42800000, v9
	v_med3_f32 v12, v8, s20, v46
	v_med3_f32 v9, v9, s20, v46
	v_cvt_pk_fp8_f32 v8, v12, v9
	v_mul_f32_e32 v10, 0x42800000, v10
	v_mul_f32_e32 v11, 0x42800000, v11
	v_med3_f32 v9, v10, s20, v46
	v_med3_f32 v10, v11, s20, v46
	v_cvt_pk_fp8_f32 v8, v9, v10 op_sel:[0,0,1]
	ds_read_b32 v9, v30 offset:560
	ds_read_b32 v10, v30 offset:692
	ds_read_b32 v11, v30 offset:824
	ds_read_b32 v12, v30 offset:956
	s_waitcnt lgkmcnt(0)
	v_mul_f32_e32 v9, 0x42800000, v9
	v_mul_f32_e32 v10, 0x42800000, v10
	v_med3_f32 v13, v9, s20, v46
	v_med3_f32 v10, v10, s20, v46
	v_cvt_pk_fp8_f32 v9, v13, v10
	v_mul_f32_e32 v11, 0x42800000, v11
	v_mul_f32_e32 v12, 0x42800000, v12
	v_med3_f32 v10, v11, s20, v46
	v_med3_f32 v11, v12, s20, v46
	v_cvt_pk_fp8_f32 v9, v10, v11 op_sel:[0,0,1]
	v_or_b32_e32 v10, s10, v27
	v_ashrrev_i32_e32 v11, 31, v10
	v_lshlrev_b64 v[10:11], 10, v[10:11]
	v_lshl_add_u64 v[10:11], v[6:7], 0, v[10:11]
	global_store_dwordx2 v[10:11], v[8:9], off nt
	ds_read_b32 v8, v30 offset:64
	ds_read_b32 v9, v30 offset:196
	ds_read_b32 v10, v30 offset:328
	ds_read_b32 v11, v30 offset:460
	s_waitcnt lgkmcnt(0)
	v_mul_f32_e32 v8, 0x42800000, v8
	v_mul_f32_e32 v9, 0x42800000, v9
	v_med3_f32 v12, v8, s20, v46
	v_med3_f32 v9, v9, s20, v46
	v_cvt_pk_fp8_f32 v8, v12, v9
	v_mul_f32_e32 v10, 0x42800000, v10
	v_mul_f32_e32 v11, 0x42800000, v11
	v_med3_f32 v9, v10, s20, v46
	v_med3_f32 v10, v11, s20, v46
	v_cvt_pk_fp8_f32 v8, v9, v10 op_sel:[0,0,1]
	ds_read_b32 v9, v30 offset:592
	ds_read_b32 v10, v30 offset:724
	ds_read_b32 v11, v30 offset:856
	ds_read_b32 v12, v30 offset:988
	s_waitcnt lgkmcnt(0)
	v_mul_f32_e32 v9, 0x42800000, v9
	v_mul_f32_e32 v10, 0x42800000, v10
	v_med3_f32 v13, v9, s20, v46
	v_med3_f32 v10, v10, s20, v46
	v_cvt_pk_fp8_f32 v9, v13, v10
	v_mul_f32_e32 v11, 0x42800000, v11
	v_mul_f32_e32 v12, 0x42800000, v12
	v_med3_f32 v10, v11, s20, v46
	v_med3_f32 v11, v12, s20, v46
	v_cvt_pk_fp8_f32 v9, v10, v11 op_sel:[0,0,1]
	v_or_b32_e32 v10, s10, v28
	v_ashrrev_i32_e32 v11, 31, v10
	v_lshlrev_b64 v[10:11], 10, v[10:11]
	v_lshl_add_u64 v[10:11], v[6:7], 0, v[10:11]
	global_store_dwordx2 v[10:11], v[8:9], off nt
	ds_read_b32 v8, v30 offset:96
	ds_read_b32 v9, v30 offset:228
	ds_read_b32 v10, v30 offset:360
	ds_read_b32 v11, v30 offset:492
	s_waitcnt lgkmcnt(0)
	v_mul_f32_e32 v8, 0x42800000, v8
	v_mul_f32_e32 v9, 0x42800000, v9
	v_med3_f32 v12, v8, s20, v46
	v_med3_f32 v9, v9, s20, v46
	v_cvt_pk_fp8_f32 v8, v12, v9
	v_mul_f32_e32 v10, 0x42800000, v10
	v_mul_f32_e32 v11, 0x42800000, v11
	v_med3_f32 v9, v10, s20, v46
	v_med3_f32 v10, v11, s20, v46
	v_cvt_pk_fp8_f32 v8, v9, v10 op_sel:[0,0,1]
	ds_read_b32 v9, v30 offset:624
	ds_read_b32 v10, v30 offset:756
	ds_read_b32 v11, v30 offset:888
	ds_read_b32 v12, v30 offset:1020
	s_waitcnt lgkmcnt(0)
	v_mul_f32_e32 v9, 0x42800000, v9
	v_mul_f32_e32 v10, 0x42800000, v10
	v_med3_f32 v13, v9, s20, v46
	v_med3_f32 v10, v10, s20, v46
	v_cvt_pk_fp8_f32 v9, v13, v10
	v_mul_f32_e32 v11, 0x42800000, v11
	v_mul_f32_e32 v12, 0x42800000, v12
	v_med3_f32 v10, v11, s20, v46
	v_med3_f32 v11, v12, s20, v46
	v_cvt_pk_fp8_f32 v9, v10, v11 op_sel:[0,0,1]
	v_or_b32_e32 v10, s10, v29
	v_ashrrev_i32_e32 v11, 31, v10
	v_lshlrev_b64 v[10:11], 10, v[10:11]
	v_lshl_add_u64 v[6:7], v[6:7], 0, v[10:11]
	global_store_dwordx2 v[6:7], v[8:9], off nt
	s_waitcnt lgkmcnt(0)
	s_branch .LBB0_2182

.LBB0_2259:
	s_or_b64 exec, exec, s[18:19]
	ds_bpermute_b32 v30, v72, v60
	ds_bpermute_b32 v31, v72, v61
	ds_bpermute_b32 v32, v72, v62
	ds_bpermute_b32 v33, v72, v63
	s_and_saveexec_b64 s[18:19], s[14:15]
	s_cbranch_execz .LBB0_2254
	s_waitcnt lgkmcnt(0)
	v_pk_mul_f32 v[26:27], v[26:27], v[30:31]
	v_pk_mul_f32 v[28:29], v[28:29], v[32:33]
	v_xor_b32_e32 v32, 0x80000000, v26
	v_xor_b32_e32 v33, 0x80000000, v27
	v_cndmask_b32_e64 v27, v33, v27, s[16:17]
	v_cndmask_b32_e64 v26, v32, v26, s[16:17]
	v_pk_fma_f32 v[22:23], v[22:23], v[60:61], v[26:27]
	v_med3_f32 v22, v22, s7, v77
	v_med3_f32 v23, v23, s7, v77
	s_ashr_i32 s24, s22, 8
	v_xor_b32_e32 v30, 0x80000000, v28
	v_xor_b32_e32 v31, 0x80000000, v29
	v_cvt_pk_fp8_f32 v26, v22, v23
	s_and_b32 s0, s24, -8
	v_cndmask_b32_e64 v29, v31, v29, s[16:17]
	v_cndmask_b32_e64 v28, v30, v28, s[16:17]
	s_ashr_i32 s1, s0, 31
	v_pk_fma_f32 v[24:25], v[24:25], v[62:63], v[28:29]
	s_and_b32 s21, s22, 0x7ff
	s_lshl_b64 s[22:23], s[0:1], 11
	v_med3_f32 v22, v24, s7, v77
	v_med3_f32 v23, v25, s7, v77
	s_or_b32 s1, s22, s21
	v_cvt_pk_fp8_f32 v26, v22, v23 op_sel:[0,0,1]
	s_mul_i32 s25, s23, 0xc0
	v_mad_u64_u32 v[22:23], s[22:23], s1, v78, v[52:53]
	s_or_b32 s22, s0, 1
	s_ashr_i32 s23, s22, 31
	s_lshl_b64 s[22:23], s[22:23], 11
	v_add_u32_e32 v23, s25, v23
	s_or_b32 s1, s22, s21
	global_store_dword v[22:23], v26, off offset:128
	s_mul_i32 s25, s23, 0xc0
	v_mad_u64_u32 v[22:23], s[22:23], s1, v78, v[52:53]
	s_or_b32 s22, s0, 2
	s_ashr_i32 s23, s22, 31
	s_lshl_b64 s[22:23], s[22:23], 11
	v_add_u32_e32 v23, s25, v23
	s_or_b32 s1, s22, s21
	global_store_dword v[22:23], v26, off offset:128
	s_mul_i32 s25, s23, 0xc0
	v_mad_u64_u32 v[22:23], s[22:23], s1, v78, v[52:53]
	s_or_b32 s22, s0, 3
	s_ashr_i32 s23, s22, 31
	s_lshl_b64 s[22:23], s[22:23], 11
	v_add_u32_e32 v23, s25, v23
	s_or_b32 s1, s22, s21
	global_store_dword v[22:23], v26, off offset:128
	s_mul_i32 s25, s23, 0xc0
	v_mad_u64_u32 v[22:23], s[22:23], s1, v78, v[52:53]
	s_or_b32 s22, s0, 4
	s_ashr_i32 s23, s22, 31
	s_lshl_b64 s[22:23], s[22:23], 11
	v_add_u32_e32 v23, s25, v23
	s_or_b32 s1, s22, s21
	global_store_dword v[22:23], v26, off offset:128
	s_mul_i32 s25, s23, 0xc0
	v_mad_u64_u32 v[22:23], s[22:23], s1, v78, v[52:53]
	s_or_b32 s22, s0, 5
	s_ashr_i32 s23, s22, 31
	s_lshl_b64 s[22:23], s[22:23], 11
	v_add_u32_e32 v23, s25, v23
	s_or_b32 s1, s22, s21
	s_or_b32 s0, s0, 6
	global_store_dword v[22:23], v26, off offset:128
	s_mul_i32 s25, s23, 0xc0
	v_mad_u64_u32 v[22:23], s[22:23], s1, v78, v[52:53]
	s_ashr_i32 s1, s0, 31
	s_lshl_b64 s[0:1], s[0:1], 11
	v_add_u32_e32 v23, s25, v23
	s_or_b32 s0, s0, s21
	global_store_dword v[22:23], v26, off offset:128
	s_mul_i32 s22, s1, 0xc0
	v_mad_u64_u32 v[22:23], s[0:1], s0, v78, v[52:53]
	s_or_b32 s0, s24, 7
	s_ashr_i32 s1, s0, 31
	s_lshl_b64 s[0:1], s[0:1], 11
	v_add_u32_e32 v23, s22, v23
	s_or_b32 s0, s0, s21
	global_store_dword v[22:23], v26, off offset:128
	s_mul_i32 s21, s1, 0xc0
	v_mad_u64_u32 v[22:23], s[0:1], s0, v78, v[52:53]
	v_add_u32_e32 v23, s21, v23
	global_store_dword v[22:23], v26, off offset:128
	s_branch .LBB0_2254

.Lpeel_exit_14:
	v_mov_b32_e32 v169, v162
	v_mov_b32_e32 v130, v163
	s_mov_b64 s[34:35], -1
	v_lshlrev_b32_e32 v154, 3, v130
	s_cmp_gt_i32 s57, 3
	v_ashrrev_i32_e32 v155, 31, v154
	s_cbranch_scc0 .LBB0_2328
	s_lshl_b32 s0, s56, 8
	s_add_i32 s0, s0, s45
	v_add_u32_e32 v248, s0, v169
	v_mov_b32_e32 v136, v248
	v_lshlrev_b64 v[132:133], 2, v[154:155]
	v_ashrrev_i32_e32 v137, 31, v136
	v_lshl_add_u64 v[130:131], s[26:27], 0, v[132:133]
	v_lshlrev_b64 v[134:135], 7, v[136:137]
	v_lshl_add_u64 v[156:157], v[130:131], 0, v[134:135]
	v_lshl_add_u64 v[132:133], s[24:25], 0, v[132:133]
	global_load_dwordx4 v[170:173], v[156:157], off
	global_load_dwordx4 v[174:177], v[156:157], off offset:16
	v_lshl_add_u64 v[134:135], v[132:133], 0, v[134:135]
	global_load_dwordx4 v[178:181], v[134:135], off
	global_load_dwordx4 v[182:185], v[134:135], off offset:16
	v_add_u32_e32 v160, 16, v136
	v_ashrrev_i32_e32 v161, 31, v160
	v_lshlrev_b64 v[134:135], 7, v[160:161]
	v_lshl_add_u64 v[156:157], v[130:131], 0, v[134:135]
	global_load_dwordx4 v[186:189], v[156:157], off
	global_load_dwordx4 v[194:197], v[156:157], off offset:16
	v_lshl_add_u64 v[134:135], v[132:133], 0, v[134:135]
	global_load_dwordx4 v[190:193], v[134:135], off
	global_load_dwordx4 v[198:201], v[134:135], off offset:16
	v_add_u32_e32 v238, 32, v136
	v_add_u32_e32 v134, 48, v136
	v_ashrrev_i32_e32 v239, 31, v238
	v_ashrrev_i32_e32 v135, 31, v134
	v_lshlrev_b64 v[202:203], 7, v[238:239]
	v_lshlrev_b64 v[204:205], 7, v[134:135]
	v_lshl_add_u64 v[206:207], v[132:133], 0, v[202:203]
	v_lshl_add_u64 v[214:215], v[130:131], 0, v[202:203]
	v_lshl_add_u64 v[222:223], v[132:133], 0, v[204:205]
	v_lshl_add_u64 v[230:231], v[130:131], 0, v[204:205]
	global_load_dwordx4 v[202:205], v[206:207], off
	s_nop 0
	global_load_dwordx4 v[206:209], v[206:207], off offset:16
	s_nop 0
	global_load_dwordx4 v[210:213], v[214:215], off
	s_nop 0
	global_load_dwordx4 v[214:217], v[214:215], off offset:16
	s_nop 0
	global_load_dwordx4 v[218:221], v[222:223], off
	s_nop 0
	global_load_dwordx4 v[222:225], v[222:223], off offset:16
	s_nop 0
	global_load_dwordx4 v[226:229], v[230:231], off
	s_nop 0
	global_load_dwordx4 v[230:233], v[230:231], off offset:16
	s_lshl_b32 s0, s57, 2
	s_add_i32 s0, s48, s0
	v_mov_b64_e32 v[156:157], s[22:23]
	s_mul_i32 s20, s0, 0xc0
	v_lshl_add_u64 v[158:159], s[20:21], 0, v[154:155]
	v_mad_i64_i32 v[136:137], s[0:1], v136, s52, v[156:157]
	v_lshl_add_u64 v[136:137], v[136:137], 0, v[158:159]
	s_mov_b64 s[34:35], 0
	s_waitcnt vmcnt(0) lgkmcnt(0)
	v_pk_mul_f32 v[240:241], v[120:121], v[172:173]
	v_pk_mul_f32 v[242:243], v[118:119], v[170:171]
	v_pk_mul_f32 v[172:173], v[128:129], v[172:173]
	v_pk_mul_f32 v[246:247], v[110:111], v[174:175]
	v_pk_mul_f32 v[170:171], v[126:127], v[170:171]
	v_pk_mul_f32 v[174:175], v[122:123], v[174:175]
	v_pk_fma_f32 v[240:241], v[128:129], v[180:181], v[240:241] neg_lo:[0,0,1] neg_hi:[0,0,1]
	v_pk_fma_f32 v[242:243], v[126:127], v[178:179], v[242:243] neg_lo:[0,0,1] neg_hi:[0,0,1]
	v_pk_fma_f32 v[172:173], v[120:121], v[180:181], v[172:173]
	v_pk_fma_f32 v[180:181], v[122:123], v[182:183], v[246:247] neg_lo:[0,0,1] neg_hi:[0,0,1]
	v_pk_fma_f32 v[170:171], v[118:119], v[178:179], v[170:171]
	v_pk_fma_f32 v[174:175], v[110:111], v[182:183], v[174:175]
	v_med3_f32 v135, v242, s51, v168
	v_med3_f32 v161, v243, s51, v168
	v_med3_f32 v180, v180, s51, v168
	v_med3_f32 v181, v181, s51, v168
	v_med3_f32 v170, v170, s51, v168
	v_med3_f32 v171, v171, s51, v168
	v_med3_f32 v174, v174, s51, v168
	v_med3_f32 v175, v175, s51, v168
	v_cvt_pk_fp8_f32 v234, v135, v161
	v_cvt_pk_fp8_f32 v235, v180, v181
	v_pk_mul_f32 v[244:245], v[112:113], v[176:177]
	v_cvt_pk_fp8_f32 v236, v170, v171
	v_cvt_pk_fp8_f32 v237, v174, v175
	v_pk_mul_f32 v[176:177], v[124:125], v[176:177]
	v_pk_fma_f32 v[178:179], v[124:125], v[184:185], v[244:245] neg_lo:[0,0,1] neg_hi:[0,0,1]
	v_pk_fma_f32 v[176:177], v[112:113], v[184:185], v[176:177]
	v_med3_f32 v184, v240, s51, v168
	v_med3_f32 v185, v241, s51, v168
	v_med3_f32 v178, v178, s51, v168
	v_med3_f32 v179, v179, s51, v168
	v_med3_f32 v172, v172, s51, v168
	v_med3_f32 v173, v173, s51, v168
	v_med3_f32 v176, v176, s51, v168
	v_med3_f32 v177, v177, s51, v168
	v_cvt_pk_fp8_f32 v234, v184, v185 op_sel:[0,0,1]
	v_cvt_pk_fp8_f32 v235, v178, v179 op_sel:[0,0,1]
	v_cvt_pk_fp8_f32 v236, v172, v173 op_sel:[0,0,1]
	v_cvt_pk_fp8_f32 v237, v176, v177 op_sel:[0,0,1]
	v_pk_mul_f32 v[170:171], v[102:103], v[186:187]
	v_pk_mul_f32 v[182:183], v[104:105], v[188:189]
	global_store_dwordx2 v[136:137], v[234:235], off offset:128
	global_store_dwordx2 v[136:137], v[236:237], off offset:160
	v_pk_fma_f32 v[136:137], v[114:115], v[190:191], v[170:171] neg_lo:[0,0,1] neg_hi:[0,0,1]
	v_pk_mul_f32 v[178:179], v[94:95], v[194:195]
	v_pk_fma_f32 v[172:173], v[116:117], v[192:193], v[182:183] neg_lo:[0,0,1] neg_hi:[0,0,1]
	v_pk_fma_f32 v[178:179], v[106:107], v[198:199], v[178:179] neg_lo:[0,0,1] neg_hi:[0,0,1]
	v_med3_f32 v135, v136, s51, v168
	v_med3_f32 v137, v137, s51, v168
	v_cvt_pk_fp8_f32 v136, v135, v137
	v_med3_f32 v135, v172, s51, v168
	v_med3_f32 v161, v173, s51, v168
	v_med3_f32 v172, v178, s51, v168
	v_med3_f32 v173, v179, s51, v168
	v_cvt_pk_fp8_f32 v137, v172, v173
	v_pk_mul_f32 v[176:177], v[96:97], v[196:197]
	v_pk_mul_f32 v[174:175], v[114:115], v[186:187]
	v_pk_fma_f32 v[176:177], v[108:109], v[200:201], v[176:177] neg_lo:[0,0,1] neg_hi:[0,0,1]
	v_pk_mul_f32 v[170:171], v[116:117], v[188:189]
	v_pk_fma_f32 v[174:175], v[102:103], v[190:191], v[174:175]
	v_pk_mul_f32 v[182:183], v[106:107], v[194:195]
	v_cvt_pk_fp8_f32 v136, v135, v161 op_sel:[0,0,1]
	v_med3_f32 v135, v176, s51, v168
	v_med3_f32 v161, v177, s51, v168
	v_pk_fma_f32 v[170:171], v[104:105], v[192:193], v[170:171]
	v_pk_fma_f32 v[182:183], v[94:95], v[198:199], v[182:183]
	v_cvt_pk_fp8_f32 v137, v135, v161 op_sel:[0,0,1]
	v_med3_f32 v135, v174, s51, v168
	v_med3_f32 v161, v175, s51, v168
	v_cvt_pk_fp8_f32 v172, v135, v161
	v_med3_f32 v135, v170, s51, v168
	v_med3_f32 v161, v171, s51, v168
	v_med3_f32 v170, v182, s51, v168
	v_med3_f32 v171, v183, s51, v168
	v_cvt_pk_fp8_f32 v173, v170, v171
	v_pk_mul_f32 v[180:181], v[108:109], v[196:197]
	v_cvt_pk_fp8_f32 v172, v135, v161 op_sel:[0,0,1]
	v_pk_fma_f32 v[180:181], v[96:97], v[200:201], v[180:181]
	v_pk_mul_f32 v[176:177], v[78:79], v[214:215]
	v_med3_f32 v135, v180, s51, v168
	v_med3_f32 v161, v181, s51, v168
	v_cvt_pk_fp8_f32 v173, v135, v161 op_sel:[0,0,1]
	v_mad_i64_i32 v[160:161], s[0:1], v160, s52, v[156:157]
	v_lshl_add_u64 v[160:161], v[160:161], 0, v[158:159]
	global_store_dwordx2 v[160:161], v[136:137], off offset:128
	global_store_dwordx2 v[160:161], v[172:173], off offset:160
	v_pk_mul_f32 v[160:161], v[86:87], v[210:211]
	v_pk_mul_f32 v[136:137], v[88:89], v[212:213]
	v_pk_fma_f32 v[160:161], v[98:99], v[202:203], v[160:161] neg_lo:[0,0,1] neg_hi:[0,0,1]
	v_pk_fma_f32 v[136:137], v[100:101], v[204:205], v[136:137] neg_lo:[0,0,1] neg_hi:[0,0,1]
	v_pk_fma_f32 v[176:177], v[90:91], v[206:207], v[176:177] neg_lo:[0,0,1] neg_hi:[0,0,1]
	v_med3_f32 v135, v160, s51, v168
	v_med3_f32 v161, v161, s51, v168
	v_cvt_pk_fp8_f32 v160, v135, v161
	v_med3_f32 v135, v136, s51, v168
	v_med3_f32 v136, v137, s51, v168
	v_med3_f32 v137, v176, s51, v168
	v_med3_f32 v176, v177, s51, v168
	v_cvt_pk_fp8_f32 v161, v137, v176
	v_pk_mul_f32 v[174:175], v[80:81], v[216:217]
	v_pk_mul_f32 v[172:173], v[98:99], v[210:211]
	v_pk_fma_f32 v[174:175], v[92:93], v[208:209], v[174:175] neg_lo:[0,0,1] neg_hi:[0,0,1]
	v_pk_mul_f32 v[170:171], v[100:101], v[212:213]
	v_pk_fma_f32 v[172:173], v[86:87], v[202:203], v[172:173]
	v_pk_mul_f32 v[180:181], v[90:91], v[214:215]
	v_cvt_pk_fp8_f32 v160, v135, v136 op_sel:[0,0,1]
	v_med3_f32 v135, v174, s51, v168
	v_med3_f32 v136, v175, s51, v168
	v_pk_fma_f32 v[170:171], v[88:89], v[204:205], v[170:171]
	v_pk_fma_f32 v[180:181], v[78:79], v[206:207], v[180:181]
	v_cvt_pk_fp8_f32 v161, v135, v136 op_sel:[0,0,1]
	v_med3_f32 v135, v172, s51, v168
	v_med3_f32 v137, v173, s51, v168
	v_cvt_pk_fp8_f32 v136, v135, v137
	v_med3_f32 v135, v170, s51, v168
	v_med3_f32 v170, v171, s51, v168
	v_med3_f32 v171, v180, s51, v168
	v_med3_f32 v172, v181, s51, v168
	v_cvt_pk_fp8_f32 v137, v171, v172
	v_pk_mul_f32 v[178:179], v[92:93], v[216:217]
	v_cvt_pk_fp8_f32 v136, v135, v170 op_sel:[0,0,1]
	v_pk_fma_f32 v[178:179], v[80:81], v[208:209], v[178:179]
	v_pk_mul_f32 v[176:177], v[66:67], v[230:231]
	v_med3_f32 v135, v178, s51, v168
	v_med3_f32 v170, v179, s51, v168
	v_cvt_pk_fp8_f32 v137, v135, v170 op_sel:[0,0,1]
	v_mad_i64_i32 v[170:171], s[0:1], v238, s52, v[156:157]
	v_lshl_add_u64 v[170:171], v[170:171], 0, v[158:159]
	global_store_dwordx2 v[170:171], v[160:161], off offset:128
	global_store_dwordx2 v[170:171], v[136:137], off offset:160
	v_pk_mul_f32 v[160:161], v[70:71], v[226:227]
	v_pk_mul_f32 v[136:137], v[72:73], v[228:229]
	v_pk_fma_f32 v[160:161], v[82:83], v[218:219], v[160:161] neg_lo:[0,0,1] neg_hi:[0,0,1]
	v_pk_fma_f32 v[136:137], v[84:85], v[220:221], v[136:137] neg_lo:[0,0,1] neg_hi:[0,0,1]
	v_pk_fma_f32 v[176:177], v[74:75], v[222:223], v[176:177] neg_lo:[0,0,1] neg_hi:[0,0,1]
	v_med3_f32 v135, v160, s51, v168
	v_med3_f32 v161, v161, s51, v168
	v_cvt_pk_fp8_f32 v160, v135, v161
	v_med3_f32 v135, v136, s51, v168
	v_med3_f32 v136, v137, s51, v168
	v_med3_f32 v137, v176, s51, v168
	v_med3_f32 v176, v177, s51, v168
	v_cvt_pk_fp8_f32 v161, v137, v176
	v_pk_mul_f32 v[174:175], v[68:69], v[232:233]
	v_pk_mul_f32 v[172:173], v[82:83], v[226:227]
	v_pk_fma_f32 v[174:175], v[76:77], v[224:225], v[174:175] neg_lo:[0,0,1] neg_hi:[0,0,1]
	v_pk_mul_f32 v[170:171], v[84:85], v[228:229]
	v_pk_fma_f32 v[172:173], v[70:71], v[218:219], v[172:173]
	v_pk_mul_f32 v[180:181], v[74:75], v[230:231]
	v_cvt_pk_fp8_f32 v160, v135, v136 op_sel:[0,0,1]
	v_med3_f32 v135, v174, s51, v168
	v_med3_f32 v136, v175, s51, v168
	v_pk_fma_f32 v[170:171], v[72:73], v[220:221], v[170:171]
	v_pk_fma_f32 v[180:181], v[66:67], v[222:223], v[180:181]
	v_cvt_pk_fp8_f32 v161, v135, v136 op_sel:[0,0,1]
	v_med3_f32 v135, v172, s51, v168
	v_med3_f32 v137, v173, s51, v168
	v_cvt_pk_fp8_f32 v136, v135, v137
	v_med3_f32 v135, v170, s51, v168
	v_med3_f32 v170, v171, s51, v168
	v_med3_f32 v171, v180, s51, v168
	v_med3_f32 v172, v181, s51, v168
	v_cvt_pk_fp8_f32 v137, v171, v172
	v_pk_mul_f32 v[178:179], v[76:77], v[232:233]
	v_cvt_pk_fp8_f32 v136, v135, v170 op_sel:[0,0,1]
	v_pk_fma_f32 v[178:179], v[68:69], v[224:225], v[178:179]
	v_add_u32_e32 v226, 0x80, v248
	v_med3_f32 v135, v178, s51, v168
	v_med3_f32 v170, v179, s51, v168
	v_cvt_pk_fp8_f32 v137, v135, v170 op_sel:[0,0,1]
	v_mad_i64_i32 v[134:135], s[0:1], v134, s52, v[156:157]
	v_lshl_add_u64 v[134:135], v[134:135], 0, v[158:159]
	global_store_dwordx2 v[134:135], v[160:161], off offset:128
	global_store_dwordx2 v[134:135], v[136:137], off offset:160
	s_nop 0
	v_ashrrev_i32_e32 v227, 31, v226
	v_lshlrev_b64 v[134:135], 7, v[226:227]
	v_lshl_add_u64 v[136:137], v[130:131], 0, v[134:135]
	global_load_dwordx4 v[170:173], v[136:137], off
	v_lshl_add_u64 v[134:135], v[132:133], 0, v[134:135]
	global_load_dwordx4 v[174:177], v[134:135], off
	global_load_dwordx4 v[178:181], v[136:137], off offset:16
	global_load_dwordx4 v[182:185], v[134:135], off offset:16
	v_add_u32_e32 v228, 16, v226
	v_ashrrev_i32_e32 v229, 31, v228
	v_lshlrev_b64 v[134:135], 7, v[228:229]
	v_lshl_add_u64 v[136:137], v[130:131], 0, v[134:135]
	global_load_dwordx4 v[186:189], v[136:137], off
	v_lshl_add_u64 v[134:135], v[132:133], 0, v[134:135]
	global_load_dwordx4 v[190:193], v[134:135], off
	global_load_dwordx4 v[194:197], v[136:137], off offset:16
	global_load_dwordx4 v[198:201], v[134:135], off offset:16
	v_add_u32_e32 v230, 32, v226
	v_ashrrev_i32_e32 v231, 31, v230
	v_lshlrev_b64 v[134:135], 7, v[230:231]
	v_lshl_add_u64 v[136:137], v[132:133], 0, v[134:135]
	v_lshl_add_u64 v[134:135], v[130:131], 0, v[134:135]
	global_load_dwordx4 v[202:205], v[136:137], off
	global_load_dwordx4 v[206:209], v[136:137], off offset:16
	global_load_dwordx4 v[210:213], v[134:135], off
	global_load_dwordx4 v[214:217], v[134:135], off offset:16
	v_add_u32_e32 v160, 48, v226
	v_ashrrev_i32_e32 v161, 31, v160
	v_lshlrev_b64 v[134:135], 7, v[160:161]
	v_lshl_add_u64 v[132:133], v[132:133], 0, v[134:135]
	v_lshl_add_u64 v[134:135], v[130:131], 0, v[134:135]
	global_load_dwordx4 v[218:221], v[132:133], off
	s_nop 0
	global_load_dwordx4 v[130:133], v[132:133], off offset:16
	s_nop 0
	global_load_dwordx4 v[222:225], v[134:135], off
	s_nop 0
	global_load_dwordx4 v[134:137], v[134:135], off offset:16
	s_waitcnt vmcnt(0) lgkmcnt(0)
	v_pk_mul_f32 v[232:233], v[56:57], v[172:173]
	v_pk_mul_f32 v[234:235], v[54:55], v[170:171]
	v_pk_mul_f32 v[172:173], v[64:65], v[172:173]
	v_pk_fma_f32 v[232:233], v[64:65], v[176:177], v[232:233] neg_lo:[0,0,1] neg_hi:[0,0,1]
	v_pk_fma_f32 v[234:235], v[62:63], v[174:175], v[234:235] neg_lo:[0,0,1] neg_hi:[0,0,1]
	v_pk_fma_f32 v[172:173], v[56:57], v[176:177], v[172:173]
	v_pk_mul_f32 v[176:177], v[46:47], v[178:179]
	v_pk_mul_f32 v[178:179], v[58:59], v[178:179]
	v_pk_fma_f32 v[176:177], v[58:59], v[182:183], v[176:177] neg_lo:[0,0,1] neg_hi:[0,0,1]
	v_pk_fma_f32 v[178:179], v[46:47], v[182:183], v[178:179]
	v_med3_f32 v161, v234, s51, v168
	v_med3_f32 v183, v235, s51, v168
	v_cvt_pk_fp8_f32 v182, v161, v183
	v_med3_f32 v176, v176, s51, v168
	v_med3_f32 v177, v177, s51, v168
	v_pk_mul_f32 v[170:171], v[62:63], v[170:171]
	v_cvt_pk_fp8_f32 v183, v176, v177
	v_pk_fma_f32 v[170:171], v[54:55], v[174:175], v[170:171]
	v_pk_mul_f32 v[174:175], v[48:49], v[180:181]
	v_pk_mul_f32 v[180:181], v[60:61], v[180:181]
	v_pk_fma_f32 v[174:175], v[60:61], v[184:185], v[174:175] neg_lo:[0,0,1] neg_hi:[0,0,1]
	v_pk_fma_f32 v[180:181], v[48:49], v[184:185], v[180:181]
	v_med3_f32 v161, v232, s51, v168
	v_med3_f32 v184, v233, s51, v168
	v_cvt_pk_fp8_f32 v182, v161, v184 op_sel:[0,0,1]
	v_med3_f32 v161, v174, s51, v168
	v_med3_f32 v174, v175, s51, v168
	v_cvt_pk_fp8_f32 v183, v161, v174 op_sel:[0,0,1]
	v_med3_f32 v161, v170, s51, v168
	v_med3_f32 v171, v171, s51, v168
	v_cvt_pk_fp8_f32 v170, v161, v171
	v_med3_f32 v161, v172, s51, v168
	v_med3_f32 v172, v173, s51, v168
	v_med3_f32 v173, v178, s51, v168
	v_med3_f32 v174, v179, s51, v168
	v_cvt_pk_fp8_f32 v171, v173, v174
	v_cvt_pk_fp8_f32 v170, v161, v172 op_sel:[0,0,1]
	v_med3_f32 v161, v180, s51, v168
	v_med3_f32 v172, v181, s51, v168
	v_cvt_pk_fp8_f32 v171, v161, v172 op_sel:[0,0,1]
	v_mad_i64_i32 v[172:173], s[0:1], v226, s52, v[156:157]
	v_lshl_add_u64 v[172:173], v[172:173], 0, v[158:159]
	global_store_dwordx2 v[172:173], v[182:183], off offset:128
	global_store_dwordx2 v[172:173], v[170:171], off offset:160
	v_pk_mul_f32 v[172:173], v[38:39], v[186:187]
	v_pk_mul_f32 v[170:171], v[40:41], v[188:189]
	v_pk_fma_f32 v[172:173], v[50:51], v[190:191], v[172:173] neg_lo:[0,0,1] neg_hi:[0,0,1]
	v_pk_mul_f32 v[180:181], v[30:31], v[194:195]
	v_pk_fma_f32 v[170:171], v[52:53], v[192:193], v[170:171] neg_lo:[0,0,1] neg_hi:[0,0,1]
	v_pk_fma_f32 v[180:181], v[42:43], v[198:199], v[180:181] neg_lo:[0,0,1] neg_hi:[0,0,1]
	v_med3_f32 v161, v172, s51, v168
	v_med3_f32 v173, v173, s51, v168
	v_cvt_pk_fp8_f32 v172, v161, v173
	v_med3_f32 v161, v170, s51, v168
	v_med3_f32 v170, v171, s51, v168
	v_med3_f32 v171, v180, s51, v168
	v_med3_f32 v180, v181, s51, v168
	v_cvt_pk_fp8_f32 v173, v171, v180
	v_pk_mul_f32 v[178:179], v[32:33], v[196:197]
	v_pk_mul_f32 v[176:177], v[50:51], v[186:187]
	v_pk_fma_f32 v[178:179], v[44:45], v[200:201], v[178:179] neg_lo:[0,0,1] neg_hi:[0,0,1]
	v_pk_mul_f32 v[174:175], v[52:53], v[188:189]
	v_pk_fma_f32 v[176:177], v[38:39], v[190:191], v[176:177]
	v_pk_mul_f32 v[184:185], v[42:43], v[194:195]
	v_cvt_pk_fp8_f32 v172, v161, v170 op_sel:[0,0,1]
	v_med3_f32 v161, v178, s51, v168
	v_med3_f32 v170, v179, s51, v168
	v_pk_fma_f32 v[174:175], v[40:41], v[192:193], v[174:175]
	v_pk_fma_f32 v[184:185], v[30:31], v[198:199], v[184:185]
	v_cvt_pk_fp8_f32 v173, v161, v170 op_sel:[0,0,1]
	v_med3_f32 v161, v176, s51, v168
	v_med3_f32 v171, v177, s51, v168
	v_cvt_pk_fp8_f32 v170, v161, v171
	v_med3_f32 v161, v174, s51, v168
	v_med3_f32 v174, v175, s51, v168
	v_med3_f32 v175, v184, s51, v168
	v_med3_f32 v176, v185, s51, v168
	v_cvt_pk_fp8_f32 v171, v175, v176
	v_pk_mul_f32 v[182:183], v[44:45], v[196:197]
	v_cvt_pk_fp8_f32 v170, v161, v174 op_sel:[0,0,1]
	v_pk_fma_f32 v[182:183], v[32:33], v[200:201], v[182:183]
	v_pk_mul_f32 v[180:181], v[14:15], v[214:215]
	v_med3_f32 v161, v182, s51, v168
	v_med3_f32 v174, v183, s51, v168
	v_cvt_pk_fp8_f32 v171, v161, v174 op_sel:[0,0,1]
	v_mad_i64_i32 v[174:175], s[0:1], v228, s52, v[156:157]
	v_lshl_add_u64 v[174:175], v[174:175], 0, v[158:159]
	global_store_dwordx2 v[174:175], v[172:173], off offset:128
	global_store_dwordx2 v[174:175], v[170:171], off offset:160
	v_pk_mul_f32 v[172:173], v[22:23], v[210:211]
	v_pk_mul_f32 v[170:171], v[24:25], v[212:213]
	v_pk_fma_f32 v[172:173], v[34:35], v[202:203], v[172:173] neg_lo:[0,0,1] neg_hi:[0,0,1]
	v_pk_fma_f32 v[170:171], v[36:37], v[204:205], v[170:171] neg_lo:[0,0,1] neg_hi:[0,0,1]
	v_pk_fma_f32 v[180:181], v[26:27], v[206:207], v[180:181] neg_lo:[0,0,1] neg_hi:[0,0,1]
	v_med3_f32 v161, v172, s51, v168
	v_med3_f32 v173, v173, s51, v168
	v_cvt_pk_fp8_f32 v172, v161, v173
	v_med3_f32 v161, v170, s51, v168
	v_med3_f32 v170, v171, s51, v168
	v_med3_f32 v171, v180, s51, v168
	v_med3_f32 v180, v181, s51, v168
	v_cvt_pk_fp8_f32 v173, v171, v180
	v_pk_mul_f32 v[178:179], v[16:17], v[216:217]
	v_pk_mul_f32 v[176:177], v[34:35], v[210:211]
	v_pk_fma_f32 v[178:179], v[28:29], v[208:209], v[178:179] neg_lo:[0,0,1] neg_hi:[0,0,1]
	v_pk_mul_f32 v[174:175], v[36:37], v[212:213]
	v_pk_fma_f32 v[176:177], v[22:23], v[202:203], v[176:177]
	v_pk_mul_f32 v[184:185], v[26:27], v[214:215]
	v_cvt_pk_fp8_f32 v172, v161, v170 op_sel:[0,0,1]
	v_med3_f32 v161, v178, s51, v168
	v_med3_f32 v170, v179, s51, v168
	v_pk_fma_f32 v[174:175], v[24:25], v[204:205], v[174:175]
	v_pk_fma_f32 v[184:185], v[14:15], v[206:207], v[184:185]
	v_cvt_pk_fp8_f32 v173, v161, v170 op_sel:[0,0,1]
	v_med3_f32 v161, v176, s51, v168
	v_med3_f32 v171, v177, s51, v168
	v_cvt_pk_fp8_f32 v170, v161, v171
	v_med3_f32 v161, v174, s51, v168
	v_med3_f32 v174, v175, s51, v168
	v_med3_f32 v175, v184, s51, v168
	v_med3_f32 v176, v185, s51, v168
	v_cvt_pk_fp8_f32 v171, v175, v176
	v_pk_mul_f32 v[182:183], v[28:29], v[216:217]
	v_cvt_pk_fp8_f32 v170, v161, v174 op_sel:[0,0,1]
	v_pk_fma_f32 v[182:183], v[16:17], v[208:209], v[182:183]
	v_pk_mul_f32 v[178:179], v[4:5], v[136:137]
	v_med3_f32 v161, v182, s51, v168
	v_med3_f32 v174, v183, s51, v168
	v_cvt_pk_fp8_f32 v171, v161, v174 op_sel:[0,0,1]
	v_mad_i64_i32 v[174:175], s[0:1], v230, s52, v[156:157]
	v_lshl_add_u64 v[174:175], v[174:175], 0, v[158:159]
	global_store_dwordx2 v[174:175], v[172:173], off offset:128
	global_store_dwordx2 v[174:175], v[170:171], off offset:160
	v_pk_mul_f32 v[172:173], v[6:7], v[222:223]
	v_pk_mul_f32 v[170:171], v[8:9], v[224:225]
	v_pk_fma_f32 v[172:173], v[18:19], v[218:219], v[172:173] neg_lo:[0,0,1] neg_hi:[0,0,1]
	v_pk_mul_f32 v[180:181], v[2:3], v[134:135]
	v_pk_mul_f32 v[136:137], v[12:13], v[136:137]
	v_pk_mul_f32 v[134:135], v[10:11], v[134:135]
	v_pk_fma_f32 v[170:171], v[20:21], v[220:221], v[170:171] neg_lo:[0,0,1] neg_hi:[0,0,1]
	v_pk_fma_f32 v[178:179], v[12:13], v[132:133], v[178:179] neg_lo:[0,0,1] neg_hi:[0,0,1]
	v_pk_fma_f32 v[180:181], v[10:11], v[130:131], v[180:181] neg_lo:[0,0,1] neg_hi:[0,0,1]
	v_pk_fma_f32 v[132:133], v[4:5], v[132:133], v[136:137]
	v_pk_fma_f32 v[130:131], v[2:3], v[130:131], v[134:135]
	v_med3_f32 v135, v172, s51, v168
	v_med3_f32 v136, v173, s51, v168
	v_cvt_pk_fp8_f32 v134, v135, v136
	v_med3_f32 v136, v170, s51, v168
	v_med3_f32 v161, v180, s51, v168
	v_med3_f32 v170, v181, s51, v168
	v_cvt_pk_fp8_f32 v135, v161, v170
	v_pk_mul_f32 v[176:177], v[18:19], v[222:223]
	v_med3_f32 v137, v171, s51, v168
	v_pk_fma_f32 v[176:177], v[6:7], v[218:219], v[176:177]
	v_cvt_pk_fp8_f32 v134, v136, v137 op_sel:[0,0,1]
	v_med3_f32 v136, v178, s51, v168
	v_med3_f32 v137, v179, s51, v168
	v_cvt_pk_fp8_f32 v135, v136, v137 op_sel:[0,0,1]
	v_med3_f32 v137, v176, s51, v168
	v_med3_f32 v161, v177, s51, v168
	v_cvt_pk_fp8_f32 v136, v137, v161
	v_med3_f32 v130, v130, s51, v168
	v_med3_f32 v131, v131, s51, v168
	v_cvt_pk_fp8_f32 v137, v130, v131
	v_pk_mul_f32 v[174:175], v[20:21], v[224:225]
	v_med3_f32 v130, v132, s51, v168
	v_pk_fma_f32 v[174:175], v[8:9], v[220:221], v[174:175]
	v_med3_f32 v131, v133, s51, v168
	v_med3_f32 v161, v174, s51, v168
	v_med3_f32 v170, v175, s51, v168
	v_cvt_pk_fp8_f32 v136, v161, v170 op_sel:[0,0,1]
	v_cvt_pk_fp8_f32 v137, v130, v131 op_sel:[0,0,1]
	v_mad_i64_i32 v[130:131], s[0:1], v160, s52, v[156:157]
	v_lshl_add_u64 v[130:131], v[130:131], 0, v[158:159]
	global_store_dwordx2 v[130:131], v[134:135], off offset:128
	global_store_dwordx2 v[130:131], v[136:137], off offset:160
.LBB0_2328:
	s_andn2_b64 vcc, exec, s[34:35]
	s_cbranch_vccnz .LBB0_2317
	v_max_f32_e32 v126, v126, v126
	v_med3_f32 v132, v126, s51, v168
	v_max_f32_e32 v126, v127, v127
	v_med3_f32 v127, v126, s51, v168
	v_cvt_pk_fp8_f32 v126, v132, v127
	v_max_f32_e32 v127, v128, v128
	v_max_f32_e32 v128, v129, v129
	v_med3_f32 v127, v127, s51, v168
	v_med3_f32 v128, v128, s51, v168
	v_max_f32_e32 v118, v118, v118
	v_cvt_pk_fp8_f32 v126, v127, v128 op_sel:[0,0,1]
	v_med3_f32 v128, v118, s51, v168
	v_max_f32_e32 v118, v119, v119
	v_med3_f32 v119, v118, s51, v168
	v_cvt_pk_fp8_f32 v118, v128, v119
	v_max_f32_e32 v122, v122, v122
	v_max_f32_e32 v123, v123, v123
	v_med3_f32 v122, v122, s51, v168
	v_med3_f32 v123, v123, s51, v168
	v_max_f32_e32 v119, v120, v120
	v_max_f32_e32 v120, v121, v121
	v_cvt_pk_fp8_f32 v127, v122, v123
	v_med3_f32 v119, v119, s51, v168
	v_med3_f32 v120, v120, s51, v168
	v_max_f32_e32 v110, v110, v110
	v_max_f32_e32 v111, v111, v111
	s_lshl_b32 s0, s56, 8
	v_cvt_pk_fp8_f32 v118, v119, v120 op_sel:[0,0,1]
	v_med3_f32 v110, v110, s51, v168
	v_med3_f32 v111, v111, s51, v168
	s_add_i32 s0, s0, s45
	v_max_f32_e32 v122, v124, v124
	v_max_f32_e32 v123, v125, v125
	v_cvt_pk_fp8_f32 v119, v110, v111
	v_add_u32_e32 v130, s0, v169
	v_med3_f32 v122, v122, s51, v168
	v_med3_f32 v123, v123, s51, v168
	s_mul_i32 s34, s57, 0x180
	v_mov_b32_e32 v131, v130
	v_cvt_pk_fp8_f32 v127, v122, v123 op_sel:[0,0,1]
	v_mov_b64_e32 v[122:123], s[22:23]
	v_max_f32_e32 v110, v112, v112
	v_max_f32_e32 v111, v113, v113
	s_ashr_i32 s35, s34, 31
	v_med3_f32 v110, v110, s51, v168
	v_mad_i64_i32 v[124:125], s[0:1], v131, s52, v[122:123]
	v_med3_f32 v111, v111, s51, v168
	v_lshl_add_u64 v[124:125], v[124:125], 0, s[34:35]
	v_cvt_pk_fp8_f32 v119, v110, v111 op_sel:[0,0,1]
	v_lshl_add_u64 v[110:111], v[124:125], 0, s[28:29]
	v_lshl_add_u64 v[110:111], v[110:111], 0, v[154:155]
	global_store_dwordx2 v[110:111], v[126:127], off
	global_store_dwordx2 v[110:111], v[118:119], off offset:192
	v_max_f32_e32 v110, v114, v114
	v_med3_f32 v111, v110, s51, v168
	v_max_f32_e32 v110, v115, v115
	v_med3_f32 v113, v110, s51, v168
	v_cvt_pk_fp8_f32 v110, v111, v113
	v_max_f32_e32 v111, v116, v116
	v_max_f32_e32 v113, v117, v117
	v_med3_f32 v111, v111, s51, v168
	v_med3_f32 v113, v113, s51, v168
	v_max_f32_e32 v106, v106, v106
	v_max_f32_e32 v107, v107, v107
	v_cvt_pk_fp8_f32 v110, v111, v113 op_sel:[0,0,1]
	v_med3_f32 v106, v106, s51, v168
	v_med3_f32 v107, v107, s51, v168
	v_max_f32_e32 v102, v102, v102
	v_cvt_pk_fp8_f32 v111, v106, v107
	v_max_f32_e32 v106, v108, v108
	v_med3_f32 v108, v102, s51, v168
	v_max_f32_e32 v102, v103, v103
	v_med3_f32 v103, v102, s51, v168
	v_cvt_pk_fp8_f32 v102, v108, v103
	v_max_f32_e32 v103, v104, v104
	v_max_f32_e32 v104, v105, v105
	v_med3_f32 v103, v103, s51, v168
	v_med3_f32 v104, v104, s51, v168
	v_max_f32_e32 v94, v94, v94
	v_max_f32_e32 v95, v95, v95
	v_cvt_pk_fp8_f32 v102, v103, v104 op_sel:[0,0,1]
	v_med3_f32 v94, v94, s51, v168
	v_med3_f32 v95, v95, s51, v168
	v_cvt_pk_fp8_f32 v103, v94, v95
	v_max_f32_e32 v107, v109, v109
	v_add_u32_e32 v112, 16, v130
	v_med3_f32 v106, v106, s51, v168
	v_med3_f32 v107, v107, s51, v168
	v_max_f32_e32 v94, v96, v96
	v_max_f32_e32 v95, v97, v97
	v_cvt_pk_fp8_f32 v111, v106, v107 op_sel:[0,0,1]
	v_mad_i64_i32 v[106:107], s[0:1], v112, s52, v[122:123]
	v_med3_f32 v94, v94, s51, v168
	v_med3_f32 v95, v95, s51, v168
	v_lshl_add_u64 v[106:107], v[106:107], 0, s[34:35]
	v_cvt_pk_fp8_f32 v103, v94, v95 op_sel:[0,0,1]
	v_lshl_add_u64 v[94:95], v[106:107], 0, s[28:29]
	v_lshl_add_u64 v[94:95], v[94:95], 0, v[154:155]
	global_store_dwordx2 v[94:95], v[110:111], off
	global_store_dwordx2 v[94:95], v[102:103], off offset:192
	v_max_f32_e32 v94, v98, v98
	v_med3_f32 v95, v94, s51, v168
	v_max_f32_e32 v94, v99, v99
	v_med3_f32 v97, v94, s51, v168
	v_cvt_pk_fp8_f32 v94, v95, v97
	v_max_f32_e32 v95, v100, v100
	v_max_f32_e32 v97, v101, v101
	v_med3_f32 v95, v95, s51, v168
	v_med3_f32 v97, v97, s51, v168
	v_max_f32_e32 v90, v90, v90
	v_max_f32_e32 v91, v91, v91
	v_cvt_pk_fp8_f32 v94, v95, v97 op_sel:[0,0,1]
	v_med3_f32 v90, v90, s51, v168
	v_med3_f32 v91, v91, s51, v168
	v_max_f32_e32 v86, v86, v86
	v_cvt_pk_fp8_f32 v95, v90, v91
	v_max_f32_e32 v90, v92, v92
	v_med3_f32 v92, v86, s51, v168
	v_max_f32_e32 v86, v87, v87
	v_med3_f32 v87, v86, s51, v168
	v_cvt_pk_fp8_f32 v86, v92, v87
	v_max_f32_e32 v87, v88, v88
	v_max_f32_e32 v88, v89, v89
	v_med3_f32 v87, v87, s51, v168
	v_med3_f32 v88, v88, s51, v168
	v_max_f32_e32 v78, v78, v78
	v_max_f32_e32 v79, v79, v79
	v_cvt_pk_fp8_f32 v86, v87, v88 op_sel:[0,0,1]
	v_med3_f32 v78, v78, s51, v168
	v_med3_f32 v79, v79, s51, v168
	v_cvt_pk_fp8_f32 v87, v78, v79
	v_max_f32_e32 v91, v93, v93
	v_add_u32_e32 v96, 32, v130
	v_med3_f32 v90, v90, s51, v168
	v_med3_f32 v91, v91, s51, v168
	v_max_f32_e32 v78, v80, v80
	v_max_f32_e32 v79, v81, v81
	v_cvt_pk_fp8_f32 v95, v90, v91 op_sel:[0,0,1]
	v_mad_i64_i32 v[90:91], s[0:1], v96, s52, v[122:123]
	v_med3_f32 v78, v78, s51, v168
	v_med3_f32 v79, v79, s51, v168
	v_lshl_add_u64 v[90:91], v[90:91], 0, s[34:35]
	v_cvt_pk_fp8_f32 v87, v78, v79 op_sel:[0,0,1]
	v_lshl_add_u64 v[78:79], v[90:91], 0, s[28:29]
	v_lshl_add_u64 v[78:79], v[78:79], 0, v[154:155]
	global_store_dwordx2 v[78:79], v[94:95], off
	global_store_dwordx2 v[78:79], v[86:87], off offset:192
	v_max_f32_e32 v78, v82, v82
	v_med3_f32 v79, v78, s51, v168
	v_max_f32_e32 v78, v83, v83
	v_med3_f32 v81, v78, s51, v168
	v_cvt_pk_fp8_f32 v78, v79, v81
	v_max_f32_e32 v79, v84, v84
	v_max_f32_e32 v81, v85, v85
	v_med3_f32 v79, v79, s51, v168
	v_med3_f32 v81, v81, s51, v168
	v_max_f32_e32 v74, v74, v74
	v_max_f32_e32 v75, v75, v75
	v_cvt_pk_fp8_f32 v78, v79, v81 op_sel:[0,0,1]
	v_med3_f32 v74, v74, s51, v168
	v_med3_f32 v75, v75, s51, v168
	v_max_f32_e32 v70, v70, v70
	v_cvt_pk_fp8_f32 v79, v74, v75
	v_max_f32_e32 v74, v76, v76
	v_med3_f32 v76, v70, s51, v168
	v_max_f32_e32 v70, v71, v71
	v_med3_f32 v71, v70, s51, v168
	v_cvt_pk_fp8_f32 v70, v76, v71
	v_max_f32_e32 v71, v72, v72
	v_max_f32_e32 v72, v73, v73
	v_med3_f32 v71, v71, s51, v168
	v_med3_f32 v72, v72, s51, v168
	v_max_f32_e32 v66, v66, v66
	v_max_f32_e32 v67, v67, v67
	v_cvt_pk_fp8_f32 v70, v71, v72 op_sel:[0,0,1]
	v_med3_f32 v66, v66, s51, v168
	v_med3_f32 v67, v67, s51, v168
	v_cvt_pk_fp8_f32 v71, v66, v67
	v_max_f32_e32 v75, v77, v77
	v_add_u32_e32 v80, 48, v130
	v_med3_f32 v74, v74, s51, v168
	v_med3_f32 v75, v75, s51, v168
	v_max_f32_e32 v66, v68, v68
	v_max_f32_e32 v67, v69, v69
	v_cvt_pk_fp8_f32 v79, v74, v75 op_sel:[0,0,1]
	v_mad_i64_i32 v[74:75], s[0:1], v80, s52, v[122:123]
	v_med3_f32 v66, v66, s51, v168
	v_med3_f32 v67, v67, s51, v168
	v_lshl_add_u64 v[74:75], v[74:75], 0, s[34:35]
	v_cvt_pk_fp8_f32 v71, v66, v67 op_sel:[0,0,1]
	v_lshl_add_u64 v[66:67], v[74:75], 0, s[28:29]
	v_lshl_add_u64 v[66:67], v[66:67], 0, v[154:155]
	v_max_f32_e32 v62, v62, v62
	global_store_dwordx2 v[66:67], v[78:79], off
	global_store_dwordx2 v[66:67], v[70:71], off offset:192
	v_med3_f32 v67, v62, s51, v168
	v_max_f32_e32 v62, v63, v63
	v_med3_f32 v63, v62, s51, v168
	v_cvt_pk_fp8_f32 v62, v67, v63
	v_max_f32_e32 v63, v64, v64
	v_max_f32_e32 v64, v65, v65
	v_med3_f32 v63, v63, s51, v168
	v_med3_f32 v64, v64, s51, v168
	v_max_f32_e32 v58, v58, v58
	v_max_f32_e32 v59, v59, v59
	v_cvt_pk_fp8_f32 v62, v63, v64 op_sel:[0,0,1]
	v_med3_f32 v58, v58, s51, v168
	v_med3_f32 v59, v59, s51, v168
	v_max_f32_e32 v54, v54, v54
	v_cvt_pk_fp8_f32 v63, v58, v59
	v_max_f32_e32 v58, v60, v60
	v_med3_f32 v60, v54, s51, v168
	v_max_f32_e32 v54, v55, v55
	v_med3_f32 v55, v54, s51, v168
	v_cvt_pk_fp8_f32 v54, v60, v55
	v_max_f32_e32 v55, v56, v56
	v_max_f32_e32 v56, v57, v57
	v_med3_f32 v55, v55, s51, v168
	v_med3_f32 v56, v56, s51, v168
	v_max_f32_e32 v46, v46, v46
	v_max_f32_e32 v47, v47, v47
	v_cvt_pk_fp8_f32 v54, v55, v56 op_sel:[0,0,1]
	v_med3_f32 v46, v46, s51, v168
	v_med3_f32 v47, v47, s51, v168
	v_cvt_pk_fp8_f32 v55, v46, v47
	v_max_f32_e32 v59, v61, v61
	v_add_u32_e32 v66, 0x80, v130
	v_med3_f32 v58, v58, s51, v168
	v_med3_f32 v59, v59, s51, v168
	v_max_f32_e32 v46, v48, v48
	v_max_f32_e32 v47, v49, v49
	v_cvt_pk_fp8_f32 v63, v58, v59 op_sel:[0,0,1]
	v_mad_i64_i32 v[58:59], s[0:1], v66, s52, v[122:123]
	v_med3_f32 v46, v46, s51, v168
	v_med3_f32 v47, v47, s51, v168
	v_lshl_add_u64 v[58:59], v[58:59], 0, s[34:35]
	v_cvt_pk_fp8_f32 v55, v46, v47 op_sel:[0,0,1]
	v_lshl_add_u64 v[46:47], v[58:59], 0, s[28:29]
	v_lshl_add_u64 v[46:47], v[46:47], 0, v[154:155]
	global_store_dwordx2 v[46:47], v[62:63], off
	global_store_dwordx2 v[46:47], v[54:55], off offset:192
	v_max_f32_e32 v46, v50, v50
	v_med3_f32 v47, v46, s51, v168
	v_max_f32_e32 v46, v51, v51
	v_med3_f32 v49, v46, s51, v168
	v_cvt_pk_fp8_f32 v46, v47, v49
	v_max_f32_e32 v47, v52, v52
	v_max_f32_e32 v49, v53, v53
	v_med3_f32 v47, v47, s51, v168
	v_med3_f32 v49, v49, s51, v168
	v_max_f32_e32 v42, v42, v42
	v_max_f32_e32 v43, v43, v43
	v_cvt_pk_fp8_f32 v46, v47, v49 op_sel:[0,0,1]
	v_med3_f32 v42, v42, s51, v168
	v_med3_f32 v43, v43, s51, v168
	v_max_f32_e32 v38, v38, v38
	v_cvt_pk_fp8_f32 v47, v42, v43
	v_max_f32_e32 v42, v44, v44
	v_med3_f32 v44, v38, s51, v168
	v_max_f32_e32 v38, v39, v39
	v_med3_f32 v39, v38, s51, v168
	v_cvt_pk_fp8_f32 v38, v44, v39
	v_max_f32_e32 v39, v40, v40
	v_max_f32_e32 v40, v41, v41
	v_med3_f32 v39, v39, s51, v168
	v_med3_f32 v40, v40, s51, v168
	v_max_f32_e32 v30, v30, v30
	v_max_f32_e32 v31, v31, v31
	v_cvt_pk_fp8_f32 v38, v39, v40 op_sel:[0,0,1]
	v_med3_f32 v30, v30, s51, v168
	v_med3_f32 v31, v31, s51, v168
	v_cvt_pk_fp8_f32 v39, v30, v31
	v_max_f32_e32 v43, v45, v45
	v_add_u32_e32 v48, 0x90, v130
	v_med3_f32 v42, v42, s51, v168
	v_med3_f32 v43, v43, s51, v168
	v_max_f32_e32 v30, v32, v32
	v_max_f32_e32 v31, v33, v33
	v_cvt_pk_fp8_f32 v47, v42, v43 op_sel:[0,0,1]
	v_mad_i64_i32 v[42:43], s[0:1], v48, s52, v[122:123]
	v_med3_f32 v30, v30, s51, v168
	v_med3_f32 v31, v31, s51, v168
	v_lshl_add_u64 v[42:43], v[42:43], 0, s[34:35]
	v_cvt_pk_fp8_f32 v39, v30, v31 op_sel:[0,0,1]
	v_lshl_add_u64 v[30:31], v[42:43], 0, s[28:29]
	v_lshl_add_u64 v[30:31], v[30:31], 0, v[154:155]
	global_store_dwordx2 v[30:31], v[46:47], off
	global_store_dwordx2 v[30:31], v[38:39], off offset:192
	v_max_f32_e32 v30, v34, v34
	v_med3_f32 v31, v30, s51, v168
	v_max_f32_e32 v30, v35, v35
	v_med3_f32 v33, v30, s51, v168
	v_cvt_pk_fp8_f32 v30, v31, v33
	v_max_f32_e32 v31, v36, v36
	v_max_f32_e32 v33, v37, v37
	v_med3_f32 v31, v31, s51, v168
	v_med3_f32 v33, v33, s51, v168
	v_max_f32_e32 v26, v26, v26
	v_max_f32_e32 v27, v27, v27
	v_cvt_pk_fp8_f32 v30, v31, v33 op_sel:[0,0,1]
	v_med3_f32 v26, v26, s51, v168
	v_med3_f32 v27, v27, s51, v168
	v_max_f32_e32 v22, v22, v22
	v_cvt_pk_fp8_f32 v31, v26, v27
	v_max_f32_e32 v26, v28, v28
	v_med3_f32 v28, v22, s51, v168
	v_max_f32_e32 v22, v23, v23
	v_med3_f32 v23, v22, s51, v168
	v_cvt_pk_fp8_f32 v22, v28, v23
	v_max_f32_e32 v23, v24, v24
	v_max_f32_e32 v24, v25, v25
	v_med3_f32 v23, v23, s51, v168
	v_med3_f32 v24, v24, s51, v168
	v_max_f32_e32 v14, v14, v14
	v_max_f32_e32 v15, v15, v15
	v_cvt_pk_fp8_f32 v22, v23, v24 op_sel:[0,0,1]
	v_med3_f32 v14, v14, s51, v168
	v_med3_f32 v15, v15, s51, v168
	v_cvt_pk_fp8_f32 v23, v14, v15
	v_max_f32_e32 v27, v29, v29
	v_add_u32_e32 v32, 0xa0, v130
	v_med3_f32 v26, v26, s51, v168
	v_med3_f32 v27, v27, s51, v168
	v_max_f32_e32 v14, v16, v16
	v_max_f32_e32 v15, v17, v17
	v_cvt_pk_fp8_f32 v31, v26, v27 op_sel:[0,0,1]
	v_mad_i64_i32 v[26:27], s[0:1], v32, s52, v[122:123]
	v_med3_f32 v14, v14, s51, v168
	v_med3_f32 v15, v15, s51, v168
	v_lshl_add_u64 v[26:27], v[26:27], 0, s[34:35]
	v_cvt_pk_fp8_f32 v23, v14, v15 op_sel:[0,0,1]
	v_lshl_add_u64 v[14:15], v[26:27], 0, s[28:29]
	v_lshl_add_u64 v[14:15], v[14:15], 0, v[154:155]
	global_store_dwordx2 v[14:15], v[30:31], off
	global_store_dwordx2 v[14:15], v[22:23], off offset:192
	v_max_f32_e32 v14, v18, v18
	v_med3_f32 v15, v14, s51, v168
	v_max_f32_e32 v14, v19, v19
	v_med3_f32 v17, v14, s51, v168
	v_cvt_pk_fp8_f32 v14, v15, v17
	v_max_f32_e32 v15, v20, v20
	v_max_f32_e32 v17, v21, v21
	v_med3_f32 v15, v15, s51, v168
	v_med3_f32 v17, v17, s51, v168
	v_max_f32_e32 v10, v10, v10
	v_max_f32_e32 v11, v11, v11
	v_cvt_pk_fp8_f32 v14, v15, v17 op_sel:[0,0,1]
	v_med3_f32 v10, v10, s51, v168
	v_med3_f32 v11, v11, s51, v168
	v_max_f32_e32 v6, v6, v6
	v_cvt_pk_fp8_f32 v15, v10, v11
	v_max_f32_e32 v10, v12, v12
	v_med3_f32 v12, v6, s51, v168
	v_max_f32_e32 v6, v7, v7
	v_med3_f32 v7, v6, s51, v168
	v_cvt_pk_fp8_f32 v6, v12, v7
	v_max_f32_e32 v7, v8, v8
	v_max_f32_e32 v8, v9, v9
	v_med3_f32 v7, v7, s51, v168
	v_med3_f32 v8, v8, s51, v168
	v_max_f32_e32 v2, v2, v2
	v_max_f32_e32 v3, v3, v3
	v_cvt_pk_fp8_f32 v6, v7, v8 op_sel:[0,0,1]
	v_med3_f32 v2, v2, s51, v168
	v_med3_f32 v3, v3, s51, v168
	v_cvt_pk_fp8_f32 v7, v2, v3
	v_max_f32_e32 v11, v13, v13
	v_add_u32_e32 v16, 0xb0, v130
	v_med3_f32 v10, v10, s51, v168
	v_med3_f32 v11, v11, s51, v168
	v_max_f32_e32 v2, v4, v4
	v_max_f32_e32 v3, v5, v5
	v_cvt_pk_fp8_f32 v15, v10, v11 op_sel:[0,0,1]
	v_mad_i64_i32 v[10:11], s[0:1], v16, s52, v[122:123]
	v_med3_f32 v2, v2, s51, v168
	v_med3_f32 v3, v3, s51, v168
	v_lshl_add_u64 v[10:11], v[10:11], 0, s[34:35]
	v_cvt_pk_fp8_f32 v7, v2, v3 op_sel:[0,0,1]
	v_lshl_add_u64 v[2:3], v[10:11], 0, s[28:29]
	v_lshl_add_u64 v[2:3], v[2:3], 0, v[154:155]
	global_store_dwordx2 v[2:3], v[14:15], off
	global_store_dwordx2 v[2:3], v[6:7], off offset:192
	s_branch .LBB0_2317

.LBB0_2344:
	s_add_u32 s39, s30, s38
	s_addc_u32 s40, s31, 0
	s_add_u32 s41, s39, 0x100
	s_addc_u32 s42, s40, 0
	s_and_b64 s[0:1], s[36:37], exec
	s_cselect_b32 s43, s21, s42
	s_cselect_b32 s42, s62, s41
	s_add_u32 s0, s28, s38
	s_addc_u32 s1, s29, 0
	s_add_u32 s38, s0, 0x100
	s_addc_u32 s41, s1, 0
	s_and_b64 s[0:1], s[36:37], exec
	s_cselect_b32 s45, s19, s41
	s_cselect_b32 s44, s63, s38
	s_add_u32 s46, s39, 0x10080
	s_addc_u32 s47, s40, 0
	s_add_i32 s70, s58, s9
	s_add_i32 m0, s27, 0xc000
	s_add_i32 s71, s27, 0xe000
	s_add_i32 s0, s70, 0x2000
	s_add_u32 s40, s44, 0x10000
	s_addc_u32 s41, s45, 0
	s_add_i32 s77, s59, s9
	ds_read_b128 v[152:155], v147
	ds_read_b128 v[156:159], v147 offset:1024
	ds_read_b128 v[160:163], v147 offset:2048
	ds_read_b128 v[164:167], v147 offset:3072
	s_add_i32 s1, s77, 0x2000
	s_add_i32 s73, 0, 0x18000
	s_add_u32 s38, s42, 0x10000
	s_addc_u32 s39, s43, 0
	s_add_i32 s72, s73, s9
	s_add_i32 s69, 0, 0x1c000
	s_add_i32 s67, s72, 0x2000
	s_add_u32 s36, s44, 0x10080
	s_addc_u32 s37, s45, 0
	s_add_i32 s65, s69, s9
	s_add_i32 s64, s65, 0x2000
	v_lshl_add_u64 v[142:143], s[46:47], 0, v[136:137]
	ds_read_b128 v[168:171], v148
	ds_read_b128 v[172:175], v148 offset:1024
	ds_read_b128 v[176:179], v148 offset:2048
	ds_read_b128 v[180:183], v148 offset:3072
	ds_read_b128 v[184:187], v148 offset:4096
	ds_read_b128 v[188:191], v148 offset:5120
	ds_read_b128 v[192:195], v148 offset:6144
	ds_read_b128 v[196:199], v148 offset:7168
	global_load_lds_dwordx4 v[142:143], off
	v_lshl_add_u64 v[142:143], s[46:47], 0, v[132:133]
	s_mov_b32 m0, s71
	s_nop 0
	global_load_lds_dwordx4 v[142:143], off
	s_waitcnt lgkmcnt(8)
	s_waitcnt vmcnt(10)
	s_barrier
	s_waitcnt lgkmcnt(0)
	s_waitcnt lgkmcnt(0)
	v_mfma_f32_16x16x32_bf16 v[126:129], v[152:155], v[168:171], v[126:129]
	v_mfma_f32_16x16x32_bf16 v[122:125], v[160:163], v[168:171], v[122:125]
	v_mfma_f32_16x16x32_bf16 v[110:113], v[152:155], v[176:179], v[110:113]
	v_mfma_f32_16x16x32_bf16 v[106:109], v[160:163], v[176:179], v[106:109]
	v_mfma_f32_16x16x32_bf16 v[94:97], v[152:155], v[184:187], v[94:97]
	v_mfma_f32_16x16x32_bf16 v[90:93], v[160:163], v[184:187], v[90:93]
	v_mfma_f32_16x16x32_bf16 v[78:81], v[152:155], v[192:195], v[78:81]
	v_mfma_f32_16x16x32_bf16 v[74:77], v[160:163], v[192:195], v[74:77]
	v_mfma_f32_16x16x32_bf16 v[126:129], v[156:159], v[172:175], v[126:129]
	v_mfma_f32_16x16x32_bf16 v[122:125], v[164:167], v[172:175], v[122:125]
	v_mfma_f32_16x16x32_bf16 v[110:113], v[156:159], v[180:183], v[110:113]
	v_mfma_f32_16x16x32_bf16 v[106:109], v[164:167], v[180:183], v[106:109]
	v_mfma_f32_16x16x32_bf16 v[94:97], v[156:159], v[188:191], v[94:97]
	v_mfma_f32_16x16x32_bf16 v[90:93], v[164:167], v[188:191], v[90:93]
	v_mfma_f32_16x16x32_bf16 v[78:81], v[156:159], v[196:199], v[78:81]
	v_mfma_f32_16x16x32_bf16 v[74:77], v[164:167], v[196:199], v[74:77]
	s_barrier
	s_mov_b32 m0, s70
	v_lshl_add_u64 v[142:143], s[44:45], 0, v[134:135]
	ds_read_b128 v[200:203], v149
	ds_read_b128 v[204:207], v149 offset:1024
	ds_read_b128 v[208:211], v149 offset:2048
	ds_read_b128 v[212:215], v149 offset:3072
	global_load_lds_dwordx4 v[142:143], off
	v_lshl_add_u64 v[216:217], s[44:45], 0, v[130:131]
	s_mov_b32 m0, s0
	s_nop 0
	global_load_lds_dwordx4 v[216:217], off
	s_waitcnt vmcnt(10)
	s_barrier
	s_waitcnt lgkmcnt(0)
	s_waitcnt lgkmcnt(0)
	v_mfma_f32_16x16x32_bf16 v[118:121], v[200:203], v[168:171], v[118:121]
	v_mfma_f32_16x16x32_bf16 v[114:117], v[208:211], v[168:171], v[114:117]
	v_mfma_f32_16x16x32_bf16 v[102:105], v[200:203], v[176:179], v[102:105]
	v_mfma_f32_16x16x32_bf16 v[98:101], v[208:211], v[176:179], v[98:101]
	v_mfma_f32_16x16x32_bf16 v[86:89], v[200:203], v[184:187], v[86:89]
	v_mfma_f32_16x16x32_bf16 v[82:85], v[208:211], v[184:187], v[82:85]
	v_mfma_f32_16x16x32_bf16 v[70:73], v[200:203], v[192:195], v[70:73]
	v_mfma_f32_16x16x32_bf16 v[66:69], v[208:211], v[192:195], v[66:69]
	v_mfma_f32_16x16x32_bf16 v[118:121], v[204:207], v[172:175], v[118:121]
	v_mfma_f32_16x16x32_bf16 v[114:117], v[212:215], v[172:175], v[114:117]
	v_mfma_f32_16x16x32_bf16 v[102:105], v[204:207], v[180:183], v[102:105]
	v_mfma_f32_16x16x32_bf16 v[98:101], v[212:215], v[180:183], v[98:101]
	v_mfma_f32_16x16x32_bf16 v[86:89], v[204:207], v[188:191], v[86:89]
	v_mfma_f32_16x16x32_bf16 v[82:85], v[212:215], v[188:191], v[82:85]
	v_mfma_f32_16x16x32_bf16 v[70:73], v[204:207], v[196:199], v[70:73]
	v_mfma_f32_16x16x32_bf16 v[66:69], v[212:215], v[196:199], v[66:69]
	s_mov_b32 m0, s27
	v_lshl_add_u64 v[218:219], s[42:43], 0, v[136:137]
	s_barrier
	ds_read_b128 v[168:171], v148 offset:16384
	ds_read_b128 v[172:175], v148 offset:17408
	ds_read_b128 v[176:179], v148 offset:18432
	ds_read_b128 v[180:183], v148 offset:19456
	ds_read_b128 v[184:187], v148 offset:20480
	ds_read_b128 v[188:191], v148 offset:21504
	ds_read_b128 v[192:195], v148 offset:22528
	ds_read_b128 v[196:199], v148 offset:23552
	global_load_lds_dwordx4 v[218:219], off
	v_lshl_add_u64 v[220:221], s[42:43], 0, v[132:133]
	s_mov_b32 m0, s48
	s_nop 0
	global_load_lds_dwordx4 v[220:221], off
	s_waitcnt vmcnt(10)
	s_barrier
	s_waitcnt lgkmcnt(0)
	s_waitcnt lgkmcnt(0)
	v_mfma_f32_16x16x32_bf16 v[62:65], v[152:155], v[168:171], v[62:65]
	v_mfma_f32_16x16x32_bf16 v[58:61], v[160:163], v[168:171], v[58:61]
	v_mfma_f32_16x16x32_bf16 v[46:49], v[152:155], v[176:179], v[46:49]
	v_mfma_f32_16x16x32_bf16 v[42:45], v[160:163], v[176:179], v[42:45]
	v_mfma_f32_16x16x32_bf16 v[30:33], v[152:155], v[184:187], v[30:33]
	v_mfma_f32_16x16x32_bf16 v[26:29], v[160:163], v[184:187], v[26:29]
	v_mfma_f32_16x16x32_bf16 v[14:17], v[152:155], v[192:195], v[14:17]
	v_mfma_f32_16x16x32_bf16 v[10:13], v[160:163], v[192:195], v[10:13]
	v_mfma_f32_16x16x32_bf16 v[62:65], v[156:159], v[172:175], v[62:65]
	v_mfma_f32_16x16x32_bf16 v[58:61], v[164:167], v[172:175], v[58:61]
	v_mfma_f32_16x16x32_bf16 v[46:49], v[156:159], v[180:183], v[46:49]
	v_mfma_f32_16x16x32_bf16 v[42:45], v[164:167], v[180:183], v[42:45]
	v_mfma_f32_16x16x32_bf16 v[30:33], v[156:159], v[188:191], v[30:33]
	v_mfma_f32_16x16x32_bf16 v[26:29], v[164:167], v[188:191], v[26:29]
	v_mfma_f32_16x16x32_bf16 v[14:17], v[156:159], v[196:199], v[14:17]
	v_mfma_f32_16x16x32_bf16 v[10:13], v[164:167], v[196:199], v[10:13]
	s_barrier
	s_mov_b32 m0, s77
	v_lshl_add_u64 v[152:153], s[40:41], 0, v[134:135]
	global_load_lds_dwordx4 v[152:153], off
	v_lshl_add_u64 v[152:153], s[40:41], 0, v[130:131]
	s_mov_b32 m0, s1
	s_nop 0
	global_load_lds_dwordx4 v[152:153], off
	s_waitcnt vmcnt(10)
	s_barrier
	v_mfma_f32_16x16x32_bf16 v[54:57], v[200:203], v[168:171], v[54:57]
	v_mfma_f32_16x16x32_bf16 v[50:53], v[208:211], v[168:171], v[50:53]
	v_mfma_f32_16x16x32_bf16 v[38:41], v[200:203], v[176:179], v[38:41]
	v_mfma_f32_16x16x32_bf16 v[34:37], v[208:211], v[176:179], v[34:37]
	v_mfma_f32_16x16x32_bf16 v[22:25], v[200:203], v[184:187], v[22:25]
	v_mfma_f32_16x16x32_bf16 v[18:21], v[208:211], v[184:187], v[18:21]
	v_mfma_f32_16x16x32_bf16 v[6:9], v[200:203], v[192:195], v[6:9]
	v_mfma_f32_16x16x32_bf16 v[2:5], v[208:211], v[192:195], v[2:5]
	v_mfma_f32_16x16x32_bf16 v[54:57], v[204:207], v[172:175], v[54:57]
	v_mfma_f32_16x16x32_bf16 v[50:53], v[212:215], v[172:175], v[50:53]
	v_mfma_f32_16x16x32_bf16 v[38:41], v[204:207], v[180:183], v[38:41]
	v_mfma_f32_16x16x32_bf16 v[34:37], v[212:215], v[180:183], v[34:37]
	v_mfma_f32_16x16x32_bf16 v[22:25], v[204:207], v[188:191], v[22:25]
	v_mfma_f32_16x16x32_bf16 v[18:21], v[212:215], v[188:191], v[18:21]
	v_mfma_f32_16x16x32_bf16 v[6:9], v[204:207], v[196:199], v[6:9]
	v_mfma_f32_16x16x32_bf16 v[2:5], v[212:215], v[196:199], v[2:5]
	v_add_u32_e32 v151, s73, v146
	s_barrier
	ds_read_b128 v[152:155], v151
	ds_read_b128 v[156:159], v151 offset:1024
	ds_read_b128 v[160:163], v151 offset:2048
	ds_read_b128 v[164:167], v151 offset:3072
	s_mov_b32 m0, s49
	v_lshl_add_u64 v[200:201], s[38:39], 0, v[136:137]
	ds_read_b128 v[168:171], v148 offset:32768
	ds_read_b128 v[172:175], v148 offset:33792
	ds_read_b128 v[176:179], v148 offset:34816
	ds_read_b128 v[180:183], v148 offset:35840
	ds_read_b128 v[184:187], v148 offset:36864
	ds_read_b128 v[188:191], v148 offset:37888
	ds_read_b128 v[192:195], v148 offset:38912
	ds_read_b128 v[196:199], v148 offset:39936
	global_load_lds_dwordx4 v[200:201], off
	v_lshl_add_u64 v[200:201], s[38:39], 0, v[132:133]
	s_mov_b32 m0, s50
	s_nop 0
	global_load_lds_dwordx4 v[200:201], off
	s_waitcnt lgkmcnt(8)
	s_waitcnt vmcnt(10)
	s_barrier
	s_waitcnt lgkmcnt(0)
	s_waitcnt lgkmcnt(0)
	v_mfma_f32_16x16x32_bf16 v[126:129], v[152:155], v[168:171], v[126:129]
	v_mfma_f32_16x16x32_bf16 v[122:125], v[160:163], v[168:171], v[122:125]
	v_mfma_f32_16x16x32_bf16 v[110:113], v[152:155], v[176:179], v[110:113]
	v_mfma_f32_16x16x32_bf16 v[106:109], v[160:163], v[176:179], v[106:109]
	v_mfma_f32_16x16x32_bf16 v[94:97], v[152:155], v[184:187], v[94:97]
	v_mfma_f32_16x16x32_bf16 v[90:93], v[160:163], v[184:187], v[90:93]
	v_mfma_f32_16x16x32_bf16 v[78:81], v[152:155], v[192:195], v[78:81]
	v_mfma_f32_16x16x32_bf16 v[74:77], v[160:163], v[192:195], v[74:77]
	v_mfma_f32_16x16x32_bf16 v[126:129], v[156:159], v[172:175], v[126:129]
	v_mfma_f32_16x16x32_bf16 v[122:125], v[164:167], v[172:175], v[122:125]
	v_mfma_f32_16x16x32_bf16 v[110:113], v[156:159], v[180:183], v[110:113]
	v_mfma_f32_16x16x32_bf16 v[106:109], v[164:167], v[180:183], v[106:109]
	v_mfma_f32_16x16x32_bf16 v[94:97], v[156:159], v[188:191], v[94:97]
	v_mfma_f32_16x16x32_bf16 v[90:93], v[164:167], v[188:191], v[90:93]
	v_mfma_f32_16x16x32_bf16 v[78:81], v[156:159], v[196:199], v[78:81]
	v_mfma_f32_16x16x32_bf16 v[74:77], v[164:167], v[196:199], v[74:77]
	s_barrier
	s_mov_b32 m0, s72
	v_add_u32_e32 v151, s69, v146
	v_lshl_add_u64 v[142:143], v[142:143], 0, s[16:17]
	ds_read_b128 v[200:203], v151
	ds_read_b128 v[204:207], v151 offset:1024
	ds_read_b128 v[208:211], v151 offset:2048
	ds_read_b128 v[212:215], v151 offset:3072
	global_load_lds_dwordx4 v[142:143], off
	v_lshl_add_u64 v[142:143], v[216:217], 0, s[16:17]
	s_mov_b32 m0, s67
	s_nop 0
	global_load_lds_dwordx4 v[142:143], off
	s_waitcnt vmcnt(10)
	s_barrier
	s_waitcnt lgkmcnt(0)
	s_waitcnt lgkmcnt(0)
	v_mfma_f32_16x16x32_bf16 v[118:121], v[200:203], v[168:171], v[118:121]
	v_mfma_f32_16x16x32_bf16 v[114:117], v[208:211], v[168:171], v[114:117]
	v_mfma_f32_16x16x32_bf16 v[102:105], v[200:203], v[176:179], v[102:105]
	v_mfma_f32_16x16x32_bf16 v[98:101], v[208:211], v[176:179], v[98:101]
	v_mfma_f32_16x16x32_bf16 v[86:89], v[200:203], v[184:187], v[86:89]
	v_mfma_f32_16x16x32_bf16 v[82:85], v[208:211], v[184:187], v[82:85]
	v_mfma_f32_16x16x32_bf16 v[70:73], v[200:203], v[192:195], v[70:73]
	v_mfma_f32_16x16x32_bf16 v[66:69], v[208:211], v[192:195], v[66:69]
	v_mfma_f32_16x16x32_bf16 v[118:121], v[204:207], v[172:175], v[118:121]
	v_mfma_f32_16x16x32_bf16 v[114:117], v[212:215], v[172:175], v[114:117]
	v_mfma_f32_16x16x32_bf16 v[102:105], v[204:207], v[180:183], v[102:105]
	v_mfma_f32_16x16x32_bf16 v[98:101], v[212:215], v[180:183], v[98:101]
	v_mfma_f32_16x16x32_bf16 v[86:89], v[204:207], v[188:191], v[86:89]
	v_mfma_f32_16x16x32_bf16 v[82:85], v[212:215], v[188:191], v[82:85]
	v_mfma_f32_16x16x32_bf16 v[70:73], v[204:207], v[196:199], v[70:73]
	v_mfma_f32_16x16x32_bf16 v[66:69], v[212:215], v[196:199], v[66:69]
	s_mov_b32 m0, s56
	v_lshl_add_u64 v[142:143], v[218:219], 0, s[16:17]
	s_barrier
	ds_read_b128 v[168:171], v148 offset:49152
	ds_read_b128 v[172:175], v148 offset:50176
	ds_read_b128 v[176:179], v148 offset:51200
	ds_read_b128 v[180:183], v148 offset:52224
	ds_read_b128 v[184:187], v148 offset:53248
	ds_read_b128 v[188:191], v148 offset:54272
	ds_read_b128 v[192:195], v148 offset:55296
	ds_read_b128 v[196:199], v148 offset:56320
	global_load_lds_dwordx4 v[142:143], off
	v_lshl_add_u64 v[142:143], v[220:221], 0, s[16:17]
	s_mov_b32 m0, s57
	s_nop 0
	global_load_lds_dwordx4 v[142:143], off
	s_waitcnt vmcnt(10)
	s_barrier
	s_waitcnt lgkmcnt(0)
	s_waitcnt lgkmcnt(0)
	v_mfma_f32_16x16x32_bf16 v[62:65], v[152:155], v[168:171], v[62:65]
	v_mfma_f32_16x16x32_bf16 v[58:61], v[160:163], v[168:171], v[58:61]
	v_mfma_f32_16x16x32_bf16 v[46:49], v[152:155], v[176:179], v[46:49]
	v_mfma_f32_16x16x32_bf16 v[42:45], v[160:163], v[176:179], v[42:45]
	v_mfma_f32_16x16x32_bf16 v[30:33], v[152:155], v[184:187], v[30:33]
	v_mfma_f32_16x16x32_bf16 v[26:29], v[160:163], v[184:187], v[26:29]
	v_mfma_f32_16x16x32_bf16 v[14:17], v[152:155], v[192:195], v[14:17]
	v_mfma_f32_16x16x32_bf16 v[10:13], v[160:163], v[192:195], v[10:13]
	v_mfma_f32_16x16x32_bf16 v[62:65], v[156:159], v[172:175], v[62:65]
	v_mfma_f32_16x16x32_bf16 v[58:61], v[164:167], v[172:175], v[58:61]
	v_mfma_f32_16x16x32_bf16 v[46:49], v[156:159], v[180:183], v[46:49]
	v_mfma_f32_16x16x32_bf16 v[42:45], v[164:167], v[180:183], v[42:45]
	v_mfma_f32_16x16x32_bf16 v[30:33], v[156:159], v[188:191], v[30:33]
	v_mfma_f32_16x16x32_bf16 v[26:29], v[164:167], v[188:191], v[26:29]
	v_mfma_f32_16x16x32_bf16 v[14:17], v[156:159], v[196:199], v[14:17]
	v_mfma_f32_16x16x32_bf16 v[10:13], v[164:167], v[196:199], v[10:13]
	s_barrier
	s_mov_b32 m0, s65
	v_lshl_add_u64 v[142:143], s[36:37], 0, v[134:135]
	global_load_lds_dwordx4 v[142:143], off
	v_lshl_add_u64 v[142:143], s[36:37], 0, v[130:131]
	s_mov_b32 m0, s64
	s_nop 0
	global_load_lds_dwordx4 v[142:143], off
	s_waitcnt vmcnt(10)
	s_barrier
	v_mfma_f32_16x16x32_bf16 v[54:57], v[200:203], v[168:171], v[54:57]
	v_mfma_f32_16x16x32_bf16 v[50:53], v[208:211], v[168:171], v[50:53]
	v_mfma_f32_16x16x32_bf16 v[38:41], v[200:203], v[176:179], v[38:41]
	v_mfma_f32_16x16x32_bf16 v[34:37], v[208:211], v[176:179], v[34:37]
	v_mfma_f32_16x16x32_bf16 v[22:25], v[200:203], v[184:187], v[22:25]
	v_mfma_f32_16x16x32_bf16 v[18:21], v[208:211], v[184:187], v[18:21]
	v_mfma_f32_16x16x32_bf16 v[6:9], v[200:203], v[192:195], v[6:9]
	v_mfma_f32_16x16x32_bf16 v[2:5], v[208:211], v[192:195], v[2:5]
	v_mfma_f32_16x16x32_bf16 v[54:57], v[204:207], v[172:175], v[54:57]
	v_mfma_f32_16x16x32_bf16 v[50:53], v[212:215], v[172:175], v[50:53]
	v_mfma_f32_16x16x32_bf16 v[38:41], v[204:207], v[180:183], v[38:41]
	v_mfma_f32_16x16x32_bf16 v[34:37], v[212:215], v[180:183], v[34:37]
	v_mfma_f32_16x16x32_bf16 v[22:25], v[204:207], v[188:191], v[22:25]
	v_mfma_f32_16x16x32_bf16 v[18:21], v[212:215], v[188:191], v[18:21]
	v_mfma_f32_16x16x32_bf16 v[6:9], v[204:207], v[196:199], v[6:9]
	v_mfma_f32_16x16x32_bf16 v[2:5], v[212:215], v[196:199], v[2:5]
	s_movk_i32 s38, 0x100
	s_andn2_b64 vcc, exec, s[34:35]
	s_mov_b64 s[36:37], -1
	s_mov_b64 s[34:35], 0
	s_barrier
	s_cbranch_vccz .LBB0_2344
	s_lshl_b32 s0, s26, 8
	v_mov_b32_e32 v143, v144
	s_add_i32 s0, s0, s53
	v_mov_b32_e32 v142, v145
	v_add_u32_e32 v151, s0, v143
	v_mov_b32_e32 v154, v151
	v_max_f32_e32 v126, v126, v126
	v_ashrrev_i32_e32 v152, 8, v154
	v_and_b32_e32 v152, -8, v152
	v_add_u32_e32 v152, s55, v152
	v_ashrrev_i32_e32 v153, 31, v152
	v_lshlrev_b64 v[152:153], 11, v[152:153]
	v_and_or_b32 v152, v154, s60, v152
	v_med3_f32 v154, v126, s61, v150
	v_max_f32_e32 v126, v127, v127
	v_med3_f32 v127, v126, s61, v150
	v_cvt_pk_fp8_f32 v126, v154, v127
	v_max_f32_e32 v127, v128, v128
	v_max_f32_e32 v128, v129, v129
	v_med3_f32 v127, v127, s61, v150
	v_med3_f32 v128, v128, s61, v150
	v_max_f32_e32 v122, v122, v122
	v_max_f32_e32 v123, v123, v123
	v_cvt_pk_fp8_f32 v126, v127, v128 op_sel:[0,0,1]
	v_med3_f32 v122, v122, s61, v150
	v_med3_f32 v123, v123, s61, v150
	v_cvt_pk_fp8_f32 v127, v122, v123
	v_max_f32_e32 v122, v124, v124
	v_max_f32_e32 v123, v125, v125
	v_med3_f32 v122, v122, s61, v150
	v_med3_f32 v123, v123, s61, v150
	v_lshl_add_u32 v142, v142, 3, s54
	v_cvt_pk_fp8_f32 v127, v122, v123 op_sel:[0,0,1]
	v_mov_b64_e32 v[122:123], s[12:13]
	v_ashrrev_i32_e32 v143, 31, v142
	v_mad_u64_u32 v[124:125], s[0:1], v152, s51, v[122:123]
	v_cvt_pk_bf16_f32 v118, v118, v119
	v_cvt_pk_bf16_f32 v119, v120, v121
	v_cvt_pk_bf16_f32 v120, v114, v115
	v_lshlrev_b64 v[114:115], 8, v[152:153]
	v_mad_i32_i24 v125, v153, s51, v125
	v_cvt_pk_bf16_f32 v121, v116, v117
	v_lshl_add_u64 v[116:117], s[14:15], 0, v[114:115]
	v_lshlrev_b64 v[114:115], 1, v[142:143]
	v_lshl_add_u64 v[124:125], v[124:125], 0, v[142:143]
	v_lshl_add_u64 v[116:117], v[116:117], 0, v[114:115]
	global_store_dwordx2 v[124:125], v[126:127], off
	global_store_dwordx4 v[116:117], v[118:121], off
	v_max_f32_e32 v110, v110, v110
	v_max_f32_e32 v106, v106, v106
	v_add_u32_e32 v118, 16, v151
	v_max_f32_e32 v107, v107, v107
	v_ashrrev_i32_e32 v116, 8, v118
	v_and_b32_e32 v116, -8, v116
	v_add_u32_e32 v116, s55, v116
	v_ashrrev_i32_e32 v117, 31, v116
	v_lshlrev_b64 v[116:117], 11, v[116:117]
	v_and_or_b32 v116, v118, s60, v116
	v_med3_f32 v118, v110, s61, v150
	v_max_f32_e32 v110, v111, v111
	v_med3_f32 v111, v110, s61, v150
	v_cvt_pk_fp8_f32 v110, v118, v111
	v_max_f32_e32 v111, v112, v112
	v_max_f32_e32 v112, v113, v113
	v_med3_f32 v111, v111, s61, v150
	v_med3_f32 v112, v112, s61, v150
	v_cvt_pk_fp8_f32 v110, v111, v112 op_sel:[0,0,1]
	v_med3_f32 v106, v106, s61, v150
	v_med3_f32 v107, v107, s61, v150
	v_cvt_pk_fp8_f32 v111, v106, v107
	v_max_f32_e32 v106, v108, v108
	v_max_f32_e32 v107, v109, v109
	v_med3_f32 v106, v106, s61, v150
	v_med3_f32 v107, v107, s61, v150
	v_cvt_pk_fp8_f32 v111, v106, v107 op_sel:[0,0,1]
	v_mad_u64_u32 v[106:107], s[0:1], v116, s51, v[122:123]
	v_cvt_pk_bf16_f32 v102, v102, v103
	v_cvt_pk_bf16_f32 v103, v104, v105
	v_cvt_pk_bf16_f32 v104, v98, v99
	v_lshlrev_b64 v[98:99], 8, v[116:117]
	v_mad_i32_i24 v107, v117, s51, v107
	v_lshl_add_u64 v[98:99], s[14:15], 0, v[98:99]
	v_lshl_add_u64 v[106:107], v[106:107], 0, v[142:143]
	v_cvt_pk_bf16_f32 v105, v100, v101
	v_lshl_add_u64 v[98:99], v[98:99], 0, v[114:115]
	v_add_u32_e32 v100, 32, v151
	global_store_dwordx2 v[106:107], v[110:111], off
	global_store_dwordx4 v[98:99], v[102:105], off
	v_max_f32_e32 v94, v94, v94
	v_ashrrev_i32_e32 v98, 8, v100
	v_and_b32_e32 v98, -8, v98
	v_add_u32_e32 v98, s55, v98
	v_ashrrev_i32_e32 v99, 31, v98
	v_lshlrev_b64 v[98:99], 11, v[98:99]
	v_and_or_b32 v98, v100, s60, v98
	v_med3_f32 v100, v94, s61, v150
	v_max_f32_e32 v94, v95, v95
	v_med3_f32 v95, v94, s61, v150
	v_cvt_pk_fp8_f32 v94, v100, v95
	v_max_f32_e32 v95, v96, v96
	v_max_f32_e32 v96, v97, v97
	v_med3_f32 v95, v95, s61, v150
	v_med3_f32 v96, v96, s61, v150
	v_max_f32_e32 v90, v90, v90
	v_max_f32_e32 v91, v91, v91
	v_cvt_pk_fp8_f32 v94, v95, v96 op_sel:[0,0,1]
	v_med3_f32 v90, v90, s61, v150
	v_med3_f32 v91, v91, s61, v150
	v_cvt_pk_fp8_f32 v95, v90, v91
	v_max_f32_e32 v90, v92, v92
	v_max_f32_e32 v91, v93, v93
	v_med3_f32 v90, v90, s61, v150
	v_med3_f32 v91, v91, s61, v150
	v_cvt_pk_fp8_f32 v95, v90, v91 op_sel:[0,0,1]
	v_mad_u64_u32 v[90:91], s[0:1], v98, s51, v[122:123]
	v_cvt_pk_bf16_f32 v86, v86, v87
	v_cvt_pk_bf16_f32 v87, v88, v89
	v_cvt_pk_bf16_f32 v88, v82, v83
	v_lshlrev_b64 v[82:83], 8, v[98:99]
	v_mad_i32_i24 v91, v99, s51, v91
	v_lshl_add_u64 v[82:83], s[14:15], 0, v[82:83]
	v_lshl_add_u64 v[90:91], v[90:91], 0, v[142:143]
	v_cvt_pk_bf16_f32 v89, v84, v85
	v_lshl_add_u64 v[82:83], v[82:83], 0, v[114:115]
	v_add_u32_e32 v84, 48, v151
	global_store_dwordx2 v[90:91], v[94:95], off
	global_store_dwordx4 v[82:83], v[86:89], off
	v_max_f32_e32 v78, v78, v78
	v_ashrrev_i32_e32 v82, 8, v84
	v_and_b32_e32 v82, -8, v82
	v_add_u32_e32 v82, s55, v82
	v_ashrrev_i32_e32 v83, 31, v82
	v_lshlrev_b64 v[82:83], 11, v[82:83]
	v_and_or_b32 v82, v84, s60, v82
	v_med3_f32 v84, v78, s61, v150
	v_max_f32_e32 v78, v79, v79
	v_med3_f32 v79, v78, s61, v150
	v_cvt_pk_fp8_f32 v78, v84, v79
	v_max_f32_e32 v79, v80, v80
	v_max_f32_e32 v80, v81, v81
	v_med3_f32 v79, v79, s61, v150
	v_med3_f32 v80, v80, s61, v150
	v_max_f32_e32 v74, v74, v74
	v_max_f32_e32 v75, v75, v75
	v_cvt_pk_fp8_f32 v78, v79, v80 op_sel:[0,0,1]
	v_med3_f32 v74, v74, s61, v150
	v_med3_f32 v75, v75, s61, v150
	v_cvt_pk_fp8_f32 v79, v74, v75
	v_max_f32_e32 v74, v76, v76
	v_max_f32_e32 v75, v77, v77
	v_med3_f32 v74, v74, s61, v150
	v_med3_f32 v75, v75, s61, v150
	v_cvt_pk_fp8_f32 v79, v74, v75 op_sel:[0,0,1]
	v_mad_u64_u32 v[74:75], s[0:1], v82, s51, v[122:123]
	v_cvt_pk_bf16_f32 v70, v70, v71
	v_cvt_pk_bf16_f32 v71, v72, v73
	v_cvt_pk_bf16_f32 v72, v66, v67
	v_lshlrev_b64 v[66:67], 8, v[82:83]
	v_mad_i32_i24 v75, v83, s51, v75
	v_lshl_add_u64 v[66:67], s[14:15], 0, v[66:67]
	v_lshl_add_u64 v[74:75], v[74:75], 0, v[142:143]
	v_cvt_pk_bf16_f32 v73, v68, v69
	v_lshl_add_u64 v[66:67], v[66:67], 0, v[114:115]
	v_add_u32_e32 v68, 0x80, v151
	global_store_dwordx2 v[74:75], v[78:79], off
	global_store_dwordx4 v[66:67], v[70:73], off
	v_max_f32_e32 v62, v62, v62
	v_ashrrev_i32_e32 v66, 8, v68
	v_and_b32_e32 v66, -8, v66
	v_add_u32_e32 v66, s55, v66
	v_ashrrev_i32_e32 v67, 31, v66
	v_lshlrev_b64 v[66:67], 11, v[66:67]
	v_and_or_b32 v66, v68, s60, v66
	v_med3_f32 v68, v62, s61, v150
	v_max_f32_e32 v62, v63, v63
	v_med3_f32 v63, v62, s61, v150
	v_cvt_pk_fp8_f32 v62, v68, v63
	v_max_f32_e32 v63, v64, v64
	v_max_f32_e32 v64, v65, v65
	v_med3_f32 v63, v63, s61, v150
	v_med3_f32 v64, v64, s61, v150
	v_max_f32_e32 v58, v58, v58
	v_max_f32_e32 v59, v59, v59
	v_cvt_pk_fp8_f32 v62, v63, v64 op_sel:[0,0,1]
	v_med3_f32 v58, v58, s61, v150
	v_med3_f32 v59, v59, s61, v150
	v_cvt_pk_fp8_f32 v63, v58, v59
	v_max_f32_e32 v58, v60, v60
	v_max_f32_e32 v59, v61, v61
	v_med3_f32 v58, v58, s61, v150
	v_med3_f32 v59, v59, s61, v150
	v_cvt_pk_fp8_f32 v63, v58, v59 op_sel:[0,0,1]
	v_mad_u64_u32 v[58:59], s[0:1], v66, s51, v[122:123]
	v_cvt_pk_bf16_f32 v54, v54, v55
	v_cvt_pk_bf16_f32 v55, v56, v57
	v_cvt_pk_bf16_f32 v56, v50, v51
	v_lshlrev_b64 v[50:51], 8, v[66:67]
	v_mad_i32_i24 v59, v67, s51, v59
	v_lshl_add_u64 v[50:51], s[14:15], 0, v[50:51]
	v_lshl_add_u64 v[58:59], v[58:59], 0, v[142:143]
	v_cvt_pk_bf16_f32 v57, v52, v53
	v_lshl_add_u64 v[50:51], v[50:51], 0, v[114:115]
	v_add_u32_e32 v52, 0x90, v151
	global_store_dwordx2 v[58:59], v[62:63], off
	global_store_dwordx4 v[50:51], v[54:57], off
	v_max_f32_e32 v46, v46, v46
	v_ashrrev_i32_e32 v50, 8, v52
	v_and_b32_e32 v50, -8, v50
	v_add_u32_e32 v50, s55, v50
	v_ashrrev_i32_e32 v51, 31, v50
	v_lshlrev_b64 v[50:51], 11, v[50:51]
	v_and_or_b32 v50, v52, s60, v50
	v_med3_f32 v52, v46, s61, v150
	v_max_f32_e32 v46, v47, v47
	v_med3_f32 v47, v46, s61, v150
	v_cvt_pk_fp8_f32 v46, v52, v47
	v_max_f32_e32 v47, v48, v48
	v_max_f32_e32 v48, v49, v49
	v_med3_f32 v47, v47, s61, v150
	v_med3_f32 v48, v48, s61, v150
	v_max_f32_e32 v42, v42, v42
	v_max_f32_e32 v43, v43, v43
	v_cvt_pk_fp8_f32 v46, v47, v48 op_sel:[0,0,1]
	v_med3_f32 v42, v42, s61, v150
	v_med3_f32 v43, v43, s61, v150
	v_cvt_pk_fp8_f32 v47, v42, v43
	v_max_f32_e32 v42, v44, v44
	v_max_f32_e32 v43, v45, v45
	v_med3_f32 v42, v42, s61, v150
	v_med3_f32 v43, v43, s61, v150
	v_cvt_pk_fp8_f32 v47, v42, v43 op_sel:[0,0,1]
	v_mad_u64_u32 v[42:43], s[0:1], v50, s51, v[122:123]
	v_cvt_pk_bf16_f32 v38, v38, v39
	v_cvt_pk_bf16_f32 v39, v40, v41
	v_cvt_pk_bf16_f32 v40, v34, v35
	v_lshlrev_b64 v[34:35], 8, v[50:51]
	v_mad_i32_i24 v43, v51, s51, v43
	v_lshl_add_u64 v[34:35], s[14:15], 0, v[34:35]
	v_lshl_add_u64 v[42:43], v[42:43], 0, v[142:143]
	v_cvt_pk_bf16_f32 v41, v36, v37
	v_lshl_add_u64 v[34:35], v[34:35], 0, v[114:115]
	v_add_u32_e32 v36, 0xa0, v151
	global_store_dwordx2 v[42:43], v[46:47], off
	global_store_dwordx4 v[34:35], v[38:41], off
	v_max_f32_e32 v30, v30, v30
	v_ashrrev_i32_e32 v34, 8, v36
	v_and_b32_e32 v34, -8, v34
	v_add_u32_e32 v34, s55, v34
	v_ashrrev_i32_e32 v35, 31, v34
	v_lshlrev_b64 v[34:35], 11, v[34:35]
	v_and_or_b32 v34, v36, s60, v34
	v_med3_f32 v36, v30, s61, v150
	v_max_f32_e32 v30, v31, v31
	v_med3_f32 v31, v30, s61, v150
	v_cvt_pk_fp8_f32 v30, v36, v31
	v_max_f32_e32 v31, v32, v32
	v_max_f32_e32 v32, v33, v33
	v_med3_f32 v31, v31, s61, v150
	v_med3_f32 v32, v32, s61, v150
	v_max_f32_e32 v26, v26, v26
	v_max_f32_e32 v27, v27, v27
	v_cvt_pk_fp8_f32 v30, v31, v32 op_sel:[0,0,1]
	v_med3_f32 v26, v26, s61, v150
	v_med3_f32 v27, v27, s61, v150
	v_cvt_pk_fp8_f32 v31, v26, v27
	v_max_f32_e32 v26, v28, v28
	v_max_f32_e32 v27, v29, v29
	v_med3_f32 v26, v26, s61, v150
	v_med3_f32 v27, v27, s61, v150
	v_cvt_pk_fp8_f32 v31, v26, v27 op_sel:[0,0,1]
	v_mad_u64_u32 v[26:27], s[0:1], v34, s51, v[122:123]
	v_cvt_pk_bf16_f32 v22, v22, v23
	v_cvt_pk_bf16_f32 v23, v24, v25
	v_cvt_pk_bf16_f32 v24, v18, v19
	v_lshlrev_b64 v[18:19], 8, v[34:35]
	v_mad_i32_i24 v27, v35, s51, v27
	v_lshl_add_u64 v[18:19], s[14:15], 0, v[18:19]
	v_lshl_add_u64 v[26:27], v[26:27], 0, v[142:143]
	v_cvt_pk_bf16_f32 v25, v20, v21
	v_lshl_add_u64 v[18:19], v[18:19], 0, v[114:115]
	v_add_u32_e32 v20, 0xb0, v151
	global_store_dwordx2 v[26:27], v[30:31], off
	global_store_dwordx4 v[18:19], v[22:25], off
	v_max_f32_e32 v14, v14, v14
	v_ashrrev_i32_e32 v18, 8, v20
	v_and_b32_e32 v18, -8, v18
	v_add_u32_e32 v18, s55, v18
	v_ashrrev_i32_e32 v19, 31, v18
	v_lshlrev_b64 v[18:19], 11, v[18:19]
	v_and_or_b32 v18, v20, s60, v18
	v_med3_f32 v20, v14, s61, v150
	v_max_f32_e32 v14, v15, v15
	v_med3_f32 v15, v14, s61, v150
	v_cvt_pk_fp8_f32 v14, v20, v15
	v_max_f32_e32 v15, v16, v16
	v_max_f32_e32 v16, v17, v17
	v_med3_f32 v15, v15, s61, v150
	v_med3_f32 v16, v16, s61, v150
	v_max_f32_e32 v10, v10, v10
	v_max_f32_e32 v11, v11, v11
	v_cvt_pk_fp8_f32 v14, v15, v16 op_sel:[0,0,1]
	v_med3_f32 v10, v10, s61, v150
	v_med3_f32 v11, v11, s61, v150
	v_cvt_pk_fp8_f32 v15, v10, v11
	v_max_f32_e32 v10, v12, v12
	v_max_f32_e32 v11, v13, v13
	v_med3_f32 v10, v10, s61, v150
	v_med3_f32 v11, v11, s61, v150
	v_cvt_pk_fp8_f32 v15, v10, v11 op_sel:[0,0,1]
	v_mad_u64_u32 v[10:11], s[0:1], v18, s51, v[122:123]
	v_cvt_pk_bf16_f32 v6, v6, v7
	v_cvt_pk_bf16_f32 v7, v8, v9
	v_cvt_pk_bf16_f32 v8, v2, v3
	v_lshlrev_b64 v[2:3], 8, v[18:19]
	v_mad_i32_i24 v11, v19, s51, v11
	v_lshl_add_u64 v[2:3], s[14:15], 0, v[2:3]
	v_readlane_b32 s72, v254, 2
	v_lshl_add_u64 v[10:11], v[10:11], 0, v[142:143]
	v_cvt_pk_bf16_f32 v9, v4, v5
	v_lshl_add_u64 v[2:3], v[2:3], 0, v[114:115]
	s_and_b64 vcc, exec, s[10:11]
	s_mov_b32 s55, s18
	s_mov_b32 s26, s20
	s_mov_b64 s[28:29], s[24:25]
	s_mov_b64 s[30:31], s[22:23]
	v_readlane_b32 s73, v254, 3
	global_store_dwordx2 v[10:11], v[14:15], off
	global_store_dwordx4 v[2:3], v[6:9], off
	s_cbranch_vccz .LBB0_2337
	s_waitcnt vmcnt(0)
	s_cmpk_gt_u32 s5, 0xff
	s_cbranch_scc1 .LBB0_2348
	s_barrier

.LBB0_2519:
	s_waitcnt vmcnt(0) lgkmcnt(0)
	v_lshlrev_b32_e32 v77, 16, v37
	v_lshlrev_b32_e32 v76, 16, v36
	v_and_b32_e32 v37, 0xffff0000, v37
	v_and_b32_e32 v36, 0xffff0000, v36
	v_pk_add_f32 v[68:69], v[76:77], v[36:37]
	v_lshlrev_b32_e32 v87, 16, v35
	v_lshlrev_b32_e32 v86, 16, v34
	v_and_b32_e32 v35, 0xffff0000, v35
	v_and_b32_e32 v34, 0xffff0000, v34
	v_lshlrev_b32_e32 v46, 16, v39
	v_and_b32_e32 v48, 0xffff0000, v39
	v_add_f32_e32 v39, v68, v69
	v_pk_add_f32 v[68:69], v[86:87], v[34:35]
	v_lshlrev_b32_e32 v42, 16, v40
	v_and_b32_e32 v43, 0xffff0000, v40
	v_lshlrev_b32_e32 v40, 16, v41
	v_and_b32_e32 v41, 0xffff0000, v41
	v_pk_add_f32 v[68:69], v[68:69], v[68:69] op_sel_hi:[0,1]
	v_lshlrev_b32_e32 v44, 16, v38
	v_and_b32_e32 v38, 0xffff0000, v38
	v_add_f32_e32 v49, 0, v39
	v_add_f32_e32 v45, v42, v43
	v_add_f32_e32 v39, v40, v41
	v_mov_b32_e32 v47, v69
	v_pk_add_f32 v[70:71], v[44:45], v[38:39]
	v_pk_add_f32 v[68:69], v[46:47], v[48:49]
	s_min_u32 s0, s30, 29
	v_pk_add_f32 v[68:69], v[70:71], v[68:69]
	s_lshl_b32 s0, s0, 3
	v_add_f32_e32 v39, v68, v69
	s_add_i32 s18, s29, s0
	s_nop 0
	v_add_f32_dpp v39, v39, v39 quad_perm:[1,0,3,2] row_mask:0xf bank_mask:0xf bound_ctrl:1
	s_nop 1
	v_add_f32_dpp v39, v39, v39 quad_perm:[2,3,0,1] row_mask:0xf bank_mask:0xf bound_ctrl:1
	s_nop 1
	v_add_f32_dpp v39, v39, v39 row_half_mirror row_mask:0xf bank_mask:0xf bound_ctrl:1
	s_nop 1
	v_add_f32_dpp v39, v39, v39 row_mirror row_mask:0xf bank_mask:0xf bound_ctrl:1
	s_nop 0
	v_readlane_b32 s19, v39, 16
	v_readlane_b32 s22, v39, 48
	v_readlane_b32 s0, v39, 0
	v_readlane_b32 s1, v39, 32
	v_mov_b32_e32 v68, s19
	v_mov_b32_e32 v69, s22
	v_pk_add_f32 v[68:69], s[0:1], v[68:69]
	s_nop 0
	v_add_f32_e32 v39, v68, v69
	v_fmac_f32_e32 v36, 0xba800000, v39
	v_fmac_f32_e32 v37, 0xba800000, v39
	v_fmac_f32_e32 v77, 0xba800000, v39
	v_fmac_f32_e32 v76, 0xba800000, v39
	v_mov_b32_e32 v88, v77
	v_mov_b32_e32 v89, v37
	v_mov_b32_e32 v77, v36
	v_fmac_f32_e32 v34, 0xba800000, v39
	v_fmac_f32_e32 v35, 0xba800000, v39
	v_fmac_f32_e32 v87, 0xba800000, v39
	v_pk_mul_f32 v[68:69], v[88:89], v[88:89]
	v_pk_mul_f32 v[36:37], v[76:77], v[76:77]
	v_fmac_f32_e32 v86, 0xba800000, v39
	v_mov_b32_e32 v90, v87
	v_mov_b32_e32 v91, v35
	v_mov_b32_e32 v87, v34
	v_pk_mov_b32 v[70:71], v[36:37], v[68:69] op_sel:[1,0]
	v_mov_b32_e32 v37, v69
	v_pk_mul_f32 v[68:69], v[90:91], v[90:91]
	v_pk_mul_f32 v[34:35], v[86:87], v[86:87]
	v_pk_add_f32 v[36:37], v[70:71], v[36:37]
	v_pk_mov_b32 v[70:71], v[34:35], v[68:69] op_sel:[1,0]
	v_mov_b32_e32 v35, v69
	v_pk_add_f32 v[34:35], v[70:71], v[34:35]
	v_fmac_f32_e32 v42, 0xba800000, v39
	v_pk_add_f32 v[34:35], v[34:35], v[34:35] op_sel_hi:[0,1]
	v_fmac_f32_e32 v43, 0xba800000, v39
	v_fmac_f32_e32 v40, 0xba800000, v39
	v_mul_f32_e32 v34, v42, v42
	v_fmac_f32_e32 v41, 0xba800000, v39
	v_pk_fma_f32 v[68:69], v[42:43], v[42:43], v[34:35] op_sel_hi:[1,1,0]
	v_mul_f32_e32 v34, v40, v40
	v_pk_add_f32 v[36:37], v[36:37], v[36:37] op_sel_hi:[0,1]
	v_pk_fma_f32 v[70:71], v[40:41], v[40:41], v[34:35] op_sel_hi:[1,1,0]
	v_fmac_f32_e32 v48, 0xba800000, v39
	v_fmac_f32_e32 v46, 0xba800000, v39
	v_fmac_f32_e32 v38, 0xba800000, v39
	v_fmac_f32_e32 v44, 0xba800000, v39
	v_mul_f32_e32 v68, v44, v44
	v_mul_f32_e32 v70, v38, v38
	v_mul_f32_e32 v36, v46, v46
	v_mul_f32_e32 v34, v48, v48
	v_pk_add_f32 v[68:69], v[68:69], v[70:71]
	v_pk_add_f32 v[34:35], v[36:37], v[34:35]
	v_mov_b32_e32 v47, v48
	v_pk_add_f32 v[34:35], v[68:69], v[34:35]
	s_nop 0
	v_add_f32_e32 v34, v34, v35
	s_nop 1
	v_add_f32_dpp v34, v34, v34 quad_perm:[1,0,3,2] row_mask:0xf bank_mask:0xf bound_ctrl:1
	s_nop 1
	v_add_f32_dpp v34, v34, v34 quad_perm:[2,3,0,1] row_mask:0xf bank_mask:0xf bound_ctrl:1
	s_nop 1
	v_add_f32_dpp v34, v34, v34 row_half_mirror row_mask:0xf bank_mask:0xf bound_ctrl:1
	s_nop 1
	v_add_f32_dpp v34, v34, v34 row_mirror row_mask:0xf bank_mask:0xf bound_ctrl:1
	s_nop 0
	v_readlane_b32 s19, v34, 16
	v_readlane_b32 s22, v34, 48
	v_readlane_b32 s0, v34, 0
	v_readlane_b32 s1, v34, 32
	v_mov_b32_e32 v34, s19
	v_mov_b32_e32 v35, s22
	v_pk_add_f32 v[34:35], s[0:1], v[34:35]
	s_mov_b32 s0, 0xf800000
	v_add_f32_e32 v34, v34, v35
	v_fmamk_f32 v34, v34, 0x3a800000, v83
	s_ashr_i32 s19, s18, 31
	v_mul_f32_e32 v35, 0x4f800000, v34
	v_cmp_gt_f32_e32 vcc, s0, v34
	s_lshl_b64 s[0:1], s[18:19], 11
	s_and_b32 s22, s30, 3
	v_cndmask_b32_e32 v36, v34, v35, vcc
	v_lshl_add_u64 v[34:35], v[54:55], 0, s[0:1]
	global_load_dwordx2 v[68:69], v[34:35], off
	global_load_dwordx2 v[70:71], v[34:35], off offset:512
	global_load_dwordx2 v[72:73], v[34:35], off offset:1024
	global_load_dwordx2 v[74:75], v[34:35], off offset:1536
	v_sqrt_f32_e32 v37, v36
	s_mul_i32 s26, s22, 0x810
	s_add_i32 s26, s87, s26
	v_add_u32_e32 v39, -1, v37
	v_fma_f32 v45, -v39, v37, v36
	v_cmp_ge_f32_e64 s[18:19], 0, v45
	v_add_u32_e32 v45, 1, v37
	s_nop 0
	v_cndmask_b32_e64 v39, v37, v39, s[18:19]
	v_fma_f32 v37, -v45, v37, v36
	v_cmp_lt_f32_e64 s[18:19], 0, v37
	s_nop 1
	v_cndmask_b32_e64 v37, v39, v45, s[18:19]
	v_mul_f32_e32 v39, 0x37800000, v37
	v_cndmask_b32_e32 v37, v37, v39, vcc
	v_cmp_class_f32_e32 vcc, v36, v84
	s_add_i32 s18, s4, s28
	s_ashr_i32 s19, s18, 31
	v_cndmask_b32_e32 v36, v37, v36, vcc
	v_div_scale_f32 v37, s[0:1], v36, v36, 1.0
	v_rcp_f32_e32 v39, v37
	s_lshl_b64 s[0:1], s[18:19], 11
	v_fma_f32 v34, -v37, v39, 1.0
	v_fmac_f32_e32 v39, v34, v39
	v_div_scale_f32 v34, vcc, 1.0, v36, 1.0
	v_mul_f32_e32 v35, v34, v39
	v_fma_f32 v45, -v37, v35, v34
	v_fmac_f32_e32 v35, v45, v39
	v_fma_f32 v34, -v37, v35, v34
	v_div_fmas_f32 v34, v34, v39, v35
	v_div_fixup_f32 v34, v34, v36, 1.0
	v_mov_b32_e32 v45, v38
	v_pk_mul_f32 v[36:37], v[76:77], v[34:35] op_sel_hi:[1,0]
	v_pk_mul_f32 v[76:77], v[88:89], v[34:35] op_sel_hi:[1,0]
	v_pk_mul_f32 v[38:39], v[44:45], v[34:35] op_sel_hi:[1,0]
	v_mov_b32_e32 v44, v78
	v_pk_fma_f32 v[76:77], v[4:5], v[76:77], v[12:13]
	v_pk_fma_f32 v[36:37], v[2:3], v[36:37], v[10:11]
	v_pk_mul_f32 v[86:87], v[86:87], v[34:35] op_sel_hi:[1,0]
	v_pk_mul_f32 v[88:89], v[90:91], v[34:35] op_sel_hi:[1,0]
	v_pk_fma_f32 v[86:87], v[6:7], v[86:87], v[14:15]
	v_pk_fma_f32 v[88:89], v[8:9], v[88:89], v[16:17]
	v_pk_mul_f32 v[42:43], v[42:43], v[34:35] op_sel_hi:[1,0]
	v_pk_mul_f32 v[40:41], v[40:41], v[34:35] op_sel_hi:[1,0]
	v_pk_mul_f32 v[34:35], v[46:47], v[34:35] op_sel_hi:[1,0]
	v_lshl_add_u32 v48, v44, 3, s26
	v_cvt_pk_bf16_f32 v44, v36, v37
	v_cvt_pk_bf16_f32 v45, v76, v77
	v_lshl_add_u64 v[46:47], v[56:57], 0, s[0:1]
	v_pk_fma_f32 v[40:41], v[20:21], v[40:41], v[28:29]
	v_pk_fma_f32 v[42:43], v[18:19], v[42:43], v[26:27]
	global_store_dwordx2 v[46:47], v[44:45], off nt
	ds_write_b64 v48, v[44:45] offset:33024
	v_cvt_pk_bf16_f32 v44, v86, v87
	v_cvt_pk_bf16_f32 v45, v88, v89
	v_pk_fma_f32 v[34:35], v[24:25], v[34:35], v[32:33]
	v_pk_fma_f32 v[38:39], v[22:23], v[38:39], v[30:31]
	global_store_dwordx2 v[46:47], v[44:45], off offset:512 nt
	ds_write_b64 v48, v[44:45] offset:33536
	v_cvt_pk_bf16_f32 v44, v42, v43
	v_cvt_pk_bf16_f32 v45, v40, v41
	global_store_dwordx2 v[46:47], v[44:45], off offset:1024 nt
	ds_write_b64 v48, v[44:45] offset:34048
	v_cvt_pk_bf16_f32 v44, v38, v39
	v_cvt_pk_bf16_f32 v45, v34, v35
	global_store_dwordx2 v[46:47], v[44:45], off offset:1536 nt
	ds_write_b64 v48, v[44:45] offset:34560
	v_med3_f32 v36, v36, s8, v85
	v_med3_f32 v37, v37, s8, v85
	v_cvt_pk_fp8_f32 v44, v36, v37
	v_med3_f32 v36, v76, s8, v85
	v_med3_f32 v37, v77, s8, v85
	v_med3_f32 v45, v86, s8, v85
	v_cvt_pk_fp8_f32 v44, v36, v37 op_sel:[0,0,1]
	v_med3_f32 v46, v87, s8, v85
	v_cvt_pk_fp8_f32 v47, v45, v46
	s_lshl_b64 s[0:1], s[18:19], 10
	v_lshl_add_u64 v[36:37], v[58:59], 0, s[0:1]
	global_store_dword v[36:37], v44, off
	v_med3_f32 v44, v88, s8, v85
	v_med3_f32 v45, v89, s8, v85
	v_cvt_pk_fp8_f32 v47, v44, v45 op_sel:[0,0,1]
	v_med3_f32 v42, v42, s8, v85
	v_med3_f32 v43, v43, s8, v85
	v_cvt_pk_fp8_f32 v44, v42, v43
	v_med3_f32 v38, v38, s8, v85
	v_med3_f32 v39, v39, s8, v85
	v_cvt_pk_fp8_f32 v42, v38, v39
	v_med3_f32 v34, v34, s8, v85
	v_med3_f32 v35, v35, s8, v85
	v_med3_f32 v40, v40, s8, v85
	v_med3_f32 v41, v41, s8, v85
	v_cvt_pk_fp8_f32 v42, v34, v35 op_sel:[0,0,1]
	v_cvt_pk_fp8_f32 v44, v40, v41 op_sel:[0,0,1]
	s_cmp_lg_u32 s22, 3
	global_store_dword v[36:37], v47, off offset:256
	global_store_dword v[36:37], v44, off offset:512
	global_store_dword v[36:37], v42, off offset:768
	s_cbranch_scc1 .LBB0_2518
	v_mov_b32_e32 v76, v78
	s_nop 0
	v_and_b32_e32 v34, 3, v76
	v_mul_u32_u24_e32 v34, 0x810, v34
	v_and_b32_e32 v35, -16, v76
	v_add3_u32 v77, s87, v34, v35
	v_and_b32_e32 v34, 15, v76
	v_mul_u32_u24_e32 v34, 0x810, v34
	v_add3_u32 v94, 0, v34, v35
	ds_read_b128 v[34:37], v77 offset:33024
	ds_read_b128 v[38:41], v94
	s_waitcnt lgkmcnt(0)
	v_mfma_f32_16x16x32_bf16 v[34:37], v[34:37], v[38:41], 0
	ds_read_b128 v[38:41], v77 offset:33088
	ds_read_b128 v[42:45], v94 offset:64
	v_cmp_gt_i32_e32 vcc, 16, v76
	s_waitcnt lgkmcnt(0)
	v_mfma_f32_16x16x32_bf16 v[38:41], v[38:41], v[42:45], 0
	ds_read_b128 v[42:45], v77 offset:33152
	ds_read_b128 v[46:49], v94 offset:128
	s_waitcnt lgkmcnt(0)
	v_mfma_f32_16x16x32_bf16 v[42:45], v[42:45], v[46:49], 0
	ds_read_b128 v[46:49], v77 offset:33216
	ds_read_b128 v[86:89], v94 offset:192
	s_waitcnt lgkmcnt(0)
	v_mfma_f32_16x16x32_bf16 v[46:49], v[46:49], v[86:89], 0
	ds_read_b128 v[86:89], v77 offset:33280
	ds_read_b128 v[90:93], v94 offset:256
	s_waitcnt lgkmcnt(0)
	v_mfma_f32_16x16x32_bf16 v[34:37], v[86:89], v[90:93], v[34:37]
	ds_read_b128 v[86:89], v77 offset:33344
	ds_read_b128 v[90:93], v94 offset:320
	s_waitcnt lgkmcnt(0)
	v_mfma_f32_16x16x32_bf16 v[38:41], v[86:89], v[90:93], v[38:41]
	ds_read_b128 v[86:89], v77 offset:33408
	ds_read_b128 v[90:93], v94 offset:384
	s_waitcnt lgkmcnt(0)
	v_mfma_f32_16x16x32_bf16 v[42:45], v[86:89], v[90:93], v[42:45]
	ds_read_b128 v[86:89], v77 offset:33472
	ds_read_b128 v[90:93], v94 offset:448
	s_waitcnt lgkmcnt(0)
	v_mfma_f32_16x16x32_bf16 v[46:49], v[86:89], v[90:93], v[46:49]
	ds_read_b128 v[86:89], v77 offset:33536
	ds_read_b128 v[90:93], v94 offset:512
	s_waitcnt lgkmcnt(0)
	v_mfma_f32_16x16x32_bf16 v[34:37], v[86:89], v[90:93], v[34:37]
	ds_read_b128 v[86:89], v77 offset:33600
	ds_read_b128 v[90:93], v94 offset:576
	s_waitcnt lgkmcnt(0)
	v_mfma_f32_16x16x32_bf16 v[38:41], v[86:89], v[90:93], v[38:41]
	ds_read_b128 v[86:89], v77 offset:33664
	ds_read_b128 v[90:93], v94 offset:640
	s_waitcnt lgkmcnt(0)
	v_mfma_f32_16x16x32_bf16 v[42:45], v[86:89], v[90:93], v[42:45]
	ds_read_b128 v[86:89], v77 offset:33728
	ds_read_b128 v[90:93], v94 offset:704
	s_waitcnt lgkmcnt(0)
	v_mfma_f32_16x16x32_bf16 v[46:49], v[86:89], v[90:93], v[46:49]
	ds_read_b128 v[86:89], v77 offset:33792
	ds_read_b128 v[90:93], v94 offset:768
	s_waitcnt lgkmcnt(0)
	v_mfma_f32_16x16x32_bf16 v[34:37], v[86:89], v[90:93], v[34:37]
	ds_read_b128 v[86:89], v77 offset:33856
	ds_read_b128 v[90:93], v94 offset:832
	s_waitcnt lgkmcnt(0)
	v_mfma_f32_16x16x32_bf16 v[38:41], v[86:89], v[90:93], v[38:41]
	ds_read_b128 v[86:89], v77 offset:33920
	ds_read_b128 v[90:93], v94 offset:896
	s_waitcnt lgkmcnt(0)
	v_mfma_f32_16x16x32_bf16 v[42:45], v[86:89], v[90:93], v[42:45]
	ds_read_b128 v[86:89], v77 offset:33984
	ds_read_b128 v[90:93], v94 offset:960
	s_waitcnt lgkmcnt(0)
	v_mfma_f32_16x16x32_bf16 v[46:49], v[86:89], v[90:93], v[46:49]
	ds_read_b128 v[86:89], v77 offset:34048
	ds_read_b128 v[90:93], v94 offset:1024
	s_waitcnt lgkmcnt(0)
	v_mfma_f32_16x16x32_bf16 v[34:37], v[86:89], v[90:93], v[34:37]
	ds_read_b128 v[86:89], v77 offset:34112
	ds_read_b128 v[90:93], v94 offset:1088
	s_waitcnt lgkmcnt(0)
	v_mfma_f32_16x16x32_bf16 v[38:41], v[86:89], v[90:93], v[38:41]
	ds_read_b128 v[86:89], v77 offset:34176
	ds_read_b128 v[90:93], v94 offset:1152
	s_waitcnt lgkmcnt(0)
	v_mfma_f32_16x16x32_bf16 v[42:45], v[86:89], v[90:93], v[42:45]
	ds_read_b128 v[86:89], v77 offset:34240
	ds_read_b128 v[90:93], v94 offset:1216
	s_waitcnt lgkmcnt(0)
	v_mfma_f32_16x16x32_bf16 v[46:49], v[86:89], v[90:93], v[46:49]
	ds_read_b128 v[86:89], v77 offset:34304
	ds_read_b128 v[90:93], v94 offset:1280
	s_waitcnt lgkmcnt(0)
	v_mfma_f32_16x16x32_bf16 v[34:37], v[86:89], v[90:93], v[34:37]
	ds_read_b128 v[86:89], v77 offset:34368
	ds_read_b128 v[90:93], v94 offset:1344
	s_waitcnt lgkmcnt(0)
	v_mfma_f32_16x16x32_bf16 v[38:41], v[86:89], v[90:93], v[38:41]
	ds_read_b128 v[86:89], v77 offset:34432
	ds_read_b128 v[90:93], v94 offset:1408
	s_waitcnt lgkmcnt(0)
	v_mfma_f32_16x16x32_bf16 v[42:45], v[86:89], v[90:93], v[42:45]
	ds_read_b128 v[86:89], v77 offset:34496
	ds_read_b128 v[90:93], v94 offset:1472
	s_waitcnt lgkmcnt(0)
	v_mfma_f32_16x16x32_bf16 v[46:49], v[86:89], v[90:93], v[46:49]
	ds_read_b128 v[86:89], v77 offset:34560
	ds_read_b128 v[90:93], v94 offset:1536
	s_waitcnt lgkmcnt(0)
	v_mfma_f32_16x16x32_bf16 v[34:37], v[86:89], v[90:93], v[34:37]
	ds_read_b128 v[86:89], v77 offset:34624
	ds_read_b128 v[90:93], v94 offset:1600
	s_waitcnt lgkmcnt(0)
	v_mfma_f32_16x16x32_bf16 v[38:41], v[86:89], v[90:93], v[38:41]
	ds_read_b128 v[86:89], v77 offset:34688
	ds_read_b128 v[90:93], v94 offset:1664
	s_waitcnt lgkmcnt(0)
	v_mfma_f32_16x16x32_bf16 v[42:45], v[86:89], v[90:93], v[42:45]
	ds_read_b128 v[86:89], v77 offset:34752
	ds_read_b128 v[90:93], v94 offset:1728
	s_waitcnt lgkmcnt(0)
	v_mfma_f32_16x16x32_bf16 v[46:49], v[86:89], v[90:93], v[46:49]
	ds_read_b128 v[86:89], v77 offset:34816
	ds_read_b128 v[90:93], v94 offset:1792
	s_waitcnt lgkmcnt(0)
	v_mfma_f32_16x16x32_bf16 v[34:37], v[86:89], v[90:93], v[34:37]
	ds_read_b128 v[86:89], v77 offset:34880
	ds_read_b128 v[90:93], v94 offset:1856
	s_waitcnt lgkmcnt(0)
	v_mfma_f32_16x16x32_bf16 v[38:41], v[86:89], v[90:93], v[38:41]
	ds_read_b128 v[86:89], v77 offset:34944
	ds_read_b128 v[90:93], v94 offset:1920
	s_waitcnt lgkmcnt(0)
	v_mfma_f32_16x16x32_bf16 v[42:45], v[86:89], v[90:93], v[42:45]
	ds_read_b128 v[86:89], v77 offset:35008
	ds_read_b128 v[90:93], v94 offset:1984
	s_nop 1
	v_pk_add_f32 v[34:35], v[34:35], v[38:39]
	v_ashrrev_i32_e32 v77, 31, v76
	s_waitcnt lgkmcnt(0)
	v_mfma_f32_16x16x32_bf16 v[46:49], v[86:89], v[90:93], v[46:49]
	s_nop 7
	v_pk_add_f32 v[38:39], v[42:43], v[46:47]
	s_nop 0
	v_pk_add_f32 v[38:39], v[34:35], v[38:39]
	v_lshlrev_b64 v[34:35], 13, v[76:77]
	v_lshl_add_u64 v[34:35], s[24:25], 0, v[34:35]
	v_mov_b32_dpp v42, v38 quad_perm:[1,0,3,2] row_mask:0xf bank_mask:0xf bound_ctrl:1
	v_max_f32_e32 v42, v42, v42
	v_max_f32_e32 v42, v38, v42
	s_nop 1
	v_mov_b32_dpp v43, v42 quad_perm:[2,3,0,1] row_mask:0xf bank_mask:0xf bound_ctrl:1
	v_max_f32_e32 v43, v43, v43
	v_max_f32_e32 v42, v42, v43
	s_nop 1
	v_mov_b32_dpp v43, v42 row_half_mirror row_mask:0xf bank_mask:0xf bound_ctrl:1
	v_max_f32_e32 v43, v43, v43
	v_max_f32_e32 v42, v42, v43
	s_nop 1
	v_mov_b32_dpp v43, v42 row_mirror row_mask:0xf bank_mask:0xf bound_ctrl:1
	v_max_f32_e32 v43, v43, v43
	v_max_f32_e32 v42, v42, v43
	v_sub_f32_e32 v38, v38, v42
	v_mul_f32_e32 v38, 0x3fb8aa3b, v38
	v_exp_f32_e32 v38, v38
	s_nop 1
	v_add_f32_dpp v42, v38, v38 quad_perm:[1,0,3,2] row_mask:0xf bank_mask:0xf bound_ctrl:1
	s_nop 1
	v_add_f32_dpp v42, v42, v42 quad_perm:[2,3,0,1] row_mask:0xf bank_mask:0xf bound_ctrl:1
	s_nop 1
	v_add_f32_dpp v42, v42, v42 row_half_mirror row_mask:0xf bank_mask:0xf bound_ctrl:1
	s_nop 1
	v_mov_b32_dpp v43, v42 row_mirror row_mask:0xf bank_mask:0xf bound_ctrl:1
	s_and_saveexec_b64 s[26:27], vcc
	s_cbranch_execz .LBB0_2522
	v_add_f32_e32 v42, v42, v43
	v_rcp_f32_e32 v42, v42
	s_sub_i32 s19, s18, 24
	s_ashr_i32 s0, s19, 11
	s_ashr_i32 s1, s0, 31
	s_and_b32 s19, s19, 0x7ff
	s_lshl_b64 s[0:1], s[0:1], 17
	v_mul_f32_e32 v38, v38, v42
	v_lshl_add_u64 v[42:43], v[34:35], 0, s[0:1]
	s_lshl_b32 s22, s19, 2
	v_lshl_add_u64 v[42:43], v[42:43], 0, s[22:23]
	global_store_dword v[42:43], v38, off

.Lpeel_exit_17:
	s_mov_b32 s98, 0x3b000000
	s_mov_b32 s99, 0xbcb8aa3b
	s_mov_b32 s100, 1.0
	v_pk_mul_f32 v[236:237], v[158:159], s[98:99] op_sel_hi:[1,0]
	v_pk_mul_f32 v[234:235], v[158:159], s[98:99] op_sel:[0,1] op_sel_hi:[1,1]
	v_exp_f32_e32 v234, v234
	v_exp_f32_e32 v235, v235
	s_nop 0
	v_pk_add_f32 v[234:235], v[234:235], s[100:101] op_sel_hi:[1,0]
	v_rcp_f32_e32 v234, v234
	v_rcp_f32_e32 v235, v235
	s_nop 0
	v_pk_mul_f32 v[236:237], v[236:237], v[234:235]
	v_pk_mul_f32 v[236:237], v[236:237], v[154:155]
	s_ashr_i32 s29, s28, 31
	s_ashr_i32 s27, s26, 31
	s_lshl_b64 s[10:11], s[28:29], 18
	s_lshl_b64 s[26:27], s[26:27], 15
	v_mov_b32_e32 v3, v194
	s_add_u32 s0, s8, s10
	v_med3_f32 v5, v236, s40, v189
	s_nop 15
	s_nop 15
	v_mov_b32_e32 v2, v195
	v_pk_mul_f32 v[238:239], v[160:161], s[98:99] op_sel_hi:[1,0]
	v_pk_mul_f32 v[234:235], v[160:161], s[98:99] op_sel:[0,1] op_sel_hi:[1,1]
	v_exp_f32_e32 v234, v234
	v_exp_f32_e32 v235, v235
	s_nop 0
	v_pk_add_f32 v[234:235], v[234:235], s[100:101] op_sel_hi:[1,0]
	v_rcp_f32_e32 v234, v234
	v_rcp_f32_e32 v235, v235
	s_nop 0
	v_pk_mul_f32 v[238:239], v[238:239], v[234:235]
	v_pk_mul_f32 v[238:239], v[238:239], v[156:157]
	v_add_u32_e32 v4, s49, v3
	s_addc_u32 s1, s9, s11
	s_add_u32 s10, s0, s26
	v_lshl_add_u32 v2, v2, 3, s50
	s_addc_u32 s11, s1, s27
	v_ashrrev_i32_e32 v3, 31, v2
	s_and_b64 vcc, exec, s[6:7]
	v_pk_mul_f32 v[240:241], v[150:151], s[98:99] op_sel_hi:[1,0]
	v_pk_mul_f32 v[234:235], v[150:151], s[98:99] op_sel:[0,1] op_sel_hi:[1,1]
	v_exp_f32_e32 v234, v234
	v_exp_f32_e32 v235, v235
	s_nop 0
	v_pk_add_f32 v[234:235], v[234:235], s[100:101] op_sel_hi:[1,0]
	v_rcp_f32_e32 v234, v234
	v_rcp_f32_e32 v235, v235
	s_nop 0
	v_pk_mul_f32 v[240:241], v[240:241], v[234:235]
	v_pk_mul_f32 v[240:241], v[240:241], v[146:147]
	v_mov_b32_e32 v174, v199
	v_mov_b32_e32 v172, v198
	v_mov_b32_e32 v170, v197
	v_mov_b32_e32 v168, v171
	s_mov_b32 s26, s24
	s_mov_b32 s28, s54
	s_mov_b64 s[30:31], s[12:13]
	v_pk_mul_f32 v[242:243], v[152:153], s[98:99] op_sel_hi:[1,0]
	v_pk_mul_f32 v[234:235], v[152:153], s[98:99] op_sel:[0,1] op_sel_hi:[1,1]
	v_exp_f32_e32 v234, v234
	v_exp_f32_e32 v235, v235
	s_nop 0
	v_pk_add_f32 v[234:235], v[234:235], s[100:101] op_sel_hi:[1,0]
	v_rcp_f32_e32 v234, v234
	v_rcp_f32_e32 v235, v235
	s_nop 0
	v_pk_mul_f32 v[242:243], v[242:243], v[234:235]
	v_pk_mul_f32 v[242:243], v[242:243], v[148:149]
	s_nop 0
	s_nop 0
	v_med3_f32 v13, v237, s40, v189
	v_cvt_pk_fp8_f32 v6, v5, v13
	v_med3_f32 v5, v238, s40, v189
	v_med3_f32 v7, v239, s40, v189
	v_med3_f32 v8, v241, s40, v189
	v_cvt_pk_fp8_f32 v6, v5, v7 op_sel:[0,0,1]
	v_med3_f32 v5, v240, s40, v189
	v_cvt_pk_fp8_f32 v7, v5, v8
	v_med3_f32 v5, v242, s40, v189
	v_med3_f32 v8, v243, s40, v189
	v_cvt_pk_fp8_f32 v7, v5, v8 op_sel:[0,0,1]
	v_ashrrev_i32_e32 v5, 31, v4
	v_lshlrev_b64 v[8:9], 7, v[4:5]
	v_lshl_add_u64 v[8:9], s[10:11], 0, v[8:9]
	v_lshl_add_u64 v[8:9], v[8:9], 0, v[2:3]
	v_pk_mul_f32 v[244:245], v[142:143], s[98:99] op_sel_hi:[1,0]
	v_pk_mul_f32 v[234:235], v[142:143], s[98:99] op_sel:[0,1] op_sel_hi:[1,1]
	v_exp_f32_e32 v234, v234
	v_exp_f32_e32 v235, v235
	s_nop 0
	v_pk_add_f32 v[234:235], v[234:235], s[100:101] op_sel_hi:[1,0]
	v_rcp_f32_e32 v234, v234
	v_rcp_f32_e32 v235, v235
	s_nop 0
	v_pk_mul_f32 v[244:245], v[244:245], v[234:235]
	v_pk_mul_f32 v[244:245], v[244:245], v[138:139]
	global_store_dwordx2 v[8:9], v[6:7], off
	s_nop 0
	s_nop 0
	v_med3_f32 v5, v244, s40, v189
	s_nop 0
	v_pk_mul_f32 v[246:247], v[144:145], s[98:99] op_sel_hi:[1,0]
	v_pk_mul_f32 v[234:235], v[144:145], s[98:99] op_sel:[0,1] op_sel_hi:[1,1]
	v_exp_f32_e32 v234, v234
	v_exp_f32_e32 v235, v235
	s_nop 0
	v_pk_add_f32 v[234:235], v[234:235], s[100:101] op_sel_hi:[1,0]
	v_rcp_f32_e32 v234, v234
	v_rcp_f32_e32 v235, v235
	s_nop 0
	v_pk_mul_f32 v[246:247], v[246:247], v[234:235]
	v_pk_mul_f32 v[246:247], v[246:247], v[140:141]
	v_med3_f32 v7, v245, s40, v189
	s_nop 0
	s_nop 0
	s_nop 0
	v_pk_mul_f32 v[248:249], v[134:135], s[98:99] op_sel_hi:[1,0]
	v_pk_mul_f32 v[234:235], v[134:135], s[98:99] op_sel:[0,1] op_sel_hi:[1,1]
	v_exp_f32_e32 v234, v234
	v_exp_f32_e32 v235, v235
	s_nop 0
	v_pk_add_f32 v[234:235], v[234:235], s[100:101] op_sel_hi:[1,0]
	v_rcp_f32_e32 v234, v234
	v_rcp_f32_e32 v235, v235
	s_nop 0
	v_pk_mul_f32 v[248:249], v[248:249], v[234:235]
	v_pk_mul_f32 v[248:249], v[248:249], v[130:131]
	s_nop 0
	s_nop 0
	s_nop 0
	s_nop 0
	v_pk_mul_f32 v[250:251], v[136:137], s[98:99] op_sel_hi:[1,0]
	v_pk_mul_f32 v[234:235], v[136:137], s[98:99] op_sel:[0,1] op_sel_hi:[1,1]
	v_exp_f32_e32 v234, v234
	v_exp_f32_e32 v235, v235
	s_nop 0
	v_pk_add_f32 v[234:235], v[234:235], s[100:101] op_sel_hi:[1,0]
	v_rcp_f32_e32 v234, v234
	v_rcp_f32_e32 v235, v235
	s_nop 0
	v_pk_mul_f32 v[250:251], v[250:251], v[234:235]
	v_pk_mul_f32 v[250:251], v[250:251], v[132:133]
	s_nop 0
	s_nop 0
	s_nop 0
	s_nop 0
	v_cvt_pk_fp8_f32 v8, v5, v7
	v_med3_f32 v5, v246, s40, v189
	v_med3_f32 v7, v247, s40, v189
	v_cvt_pk_fp8_f32 v8, v5, v7 op_sel:[0,0,1]
	v_med3_f32 v5, v248, s40, v189
	v_med3_f32 v7, v249, s40, v189
	v_cvt_pk_fp8_f32 v9, v5, v7
	v_add_u32_e32 v6, 16, v4
	v_med3_f32 v5, v250, s40, v189
	v_med3_f32 v7, v251, s40, v189
	v_cvt_pk_fp8_f32 v9, v5, v7 op_sel:[0,0,1]
	v_ashrrev_i32_e32 v7, 31, v6
	v_lshlrev_b64 v[6:7], 7, v[6:7]
	v_lshl_add_u64 v[6:7], s[10:11], 0, v[6:7]
	v_lshl_add_u64 v[6:7], v[6:7], 0, v[2:3]
	v_pk_mul_f32 v[236:237], v[126:127], s[98:99] op_sel_hi:[1,0]
	v_pk_mul_f32 v[234:235], v[126:127], s[98:99] op_sel:[0,1] op_sel_hi:[1,1]
	v_exp_f32_e32 v234, v234
	v_exp_f32_e32 v235, v235
	s_nop 0
	v_pk_add_f32 v[234:235], v[234:235], s[100:101] op_sel_hi:[1,0]
	v_rcp_f32_e32 v234, v234
	v_rcp_f32_e32 v235, v235
	s_nop 0
	v_pk_mul_f32 v[236:237], v[236:237], v[234:235]
	v_pk_mul_f32 v[236:237], v[236:237], v[122:123]
	global_store_dwordx2 v[6:7], v[8:9], off
	s_nop 0
	s_nop 0
	v_med3_f32 v5, v236, s40, v189
	s_nop 0
	v_pk_mul_f32 v[238:239], v[128:129], s[98:99] op_sel_hi:[1,0]
	v_pk_mul_f32 v[234:235], v[128:129], s[98:99] op_sel:[0,1] op_sel_hi:[1,1]
	v_exp_f32_e32 v234, v234
	v_exp_f32_e32 v235, v235
	s_nop 0
	v_pk_add_f32 v[234:235], v[234:235], s[100:101] op_sel_hi:[1,0]
	v_rcp_f32_e32 v234, v234
	v_rcp_f32_e32 v235, v235
	s_nop 0
	v_pk_mul_f32 v[238:239], v[238:239], v[234:235]
	v_pk_mul_f32 v[238:239], v[238:239], v[124:125]
	v_med3_f32 v7, v237, s40, v189
	s_nop 0
	s_nop 0
	s_nop 0
	v_pk_mul_f32 v[240:241], v[118:119], s[98:99] op_sel_hi:[1,0]
	v_pk_mul_f32 v[234:235], v[118:119], s[98:99] op_sel:[0,1] op_sel_hi:[1,1]
	v_exp_f32_e32 v234, v234
	v_exp_f32_e32 v235, v235
	s_nop 0
	v_pk_add_f32 v[234:235], v[234:235], s[100:101] op_sel_hi:[1,0]
	v_rcp_f32_e32 v234, v234
	v_rcp_f32_e32 v235, v235
	s_nop 0
	v_pk_mul_f32 v[240:241], v[240:241], v[234:235]
	v_pk_mul_f32 v[240:241], v[240:241], v[114:115]
	s_nop 0
	s_nop 0
	s_nop 0
	s_nop 0
	v_pk_mul_f32 v[242:243], v[120:121], s[98:99] op_sel_hi:[1,0]
	v_pk_mul_f32 v[234:235], v[120:121], s[98:99] op_sel:[0,1] op_sel_hi:[1,1]
	v_exp_f32_e32 v234, v234
	v_exp_f32_e32 v235, v235
	s_nop 0
	v_pk_add_f32 v[234:235], v[234:235], s[100:101] op_sel_hi:[1,0]
	v_rcp_f32_e32 v234, v234
	v_rcp_f32_e32 v235, v235
	s_nop 0
	v_pk_mul_f32 v[242:243], v[242:243], v[234:235]
	v_pk_mul_f32 v[242:243], v[242:243], v[116:117]
	s_nop 0
	s_nop 0
	s_nop 0
	s_nop 0
	v_cvt_pk_fp8_f32 v8, v5, v7
	v_med3_f32 v5, v238, s40, v189
	v_med3_f32 v7, v239, s40, v189
	v_cvt_pk_fp8_f32 v8, v5, v7 op_sel:[0,0,1]
	v_med3_f32 v5, v240, s40, v189
	v_med3_f32 v7, v241, s40, v189
	v_cvt_pk_fp8_f32 v9, v5, v7
	v_add_u32_e32 v6, 32, v4
	v_med3_f32 v5, v242, s40, v189
	v_med3_f32 v7, v243, s40, v189
	v_cvt_pk_fp8_f32 v9, v5, v7 op_sel:[0,0,1]
	v_ashrrev_i32_e32 v7, 31, v6
	v_lshlrev_b64 v[6:7], 7, v[6:7]
	v_lshl_add_u64 v[6:7], s[10:11], 0, v[6:7]
	v_lshl_add_u64 v[6:7], v[6:7], 0, v[2:3]
	v_pk_mul_f32 v[244:245], v[110:111], s[98:99] op_sel_hi:[1,0]
	v_pk_mul_f32 v[234:235], v[110:111], s[98:99] op_sel:[0,1] op_sel_hi:[1,1]
	v_exp_f32_e32 v234, v234
	v_exp_f32_e32 v235, v235
	s_nop 0
	v_pk_add_f32 v[234:235], v[234:235], s[100:101] op_sel_hi:[1,0]
	v_rcp_f32_e32 v234, v234
	v_rcp_f32_e32 v235, v235
	s_nop 0
	v_pk_mul_f32 v[244:245], v[244:245], v[234:235]
	v_pk_mul_f32 v[244:245], v[244:245], v[106:107]
	global_store_dwordx2 v[6:7], v[8:9], off
	s_nop 0
	s_nop 0
	v_med3_f32 v5, v244, s40, v189
	s_nop 0
	v_pk_mul_f32 v[246:247], v[112:113], s[98:99] op_sel_hi:[1,0]
	v_pk_mul_f32 v[234:235], v[112:113], s[98:99] op_sel:[0,1] op_sel_hi:[1,1]
	v_exp_f32_e32 v234, v234
	v_exp_f32_e32 v235, v235
	s_nop 0
	v_pk_add_f32 v[234:235], v[234:235], s[100:101] op_sel_hi:[1,0]
	v_rcp_f32_e32 v234, v234
	v_rcp_f32_e32 v235, v235
	s_nop 0
	v_pk_mul_f32 v[246:247], v[246:247], v[234:235]
	v_pk_mul_f32 v[246:247], v[246:247], v[108:109]
	v_med3_f32 v7, v245, s40, v189
	s_nop 0
	s_nop 0
	s_nop 0
	v_pk_mul_f32 v[248:249], v[102:103], s[98:99] op_sel_hi:[1,0]
	v_pk_mul_f32 v[234:235], v[102:103], s[98:99] op_sel:[0,1] op_sel_hi:[1,1]
	v_exp_f32_e32 v234, v234
	v_exp_f32_e32 v235, v235
	s_nop 0
	v_pk_add_f32 v[234:235], v[234:235], s[100:101] op_sel_hi:[1,0]
	v_rcp_f32_e32 v234, v234
	v_rcp_f32_e32 v235, v235
	s_nop 0
	v_pk_mul_f32 v[248:249], v[248:249], v[234:235]
	v_pk_mul_f32 v[248:249], v[248:249], v[98:99]
	s_nop 0
	s_nop 0
	s_nop 0
	s_nop 0
	v_pk_mul_f32 v[250:251], v[104:105], s[98:99] op_sel_hi:[1,0]
	v_pk_mul_f32 v[234:235], v[104:105], s[98:99] op_sel:[0,1] op_sel_hi:[1,1]
	v_exp_f32_e32 v234, v234
	v_exp_f32_e32 v235, v235
	s_nop 0
	v_pk_add_f32 v[234:235], v[234:235], s[100:101] op_sel_hi:[1,0]
	v_rcp_f32_e32 v234, v234
	v_rcp_f32_e32 v235, v235
	s_nop 0
	v_pk_mul_f32 v[250:251], v[250:251], v[234:235]
	v_pk_mul_f32 v[250:251], v[250:251], v[100:101]
	s_nop 0
	s_nop 0
	s_nop 0
	s_nop 0
	v_cvt_pk_fp8_f32 v8, v5, v7
	v_med3_f32 v5, v246, s40, v189
	v_med3_f32 v7, v247, s40, v189
	v_cvt_pk_fp8_f32 v8, v5, v7 op_sel:[0,0,1]
	v_med3_f32 v5, v248, s40, v189
	v_med3_f32 v7, v249, s40, v189
	v_cvt_pk_fp8_f32 v9, v5, v7
	v_add_u32_e32 v6, 48, v4
	v_med3_f32 v5, v250, s40, v189
	v_med3_f32 v7, v251, s40, v189
	v_cvt_pk_fp8_f32 v9, v5, v7 op_sel:[0,0,1]
	v_ashrrev_i32_e32 v7, 31, v6
	v_lshlrev_b64 v[6:7], 7, v[6:7]
	v_lshl_add_u64 v[6:7], s[10:11], 0, v[6:7]
	v_lshl_add_u64 v[6:7], v[6:7], 0, v[2:3]
	v_pk_mul_f32 v[236:237], v[94:95], s[98:99] op_sel_hi:[1,0]
	v_pk_mul_f32 v[234:235], v[94:95], s[98:99] op_sel:[0,1] op_sel_hi:[1,1]
	v_exp_f32_e32 v234, v234
	v_exp_f32_e32 v235, v235
	s_nop 0
	v_pk_add_f32 v[234:235], v[234:235], s[100:101] op_sel_hi:[1,0]
	v_rcp_f32_e32 v234, v234
	v_rcp_f32_e32 v235, v235
	s_nop 0
	v_pk_mul_f32 v[236:237], v[236:237], v[234:235]
	v_pk_mul_f32 v[236:237], v[236:237], v[90:91]
	global_store_dwordx2 v[6:7], v[8:9], off
	v_add_u32_e32 v6, 0x80, v4
	s_nop 0
	v_med3_f32 v5, v236, s40, v189
	s_nop 0
	v_pk_mul_f32 v[238:239], v[96:97], s[98:99] op_sel_hi:[1,0]
	v_pk_mul_f32 v[234:235], v[96:97], s[98:99] op_sel:[0,1] op_sel_hi:[1,1]
	v_exp_f32_e32 v234, v234
	v_exp_f32_e32 v235, v235
	s_nop 0
	v_pk_add_f32 v[234:235], v[234:235], s[100:101] op_sel_hi:[1,0]
	v_rcp_f32_e32 v234, v234
	v_rcp_f32_e32 v235, v235
	s_nop 0
	v_pk_mul_f32 v[238:239], v[238:239], v[234:235]
	v_pk_mul_f32 v[238:239], v[238:239], v[92:93]
	v_med3_f32 v7, v237, s40, v189
	s_nop 0
	s_nop 0
	s_nop 0
	v_pk_mul_f32 v[240:241], v[86:87], s[98:99] op_sel_hi:[1,0]
	v_pk_mul_f32 v[234:235], v[86:87], s[98:99] op_sel:[0,1] op_sel_hi:[1,1]
	v_exp_f32_e32 v234, v234
	v_exp_f32_e32 v235, v235
	s_nop 0
	v_pk_add_f32 v[234:235], v[234:235], s[100:101] op_sel_hi:[1,0]
	v_rcp_f32_e32 v234, v234
	v_rcp_f32_e32 v235, v235
	s_nop 0
	v_pk_mul_f32 v[240:241], v[240:241], v[234:235]
	v_pk_mul_f32 v[240:241], v[240:241], v[82:83]
	s_nop 0
	s_nop 0
	s_nop 0
	s_nop 0
	v_pk_mul_f32 v[242:243], v[88:89], s[98:99] op_sel_hi:[1,0]
	v_pk_mul_f32 v[234:235], v[88:89], s[98:99] op_sel:[0,1] op_sel_hi:[1,1]
	v_exp_f32_e32 v234, v234
	v_exp_f32_e32 v235, v235
	s_nop 0
	v_pk_add_f32 v[234:235], v[234:235], s[100:101] op_sel_hi:[1,0]
	v_rcp_f32_e32 v234, v234
	v_rcp_f32_e32 v235, v235
	s_nop 0
	v_pk_mul_f32 v[242:243], v[242:243], v[234:235]
	v_pk_mul_f32 v[242:243], v[242:243], v[84:85]
	s_nop 0
	s_nop 0
	s_nop 0
	s_nop 0
	v_cvt_pk_fp8_f32 v8, v5, v7
	v_med3_f32 v5, v238, s40, v189
	v_med3_f32 v7, v239, s40, v189
	v_cvt_pk_fp8_f32 v8, v5, v7 op_sel:[0,0,1]
	v_med3_f32 v5, v240, s40, v189
	v_med3_f32 v7, v241, s40, v189
	v_cvt_pk_fp8_f32 v9, v5, v7
	v_med3_f32 v5, v242, s40, v189
	v_med3_f32 v7, v243, s40, v189
	v_cvt_pk_fp8_f32 v9, v5, v7 op_sel:[0,0,1]
	v_ashrrev_i32_e32 v7, 31, v6
	v_lshlrev_b64 v[6:7], 7, v[6:7]
	v_lshl_add_u64 v[6:7], s[10:11], 0, v[6:7]
	v_lshl_add_u64 v[6:7], v[6:7], 0, v[2:3]
	v_pk_mul_f32 v[244:245], v[78:79], s[98:99] op_sel_hi:[1,0]
	v_pk_mul_f32 v[234:235], v[78:79], s[98:99] op_sel:[0,1] op_sel_hi:[1,1]
	v_exp_f32_e32 v234, v234
	v_exp_f32_e32 v235, v235
	s_nop 0
	v_pk_add_f32 v[234:235], v[234:235], s[100:101] op_sel_hi:[1,0]
	v_rcp_f32_e32 v234, v234
	v_rcp_f32_e32 v235, v235
	s_nop 0
	v_pk_mul_f32 v[244:245], v[244:245], v[234:235]
	v_pk_mul_f32 v[244:245], v[244:245], v[74:75]
	global_store_dwordx2 v[6:7], v[8:9], off
	s_nop 0
	s_nop 0
	v_med3_f32 v5, v244, s40, v189
	s_nop 0
	v_pk_mul_f32 v[246:247], v[80:81], s[98:99] op_sel_hi:[1,0]
	v_pk_mul_f32 v[234:235], v[80:81], s[98:99] op_sel:[0,1] op_sel_hi:[1,1]
	v_exp_f32_e32 v234, v234
	v_exp_f32_e32 v235, v235
	s_nop 0
	v_pk_add_f32 v[234:235], v[234:235], s[100:101] op_sel_hi:[1,0]
	v_rcp_f32_e32 v234, v234
	v_rcp_f32_e32 v235, v235
	s_nop 0
	v_pk_mul_f32 v[246:247], v[246:247], v[234:235]
	v_pk_mul_f32 v[246:247], v[246:247], v[76:77]
	v_med3_f32 v7, v245, s40, v189
	s_nop 0
	s_nop 0
	s_nop 0
	v_pk_mul_f32 v[248:249], v[70:71], s[98:99] op_sel_hi:[1,0]
	v_pk_mul_f32 v[234:235], v[70:71], s[98:99] op_sel:[0,1] op_sel_hi:[1,1]
	v_exp_f32_e32 v234, v234
	v_exp_f32_e32 v235, v235
	s_nop 0
	v_pk_add_f32 v[234:235], v[234:235], s[100:101] op_sel_hi:[1,0]
	v_rcp_f32_e32 v234, v234
	v_rcp_f32_e32 v235, v235
	s_nop 0
	v_pk_mul_f32 v[248:249], v[248:249], v[234:235]
	v_pk_mul_f32 v[248:249], v[248:249], v[66:67]
	s_nop 0
	s_nop 0
	s_nop 0
	s_nop 0
	v_pk_mul_f32 v[250:251], v[72:73], s[98:99] op_sel_hi:[1,0]
	v_pk_mul_f32 v[234:235], v[72:73], s[98:99] op_sel:[0,1] op_sel_hi:[1,1]
	v_exp_f32_e32 v234, v234
	v_exp_f32_e32 v235, v235
	s_nop 0
	v_pk_add_f32 v[234:235], v[234:235], s[100:101] op_sel_hi:[1,0]
	v_rcp_f32_e32 v234, v234
	v_rcp_f32_e32 v235, v235
	s_nop 0
	v_pk_mul_f32 v[250:251], v[250:251], v[234:235]
	v_pk_mul_f32 v[250:251], v[250:251], v[68:69]
	s_nop 0
	s_nop 0
	s_nop 0
	s_nop 0
	v_cvt_pk_fp8_f32 v8, v5, v7
	v_med3_f32 v5, v246, s40, v189
	v_med3_f32 v7, v247, s40, v189
	v_cvt_pk_fp8_f32 v8, v5, v7 op_sel:[0,0,1]
	v_med3_f32 v5, v248, s40, v189
	v_med3_f32 v7, v249, s40, v189
	v_cvt_pk_fp8_f32 v9, v5, v7
	v_add_u32_e32 v6, 0x90, v4
	v_med3_f32 v5, v250, s40, v189
	v_med3_f32 v7, v251, s40, v189
	v_cvt_pk_fp8_f32 v9, v5, v7 op_sel:[0,0,1]
	v_ashrrev_i32_e32 v7, 31, v6
	v_lshlrev_b64 v[6:7], 7, v[6:7]
	v_lshl_add_u64 v[6:7], s[10:11], 0, v[6:7]
	v_lshl_add_u64 v[6:7], v[6:7], 0, v[2:3]
	v_pk_mul_f32 v[236:237], v[62:63], s[98:99] op_sel_hi:[1,0]
	v_pk_mul_f32 v[234:235], v[62:63], s[98:99] op_sel:[0,1] op_sel_hi:[1,1]
	v_exp_f32_e32 v234, v234
	v_exp_f32_e32 v235, v235
	s_nop 0
	v_pk_add_f32 v[234:235], v[234:235], s[100:101] op_sel_hi:[1,0]
	v_rcp_f32_e32 v234, v234
	v_rcp_f32_e32 v235, v235
	s_nop 0
	v_pk_mul_f32 v[236:237], v[236:237], v[234:235]
	v_pk_mul_f32 v[236:237], v[236:237], v[58:59]
	global_store_dwordx2 v[6:7], v[8:9], off
	s_nop 0
	s_nop 0
	v_med3_f32 v5, v236, s40, v189
	s_nop 0
	v_pk_mul_f32 v[238:239], v[64:65], s[98:99] op_sel_hi:[1,0]
	v_pk_mul_f32 v[234:235], v[64:65], s[98:99] op_sel:[0,1] op_sel_hi:[1,1]
	v_exp_f32_e32 v234, v234
	v_exp_f32_e32 v235, v235
	s_nop 0
	v_pk_add_f32 v[234:235], v[234:235], s[100:101] op_sel_hi:[1,0]
	v_rcp_f32_e32 v234, v234
	v_rcp_f32_e32 v235, v235
	s_nop 0
	v_pk_mul_f32 v[238:239], v[238:239], v[234:235]
	v_pk_mul_f32 v[238:239], v[238:239], v[60:61]
	v_med3_f32 v7, v237, s40, v189
	s_nop 0
	s_nop 0
	s_nop 0
	v_pk_mul_f32 v[240:241], v[54:55], s[98:99] op_sel_hi:[1,0]
	v_pk_mul_f32 v[234:235], v[54:55], s[98:99] op_sel:[0,1] op_sel_hi:[1,1]
	v_exp_f32_e32 v234, v234
	v_exp_f32_e32 v235, v235
	s_nop 0
	v_pk_add_f32 v[234:235], v[234:235], s[100:101] op_sel_hi:[1,0]
	v_rcp_f32_e32 v234, v234
	v_rcp_f32_e32 v235, v235
	s_nop 0
	v_pk_mul_f32 v[240:241], v[240:241], v[234:235]
	v_pk_mul_f32 v[240:241], v[240:241], v[50:51]
	s_nop 0
	s_nop 0
	s_nop 0
	s_nop 0
	v_pk_mul_f32 v[242:243], v[56:57], s[98:99] op_sel_hi:[1,0]
	v_pk_mul_f32 v[234:235], v[56:57], s[98:99] op_sel:[0,1] op_sel_hi:[1,1]
	v_exp_f32_e32 v234, v234
	v_exp_f32_e32 v235, v235
	s_nop 0
	v_pk_add_f32 v[234:235], v[234:235], s[100:101] op_sel_hi:[1,0]
	v_rcp_f32_e32 v234, v234
	v_rcp_f32_e32 v235, v235
	s_nop 0
	v_pk_mul_f32 v[242:243], v[242:243], v[234:235]
	v_pk_mul_f32 v[242:243], v[242:243], v[52:53]
	s_nop 0
	s_nop 0
	s_nop 0
	s_nop 0
	v_cvt_pk_fp8_f32 v8, v5, v7
	v_med3_f32 v5, v238, s40, v189
	v_med3_f32 v7, v239, s40, v189
	v_cvt_pk_fp8_f32 v8, v5, v7 op_sel:[0,0,1]
	v_med3_f32 v5, v240, s40, v189
	v_med3_f32 v7, v241, s40, v189
	v_cvt_pk_fp8_f32 v9, v5, v7
	v_add_u32_e32 v6, 0xa0, v4
	v_med3_f32 v5, v242, s40, v189
	v_med3_f32 v7, v243, s40, v189
	v_cvt_pk_fp8_f32 v9, v5, v7 op_sel:[0,0,1]
	v_ashrrev_i32_e32 v7, 31, v6
	v_lshlrev_b64 v[6:7], 7, v[6:7]
	v_lshl_add_u64 v[6:7], s[10:11], 0, v[6:7]
	v_lshl_add_u64 v[6:7], v[6:7], 0, v[2:3]
	v_pk_mul_f32 v[244:245], v[46:47], s[98:99] op_sel_hi:[1,0]
	v_pk_mul_f32 v[234:235], v[46:47], s[98:99] op_sel:[0,1] op_sel_hi:[1,1]
	v_exp_f32_e32 v234, v234
	v_exp_f32_e32 v235, v235
	s_nop 0
	v_pk_add_f32 v[234:235], v[234:235], s[100:101] op_sel_hi:[1,0]
	v_rcp_f32_e32 v234, v234
	v_rcp_f32_e32 v235, v235
	s_nop 0
	v_pk_mul_f32 v[244:245], v[244:245], v[234:235]
	v_pk_mul_f32 v[244:245], v[244:245], v[42:43]
	global_store_dwordx2 v[6:7], v[8:9], off
	v_add_u32_e32 v4, 0xb0, v4
	s_nop 0
	v_med3_f32 v5, v244, s40, v189
	s_nop 0
	v_pk_mul_f32 v[246:247], v[48:49], s[98:99] op_sel_hi:[1,0]
	v_pk_mul_f32 v[234:235], v[48:49], s[98:99] op_sel:[0,1] op_sel_hi:[1,1]
	v_exp_f32_e32 v234, v234
	v_exp_f32_e32 v235, v235
	s_nop 0
	v_pk_add_f32 v[234:235], v[234:235], s[100:101] op_sel_hi:[1,0]
	v_rcp_f32_e32 v234, v234
	v_rcp_f32_e32 v235, v235
	s_nop 0
	v_pk_mul_f32 v[246:247], v[246:247], v[234:235]
	v_pk_mul_f32 v[246:247], v[246:247], v[44:45]
	s_nop 0
	s_nop 0
	v_pk_mul_f32 v[248:249], v[38:39], s[98:99] op_sel_hi:[1,0]
	v_pk_mul_f32 v[234:235], v[38:39], s[98:99] op_sel:[0,1] op_sel_hi:[1,1]
	v_exp_f32_e32 v234, v234
	v_exp_f32_e32 v235, v235
	s_nop 0
	v_pk_add_f32 v[234:235], v[234:235], s[100:101] op_sel_hi:[1,0]
	v_rcp_f32_e32 v234, v234
	v_rcp_f32_e32 v235, v235
	s_nop 0
	v_pk_mul_f32 v[248:249], v[248:249], v[234:235]
	v_pk_mul_f32 v[248:249], v[248:249], v[34:35]
	s_nop 0
	s_nop 0
	v_pk_mul_f32 v[250:251], v[40:41], s[98:99] op_sel_hi:[1,0]
	v_pk_mul_f32 v[234:235], v[40:41], s[98:99] op_sel:[0,1] op_sel_hi:[1,1]
	v_exp_f32_e32 v234, v234
	v_exp_f32_e32 v235, v235
	s_nop 0
	v_pk_add_f32 v[234:235], v[234:235], s[100:101] op_sel_hi:[1,0]
	v_rcp_f32_e32 v234, v234
	v_rcp_f32_e32 v235, v235
	s_nop 0
	v_pk_mul_f32 v[250:251], v[250:251], v[234:235]
	v_pk_mul_f32 v[250:251], v[250:251], v[36:37]
	s_nop 0
	s_nop 0
	v_med3_f32 v13, v245, s40, v189
	v_cvt_pk_fp8_f32 v6, v5, v13
	v_med3_f32 v5, v246, s40, v189
	v_med3_f32 v7, v247, s40, v189
	v_med3_f32 v8, v249, s40, v189
	v_cvt_pk_fp8_f32 v6, v5, v7 op_sel:[0,0,1]
	v_med3_f32 v5, v248, s40, v189
	v_cvt_pk_fp8_f32 v7, v5, v8
	v_med3_f32 v5, v250, s40, v189
	v_med3_f32 v8, v251, s40, v189
	v_cvt_pk_fp8_f32 v7, v5, v8 op_sel:[0,0,1]
	v_ashrrev_i32_e32 v5, 31, v4
	v_lshlrev_b64 v[4:5], 7, v[4:5]
	v_lshl_add_u64 v[4:5], s[10:11], 0, v[4:5]
	v_lshl_add_u64 v[2:3], v[4:5], 0, v[2:3]
	global_store_dwordx2 v[2:3], v[6:7], off
	s_cbranch_vccz .LBB0_2738
	s_waitcnt vmcnt(0)
	s_cmpk_gt_u32 s42, 0xff
	s_cbranch_scc1 .LBB0_2684
	s_barrier
	s_branch .LBB0_2684

.Lpeel_exit_18:
	v_pk_mul_f32 v[8:9], v[142:143], s[14:15] op_sel_hi:[1,0]
	v_pk_mul_f32 v[6:7], v[144:145], s[14:15] op_sel_hi:[1,0]
	v_med3_f32 v14, v8, s47, v172
	v_med3_f32 v9, v9, s47, v172
	v_cvt_pk_fp8_f32 v8, v14, v9
	v_pk_mul_f32 v[12:13], v[138:139], s[14:15] op_sel_hi:[1,0]
	v_pk_mul_f32 v[10:11], v[140:141], s[14:15] op_sel_hi:[1,0]
	v_med3_f32 v6, v6, s47, v172
	v_med3_f32 v7, v7, s47, v172
	v_med3_f32 v12, v12, s47, v172
	v_med3_f32 v13, v13, s47, v172
	v_mov_b32_e32 v3, v1
	v_mov_b32_e32 v2, v166
	s_lshl_b32 s0, s48, 8
	v_cvt_pk_fp8_f32 v9, v12, v13
	v_cvt_pk_fp8_f32 v8, v6, v7 op_sel:[0,0,1]
	v_med3_f32 v6, v10, s47, v172
	v_med3_f32 v7, v11, s47, v172
	v_pk_mul_f32 v[10:11], v[134:135], s[14:15] op_sel_hi:[1,0]
	s_nop 15
	s_nop 15
	s_or_b32 s0, s0, s42
	v_pk_mul_f32 v[14:15], v[130:131], s[14:15] op_sel_hi:[1,0]
	v_med3_f32 v17, v10, s47, v172
	v_med3_f32 v11, v11, s47, v172
	v_lshl_add_u32 v2, v2, 3, s0
	s_lshl_b32 s0, s24, 8
	v_cvt_pk_fp8_f32 v10, v17, v11
	v_med3_f32 v14, v14, s47, v172
	v_med3_f32 v15, v15, s47, v172
	s_add_i32 s0, s0, s15
	v_cvt_pk_fp8_f32 v11, v14, v15
	v_add_u32_e32 v16, s0, v3
	v_cvt_pk_fp8_f32 v9, v6, v7 op_sel:[0,0,1]
	v_pk_mul_f32 v[6:7], v[136:137], s[14:15] op_sel_hi:[1,0]
	v_mov_b32_e32 v4, v16
	v_pk_mul_f32 v[12:13], v[132:133], s[14:15] op_sel_hi:[1,0]
	v_med3_f32 v6, v6, s47, v172
	v_med3_f32 v7, v7, s47, v172
	v_cvt_pk_fp8_f32 v10, v6, v7 op_sel:[0,0,1]
	v_ashrrev_i32_e32 v5, 31, v4
	v_med3_f32 v6, v12, s47, v172
	v_med3_f32 v7, v13, s47, v172
	v_lshlrev_b64 v[4:5], 10, v[4:5]
	v_cvt_pk_fp8_f32 v11, v6, v7 op_sel:[0,0,1]
	v_ashrrev_i32_e32 v3, 31, v2
	v_lshl_add_u64 v[4:5], s[10:11], 0, v[4:5]
	v_lshl_add_u64 v[4:5], v[4:5], 0, v[2:3]
	global_store_dwordx2 v[4:5], v[8:9], off
	global_store_dwordx2 v[4:5], v[10:11], off offset:128
	v_pk_mul_f32 v[8:9], v[126:127], s[14:15] op_sel_hi:[1,0]
	v_pk_mul_f32 v[6:7], v[128:129], s[14:15] op_sel_hi:[1,0]
	v_med3_f32 v14, v8, s47, v172
	v_med3_f32 v9, v9, s47, v172
	v_cvt_pk_fp8_f32 v8, v14, v9
	v_pk_mul_f32 v[12:13], v[122:123], s[14:15] op_sel_hi:[1,0]
	v_pk_mul_f32 v[10:11], v[124:125], s[14:15] op_sel_hi:[1,0]
	v_med3_f32 v6, v6, s47, v172
	v_med3_f32 v7, v7, s47, v172
	v_med3_f32 v12, v12, s47, v172
	v_med3_f32 v13, v13, s47, v172
	v_cvt_pk_fp8_f32 v9, v12, v13
	v_cvt_pk_fp8_f32 v8, v6, v7 op_sel:[0,0,1]
	v_med3_f32 v6, v10, s47, v172
	v_med3_f32 v7, v11, s47, v172
	v_pk_mul_f32 v[10:11], v[118:119], s[14:15] op_sel_hi:[1,0]
	v_pk_mul_f32 v[14:15], v[114:115], s[14:15] op_sel_hi:[1,0]
	v_med3_f32 v17, v10, s47, v172
	v_med3_f32 v11, v11, s47, v172
	v_cvt_pk_fp8_f32 v10, v17, v11
	v_med3_f32 v14, v14, s47, v172
	v_med3_f32 v15, v15, s47, v172
	v_cvt_pk_fp8_f32 v11, v14, v15
	v_cvt_pk_fp8_f32 v9, v6, v7 op_sel:[0,0,1]
	v_pk_mul_f32 v[6:7], v[120:121], s[14:15] op_sel_hi:[1,0]
	v_add_u32_e32 v4, 16, v16
	v_pk_mul_f32 v[12:13], v[116:117], s[14:15] op_sel_hi:[1,0]
	v_med3_f32 v6, v6, s47, v172
	v_med3_f32 v7, v7, s47, v172
	v_cvt_pk_fp8_f32 v10, v6, v7 op_sel:[0,0,1]
	v_ashrrev_i32_e32 v5, 31, v4
	v_med3_f32 v6, v12, s47, v172
	v_med3_f32 v7, v13, s47, v172
	v_lshlrev_b64 v[4:5], 10, v[4:5]
	v_cvt_pk_fp8_f32 v11, v6, v7 op_sel:[0,0,1]
	v_lshl_add_u64 v[4:5], s[10:11], 0, v[4:5]
	v_lshl_add_u64 v[4:5], v[4:5], 0, v[2:3]
	global_store_dwordx2 v[4:5], v[8:9], off
	global_store_dwordx2 v[4:5], v[10:11], off offset:128
	v_pk_mul_f32 v[8:9], v[110:111], s[14:15] op_sel_hi:[1,0]
	v_pk_mul_f32 v[6:7], v[112:113], s[14:15] op_sel_hi:[1,0]
	v_med3_f32 v14, v8, s47, v172
	v_med3_f32 v9, v9, s47, v172
	v_cvt_pk_fp8_f32 v8, v14, v9
	v_pk_mul_f32 v[12:13], v[106:107], s[14:15] op_sel_hi:[1,0]
	v_pk_mul_f32 v[10:11], v[108:109], s[14:15] op_sel_hi:[1,0]
	v_med3_f32 v6, v6, s47, v172
	v_med3_f32 v7, v7, s47, v172
	v_med3_f32 v12, v12, s47, v172
	v_med3_f32 v13, v13, s47, v172
	v_cvt_pk_fp8_f32 v9, v12, v13
	v_cvt_pk_fp8_f32 v8, v6, v7 op_sel:[0,0,1]
	v_med3_f32 v6, v10, s47, v172
	v_med3_f32 v7, v11, s47, v172
	v_pk_mul_f32 v[10:11], v[102:103], s[14:15] op_sel_hi:[1,0]
	v_pk_mul_f32 v[14:15], v[98:99], s[14:15] op_sel_hi:[1,0]
	v_med3_f32 v17, v10, s47, v172
	v_med3_f32 v11, v11, s47, v172
	v_cvt_pk_fp8_f32 v10, v17, v11
	v_med3_f32 v14, v14, s47, v172
	v_med3_f32 v15, v15, s47, v172
	v_cvt_pk_fp8_f32 v11, v14, v15
	v_cvt_pk_fp8_f32 v9, v6, v7 op_sel:[0,0,1]
	v_pk_mul_f32 v[6:7], v[104:105], s[14:15] op_sel_hi:[1,0]
	v_add_u32_e32 v4, 32, v16
	v_pk_mul_f32 v[12:13], v[100:101], s[14:15] op_sel_hi:[1,0]
	v_med3_f32 v6, v6, s47, v172
	v_med3_f32 v7, v7, s47, v172
	v_cvt_pk_fp8_f32 v10, v6, v7 op_sel:[0,0,1]
	v_ashrrev_i32_e32 v5, 31, v4
	v_med3_f32 v6, v12, s47, v172
	v_med3_f32 v7, v13, s47, v172
	v_lshlrev_b64 v[4:5], 10, v[4:5]
	v_cvt_pk_fp8_f32 v11, v6, v7 op_sel:[0,0,1]
	v_lshl_add_u64 v[4:5], s[10:11], 0, v[4:5]
	v_lshl_add_u64 v[4:5], v[4:5], 0, v[2:3]
	global_store_dwordx2 v[4:5], v[8:9], off
	global_store_dwordx2 v[4:5], v[10:11], off offset:128
	v_pk_mul_f32 v[8:9], v[94:95], s[14:15] op_sel_hi:[1,0]
	v_pk_mul_f32 v[6:7], v[96:97], s[14:15] op_sel_hi:[1,0]
	v_med3_f32 v14, v8, s47, v172
	v_med3_f32 v9, v9, s47, v172
	v_cvt_pk_fp8_f32 v8, v14, v9
	v_pk_mul_f32 v[12:13], v[90:91], s[14:15] op_sel_hi:[1,0]
	v_pk_mul_f32 v[10:11], v[92:93], s[14:15] op_sel_hi:[1,0]
	v_med3_f32 v6, v6, s47, v172
	v_med3_f32 v7, v7, s47, v172
	v_med3_f32 v12, v12, s47, v172
	v_med3_f32 v13, v13, s47, v172
	v_cvt_pk_fp8_f32 v9, v12, v13
	v_cvt_pk_fp8_f32 v8, v6, v7 op_sel:[0,0,1]
	v_med3_f32 v6, v10, s47, v172
	v_med3_f32 v7, v11, s47, v172
	v_pk_mul_f32 v[10:11], v[86:87], s[14:15] op_sel_hi:[1,0]
	v_pk_mul_f32 v[14:15], v[82:83], s[14:15] op_sel_hi:[1,0]
	v_med3_f32 v17, v10, s47, v172
	v_med3_f32 v11, v11, s47, v172
	v_cvt_pk_fp8_f32 v10, v17, v11
	v_med3_f32 v14, v14, s47, v172
	v_med3_f32 v15, v15, s47, v172
	v_cvt_pk_fp8_f32 v11, v14, v15
	v_cvt_pk_fp8_f32 v9, v6, v7 op_sel:[0,0,1]
	v_pk_mul_f32 v[6:7], v[88:89], s[14:15] op_sel_hi:[1,0]
	v_add_u32_e32 v4, 48, v16
	v_pk_mul_f32 v[12:13], v[84:85], s[14:15] op_sel_hi:[1,0]
	v_med3_f32 v6, v6, s47, v172
	v_med3_f32 v7, v7, s47, v172
	v_cvt_pk_fp8_f32 v10, v6, v7 op_sel:[0,0,1]
	v_ashrrev_i32_e32 v5, 31, v4
	v_med3_f32 v6, v12, s47, v172
	v_med3_f32 v7, v13, s47, v172
	v_lshlrev_b64 v[4:5], 10, v[4:5]
	v_cvt_pk_fp8_f32 v11, v6, v7 op_sel:[0,0,1]
	v_lshl_add_u64 v[4:5], s[10:11], 0, v[4:5]
	v_lshl_add_u64 v[4:5], v[4:5], 0, v[2:3]
	global_store_dwordx2 v[4:5], v[8:9], off
	global_store_dwordx2 v[4:5], v[10:11], off offset:128
	v_pk_mul_f32 v[8:9], v[78:79], s[14:15] op_sel_hi:[1,0]
	v_pk_mul_f32 v[6:7], v[80:81], s[14:15] op_sel_hi:[1,0]
	v_med3_f32 v14, v8, s47, v172
	v_med3_f32 v9, v9, s47, v172
	v_cvt_pk_fp8_f32 v8, v14, v9
	v_pk_mul_f32 v[12:13], v[74:75], s[14:15] op_sel_hi:[1,0]
	v_pk_mul_f32 v[10:11], v[76:77], s[14:15] op_sel_hi:[1,0]
	v_med3_f32 v6, v6, s47, v172
	v_med3_f32 v7, v7, s47, v172
	v_med3_f32 v12, v12, s47, v172
	v_med3_f32 v13, v13, s47, v172
	v_cvt_pk_fp8_f32 v9, v12, v13
	v_cvt_pk_fp8_f32 v8, v6, v7 op_sel:[0,0,1]
	v_med3_f32 v6, v10, s47, v172
	v_med3_f32 v7, v11, s47, v172
	v_pk_mul_f32 v[10:11], v[70:71], s[14:15] op_sel_hi:[1,0]
	v_pk_mul_f32 v[14:15], v[66:67], s[14:15] op_sel_hi:[1,0]
	v_med3_f32 v17, v10, s47, v172
	v_med3_f32 v11, v11, s47, v172
	v_cvt_pk_fp8_f32 v10, v17, v11
	v_med3_f32 v14, v14, s47, v172
	v_med3_f32 v15, v15, s47, v172
	v_cvt_pk_fp8_f32 v11, v14, v15
	v_cvt_pk_fp8_f32 v9, v6, v7 op_sel:[0,0,1]
	v_pk_mul_f32 v[6:7], v[72:73], s[14:15] op_sel_hi:[1,0]
	v_add_u32_e32 v4, 0x80, v16
	v_pk_mul_f32 v[12:13], v[68:69], s[14:15] op_sel_hi:[1,0]
	v_med3_f32 v6, v6, s47, v172
	v_med3_f32 v7, v7, s47, v172
	v_cvt_pk_fp8_f32 v10, v6, v7 op_sel:[0,0,1]
	v_ashrrev_i32_e32 v5, 31, v4
	v_med3_f32 v6, v12, s47, v172
	v_med3_f32 v7, v13, s47, v172
	v_lshlrev_b64 v[4:5], 10, v[4:5]
	v_cvt_pk_fp8_f32 v11, v6, v7 op_sel:[0,0,1]
	v_lshl_add_u64 v[4:5], s[10:11], 0, v[4:5]
	v_lshl_add_u64 v[4:5], v[4:5], 0, v[2:3]
	global_store_dwordx2 v[4:5], v[8:9], off
	global_store_dwordx2 v[4:5], v[10:11], off offset:128
	v_pk_mul_f32 v[8:9], v[62:63], s[14:15] op_sel_hi:[1,0]
	v_pk_mul_f32 v[6:7], v[64:65], s[14:15] op_sel_hi:[1,0]
	v_med3_f32 v14, v8, s47, v172
	v_med3_f32 v9, v9, s47, v172
	v_cvt_pk_fp8_f32 v8, v14, v9
	v_pk_mul_f32 v[12:13], v[58:59], s[14:15] op_sel_hi:[1,0]
	v_pk_mul_f32 v[10:11], v[60:61], s[14:15] op_sel_hi:[1,0]
	v_med3_f32 v6, v6, s47, v172
	v_med3_f32 v7, v7, s47, v172
	v_med3_f32 v12, v12, s47, v172
	v_med3_f32 v13, v13, s47, v172
	v_cvt_pk_fp8_f32 v9, v12, v13
	v_cvt_pk_fp8_f32 v8, v6, v7 op_sel:[0,0,1]
	v_med3_f32 v6, v10, s47, v172
	v_med3_f32 v7, v11, s47, v172
	v_pk_mul_f32 v[10:11], v[54:55], s[14:15] op_sel_hi:[1,0]
	v_pk_mul_f32 v[14:15], v[50:51], s[14:15] op_sel_hi:[1,0]
	v_med3_f32 v17, v10, s47, v172
	v_med3_f32 v11, v11, s47, v172
	v_cvt_pk_fp8_f32 v10, v17, v11
	v_med3_f32 v14, v14, s47, v172
	v_med3_f32 v15, v15, s47, v172
	v_cvt_pk_fp8_f32 v11, v14, v15
	v_cvt_pk_fp8_f32 v9, v6, v7 op_sel:[0,0,1]
	v_pk_mul_f32 v[6:7], v[56:57], s[14:15] op_sel_hi:[1,0]
	v_add_u32_e32 v4, 0x90, v16
	v_pk_mul_f32 v[12:13], v[52:53], s[14:15] op_sel_hi:[1,0]
	v_med3_f32 v6, v6, s47, v172
	v_med3_f32 v7, v7, s47, v172
	v_cvt_pk_fp8_f32 v10, v6, v7 op_sel:[0,0,1]
	v_ashrrev_i32_e32 v5, 31, v4
	v_med3_f32 v6, v12, s47, v172
	v_med3_f32 v7, v13, s47, v172
	v_lshlrev_b64 v[4:5], 10, v[4:5]
	v_cvt_pk_fp8_f32 v11, v6, v7 op_sel:[0,0,1]
	v_lshl_add_u64 v[4:5], s[10:11], 0, v[4:5]
	v_lshl_add_u64 v[4:5], v[4:5], 0, v[2:3]
	global_store_dwordx2 v[4:5], v[8:9], off
	global_store_dwordx2 v[4:5], v[10:11], off offset:128
	v_pk_mul_f32 v[8:9], v[46:47], s[14:15] op_sel_hi:[1,0]
	v_pk_mul_f32 v[6:7], v[48:49], s[14:15] op_sel_hi:[1,0]
	v_med3_f32 v14, v8, s47, v172
	v_med3_f32 v9, v9, s47, v172
	v_cvt_pk_fp8_f32 v8, v14, v9
	v_pk_mul_f32 v[12:13], v[42:43], s[14:15] op_sel_hi:[1,0]
	v_pk_mul_f32 v[10:11], v[44:45], s[14:15] op_sel_hi:[1,0]
	v_med3_f32 v6, v6, s47, v172
	v_med3_f32 v7, v7, s47, v172
	v_med3_f32 v12, v12, s47, v172
	v_med3_f32 v13, v13, s47, v172
	v_cvt_pk_fp8_f32 v9, v12, v13
	v_cvt_pk_fp8_f32 v8, v6, v7 op_sel:[0,0,1]
	v_med3_f32 v6, v10, s47, v172
	v_med3_f32 v7, v11, s47, v172
	v_pk_mul_f32 v[10:11], v[38:39], s[14:15] op_sel_hi:[1,0]
	v_pk_mul_f32 v[14:15], v[34:35], s[14:15] op_sel_hi:[1,0]
	v_med3_f32 v17, v10, s47, v172
	v_med3_f32 v11, v11, s47, v172
	v_cvt_pk_fp8_f32 v10, v17, v11
	v_med3_f32 v14, v14, s47, v172
	v_med3_f32 v15, v15, s47, v172
	v_cvt_pk_fp8_f32 v11, v14, v15
	v_cvt_pk_fp8_f32 v9, v6, v7 op_sel:[0,0,1]
	v_pk_mul_f32 v[6:7], v[40:41], s[14:15] op_sel_hi:[1,0]
	v_add_u32_e32 v4, 0xa0, v16
	v_pk_mul_f32 v[12:13], v[36:37], s[14:15] op_sel_hi:[1,0]
	v_med3_f32 v6, v6, s47, v172
	v_med3_f32 v7, v7, s47, v172
	v_cvt_pk_fp8_f32 v10, v6, v7 op_sel:[0,0,1]
	v_ashrrev_i32_e32 v5, 31, v4
	v_med3_f32 v6, v12, s47, v172
	v_med3_f32 v7, v13, s47, v172
	v_lshlrev_b64 v[4:5], 10, v[4:5]
	v_cvt_pk_fp8_f32 v11, v6, v7 op_sel:[0,0,1]
	v_lshl_add_u64 v[4:5], s[10:11], 0, v[4:5]
	v_lshl_add_u64 v[4:5], v[4:5], 0, v[2:3]
	global_store_dwordx2 v[4:5], v[8:9], off
	global_store_dwordx2 v[4:5], v[10:11], off offset:128
	v_pk_mul_f32 v[8:9], v[30:31], s[14:15] op_sel_hi:[1,0]
	v_pk_mul_f32 v[6:7], v[32:33], s[14:15] op_sel_hi:[1,0]
	v_med3_f32 v14, v8, s47, v172
	v_med3_f32 v9, v9, s47, v172
	v_cvt_pk_fp8_f32 v8, v14, v9
	v_pk_mul_f32 v[12:13], v[26:27], s[14:15] op_sel_hi:[1,0]
	v_pk_mul_f32 v[10:11], v[28:29], s[14:15] op_sel_hi:[1,0]
	v_med3_f32 v6, v6, s47, v172
	v_med3_f32 v7, v7, s47, v172
	v_med3_f32 v12, v12, s47, v172
	v_med3_f32 v13, v13, s47, v172
	v_cvt_pk_fp8_f32 v9, v12, v13
	v_cvt_pk_fp8_f32 v8, v6, v7 op_sel:[0,0,1]
	v_med3_f32 v6, v10, s47, v172
	v_med3_f32 v7, v11, s47, v172
	v_pk_mul_f32 v[10:11], v[22:23], s[14:15] op_sel_hi:[1,0]
	v_add_u32_e32 v4, 0xb0, v16
	v_pk_mul_f32 v[14:15], v[18:19], s[14:15] op_sel_hi:[1,0]
	v_med3_f32 v16, v10, s47, v172
	v_med3_f32 v11, v11, s47, v172
	v_cvt_pk_fp8_f32 v10, v16, v11
	v_med3_f32 v14, v14, s47, v172
	v_med3_f32 v15, v15, s47, v172
	v_cvt_pk_fp8_f32 v11, v14, v15
	v_cvt_pk_fp8_f32 v9, v6, v7 op_sel:[0,0,1]
	v_pk_mul_f32 v[6:7], v[24:25], s[14:15] op_sel_hi:[1,0]
	v_pk_mul_f32 v[12:13], v[20:21], s[14:15] op_sel_hi:[1,0]
	v_med3_f32 v6, v6, s47, v172
	v_med3_f32 v7, v7, s47, v172
	v_cvt_pk_fp8_f32 v10, v6, v7 op_sel:[0,0,1]
	v_ashrrev_i32_e32 v5, 31, v4
	v_med3_f32 v6, v12, s47, v172
	v_med3_f32 v7, v13, s47, v172
	v_lshlrev_b64 v[4:5], 10, v[4:5]
	v_cvt_pk_fp8_f32 v11, v6, v7 op_sel:[0,0,1]
	v_lshl_add_u64 v[4:5], s[10:11], 0, v[4:5]
	v_lshl_add_u64 v[2:3], v[4:5], 0, v[2:3]
	s_and_b64 vcc, exec, s[6:7]
	s_mov_b32 s48, s16
	s_mov_b32 s24, s18
	s_mov_b64 s[26:27], s[22:23]
	s_mov_b64 s[28:29], s[20:21]
	global_store_dwordx2 v[2:3], v[8:9], off
	global_store_dwordx2 v[2:3], v[10:11], off offset:128
	s_cbranch_vccz .LBB0_2809
	s_waitcnt vmcnt(0)
	s_cmpk_gt_u32 s4, 0xff
	s_cbranch_scc1 .LBB0_2820
	s_barrier
